# GEMM K-loops: m0 write moved ahead of the address add so the LDS-DMA hazard nop is gone (95 sites)
# speedup vs baseline: 1.0117x; 1.0059x over previous
; #define PG8_STAGE(bufoff, gbase) do { _Pragma("unroll") for (int _i = 0; _i < 2; ++_i) \
;         __builtin_amdgcn_global_load_lds((const unsigned*)((const char*)(gbase) + voff[_i]), (LAS unsigned*)(lds + (bufoff) + ldsw + _i * 8192), 16, 0, 0); } while (0)
; #define PG8_LDA(dst, b, h) do { _Pragma("unroll") for (int m = 0; m < 4; ++m) _Pragma("unroll") for (int k = 0; k < 2; ++k) dst[m][k] = *(const LAS bf16x8*)(lds + PG8_SA(b, h) + aoff + m * 2048 + k * 1024); } while (0)
; #define PG8_LDB(dst, b, h) do { _Pragma("unroll") for (int n = 0; n < 2; ++n) _Pragma("unroll") for (int k = 0; k < 2; ++k) dst[n][k] = *(const LAS bf16x8*)(lds + PG8_SB(b, h) + boff + n * 2048 + k * 1024); } while (0)
; #define PG8_WAIT_L(n) asm volatile("s_waitcnt lgkmcnt(" #n ")" ::: "memory")
; #define PG8_BAR __builtin_amdgcn_s_barrier()
; #define PG8_SCHED __builtin_amdgcn_sched_barrier(0)
;     ...
;             PG8_LDB(B0, 0, 0); PG8_SCHED; PG8_LDA(At, 0, 0); PG8_STAGE(PG8_SA(1, 1), a1 + hstep);
;             PG8_WAIT_L(8); PG8_BAR; PG8_WAIT_L(0); PG8_MMA(0, 0, At, B0); PG8_BAR; PG8_SCHED;
;             PG8_LDB(B1, 0, 1); PG8_STAGE(PG8_SB(0, 0), b2);
;             PG8_BAR; PG8_WAIT_L(0); PG8_MMA(0, 1, At, B1); PG8_BAR;
;             PG8_LDA(At, 0, 1); PG8_STAGE(PG8_SA(0, 0), a2);
;             PG8_BAR; PG8_WAIT_L(0); PG8_MMA(1, 0, At, B0); PG8_BAR; PG8_SCHED;
.LBB0_161:
	s_add_u32 s0, s10, 0xfffc0080
	s_addc_u32 s1, s11, -1
	s_add_i32 s29, 0, 0x10000
	v_add_u32_e32 v162, s29, v1
	ds_read_b128 v[158:161], v162
	ds_read_b128 v[168:171], v162 offset:1024
	ds_read_b128 v[172:175], v162 offset:2048
	ds_read_b128 v[194:197], v162 offset:3072
	s_cmp_eq_u32 s28, 12
	s_cselect_b32 s15, s4, s1
	s_cselect_b32 s14, s7, s0
	s_cselect_b32 s13, s18, s23
	s_cselect_b32 s12, s19, s22
	v_lshl_add_u64 v[162:163], s[10:11], 0, v[154:155]
	s_add_i32 m0, s17, 0xc000
	ds_read_b128 v[198:201], v166
	ds_read_b128 v[202:205], v166 offset:1024
	ds_read_b128 v[206:209], v166 offset:2048
	ds_read_b128 v[210:213], v166 offset:3072
	ds_read_b128 v[214:217], v166 offset:4096
	ds_read_b128 v[218:221], v166 offset:5120
	ds_read_b128 v[222:225], v166 offset:6144
	ds_read_b128 v[226:229], v166 offset:7168
	global_load_lds_dwordx4 v[162:163], off
	s_add_i32 m0, s17, 0xe000
	v_lshl_add_u64 v[162:163], s[10:11], 0, v[156:157]
	global_load_lds_dwordx4 v[162:163], off
	s_waitcnt lgkmcnt(8)
	s_barrier
	s_waitcnt lgkmcnt(0)
	s_setprio 1
	v_mfma_f32_16x16x32_bf16 v[126:129], v[198:201], v[158:161], v[126:129]
	v_mfma_f32_16x16x32_bf16 v[110:113], v[198:201], v[172:175], v[110:113]
	v_mfma_f32_16x16x32_bf16 v[122:125], v[206:209], v[158:161], v[122:125]
	v_mfma_f32_16x16x32_bf16 v[106:109], v[206:209], v[172:175], v[106:109]
	v_mfma_f32_16x16x32_bf16 v[118:121], v[214:217], v[158:161], v[118:121]
	v_mfma_f32_16x16x32_bf16 v[102:105], v[214:217], v[172:175], v[102:105]
	v_mfma_f32_16x16x32_bf16 v[114:117], v[222:225], v[158:161], v[114:117]
	v_mfma_f32_16x16x32_bf16 v[94:97], v[222:225], v[172:175], v[94:97]
	v_mfma_f32_16x16x32_bf16 v[126:129], v[202:205], v[168:171], v[126:129]
	v_mfma_f32_16x16x32_bf16 v[110:113], v[202:205], v[194:197], v[110:113]
	v_mfma_f32_16x16x32_bf16 v[122:125], v[210:213], v[168:171], v[122:125]
	v_mfma_f32_16x16x32_bf16 v[106:109], v[210:213], v[194:197], v[106:109]
	v_mfma_f32_16x16x32_bf16 v[118:121], v[218:221], v[168:171], v[118:121]
	v_mfma_f32_16x16x32_bf16 v[102:105], v[218:221], v[194:197], v[102:105]
	v_mfma_f32_16x16x32_bf16 v[114:117], v[226:229], v[168:171], v[114:117]
	v_mfma_f32_16x16x32_bf16 v[94:97], v[226:229], v[194:197], v[94:97]
	s_setprio 0
	s_barrier
	s_add_i32 s0, 0, 0x14000
	v_add_u32_e32 v162, s0, v1
	s_add_i32 s1, s29, s16
	ds_read_b128 v[230:233], v162
	ds_read_b128 v[234:237], v162 offset:1024
	ds_read_b128 v[238:241], v162 offset:2048
	ds_read_b128 v[242:245], v162 offset:3072
	v_lshl_add_u64 v[162:163], s[12:13], 0, v[132:133]
	s_mov_b32 m0, s1
	v_lshl_add_u64 v[246:247], s[12:13], 0, v[130:131]
	global_load_lds_dwordx4 v[162:163], off
	s_add_i32 m0, s1, 0x2000
	s_nop 0
	global_load_lds_dwordx4 v[246:247], off
	s_barrier
	s_waitcnt lgkmcnt(0)
	s_setprio 1
	v_mfma_f32_16x16x32_bf16 v[82:85], v[198:201], v[230:233], v[82:85]
	v_mfma_f32_16x16x32_bf16 v[50:53], v[198:201], v[238:241], v[50:53]
	v_mfma_f32_16x16x32_bf16 v[74:77], v[206:209], v[230:233], v[74:77]
	v_mfma_f32_16x16x32_bf16 v[42:45], v[206:209], v[238:241], v[42:45]
	v_mfma_f32_16x16x32_bf16 v[66:69], v[214:217], v[230:233], v[66:69]
	v_mfma_f32_16x16x32_bf16 v[38:41], v[214:217], v[238:241], v[38:41]
	v_mfma_f32_16x16x32_bf16 v[58:61], v[222:225], v[230:233], v[58:61]
	v_mfma_f32_16x16x32_bf16 v[30:33], v[222:225], v[238:241], v[30:33]
	v_mfma_f32_16x16x32_bf16 v[82:85], v[202:205], v[234:237], v[82:85]
	v_mfma_f32_16x16x32_bf16 v[50:53], v[202:205], v[242:245], v[50:53]
	v_mfma_f32_16x16x32_bf16 v[74:77], v[210:213], v[234:237], v[74:77]
	v_mfma_f32_16x16x32_bf16 v[42:45], v[210:213], v[242:245], v[42:45]
	v_mfma_f32_16x16x32_bf16 v[66:69], v[218:221], v[234:237], v[66:69]
	v_mfma_f32_16x16x32_bf16 v[38:41], v[218:221], v[242:245], v[38:41]
	v_mfma_f32_16x16x32_bf16 v[58:61], v[226:229], v[234:237], v[58:61]
	v_mfma_f32_16x16x32_bf16 v[30:33], v[226:229], v[242:245], v[30:33]
	s_setprio 0
	s_mov_b32 m0, s17
	v_lshl_add_u64 v[248:249], s[14:15], 0, v[132:133]
	s_barrier
	ds_read_b128 v[198:201], v166 offset:16384
	ds_read_b128 v[202:205], v166 offset:17408
	ds_read_b128 v[206:209], v166 offset:18432
	ds_read_b128 v[210:213], v166 offset:19456
	ds_read_b128 v[214:217], v166 offset:20480
	ds_read_b128 v[218:221], v166 offset:21504
	ds_read_b128 v[222:225], v166 offset:22528
	ds_read_b128 v[226:229], v166 offset:23552
	global_load_lds_dwordx4 v[248:249], off
	s_mov_b32 m0, s20
	v_lshl_add_u64 v[192:193], s[14:15], 0, v[130:131]
	global_load_lds_dwordx4 v[192:193], off
	s_barrier
	s_waitcnt lgkmcnt(0)
	s_setprio 1
	v_mfma_f32_16x16x32_bf16 v[98:101], v[198:201], v[158:161], v[98:101]
	v_mfma_f32_16x16x32_bf16 v[70:73], v[198:201], v[172:175], v[70:73]
	v_mfma_f32_16x16x32_bf16 v[90:93], v[206:209], v[158:161], v[90:93]
	v_mfma_f32_16x16x32_bf16 v[62:65], v[206:209], v[172:175], v[62:65]
	v_mfma_f32_16x16x32_bf16 v[86:89], v[214:217], v[158:161], v[86:89]
	v_mfma_f32_16x16x32_bf16 v[54:57], v[214:217], v[172:175], v[54:57]
	v_mfma_f32_16x16x32_bf16 v[78:81], v[222:225], v[158:161], v[78:81]
	v_mfma_f32_16x16x32_bf16 v[46:49], v[222:225], v[172:175], v[46:49]
	v_mfma_f32_16x16x32_bf16 v[98:101], v[202:205], v[168:171], v[98:101]
	v_mfma_f32_16x16x32_bf16 v[70:73], v[202:205], v[194:197], v[70:73]
	v_mfma_f32_16x16x32_bf16 v[90:93], v[210:213], v[168:171], v[90:93]
	v_mfma_f32_16x16x32_bf16 v[62:65], v[210:213], v[194:197], v[62:65]
	v_mfma_f32_16x16x32_bf16 v[86:89], v[218:221], v[168:171], v[86:89]
	v_mfma_f32_16x16x32_bf16 v[54:57], v[218:221], v[194:197], v[54:57]
	v_mfma_f32_16x16x32_bf16 v[78:81], v[226:229], v[168:171], v[78:81]
	v_mfma_f32_16x16x32_bf16 v[46:49], v[226:229], v[194:197], v[46:49]
	s_setprio 0
	s_barrier
; #define PG8_STAGE(bufoff, gbase) do { _Pragma("unroll") for (int _i = 0; _i < 2; ++_i) \
;         __builtin_amdgcn_global_load_lds((const unsigned*)((const char*)(gbase) + voff[_i]), (LAS unsigned*)(lds + (bufoff) + ldsw + _i * 8192), 16, 0, 0); } while (0)
; #define PG8_LDA(dst, b, h) do { _Pragma("unroll") for (int m = 0; m < 4; ++m) _Pragma("unroll") for (int k = 0; k < 2; ++k) dst[m][k] = *(const LAS bf16x8*)(lds + PG8_SA(b, h) + aoff + m * 2048 + k * 1024); } while (0)
; #define PG8_LDB(dst, b, h) do { _Pragma("unroll") for (int n = 0; n < 2; ++n) _Pragma("unroll") for (int k = 0; k < 2; ++k) dst[n][k] = *(const LAS bf16x8*)(lds + PG8_SB(b, h) + boff + n * 2048 + k * 1024); } while (0)
; #define PG8_WAIT_V(n) asm volatile("s_waitcnt vmcnt(" #n ")" ::: "memory")
; #define PG8_WAIT_L(n) asm volatile("s_waitcnt lgkmcnt(" #n ")" ::: "memory")
; #define PG8_BAR __builtin_amdgcn_s_barrier()
; #define PG8_SCHED __builtin_amdgcn_sched_barrier(0)
;     ...
;             PG8_STAGE(PG8_SB(0, 1), b2 + hstep);
;             PG8_WAIT_V(6); PG8_BAR; PG8_MMA(1, 1, At, B1); PG8_BAR;
;             PG8_LDB(B0, 1, 0); PG8_SCHED; PG8_LDA(At, 1, 0); PG8_STAGE(PG8_SA(0, 1), a2 + hstep);
;             PG8_WAIT_L(8); PG8_BAR; PG8_WAIT_L(0); PG8_MMA(0, 0, At, B0); PG8_BAR; PG8_SCHED;
;             PG8_LDB(B1, 1, 1); PG8_STAGE(PG8_SB(1, 0), b3);
;             PG8_BAR; PG8_WAIT_L(0); PG8_MMA(0, 1, At, B1); PG8_BAR;
;             PG8_LDA(At, 1, 1); PG8_STAGE(PG8_SA(1, 0), a3);
;             PG8_BAR; PG8_WAIT_L(0); PG8_MMA(1, 0, At, B0); PG8_BAR; PG8_SCHED;
	s_add_u32 s30, s12, 0x40000
	s_addc_u32 s31, s13, 0
	s_add_i32 s0, s0, s16
	s_mov_b32 m0, s0
	v_lshl_add_u64 v[158:159], s[30:31], 0, v[132:133]
	global_load_lds_dwordx4 v[158:159], off
	s_add_i32 m0, s0, 0x2000
	v_lshl_add_u64 v[158:159], s[30:31], 0, v[130:131]
	global_load_lds_dwordx4 v[158:159], off
	s_waitcnt vmcnt(6)
	s_barrier
	s_setprio 1
	v_mfma_f32_16x16x32_bf16 v[34:37], v[198:201], v[230:233], v[34:37]
	v_mfma_f32_16x16x32_bf16 v[14:17], v[198:201], v[238:241], v[14:17]
	v_mfma_f32_16x16x32_bf16 v[26:29], v[206:209], v[230:233], v[26:29]
	v_mfma_f32_16x16x32_bf16 v[10:13], v[206:209], v[238:241], v[10:13]
	v_mfma_f32_16x16x32_bf16 v[22:25], v[214:217], v[230:233], v[22:25]
	v_mfma_f32_16x16x32_bf16 v[6:9], v[214:217], v[238:241], v[6:9]
	v_mfma_f32_16x16x32_bf16 v[18:21], v[222:225], v[230:233], v[18:21]
	v_mfma_f32_16x16x32_bf16 v[2:5], v[222:225], v[238:241], v[2:5]
	v_mfma_f32_16x16x32_bf16 v[34:37], v[202:205], v[234:237], v[34:37]
	v_mfma_f32_16x16x32_bf16 v[14:17], v[202:205], v[242:245], v[14:17]
	v_mfma_f32_16x16x32_bf16 v[26:29], v[210:213], v[234:237], v[26:29]
	v_mfma_f32_16x16x32_bf16 v[10:13], v[210:213], v[242:245], v[10:13]
	v_mfma_f32_16x16x32_bf16 v[22:25], v[218:221], v[234:237], v[22:25]
	v_mfma_f32_16x16x32_bf16 v[6:9], v[218:221], v[242:245], v[6:9]
	v_mfma_f32_16x16x32_bf16 v[18:21], v[226:229], v[234:237], v[18:21]
	v_mfma_f32_16x16x32_bf16 v[2:5], v[226:229], v[242:245], v[2:5]
	s_setprio 0
	s_add_i32 s0, 0, 0x18000
	v_add_u32_e32 v194, s0, v1
	s_barrier
	ds_read_b128 v[158:161], v194
	ds_read_b128 v[168:171], v194 offset:1024
	ds_read_b128 v[172:175], v194 offset:2048
	ds_read_b128 v[194:197], v194 offset:3072
	s_add_u32 s14, s14, 0x40000
	s_addc_u32 s15, s15, 0
	s_mov_b32 m0, s40
	v_lshl_add_u64 v[230:231], s[14:15], 0, v[132:133]
	ds_read_b128 v[198:201], v166 offset:32768
	ds_read_b128 v[202:205], v166 offset:33792
	ds_read_b128 v[206:209], v166 offset:34816
	ds_read_b128 v[210:213], v166 offset:35840
	ds_read_b128 v[214:217], v166 offset:36864
	ds_read_b128 v[218:221], v166 offset:37888
	ds_read_b128 v[222:225], v166 offset:38912
	ds_read_b128 v[226:229], v166 offset:39936
	global_load_lds_dwordx4 v[230:231], off
	s_mov_b32 m0, s41
	v_lshl_add_u64 v[230:231], s[14:15], 0, v[130:131]
	global_load_lds_dwordx4 v[230:231], off
	s_waitcnt lgkmcnt(8)
	s_barrier
	s_waitcnt lgkmcnt(0)
	s_setprio 1
	v_mfma_f32_16x16x32_bf16 v[126:129], v[198:201], v[158:161], v[126:129]
	v_mfma_f32_16x16x32_bf16 v[110:113], v[198:201], v[172:175], v[110:113]
	v_mfma_f32_16x16x32_bf16 v[122:125], v[206:209], v[158:161], v[122:125]
	v_mfma_f32_16x16x32_bf16 v[106:109], v[206:209], v[172:175], v[106:109]
	v_mfma_f32_16x16x32_bf16 v[118:121], v[214:217], v[158:161], v[118:121]
	v_mfma_f32_16x16x32_bf16 v[102:105], v[214:217], v[172:175], v[102:105]
	v_mfma_f32_16x16x32_bf16 v[114:117], v[222:225], v[158:161], v[114:117]
	v_mfma_f32_16x16x32_bf16 v[94:97], v[222:225], v[172:175], v[94:97]
	v_mfma_f32_16x16x32_bf16 v[126:129], v[202:205], v[168:171], v[126:129]
	v_mfma_f32_16x16x32_bf16 v[110:113], v[202:205], v[194:197], v[110:113]
	v_mfma_f32_16x16x32_bf16 v[122:125], v[210:213], v[168:171], v[122:125]
	v_mfma_f32_16x16x32_bf16 v[106:109], v[210:213], v[194:197], v[106:109]
	v_mfma_f32_16x16x32_bf16 v[118:121], v[218:221], v[168:171], v[118:121]
	v_mfma_f32_16x16x32_bf16 v[102:105], v[218:221], v[194:197], v[102:105]
	v_mfma_f32_16x16x32_bf16 v[114:117], v[226:229], v[168:171], v[114:117]
	v_mfma_f32_16x16x32_bf16 v[94:97], v[226:229], v[194:197], v[94:97]
	s_setprio 0
	s_barrier
	s_add_i32 s1, 0, 0x1c000
	s_add_i32 s0, s0, s16
	v_add_u32_e32 v242, s1, v1
	v_lshl_add_u64 v[162:163], v[162:163], 0, s[88:89]
	s_mov_b32 m0, s0
	ds_read_b128 v[230:233], v242
	ds_read_b128 v[234:237], v242 offset:1024
	ds_read_b128 v[238:241], v242 offset:2048
	ds_read_b128 v[242:245], v242 offset:3072
	global_load_lds_dwordx4 v[162:163], off
	s_add_i32 m0, s0, 0x2000
	v_lshl_add_u64 v[162:163], v[246:247], 0, s[88:89]
	global_load_lds_dwordx4 v[162:163], off
	s_barrier
	s_waitcnt lgkmcnt(0)
	s_setprio 1
	v_mfma_f32_16x16x32_bf16 v[82:85], v[198:201], v[230:233], v[82:85]
	v_mfma_f32_16x16x32_bf16 v[50:53], v[198:201], v[238:241], v[50:53]
	v_mfma_f32_16x16x32_bf16 v[74:77], v[206:209], v[230:233], v[74:77]
	v_mfma_f32_16x16x32_bf16 v[42:45], v[206:209], v[238:241], v[42:45]
	v_mfma_f32_16x16x32_bf16 v[66:69], v[214:217], v[230:233], v[66:69]
	v_mfma_f32_16x16x32_bf16 v[38:41], v[214:217], v[238:241], v[38:41]
	v_mfma_f32_16x16x32_bf16 v[58:61], v[222:225], v[230:233], v[58:61]
	v_mfma_f32_16x16x32_bf16 v[30:33], v[222:225], v[238:241], v[30:33]
	v_mfma_f32_16x16x32_bf16 v[82:85], v[202:205], v[234:237], v[82:85]
	v_mfma_f32_16x16x32_bf16 v[50:53], v[202:205], v[242:245], v[50:53]
	v_mfma_f32_16x16x32_bf16 v[74:77], v[210:213], v[234:237], v[74:77]
	v_mfma_f32_16x16x32_bf16 v[42:45], v[210:213], v[242:245], v[42:45]
	v_mfma_f32_16x16x32_bf16 v[66:69], v[218:221], v[234:237], v[66:69]
	v_mfma_f32_16x16x32_bf16 v[38:41], v[218:221], v[242:245], v[38:41]
	v_mfma_f32_16x16x32_bf16 v[58:61], v[226:229], v[234:237], v[58:61]
	v_mfma_f32_16x16x32_bf16 v[30:33], v[226:229], v[242:245], v[30:33]
	s_setprio 0
	s_mov_b32 m0, s58
	v_lshl_add_u64 v[162:163], v[248:249], 0, s[88:89]
	s_barrier
	ds_read_b128 v[198:201], v166 offset:49152
	ds_read_b128 v[202:205], v166 offset:50176
	ds_read_b128 v[206:209], v166 offset:51200
	ds_read_b128 v[210:213], v166 offset:52224
	ds_read_b128 v[214:217], v166 offset:53248
	ds_read_b128 v[218:221], v166 offset:54272
	ds_read_b128 v[222:225], v166 offset:55296
	ds_read_b128 v[226:229], v166 offset:56320
	global_load_lds_dwordx4 v[162:163], off
	s_mov_b32 m0, s59
	v_lshl_add_u64 v[162:163], v[192:193], 0, s[88:89]
	global_load_lds_dwordx4 v[162:163], off
	s_barrier
; #define PG8_STAGE(bufoff, gbase) do { _Pragma("unroll") for (int _i = 0; _i < 2; ++_i) \
;         __builtin_amdgcn_global_load_lds((const unsigned*)((const char*)(gbase) + voff[_i]), (LAS unsigned*)(lds + (bufoff) + ldsw + _i * 8192), 16, 0, 0); } while (0)
; #define PG8_WAIT_V(n) asm volatile("s_waitcnt vmcnt(" #n ")" ::: "memory")
; #define PG8_WAIT_L(n) asm volatile("s_waitcnt lgkmcnt(" #n ")" ::: "memory")
; #define PG8_BAR __builtin_amdgcn_s_barrier()
; #define PG8_SCHED __builtin_amdgcn_sched_barrier(0)
;     ...
;             PG8_BAR; PG8_WAIT_L(0); PG8_MMA(1, 0, At, B0); PG8_BAR; PG8_SCHED;
;             PG8_STAGE(PG8_SB(1, 1), b3 + hstep);
;             PG8_WAIT_V(6); PG8_BAR; PG8_MMA(1, 1, At, B1); PG8_BAR;
;     __device__ __forceinline__ void operator()(Acc& acc, int pm, int pn, int wr, int wc, int fr, int fq) const {
;         if (pn >= 8) { store_vT(acc, vT, (pn - 8) * 256, pm, wr, wc, fr, fq); return; }
;         const int head = pn * 4 + wc;
;         const bool isk = head >= 16;
;         const float* g = isk ? kg : qg;
;         const float sc = isk ? 1.0f : 0.125f;
;         float gv[2][2];
; #pragma unroll
;         for (int bj = 0; bj < 2; ++bj)
; #pragma unroll
;             for (int n = 0; n < 2; ++n) gv[bj][n] = g[bj * 32 + n * 16 + fr] * sc;
; #pragma unroll
;         for (int ai = 0; ai < 2; ++ai)
; #pragma unroll
;             for (int m = 0; m < 4; ++m)
; #pragma unroll
;                 for (int j = 0; j < 4; ++j) {
;                     float ss = acc[ai][0][m][0][j] * acc[ai][0][m][0][j] + acc[ai][0][m][1][j] * acc[ai][0][m][1][j] +
;                                acc[ai][1][m][0][j] * acc[ai][1][m][0][j] + acc[ai][1][m][1][j] * acc[ai][1][m][1][j];
;                     ss += __shfl_xor(ss, 1); ss += __shfl_xor(ss, 2); ss += __shfl_xor(ss, 4); ss += __shfl_xor(ss, 8);
;                     const float rs = rsqrtf(ss * (1.0f / 64.0f) + EPSV);
	s_waitcnt lgkmcnt(0)
	s_setprio 1
	v_mfma_f32_16x16x32_bf16 v[98:101], v[198:201], v[158:161], v[98:101]
	v_mfma_f32_16x16x32_bf16 v[70:73], v[198:201], v[172:175], v[70:73]
	v_mfma_f32_16x16x32_bf16 v[90:93], v[206:209], v[158:161], v[90:93]
	v_mfma_f32_16x16x32_bf16 v[62:65], v[206:209], v[172:175], v[62:65]
	v_mfma_f32_16x16x32_bf16 v[86:89], v[214:217], v[158:161], v[86:89]
	v_mfma_f32_16x16x32_bf16 v[54:57], v[214:217], v[172:175], v[54:57]
	v_mfma_f32_16x16x32_bf16 v[78:81], v[222:225], v[158:161], v[78:81]
	v_mfma_f32_16x16x32_bf16 v[46:49], v[222:225], v[172:175], v[46:49]
	v_mfma_f32_16x16x32_bf16 v[98:101], v[202:205], v[168:171], v[98:101]
	v_mfma_f32_16x16x32_bf16 v[70:73], v[202:205], v[194:197], v[70:73]
	v_mfma_f32_16x16x32_bf16 v[90:93], v[210:213], v[168:171], v[90:93]
	v_mfma_f32_16x16x32_bf16 v[62:65], v[210:213], v[194:197], v[62:65]
	v_mfma_f32_16x16x32_bf16 v[86:89], v[218:221], v[168:171], v[86:89]
	v_mfma_f32_16x16x32_bf16 v[54:57], v[218:221], v[194:197], v[54:57]
	v_mfma_f32_16x16x32_bf16 v[78:81], v[226:229], v[168:171], v[78:81]
	v_mfma_f32_16x16x32_bf16 v[46:49], v[226:229], v[194:197], v[46:49]
	s_setprio 0
	s_barrier
	s_add_u32 s12, s12, 0x40080
	s_addc_u32 s13, s13, 0
	s_add_i32 s0, s1, s16
	s_mov_b32 m0, s0
	v_lshl_add_u64 v[158:159], s[12:13], 0, v[132:133]
	global_load_lds_dwordx4 v[158:159], off
	s_add_i32 m0, s0, 0x2000
	v_lshl_add_u64 v[158:159], s[12:13], 0, v[130:131]
	global_load_lds_dwordx4 v[158:159], off
	s_waitcnt vmcnt(6)
	s_barrier
	s_setprio 1
	v_mfma_f32_16x16x32_bf16 v[34:37], v[198:201], v[230:233], v[34:37]
	v_mfma_f32_16x16x32_bf16 v[14:17], v[198:201], v[238:241], v[14:17]
	v_mfma_f32_16x16x32_bf16 v[26:29], v[206:209], v[230:233], v[26:29]
	v_mfma_f32_16x16x32_bf16 v[10:13], v[206:209], v[238:241], v[10:13]
	v_mfma_f32_16x16x32_bf16 v[22:25], v[214:217], v[230:233], v[22:25]
	v_mfma_f32_16x16x32_bf16 v[6:9], v[214:217], v[238:241], v[6:9]
	v_mfma_f32_16x16x32_bf16 v[18:21], v[222:225], v[230:233], v[18:21]
	v_mfma_f32_16x16x32_bf16 v[2:5], v[222:225], v[238:241], v[2:5]
	v_mfma_f32_16x16x32_bf16 v[34:37], v[202:205], v[234:237], v[34:37]
	v_mfma_f32_16x16x32_bf16 v[14:17], v[202:205], v[242:245], v[14:17]
	v_mfma_f32_16x16x32_bf16 v[26:29], v[210:213], v[234:237], v[26:29]
	v_mfma_f32_16x16x32_bf16 v[10:13], v[210:213], v[242:245], v[10:13]
	v_mfma_f32_16x16x32_bf16 v[22:25], v[218:221], v[234:237], v[22:25]
	v_mfma_f32_16x16x32_bf16 v[6:9], v[218:221], v[242:245], v[6:9]
	v_mfma_f32_16x16x32_bf16 v[18:21], v[226:229], v[234:237], v[18:21]
	v_mfma_f32_16x16x32_bf16 v[2:5], v[226:229], v[242:245], v[2:5]
	s_setprio 0
	s_add_i32 s28, s28, 2
	s_add_u32 s10, s10, 0x100
	s_addc_u32 s11, s11, 0
	s_add_u32 s22, s22, 0x100
	s_addc_u32 s23, s23, 0
	s_cmp_gt_u32 s28, 13
	s_barrier
	s_cbranch_scc0 .LBB0_161
	s_cmp_lt_i32 s95, 8
	s_mov_b64 s[10:11], -1
	s_cbranch_scc0 .LBB0_164
	s_lshl_b32 s0, s95, 2
	s_or_b32 s0, s0, s90
	s_cmp_gt_i32 s0, 15
	s_cselect_b64 s[10:11], -1, 0
	v_readlane_b32 s60, v254, 42
	v_cndmask_b32_e64 v158, v189, 1.0, s[10:11]
	s_and_b64 s[10:11], s[10:11], exec
	v_readlane_b32 s72, v254, 54
	v_readlane_b32 s73, v254, 55
	v_readlane_b32 s74, v254, 56
	v_readlane_b32 s75, v254, 57
	s_cselect_b32 s11, s75, s73
	s_cselect_b32 s10, s74, s72
	global_load_dword v159, v167, s[10:11]
	v_mov_b32_e32 v162, v126
	v_mov_b32_e32 v163, v110
	v_mov_b32_e32 v198, v127
	v_mov_b32_e32 v199, v111
	v_pk_mul_f32 v[162:163], v[162:163], v[162:163]
	v_mov_b32_e32 v194, v82
	v_mov_b32_e32 v195, v50
	v_pk_mul_f32 v[198:199], v[198:199], v[198:199]
	v_mov_b32_e32 v200, v83
	v_mov_b32_e32 v201, v51
	v_pk_mul_f32 v[194:195], v[194:195], v[194:195]
	v_pk_mul_f32 v[200:201], v[200:201], v[200:201]
	v_mov_b32_e32 v202, v198
	v_mov_b32_e32 v203, v162
	v_mov_b32_e32 v162, v199
	v_cmp_lt_i32_e32 vcc, v188, v182
	v_pk_add_f32 v[162:163], v[202:203], v[162:163]
	v_mov_b32_e32 v198, v200
	v_mov_b32_e32 v199, v194
	v_pk_add_f32 v[162:163], v[162:163], v[198:199]
	v_mov_b32_e32 v194, v201
	v_pk_add_f32 v[162:163], v[162:163], v[194:195]
	s_mov_b32 s4, 0x358637bd
	v_lshl_add_u32 v160, s5, 8, v164
	v_ashrrev_i32_e32 v161, 31, v160
	v_lshlrev_b64 v[196:197], 12, v[160:161]
	v_mov_b32_e32 v200, v129
	v_mov_b32_e32 v201, v113
	v_pk_mul_f32 v[200:201], v[200:201], v[200:201]
	v_mov_b32_e32 v202, v85
	v_mov_b32_e32 v203, v53
	v_pk_mul_f32 v[202:203], v[202:203], v[202:203]
	v_mov_b32_e32 v204, v200
	v_mov_b32_e32 v200, v202
	v_or_b32_e32 v198, 2, v160
	v_ashrrev_i32_e32 v199, 31, v198
	v_lshlrev_b64 v[198:199], 12, v[198:199]
	v_mov_b32_e32 v202, v75
	v_readlane_b32 s74, v255, 22
	v_readlane_b32 s61, v254, 43
	v_readlane_b32 s62, v254, 44
	v_readlane_b32 s63, v254, 45
	v_readlane_b32 s64, v254, 46
	v_readlane_b32 s65, v254, 47
	v_readlane_b32 s66, v254, 48
	v_readlane_b32 s67, v254, 49
	v_readlane_b32 s68, v254, 50
	v_readlane_b32 s69, v254, 51
	v_readlane_b32 s70, v254, 52
	v_readlane_b32 s71, v254, 53
	v_readlane_b32 s75, v255, 23
	s_waitcnt vmcnt(0)
	v_mul_f32_e32 v168, v158, v159
	global_load_dword v159, v167, s[10:11] offset:64
	s_waitcnt vmcnt(0)
	v_mul_f32_e32 v169, v158, v159
	global_load_dword v159, v167, s[10:11] offset:128
	s_waitcnt vmcnt(0)
	v_mul_f32_e32 v170, v158, v159
	global_load_dword v159, v167, s[10:11] offset:192
	s_lshl_b32 s10, s0, 6
	s_ashr_i32 s11, s10, 31
	s_waitcnt vmcnt(0)
	v_mul_f32_e32 v171, v158, v159
	v_cndmask_b32_e32 v158, v180, v188, vcc
	v_lshlrev_b32_e32 v175, 2, v158
	ds_bpermute_b32 v195, v175, v163
	ds_bpermute_b32 v194, v175, v162
	v_cmp_lt_i32_e32 vcc, v187, v182
	s_waitcnt lgkmcnt(0)
; __device__ __forceinline__ unsigned f2bf(float f) { const __bf16 b = (__bf16)f; return (unsigned)__builtin_bit_cast(unsigned short, b); }
;     __device__ __forceinline__ void operator()(Acc& acc, int pm, int pn, int wr, int wc, int fr, int fq) const {
;     ...
;                     float ss = acc[ai][0][m][0][j] * acc[ai][0][m][0][j] + acc[ai][0][m][1][j] * acc[ai][0][m][1][j] +
;                                acc[ai][1][m][0][j] * acc[ai][1][m][0][j] + acc[ai][1][m][1][j] * acc[ai][1][m][1][j];
;                     ss += __shfl_xor(ss, 1); ss += __shfl_xor(ss, 2); ss += __shfl_xor(ss, 4); ss += __shfl_xor(ss, 8);
;                     const float rs = rsqrtf(ss * (1.0f / 64.0f) + EPSV);
;                     bf16_t* rp = qk + (size_t)(pm * 256 + ai * 128 + wr * 64 + m * 16 + fq * 4 + j) * 2048 + head * 64 + fr;
; #pragma unroll
;                     for (int bj = 0; bj < 2; ++bj)
; #pragma unroll
;                         for (int n = 0; n < 2; ++n) rp[bj * 32 + n * 16] = (bf16_t)f2bf(acc[ai][bj][m][n][j] * rs * gv[bj][n]);
	v_pk_add_f32 v[162:163], v[162:163], v[194:195]
	v_cndmask_b32_e32 v158, v180, v187, vcc
	v_lshlrev_b32_e32 v174, 2, v158
	ds_bpermute_b32 v195, v174, v163
	ds_bpermute_b32 v194, v174, v162
	v_cmp_lt_i32_e32 vcc, v186, v182
	s_waitcnt lgkmcnt(0)
	v_pk_add_f32 v[162:163], v[162:163], v[194:195]
	v_cndmask_b32_e32 v158, v180, v186, vcc
	v_lshlrev_b32_e32 v173, 2, v158
	ds_bpermute_b32 v195, v173, v163
	ds_bpermute_b32 v194, v173, v162
	v_cmp_lt_i32_e32 vcc, v185, v182
	s_waitcnt lgkmcnt(0)
	v_pk_add_f32 v[162:163], v[162:163], v[194:195]
	v_cndmask_b32_e32 v158, v180, v185, vcc
	v_lshlrev_b32_e32 v172, 2, v158
	ds_bpermute_b32 v195, v172, v163
	ds_bpermute_b32 v194, v172, v162
	v_lshl_add_u64 v[158:159], s[10:11], 1, v[150:151]
	v_lshl_add_u64 v[196:197], v[158:159], 0, v[196:197]
	v_lshl_add_u64 v[198:199], v[158:159], 0, v[198:199]
	s_mov_b64 s[10:11], 0
	s_waitcnt lgkmcnt(0)
	v_pk_add_f32 v[194:195], v[162:163], v[194:195]
	v_mov_b64_e32 v[162:163], s[4:5]
	v_pk_fma_f32 v[194:195], v[194:195], s[8:9], v[162:163] op_sel_hi:[1,0,0]
	s_nop 0
	v_mul_f32_e32 v161, 0x4b800000, v195
	v_cmp_gt_f32_e64 s[46:47], s93, v195
	v_cmp_gt_f32_e32 vcc, s93, v194
	s_nop 0
	v_cndmask_b32_e64 v161, v195, v161, s[46:47]
	v_rsq_f32_e32 v161, v161
	s_nop 0
	v_mul_f32_e32 v192, 0x45800000, v161
	v_cndmask_b32_e64 v161, v161, v192, s[46:47]
	v_mul_f32_e32 v192, v126, v161
	v_mul_f32_e32 v192, v168, v192
	v_cvt_pk_bf16_f32 v192, v192, s0
	global_store_short v[196:197], v192, off
	v_mul_f32_e32 v192, v110, v161
	v_mul_f32_e32 v192, v169, v192
	v_cvt_pk_bf16_f32 v192, v192, s0
	global_store_short v[196:197], v192, off offset:32
	v_mul_f32_e32 v192, v82, v161
	v_mul_f32_e32 v161, v50, v161
	v_mul_f32_e32 v161, v171, v161
	v_cvt_pk_bf16_f32 v161, v161, s0
	global_store_short v[196:197], v161, off offset:96
	v_mul_f32_e32 v161, 0x4b800000, v194
	v_cndmask_b32_e32 v161, v194, v161, vcc
	v_rsq_f32_e32 v161, v161
	v_mul_f32_e32 v192, v170, v192
	v_cvt_pk_bf16_f32 v192, v192, s0
	global_store_short v[196:197], v192, off offset:64
	v_mul_f32_e32 v192, 0x45800000, v161
	v_cndmask_b32_e32 v161, v161, v192, vcc
	v_or_b32_e32 v194, 1, v160
	v_ashrrev_i32_e32 v195, 31, v194
	v_mul_f32_e32 v192, v127, v161
	v_lshlrev_b64 v[194:195], 12, v[194:195]
	v_mul_f32_e32 v192, v168, v192
	v_lshl_add_u64 v[194:195], v[158:159], 0, v[194:195]
	v_cvt_pk_bf16_f32 v192, v192, s0
	global_store_short v[194:195], v192, off
	v_mul_f32_e32 v192, v111, v161
	v_mul_f32_e32 v192, v169, v192
	v_cvt_pk_bf16_f32 v192, v192, s0
	global_store_short v[194:195], v192, off offset:32
	v_mul_f32_e32 v192, v83, v161
	v_mul_f32_e32 v161, v51, v161
	v_mul_f32_e32 v192, v170, v192
	v_mul_f32_e32 v161, v171, v161
	v_cvt_pk_bf16_f32 v192, v192, s0
	v_cvt_pk_bf16_f32 v161, v161, s0
	global_store_short v[194:195], v192, off offset:64
	global_store_short v[194:195], v161, off offset:96
	v_mov_b32_e32 v194, v128
	v_mov_b32_e32 v195, v112
	v_pk_mul_f32 v[194:195], v[194:195], v[194:195]
	v_mov_b32_e32 v196, v84
	v_mov_b32_e32 v197, v52
	v_pk_mul_f32 v[196:197], v[196:197], v[196:197]
	v_mov_b32_e32 v205, v194
	v_mov_b32_e32 v194, v201
	v_pk_add_f32 v[194:195], v[204:205], v[194:195]
	v_mov_b32_e32 v201, v196
	v_pk_add_f32 v[194:195], v[194:195], v[200:201]
	v_mov_b32_e32 v196, v203
	v_pk_add_f32 v[194:195], v[194:195], v[196:197]
	ds_bpermute_b32 v197, v175, v195
	ds_bpermute_b32 v196, v175, v194
	v_mov_b32_e32 v200, v123
	v_mov_b32_e32 v201, v107
	v_pk_mul_f32 v[200:201], v[200:201], v[200:201]
	v_mov_b32_e32 v203, v43
	s_waitcnt lgkmcnt(0)
	v_pk_add_f32 v[194:195], v[194:195], v[196:197]
	ds_bpermute_b32 v197, v174, v195
	ds_bpermute_b32 v196, v174, v194
	v_pk_mul_f32 v[202:203], v[202:203], v[202:203]
	v_mov_b32_e32 v204, v200
	v_mov_b32_e32 v200, v202
	v_mov_b32_e32 v202, v77
	s_waitcnt lgkmcnt(0)
	v_pk_add_f32 v[194:195], v[194:195], v[196:197]
	ds_bpermute_b32 v197, v173, v195
	ds_bpermute_b32 v196, v173, v194
	s_waitcnt lgkmcnt(0)
	v_pk_add_f32 v[194:195], v[194:195], v[196:197]
	ds_bpermute_b32 v197, v172, v195
	ds_bpermute_b32 v196, v172, v194
	s_waitcnt lgkmcnt(0)
	v_pk_add_f32 v[194:195], v[194:195], v[196:197]
	s_nop 0
	v_pk_fma_f32 v[194:195], v[194:195], s[8:9], v[162:163] op_sel_hi:[1,0,0]
	v_mov_b32_e32 v196, v122
	v_mul_f32_e32 v161, 0x4b800000, v195
	v_cmp_gt_f32_e64 s[46:47], s93, v195
	v_mov_b32_e32 v197, v106
	v_pk_mul_f32 v[196:197], v[196:197], v[196:197]
	v_cndmask_b32_e64 v161, v195, v161, s[46:47]
	v_rsq_f32_e32 v161, v161
	v_mov_b32_e32 v205, v196
	v_mov_b32_e32 v196, v201
	v_pk_add_f32 v[196:197], v[204:205], v[196:197]
	v_mul_f32_e32 v192, 0x45800000, v161
	v_cndmask_b32_e64 v161, v161, v192, s[46:47]
	v_mul_f32_e32 v192, v128, v161
	v_mul_f32_e32 v192, v168, v192
	v_cvt_pk_bf16_f32 v192, v192, s0
	global_store_short v[198:199], v192, off
	v_mul_f32_e32 v192, v112, v161
	v_mul_f32_e32 v192, v169, v192
	v_cvt_pk_bf16_f32 v192, v192, s0
	global_store_short v[198:199], v192, off offset:32
	v_mul_f32_e32 v192, v84, v161
	v_mul_f32_e32 v161, v52, v161
	v_mul_f32_e32 v192, v170, v192
	v_mul_f32_e32 v161, v171, v161
	v_cvt_pk_bf16_f32 v192, v192, s0
	v_cvt_pk_bf16_f32 v161, v161, s0
	global_store_short v[198:199], v192, off offset:64
	global_store_short v[198:199], v161, off offset:96
	v_mov_b32_e32 v198, v74
	v_mov_b32_e32 v199, v42
	v_pk_mul_f32 v[198:199], v[198:199], v[198:199]
	v_cmp_gt_f32_e32 vcc, s93, v194
	v_mov_b32_e32 v201, v198
	v_pk_add_f32 v[196:197], v[196:197], v[200:201]
	v_mov_b32_e32 v198, v203
	v_pk_add_f32 v[196:197], v[196:197], v[198:199]
	ds_bpermute_b32 v199, v175, v197
	ds_bpermute_b32 v198, v175, v196
	v_mul_f32_e32 v161, 0x4b800000, v194
	v_cndmask_b32_e32 v161, v194, v161, vcc
	v_rsq_f32_e32 v161, v161
	v_or_b32_e32 v194, 3, v160
	s_waitcnt lgkmcnt(0)
; __device__ __forceinline__ unsigned f2bf(float f) { const __bf16 b = (__bf16)f; return (unsigned)__builtin_bit_cast(unsigned short, b); }
;     __device__ __forceinline__ void operator()(Acc& acc, int pm, int pn, int wr, int wc, int fr, int fq) const {
;     ...
;                     float ss = acc[ai][0][m][0][j] * acc[ai][0][m][0][j] + acc[ai][0][m][1][j] * acc[ai][0][m][1][j] +
;                                acc[ai][1][m][0][j] * acc[ai][1][m][0][j] + acc[ai][1][m][1][j] * acc[ai][1][m][1][j];
;                     ss += __shfl_xor(ss, 1); ss += __shfl_xor(ss, 2); ss += __shfl_xor(ss, 4); ss += __shfl_xor(ss, 8);
;                     const float rs = rsqrtf(ss * (1.0f / 64.0f) + EPSV);
;                     bf16_t* rp = qk + (size_t)(pm * 256 + ai * 128 + wr * 64 + m * 16 + fq * 4 + j) * 2048 + head * 64 + fr;
; #pragma unroll
;                     for (int bj = 0; bj < 2; ++bj)
; #pragma unroll
;                         for (int n = 0; n < 2; ++n) rp[bj * 32 + n * 16] = (bf16_t)f2bf(acc[ai][bj][m][n][j] * rs * gv[bj][n]);
	v_pk_add_f32 v[196:197], v[196:197], v[198:199]
	ds_bpermute_b32 v199, v174, v197
	ds_bpermute_b32 v198, v174, v196
	v_mul_f32_e32 v192, 0x45800000, v161
	v_cndmask_b32_e32 v161, v161, v192, vcc
	v_ashrrev_i32_e32 v195, 31, v194
	v_mul_f32_e32 v192, v129, v161
	s_waitcnt lgkmcnt(0)
	v_pk_add_f32 v[196:197], v[196:197], v[198:199]
	ds_bpermute_b32 v199, v173, v197
	ds_bpermute_b32 v198, v173, v196
	v_lshlrev_b64 v[194:195], 12, v[194:195]
	v_mul_f32_e32 v192, v168, v192
	v_lshl_add_u64 v[194:195], v[158:159], 0, v[194:195]
	v_cvt_pk_bf16_f32 v192, v192, s0
	s_waitcnt lgkmcnt(0)
	v_pk_add_f32 v[196:197], v[196:197], v[198:199]
	ds_bpermute_b32 v199, v172, v197
	ds_bpermute_b32 v198, v172, v196
	global_store_short v[194:195], v192, off
	v_mul_f32_e32 v192, v113, v161
	v_mul_f32_e32 v192, v169, v192
	v_cvt_pk_bf16_f32 v192, v192, s0
	global_store_short v[194:195], v192, off offset:32
	v_mul_f32_e32 v192, v85, v161
	v_mul_f32_e32 v161, v53, v161
	v_mul_f32_e32 v161, v171, v161
	s_waitcnt lgkmcnt(0)
	v_pk_add_f32 v[196:197], v[196:197], v[198:199]
	v_cvt_pk_bf16_f32 v161, v161, s0
	v_pk_fma_f32 v[196:197], v[196:197], s[8:9], v[162:163] op_sel_hi:[1,0,0]
	global_store_short v[194:195], v161, off offset:96
	v_mul_f32_e32 v161, 0x4b800000, v197
	v_cmp_gt_f32_e64 s[46:47], s93, v197
	v_mul_f32_e32 v192, v170, v192
	v_cvt_pk_bf16_f32 v192, v192, s0
	v_cndmask_b32_e64 v161, v197, v161, s[46:47]
	v_rsq_f32_e32 v161, v161
	global_store_short v[194:195], v192, off offset:64
	v_or_b32_e32 v194, 16, v160
	v_ashrrev_i32_e32 v195, 31, v194
	v_mul_f32_e32 v192, 0x45800000, v161
	v_cndmask_b32_e64 v161, v161, v192, s[46:47]
	v_mul_f32_e32 v192, v122, v161
	v_lshlrev_b64 v[194:195], 12, v[194:195]
	v_mul_f32_e32 v192, v168, v192
	v_lshl_add_u64 v[194:195], v[158:159], 0, v[194:195]
	v_cvt_pk_bf16_f32 v192, v192, s0
	global_store_short v[194:195], v192, off
	v_mul_f32_e32 v192, v106, v161
	v_mul_f32_e32 v192, v169, v192
	v_cvt_pk_bf16_f32 v192, v192, s0
	global_store_short v[194:195], v192, off offset:32
	v_mul_f32_e32 v192, v74, v161
	v_mul_f32_e32 v161, v42, v161
	v_mul_f32_e32 v161, v171, v161
	v_cvt_pk_bf16_f32 v161, v161, s0
	v_cmp_gt_f32_e32 vcc, s93, v196
	global_store_short v[194:195], v161, off offset:96
	v_mul_f32_e32 v161, 0x4b800000, v196
	v_cndmask_b32_e32 v161, v196, v161, vcc
	v_rsq_f32_e32 v161, v161
	v_mul_f32_e32 v192, v170, v192
	v_cvt_pk_bf16_f32 v192, v192, s0
	global_store_short v[194:195], v192, off offset:64
	v_mul_f32_e32 v192, 0x45800000, v161
	v_cndmask_b32_e32 v161, v161, v192, vcc
	v_or_b32_e32 v194, 17, v160
	v_ashrrev_i32_e32 v195, 31, v194
	v_mul_f32_e32 v192, v123, v161
	v_lshlrev_b64 v[194:195], 12, v[194:195]
	v_mul_f32_e32 v192, v168, v192
	v_lshl_add_u64 v[194:195], v[158:159], 0, v[194:195]
	v_cvt_pk_bf16_f32 v192, v192, s0
	global_store_short v[194:195], v192, off
	v_mul_f32_e32 v192, v107, v161
	v_mul_f32_e32 v192, v169, v192
	v_cvt_pk_bf16_f32 v192, v192, s0
	global_store_short v[194:195], v192, off offset:32
	v_mul_f32_e32 v192, v75, v161
	v_mul_f32_e32 v161, v43, v161
	v_mul_f32_e32 v192, v170, v192
	v_mul_f32_e32 v161, v171, v161
	v_cvt_pk_bf16_f32 v192, v192, s0
	v_cvt_pk_bf16_f32 v161, v161, s0
	global_store_short v[194:195], v192, off offset:64
	global_store_short v[194:195], v161, off offset:96
	v_mov_b32_e32 v194, v124
	v_mov_b32_e32 v195, v108
	v_mov_b32_e32 v200, v125
	v_mov_b32_e32 v201, v109
	v_pk_mul_f32 v[194:195], v[194:195], v[194:195]
	v_mov_b32_e32 v196, v76
	v_mov_b32_e32 v197, v44
	v_pk_mul_f32 v[200:201], v[200:201], v[200:201]
	v_mov_b32_e32 v203, v45
	v_pk_mul_f32 v[196:197], v[196:197], v[196:197]
	v_pk_mul_f32 v[202:203], v[202:203], v[202:203]
	v_mov_b32_e32 v204, v200
	v_mov_b32_e32 v205, v194
	v_mov_b32_e32 v194, v201
	v_pk_add_f32 v[194:195], v[204:205], v[194:195]
	v_mov_b32_e32 v200, v202
	v_mov_b32_e32 v201, v196
	v_pk_add_f32 v[194:195], v[194:195], v[200:201]
	v_mov_b32_e32 v196, v203
	v_pk_add_f32 v[194:195], v[194:195], v[196:197]
	ds_bpermute_b32 v197, v175, v195
	ds_bpermute_b32 v196, v175, v194
	v_or_b32_e32 v198, 18, v160
	v_ashrrev_i32_e32 v199, 31, v198
	v_lshlrev_b64 v[198:199], 12, v[198:199]
	v_lshl_add_u64 v[198:199], v[158:159], 0, v[198:199]
	s_waitcnt lgkmcnt(0)
	v_pk_add_f32 v[194:195], v[194:195], v[196:197]
	ds_bpermute_b32 v197, v174, v195
	ds_bpermute_b32 v196, v174, v194
	v_mov_b32_e32 v200, v119
	v_mov_b32_e32 v201, v103
	v_pk_mul_f32 v[200:201], v[200:201], v[200:201]
	v_mov_b32_e32 v202, v67
	s_waitcnt lgkmcnt(0)
	v_pk_add_f32 v[194:195], v[194:195], v[196:197]
	ds_bpermute_b32 v197, v173, v195
	ds_bpermute_b32 v196, v173, v194
	v_mov_b32_e32 v203, v39
	v_pk_mul_f32 v[202:203], v[202:203], v[202:203]
	v_mov_b32_e32 v204, v200
	v_mov_b32_e32 v200, v202
	s_waitcnt lgkmcnt(0)
	v_pk_add_f32 v[194:195], v[194:195], v[196:197]
	ds_bpermute_b32 v197, v172, v195
	ds_bpermute_b32 v196, v172, v194
	v_mov_b32_e32 v202, v69
	s_waitcnt lgkmcnt(0)
; __device__ __forceinline__ unsigned f2bf(float f) { const __bf16 b = (__bf16)f; return (unsigned)__builtin_bit_cast(unsigned short, b); }
;     __device__ __forceinline__ void operator()(Acc& acc, int pm, int pn, int wr, int wc, int fr, int fq) const {
;     ...
;                     float ss = acc[ai][0][m][0][j] * acc[ai][0][m][0][j] + acc[ai][0][m][1][j] * acc[ai][0][m][1][j] +
;                                acc[ai][1][m][0][j] * acc[ai][1][m][0][j] + acc[ai][1][m][1][j] * acc[ai][1][m][1][j];
;                     ss += __shfl_xor(ss, 1); ss += __shfl_xor(ss, 2); ss += __shfl_xor(ss, 4); ss += __shfl_xor(ss, 8);
;                     const float rs = rsqrtf(ss * (1.0f / 64.0f) + EPSV);
;                     bf16_t* rp = qk + (size_t)(pm * 256 + ai * 128 + wr * 64 + m * 16 + fq * 4 + j) * 2048 + head * 64 + fr;
; #pragma unroll
;                     for (int bj = 0; bj < 2; ++bj)
; #pragma unroll
;                         for (int n = 0; n < 2; ++n) rp[bj * 32 + n * 16] = (bf16_t)f2bf(acc[ai][bj][m][n][j] * rs * gv[bj][n]);
	v_pk_add_f32 v[194:195], v[194:195], v[196:197]
	s_nop 0
	v_pk_fma_f32 v[194:195], v[194:195], s[8:9], v[162:163] op_sel_hi:[1,0,0]
	v_mov_b32_e32 v196, v118
	v_mul_f32_e32 v161, 0x4b800000, v195
	v_cmp_gt_f32_e64 s[46:47], s93, v195
	v_mov_b32_e32 v197, v102
	v_pk_mul_f32 v[196:197], v[196:197], v[196:197]
	v_cndmask_b32_e64 v161, v195, v161, s[46:47]
	v_rsq_f32_e32 v161, v161
	v_mov_b32_e32 v205, v196
	v_mov_b32_e32 v196, v201
	v_pk_add_f32 v[196:197], v[204:205], v[196:197]
	v_mul_f32_e32 v192, 0x45800000, v161
	v_cndmask_b32_e64 v161, v161, v192, s[46:47]
	v_mul_f32_e32 v192, v124, v161
	v_mul_f32_e32 v192, v168, v192
	v_cvt_pk_bf16_f32 v192, v192, s0
	global_store_short v[198:199], v192, off
	v_mul_f32_e32 v192, v108, v161
	v_mul_f32_e32 v192, v169, v192
	v_cvt_pk_bf16_f32 v192, v192, s0
	global_store_short v[198:199], v192, off offset:32
	v_mul_f32_e32 v192, v76, v161
	v_mul_f32_e32 v161, v44, v161
	v_mul_f32_e32 v192, v170, v192
	v_mul_f32_e32 v161, v171, v161
	v_cvt_pk_bf16_f32 v192, v192, s0
	v_cvt_pk_bf16_f32 v161, v161, s0
	global_store_short v[198:199], v192, off offset:64
	global_store_short v[198:199], v161, off offset:96
	v_mov_b32_e32 v198, v66
	v_mov_b32_e32 v199, v38
	v_pk_mul_f32 v[198:199], v[198:199], v[198:199]
	v_cmp_gt_f32_e32 vcc, s93, v194
	v_mov_b32_e32 v201, v198
	v_pk_add_f32 v[196:197], v[196:197], v[200:201]
	v_mov_b32_e32 v198, v203
	v_pk_add_f32 v[196:197], v[196:197], v[198:199]
	ds_bpermute_b32 v199, v175, v197
	ds_bpermute_b32 v198, v175, v196
	v_mul_f32_e32 v161, 0x4b800000, v194
	v_cndmask_b32_e32 v161, v194, v161, vcc
	v_rsq_f32_e32 v161, v161
	v_or_b32_e32 v194, 19, v160
	s_waitcnt lgkmcnt(0)
	v_pk_add_f32 v[196:197], v[196:197], v[198:199]
	ds_bpermute_b32 v199, v174, v197
	ds_bpermute_b32 v198, v174, v196
	v_mul_f32_e32 v192, 0x45800000, v161
	v_cndmask_b32_e32 v161, v161, v192, vcc
	v_ashrrev_i32_e32 v195, 31, v194
	v_mul_f32_e32 v192, v125, v161
	s_waitcnt lgkmcnt(0)
	v_pk_add_f32 v[196:197], v[196:197], v[198:199]
	ds_bpermute_b32 v199, v173, v197
	ds_bpermute_b32 v198, v173, v196
	v_lshlrev_b64 v[194:195], 12, v[194:195]
	v_mul_f32_e32 v192, v168, v192
	v_lshl_add_u64 v[194:195], v[158:159], 0, v[194:195]
	v_cvt_pk_bf16_f32 v192, v192, s0
	s_waitcnt lgkmcnt(0)
	v_pk_add_f32 v[196:197], v[196:197], v[198:199]
	ds_bpermute_b32 v199, v172, v197
	ds_bpermute_b32 v198, v172, v196
	global_store_short v[194:195], v192, off
	v_mul_f32_e32 v192, v109, v161
	v_mul_f32_e32 v192, v169, v192
	v_cvt_pk_bf16_f32 v192, v192, s0
	global_store_short v[194:195], v192, off offset:32
	v_mul_f32_e32 v192, v77, v161
	v_mul_f32_e32 v161, v45, v161
	v_mul_f32_e32 v161, v171, v161
	s_waitcnt lgkmcnt(0)
	v_pk_add_f32 v[196:197], v[196:197], v[198:199]
	v_cvt_pk_bf16_f32 v161, v161, s0
	v_pk_fma_f32 v[196:197], v[196:197], s[8:9], v[162:163] op_sel_hi:[1,0,0]
	global_store_short v[194:195], v161, off offset:96
	v_mul_f32_e32 v161, 0x4b800000, v197
	v_cmp_gt_f32_e64 s[46:47], s93, v197
	v_mul_f32_e32 v192, v170, v192
	v_cvt_pk_bf16_f32 v192, v192, s0
	v_cndmask_b32_e64 v161, v197, v161, s[46:47]
	v_rsq_f32_e32 v161, v161
	global_store_short v[194:195], v192, off offset:64
	v_or_b32_e32 v194, 32, v160
	v_ashrrev_i32_e32 v195, 31, v194
	v_mul_f32_e32 v192, 0x45800000, v161
	v_cndmask_b32_e64 v161, v161, v192, s[46:47]
	v_mul_f32_e32 v192, v118, v161
	v_lshlrev_b64 v[194:195], 12, v[194:195]
	v_mul_f32_e32 v192, v168, v192
	v_lshl_add_u64 v[194:195], v[158:159], 0, v[194:195]
	v_cvt_pk_bf16_f32 v192, v192, s0
	global_store_short v[194:195], v192, off
	v_mul_f32_e32 v192, v102, v161
	v_mul_f32_e32 v192, v169, v192
	v_cvt_pk_bf16_f32 v192, v192, s0
	global_store_short v[194:195], v192, off offset:32
	v_mul_f32_e32 v192, v66, v161
	v_mul_f32_e32 v161, v38, v161
	v_mul_f32_e32 v161, v171, v161
	v_cvt_pk_bf16_f32 v161, v161, s0
	v_cmp_gt_f32_e32 vcc, s93, v196
	global_store_short v[194:195], v161, off offset:96
	v_mul_f32_e32 v161, 0x4b800000, v196
	v_cndmask_b32_e32 v161, v196, v161, vcc
	v_rsq_f32_e32 v161, v161
	v_mul_f32_e32 v192, v170, v192
	v_cvt_pk_bf16_f32 v192, v192, s0
	global_store_short v[194:195], v192, off offset:64
	v_mul_f32_e32 v192, 0x45800000, v161
	v_cndmask_b32_e32 v161, v161, v192, vcc
	v_or_b32_e32 v194, 33, v160
	v_ashrrev_i32_e32 v195, 31, v194
	v_mul_f32_e32 v192, v119, v161
	v_lshlrev_b64 v[194:195], 12, v[194:195]
	v_mul_f32_e32 v192, v168, v192
	v_lshl_add_u64 v[194:195], v[158:159], 0, v[194:195]
	v_cvt_pk_bf16_f32 v192, v192, s0
	global_store_short v[194:195], v192, off
	v_mul_f32_e32 v192, v103, v161
	v_mul_f32_e32 v192, v169, v192
	v_cvt_pk_bf16_f32 v192, v192, s0
	global_store_short v[194:195], v192, off offset:32
	v_mul_f32_e32 v192, v67, v161
	v_mul_f32_e32 v161, v39, v161
	v_mul_f32_e32 v192, v170, v192
	v_mul_f32_e32 v161, v171, v161
	v_cvt_pk_bf16_f32 v192, v192, s0
	v_cvt_pk_bf16_f32 v161, v161, s0
	global_store_short v[194:195], v192, off offset:64
	global_store_short v[194:195], v161, off offset:96
	v_mov_b32_e32 v194, v120
	v_mov_b32_e32 v195, v104
	v_mov_b32_e32 v200, v121
	v_mov_b32_e32 v201, v105
	v_pk_mul_f32 v[194:195], v[194:195], v[194:195]
	v_mov_b32_e32 v196, v68
	v_mov_b32_e32 v197, v40
	v_pk_mul_f32 v[200:201], v[200:201], v[200:201]
	v_mov_b32_e32 v203, v41
	v_pk_mul_f32 v[196:197], v[196:197], v[196:197]
	v_pk_mul_f32 v[202:203], v[202:203], v[202:203]
	v_mov_b32_e32 v204, v200
	v_mov_b32_e32 v205, v194
	v_mov_b32_e32 v194, v201
	v_pk_add_f32 v[194:195], v[204:205], v[194:195]
	v_mov_b32_e32 v200, v202
	v_mov_b32_e32 v201, v196
	v_pk_add_f32 v[194:195], v[194:195], v[200:201]
	v_mov_b32_e32 v196, v203
	v_pk_add_f32 v[194:195], v[194:195], v[196:197]
	ds_bpermute_b32 v197, v175, v195
	ds_bpermute_b32 v196, v175, v194
	v_or_b32_e32 v198, 34, v160
	v_ashrrev_i32_e32 v199, 31, v198
	v_lshlrev_b64 v[198:199], 12, v[198:199]
	v_lshl_add_u64 v[198:199], v[158:159], 0, v[198:199]
	s_waitcnt lgkmcnt(0)
; __device__ __forceinline__ unsigned f2bf(float f) { const __bf16 b = (__bf16)f; return (unsigned)__builtin_bit_cast(unsigned short, b); }
;     __device__ __forceinline__ void operator()(Acc& acc, int pm, int pn, int wr, int wc, int fr, int fq) const {
;     ...
;                     float ss = acc[ai][0][m][0][j] * acc[ai][0][m][0][j] + acc[ai][0][m][1][j] * acc[ai][0][m][1][j] +
;                                acc[ai][1][m][0][j] * acc[ai][1][m][0][j] + acc[ai][1][m][1][j] * acc[ai][1][m][1][j];
;                     ss += __shfl_xor(ss, 1); ss += __shfl_xor(ss, 2); ss += __shfl_xor(ss, 4); ss += __shfl_xor(ss, 8);
;                     const float rs = rsqrtf(ss * (1.0f / 64.0f) + EPSV);
;                     bf16_t* rp = qk + (size_t)(pm * 256 + ai * 128 + wr * 64 + m * 16 + fq * 4 + j) * 2048 + head * 64 + fr;
; #pragma unroll
;                     for (int bj = 0; bj < 2; ++bj)
; #pragma unroll
;                         for (int n = 0; n < 2; ++n) rp[bj * 32 + n * 16] = (bf16_t)f2bf(acc[ai][bj][m][n][j] * rs * gv[bj][n]);
	v_pk_add_f32 v[194:195], v[194:195], v[196:197]
	ds_bpermute_b32 v197, v174, v195
	ds_bpermute_b32 v196, v174, v194
	v_mov_b32_e32 v200, v115
	v_mov_b32_e32 v201, v95
	v_pk_mul_f32 v[200:201], v[200:201], v[200:201]
	v_mov_b32_e32 v202, v59
	s_waitcnt lgkmcnt(0)
	v_pk_add_f32 v[194:195], v[194:195], v[196:197]
	ds_bpermute_b32 v197, v173, v195
	ds_bpermute_b32 v196, v173, v194
	v_mov_b32_e32 v203, v31
	v_pk_mul_f32 v[202:203], v[202:203], v[202:203]
	v_mov_b32_e32 v204, v200
	v_mov_b32_e32 v200, v202
	s_waitcnt lgkmcnt(0)
	v_pk_add_f32 v[194:195], v[194:195], v[196:197]
	ds_bpermute_b32 v197, v172, v195
	ds_bpermute_b32 v196, v172, v194
	v_mov_b32_e32 v202, v61
	s_waitcnt lgkmcnt(0)
	v_pk_add_f32 v[194:195], v[194:195], v[196:197]
	s_nop 0
	v_pk_fma_f32 v[194:195], v[194:195], s[8:9], v[162:163] op_sel_hi:[1,0,0]
	v_mov_b32_e32 v196, v114
	v_mul_f32_e32 v161, 0x4b800000, v195
	v_cmp_gt_f32_e64 s[46:47], s93, v195
	v_mov_b32_e32 v197, v94
	v_pk_mul_f32 v[196:197], v[196:197], v[196:197]
	v_cndmask_b32_e64 v161, v195, v161, s[46:47]
	v_rsq_f32_e32 v161, v161
	v_mov_b32_e32 v205, v196
	v_mov_b32_e32 v196, v201
	v_pk_add_f32 v[196:197], v[204:205], v[196:197]
	v_mul_f32_e32 v192, 0x45800000, v161
	v_cndmask_b32_e64 v161, v161, v192, s[46:47]
	v_mul_f32_e32 v192, v120, v161
	v_mul_f32_e32 v192, v168, v192
	v_cvt_pk_bf16_f32 v192, v192, s0
	global_store_short v[198:199], v192, off
	v_mul_f32_e32 v192, v104, v161
	v_mul_f32_e32 v192, v169, v192
	v_cvt_pk_bf16_f32 v192, v192, s0
	global_store_short v[198:199], v192, off offset:32
	v_mul_f32_e32 v192, v68, v161
	v_mul_f32_e32 v161, v40, v161
	v_mul_f32_e32 v192, v170, v192
	v_mul_f32_e32 v161, v171, v161
	v_cvt_pk_bf16_f32 v192, v192, s0
	v_cvt_pk_bf16_f32 v161, v161, s0
	global_store_short v[198:199], v192, off offset:64
	global_store_short v[198:199], v161, off offset:96
	v_mov_b32_e32 v198, v58
	v_mov_b32_e32 v199, v30
	v_pk_mul_f32 v[198:199], v[198:199], v[198:199]
	v_cmp_gt_f32_e32 vcc, s93, v194
	v_mov_b32_e32 v201, v198
	v_pk_add_f32 v[196:197], v[196:197], v[200:201]
	v_mov_b32_e32 v198, v203
	v_pk_add_f32 v[196:197], v[196:197], v[198:199]
	ds_bpermute_b32 v199, v175, v197
	ds_bpermute_b32 v198, v175, v196
	v_mul_f32_e32 v161, 0x4b800000, v194
	v_cndmask_b32_e32 v161, v194, v161, vcc
	v_rsq_f32_e32 v161, v161
	v_or_b32_e32 v194, 35, v160
	s_waitcnt lgkmcnt(0)
	v_pk_add_f32 v[196:197], v[196:197], v[198:199]
	ds_bpermute_b32 v199, v174, v197
	ds_bpermute_b32 v198, v174, v196
	v_mul_f32_e32 v192, 0x45800000, v161
	v_cndmask_b32_e32 v161, v161, v192, vcc
	v_ashrrev_i32_e32 v195, 31, v194
	v_mul_f32_e32 v192, v121, v161
	s_waitcnt lgkmcnt(0)
	v_pk_add_f32 v[196:197], v[196:197], v[198:199]
	ds_bpermute_b32 v199, v173, v197
	ds_bpermute_b32 v198, v173, v196
	v_lshlrev_b64 v[194:195], 12, v[194:195]
	v_mul_f32_e32 v192, v168, v192
	v_lshl_add_u64 v[194:195], v[158:159], 0, v[194:195]
	v_cvt_pk_bf16_f32 v192, v192, s0
	s_waitcnt lgkmcnt(0)
	v_pk_add_f32 v[196:197], v[196:197], v[198:199]
	ds_bpermute_b32 v199, v172, v197
	ds_bpermute_b32 v198, v172, v196
	global_store_short v[194:195], v192, off
	v_mul_f32_e32 v192, v105, v161
	v_mul_f32_e32 v192, v169, v192
	v_cvt_pk_bf16_f32 v192, v192, s0
	global_store_short v[194:195], v192, off offset:32
	v_mul_f32_e32 v192, v69, v161
	v_mul_f32_e32 v161, v41, v161
	v_mul_f32_e32 v161, v171, v161
	s_waitcnt lgkmcnt(0)
	v_pk_add_f32 v[196:197], v[196:197], v[198:199]
	v_cvt_pk_bf16_f32 v161, v161, s0
	v_pk_fma_f32 v[196:197], v[196:197], s[8:9], v[162:163] op_sel_hi:[1,0,0]
	global_store_short v[194:195], v161, off offset:96
	v_mul_f32_e32 v161, 0x4b800000, v197
	v_cmp_gt_f32_e64 s[46:47], s93, v197
	v_mul_f32_e32 v192, v170, v192
	v_cvt_pk_bf16_f32 v192, v192, s0
	v_cndmask_b32_e64 v161, v197, v161, s[46:47]
	v_rsq_f32_e32 v161, v161
	global_store_short v[194:195], v192, off offset:64
	v_or_b32_e32 v194, 48, v160
	v_ashrrev_i32_e32 v195, 31, v194
	v_mul_f32_e32 v192, 0x45800000, v161
	v_cndmask_b32_e64 v161, v161, v192, s[46:47]
	v_mul_f32_e32 v192, v114, v161
	v_lshlrev_b64 v[194:195], 12, v[194:195]
	v_mul_f32_e32 v192, v168, v192
	v_lshl_add_u64 v[194:195], v[158:159], 0, v[194:195]
	v_cvt_pk_bf16_f32 v192, v192, s0
	global_store_short v[194:195], v192, off
	v_mul_f32_e32 v192, v94, v161
	v_mul_f32_e32 v192, v169, v192
	v_cvt_pk_bf16_f32 v192, v192, s0
	global_store_short v[194:195], v192, off offset:32
	v_mul_f32_e32 v192, v58, v161
	v_mul_f32_e32 v161, v30, v161
	v_mul_f32_e32 v161, v171, v161
	v_cvt_pk_bf16_f32 v161, v161, s0
	v_cmp_gt_f32_e32 vcc, s93, v196
	global_store_short v[194:195], v161, off offset:96
	v_mul_f32_e32 v161, 0x4b800000, v196
	v_cndmask_b32_e32 v161, v196, v161, vcc
	v_rsq_f32_e32 v161, v161
	v_mul_f32_e32 v192, v170, v192
	v_cvt_pk_bf16_f32 v192, v192, s0
	global_store_short v[194:195], v192, off offset:64
	v_mul_f32_e32 v192, 0x45800000, v161
	v_cndmask_b32_e32 v161, v161, v192, vcc
	v_or_b32_e32 v194, 49, v160
	v_ashrrev_i32_e32 v195, 31, v194
	v_mul_f32_e32 v192, v115, v161
	v_lshlrev_b64 v[194:195], 12, v[194:195]
	v_mul_f32_e32 v192, v168, v192
	v_lshl_add_u64 v[194:195], v[158:159], 0, v[194:195]
	v_cvt_pk_bf16_f32 v192, v192, s0
	global_store_short v[194:195], v192, off
	v_mul_f32_e32 v192, v95, v161
	v_mul_f32_e32 v192, v169, v192
	v_cvt_pk_bf16_f32 v192, v192, s0
	global_store_short v[194:195], v192, off offset:32
	v_mul_f32_e32 v192, v59, v161
	v_mul_f32_e32 v161, v31, v161
	v_mul_f32_e32 v192, v170, v192
	v_mul_f32_e32 v161, v171, v161
	v_cvt_pk_bf16_f32 v192, v192, s0
	v_cvt_pk_bf16_f32 v161, v161, s0
	global_store_short v[194:195], v192, off offset:64
	global_store_short v[194:195], v161, off offset:96
	v_mov_b32_e32 v194, v116
	v_mov_b32_e32 v195, v96
	v_mov_b32_e32 v200, v117
	v_mov_b32_e32 v201, v97
	v_pk_mul_f32 v[194:195], v[194:195], v[194:195]
	v_mov_b32_e32 v196, v60
	v_mov_b32_e32 v197, v32
	v_pk_mul_f32 v[200:201], v[200:201], v[200:201]
	v_mov_b32_e32 v203, v33
	v_pk_mul_f32 v[196:197], v[196:197], v[196:197]
	v_pk_mul_f32 v[202:203], v[202:203], v[202:203]
	v_mov_b32_e32 v204, v200
	v_mov_b32_e32 v205, v194
	v_mov_b32_e32 v194, v201
	v_pk_add_f32 v[194:195], v[204:205], v[194:195]
	v_mov_b32_e32 v200, v202
	v_mov_b32_e32 v201, v196
	v_pk_add_f32 v[194:195], v[194:195], v[200:201]
	v_mov_b32_e32 v196, v203
	v_pk_add_f32 v[194:195], v[194:195], v[196:197]
	ds_bpermute_b32 v197, v175, v195
	ds_bpermute_b32 v196, v175, v194
	v_or_b32_e32 v198, 50, v160
	v_ashrrev_i32_e32 v199, 31, v198
	v_lshlrev_b64 v[198:199], 12, v[198:199]
	v_lshl_add_u64 v[198:199], v[158:159], 0, v[198:199]
	s_waitcnt lgkmcnt(0)
; __device__ __forceinline__ unsigned f2bf(float f) { const __bf16 b = (__bf16)f; return (unsigned)__builtin_bit_cast(unsigned short, b); }
;     __device__ __forceinline__ void operator()(Acc& acc, int pm, int pn, int wr, int wc, int fr, int fq) const {
;     ...
;                     float ss = acc[ai][0][m][0][j] * acc[ai][0][m][0][j] + acc[ai][0][m][1][j] * acc[ai][0][m][1][j] +
;                                acc[ai][1][m][0][j] * acc[ai][1][m][0][j] + acc[ai][1][m][1][j] * acc[ai][1][m][1][j];
;                     ss += __shfl_xor(ss, 1); ss += __shfl_xor(ss, 2); ss += __shfl_xor(ss, 4); ss += __shfl_xor(ss, 8);
;                     const float rs = rsqrtf(ss * (1.0f / 64.0f) + EPSV);
;                     bf16_t* rp = qk + (size_t)(pm * 256 + ai * 128 + wr * 64 + m * 16 + fq * 4 + j) * 2048 + head * 64 + fr;
; #pragma unroll
;                     for (int bj = 0; bj < 2; ++bj)
; #pragma unroll
;                         for (int n = 0; n < 2; ++n) rp[bj * 32 + n * 16] = (bf16_t)f2bf(acc[ai][bj][m][n][j] * rs * gv[bj][n]);
	v_pk_add_f32 v[194:195], v[194:195], v[196:197]
	ds_bpermute_b32 v197, v174, v195
	ds_bpermute_b32 v196, v174, v194
	v_mov_b32_e32 v200, v99
	v_mov_b32_e32 v201, v71
	v_pk_mul_f32 v[200:201], v[200:201], v[200:201]
	v_mov_b32_e32 v202, v35
	s_waitcnt lgkmcnt(0)
	v_pk_add_f32 v[194:195], v[194:195], v[196:197]
	ds_bpermute_b32 v197, v173, v195
	ds_bpermute_b32 v196, v173, v194
	v_mov_b32_e32 v203, v15
	v_pk_mul_f32 v[202:203], v[202:203], v[202:203]
	v_mov_b32_e32 v204, v200
	v_mov_b32_e32 v200, v202
	s_waitcnt lgkmcnt(0)
	v_pk_add_f32 v[194:195], v[194:195], v[196:197]
	ds_bpermute_b32 v197, v172, v195
	ds_bpermute_b32 v196, v172, v194
	v_mov_b32_e32 v202, v37
	s_waitcnt lgkmcnt(0)
	v_pk_add_f32 v[194:195], v[194:195], v[196:197]
	s_nop 0
	v_pk_fma_f32 v[194:195], v[194:195], s[8:9], v[162:163] op_sel_hi:[1,0,0]
	v_mov_b32_e32 v196, v98
	v_mul_f32_e32 v161, 0x4b800000, v195
	v_cmp_gt_f32_e64 s[46:47], s93, v195
	v_mov_b32_e32 v197, v70
	v_pk_mul_f32 v[196:197], v[196:197], v[196:197]
	v_cndmask_b32_e64 v161, v195, v161, s[46:47]
	v_rsq_f32_e32 v161, v161
	v_mov_b32_e32 v205, v196
	v_mov_b32_e32 v196, v201
	v_pk_add_f32 v[196:197], v[204:205], v[196:197]
	v_mul_f32_e32 v192, 0x45800000, v161
	v_cndmask_b32_e64 v161, v161, v192, s[46:47]
	v_mul_f32_e32 v192, v116, v161
	v_mul_f32_e32 v192, v168, v192
	v_cvt_pk_bf16_f32 v192, v192, s0
	global_store_short v[198:199], v192, off
	v_mul_f32_e32 v192, v96, v161
	v_mul_f32_e32 v192, v169, v192
	v_cvt_pk_bf16_f32 v192, v192, s0
	global_store_short v[198:199], v192, off offset:32
	v_mul_f32_e32 v192, v60, v161
	v_mul_f32_e32 v161, v32, v161
	v_mul_f32_e32 v192, v170, v192
	v_mul_f32_e32 v161, v171, v161
	v_cvt_pk_bf16_f32 v192, v192, s0
	v_cvt_pk_bf16_f32 v161, v161, s0
	global_store_short v[198:199], v192, off offset:64
	global_store_short v[198:199], v161, off offset:96
	v_mov_b32_e32 v198, v34
	v_mov_b32_e32 v199, v14
	v_pk_mul_f32 v[198:199], v[198:199], v[198:199]
	v_cmp_gt_f32_e32 vcc, s93, v194
	v_mov_b32_e32 v201, v198
	v_pk_add_f32 v[196:197], v[196:197], v[200:201]
	v_mov_b32_e32 v198, v203
	v_pk_add_f32 v[196:197], v[196:197], v[198:199]
	ds_bpermute_b32 v199, v175, v197
	ds_bpermute_b32 v198, v175, v196
	v_mul_f32_e32 v161, 0x4b800000, v194
	v_cndmask_b32_e32 v161, v194, v161, vcc
	v_rsq_f32_e32 v161, v161
	v_or_b32_e32 v194, 51, v160
	s_waitcnt lgkmcnt(0)
	v_pk_add_f32 v[196:197], v[196:197], v[198:199]
	ds_bpermute_b32 v199, v174, v197
	ds_bpermute_b32 v198, v174, v196
	v_mul_f32_e32 v192, 0x45800000, v161
	v_cndmask_b32_e32 v161, v161, v192, vcc
	v_ashrrev_i32_e32 v195, 31, v194
	v_mul_f32_e32 v192, v117, v161
	s_waitcnt lgkmcnt(0)
	v_pk_add_f32 v[196:197], v[196:197], v[198:199]
	ds_bpermute_b32 v199, v173, v197
	ds_bpermute_b32 v198, v173, v196
	v_lshlrev_b64 v[194:195], 12, v[194:195]
	v_mul_f32_e32 v192, v168, v192
	v_lshl_add_u64 v[194:195], v[158:159], 0, v[194:195]
	v_cvt_pk_bf16_f32 v192, v192, s0
	s_waitcnt lgkmcnt(0)
	v_pk_add_f32 v[196:197], v[196:197], v[198:199]
	ds_bpermute_b32 v199, v172, v197
	ds_bpermute_b32 v198, v172, v196
	global_store_short v[194:195], v192, off
	v_mul_f32_e32 v192, v97, v161
	v_mul_f32_e32 v192, v169, v192
	v_cvt_pk_bf16_f32 v192, v192, s0
	global_store_short v[194:195], v192, off offset:32
	v_mul_f32_e32 v192, v61, v161
	v_mul_f32_e32 v161, v33, v161
	v_mul_f32_e32 v161, v171, v161
	s_waitcnt lgkmcnt(0)
	v_pk_add_f32 v[196:197], v[196:197], v[198:199]
	v_cvt_pk_bf16_f32 v161, v161, s0
	v_pk_fma_f32 v[196:197], v[196:197], s[8:9], v[162:163] op_sel_hi:[1,0,0]
	global_store_short v[194:195], v161, off offset:96
	v_mul_f32_e32 v161, 0x4b800000, v197
	v_cmp_gt_f32_e64 s[46:47], s93, v197
	v_mul_f32_e32 v192, v170, v192
	v_cvt_pk_bf16_f32 v192, v192, s0
	v_cndmask_b32_e64 v161, v197, v161, s[46:47]
	v_rsq_f32_e32 v161, v161
	global_store_short v[194:195], v192, off offset:64
	v_add_u32_e32 v194, 0x80, v160
	v_ashrrev_i32_e32 v195, 31, v194
	v_mul_f32_e32 v192, 0x45800000, v161
	v_cndmask_b32_e64 v161, v161, v192, s[46:47]
	v_mul_f32_e32 v192, v98, v161
	v_lshlrev_b64 v[194:195], 12, v[194:195]
	v_mul_f32_e32 v192, v168, v192
	v_lshl_add_u64 v[194:195], v[158:159], 0, v[194:195]
	v_cvt_pk_bf16_f32 v192, v192, s0
	global_store_short v[194:195], v192, off
	v_mul_f32_e32 v192, v70, v161
	v_mul_f32_e32 v192, v169, v192
	v_cvt_pk_bf16_f32 v192, v192, s0
	global_store_short v[194:195], v192, off offset:32
	v_mul_f32_e32 v192, v34, v161
	v_mul_f32_e32 v161, v14, v161
	v_mul_f32_e32 v161, v171, v161
	v_cvt_pk_bf16_f32 v161, v161, s0
	v_cmp_gt_f32_e32 vcc, s93, v196
	global_store_short v[194:195], v161, off offset:96
	v_mul_f32_e32 v161, 0x4b800000, v196
	v_cndmask_b32_e32 v161, v196, v161, vcc
	v_rsq_f32_e32 v161, v161
	v_mul_f32_e32 v192, v170, v192
	v_cvt_pk_bf16_f32 v192, v192, s0
	global_store_short v[194:195], v192, off offset:64
	v_mul_f32_e32 v192, 0x45800000, v161
	v_cndmask_b32_e32 v161, v161, v192, vcc
	v_add_u32_e32 v194, 0x81, v160
	v_ashrrev_i32_e32 v195, 31, v194
	v_mul_f32_e32 v192, v99, v161
	v_lshlrev_b64 v[194:195], 12, v[194:195]
	v_mul_f32_e32 v192, v168, v192
	v_lshl_add_u64 v[194:195], v[158:159], 0, v[194:195]
	v_cvt_pk_bf16_f32 v192, v192, s0
	global_store_short v[194:195], v192, off
	v_mul_f32_e32 v192, v71, v161
	v_mul_f32_e32 v192, v169, v192
	v_cvt_pk_bf16_f32 v192, v192, s0
	global_store_short v[194:195], v192, off offset:32
	v_mul_f32_e32 v192, v35, v161
	v_mul_f32_e32 v161, v15, v161
	v_mul_f32_e32 v192, v170, v192
	v_mul_f32_e32 v161, v171, v161
	v_cvt_pk_bf16_f32 v192, v192, s0
	v_cvt_pk_bf16_f32 v161, v161, s0
	global_store_short v[194:195], v192, off offset:64
	global_store_short v[194:195], v161, off offset:96
	v_mov_b32_e32 v194, v100
	v_mov_b32_e32 v195, v72
	v_mov_b32_e32 v200, v101
	v_mov_b32_e32 v201, v73
	v_pk_mul_f32 v[194:195], v[194:195], v[194:195]
	v_mov_b32_e32 v196, v36
	v_mov_b32_e32 v197, v16
	v_pk_mul_f32 v[200:201], v[200:201], v[200:201]
	v_mov_b32_e32 v203, v17
	v_pk_mul_f32 v[196:197], v[196:197], v[196:197]
	v_pk_mul_f32 v[202:203], v[202:203], v[202:203]
	v_mov_b32_e32 v204, v200
	v_mov_b32_e32 v205, v194
	v_mov_b32_e32 v194, v201
	v_pk_add_f32 v[194:195], v[204:205], v[194:195]
	v_mov_b32_e32 v200, v202
	v_mov_b32_e32 v201, v196
	v_pk_add_f32 v[194:195], v[194:195], v[200:201]
	v_mov_b32_e32 v196, v203
	v_pk_add_f32 v[194:195], v[194:195], v[196:197]
	ds_bpermute_b32 v197, v175, v195
	ds_bpermute_b32 v196, v175, v194
	v_add_u32_e32 v198, 0x82, v160
	v_ashrrev_i32_e32 v199, 31, v198
	v_lshlrev_b64 v[198:199], 12, v[198:199]
	v_lshl_add_u64 v[198:199], v[158:159], 0, v[198:199]
	s_waitcnt lgkmcnt(0)
; __device__ __forceinline__ unsigned f2bf(float f) { const __bf16 b = (__bf16)f; return (unsigned)__builtin_bit_cast(unsigned short, b); }
;     __device__ __forceinline__ void operator()(Acc& acc, int pm, int pn, int wr, int wc, int fr, int fq) const {
;     ...
;                     float ss = acc[ai][0][m][0][j] * acc[ai][0][m][0][j] + acc[ai][0][m][1][j] * acc[ai][0][m][1][j] +
;                                acc[ai][1][m][0][j] * acc[ai][1][m][0][j] + acc[ai][1][m][1][j] * acc[ai][1][m][1][j];
;                     ss += __shfl_xor(ss, 1); ss += __shfl_xor(ss, 2); ss += __shfl_xor(ss, 4); ss += __shfl_xor(ss, 8);
;                     const float rs = rsqrtf(ss * (1.0f / 64.0f) + EPSV);
;                     bf16_t* rp = qk + (size_t)(pm * 256 + ai * 128 + wr * 64 + m * 16 + fq * 4 + j) * 2048 + head * 64 + fr;
; #pragma unroll
;                     for (int bj = 0; bj < 2; ++bj)
; #pragma unroll
;                         for (int n = 0; n < 2; ++n) rp[bj * 32 + n * 16] = (bf16_t)f2bf(acc[ai][bj][m][n][j] * rs * gv[bj][n]);
	v_pk_add_f32 v[194:195], v[194:195], v[196:197]
	ds_bpermute_b32 v197, v174, v195
	ds_bpermute_b32 v196, v174, v194
	v_mov_b32_e32 v200, v91
	v_mov_b32_e32 v201, v63
	v_pk_mul_f32 v[200:201], v[200:201], v[200:201]
	v_mov_b32_e32 v202, v27
	s_waitcnt lgkmcnt(0)
	v_pk_add_f32 v[194:195], v[194:195], v[196:197]
	ds_bpermute_b32 v197, v173, v195
	ds_bpermute_b32 v196, v173, v194
	v_mov_b32_e32 v203, v11
	v_pk_mul_f32 v[202:203], v[202:203], v[202:203]
	v_mov_b32_e32 v204, v200
	v_mov_b32_e32 v200, v202
	s_waitcnt lgkmcnt(0)
	v_pk_add_f32 v[194:195], v[194:195], v[196:197]
	ds_bpermute_b32 v197, v172, v195
	ds_bpermute_b32 v196, v172, v194
	v_mov_b32_e32 v202, v29
	s_waitcnt lgkmcnt(0)
	v_pk_add_f32 v[194:195], v[194:195], v[196:197]
	s_nop 0
	v_pk_fma_f32 v[194:195], v[194:195], s[8:9], v[162:163] op_sel_hi:[1,0,0]
	v_mov_b32_e32 v196, v90
	v_mul_f32_e32 v161, 0x4b800000, v195
	v_cmp_gt_f32_e64 s[46:47], s93, v195
	v_mov_b32_e32 v197, v62
	v_pk_mul_f32 v[196:197], v[196:197], v[196:197]
	v_cndmask_b32_e64 v161, v195, v161, s[46:47]
	v_rsq_f32_e32 v161, v161
	v_mov_b32_e32 v205, v196
	v_mov_b32_e32 v196, v201
	v_pk_add_f32 v[196:197], v[204:205], v[196:197]
	v_mul_f32_e32 v192, 0x45800000, v161
	v_cndmask_b32_e64 v161, v161, v192, s[46:47]
	v_mul_f32_e32 v192, v100, v161
	v_mul_f32_e32 v192, v168, v192
	v_cvt_pk_bf16_f32 v192, v192, s0
	global_store_short v[198:199], v192, off
	v_mul_f32_e32 v192, v72, v161
	v_mul_f32_e32 v192, v169, v192
	v_cvt_pk_bf16_f32 v192, v192, s0
	global_store_short v[198:199], v192, off offset:32
	v_mul_f32_e32 v192, v36, v161
	v_mul_f32_e32 v161, v16, v161
	v_mul_f32_e32 v192, v170, v192
	v_mul_f32_e32 v161, v171, v161
	v_cvt_pk_bf16_f32 v192, v192, s0
	v_cvt_pk_bf16_f32 v161, v161, s0
	global_store_short v[198:199], v192, off offset:64
	global_store_short v[198:199], v161, off offset:96
	v_mov_b32_e32 v198, v26
	v_mov_b32_e32 v199, v10
	v_pk_mul_f32 v[198:199], v[198:199], v[198:199]
	v_cmp_gt_f32_e32 vcc, s93, v194
	v_mov_b32_e32 v201, v198
	v_pk_add_f32 v[196:197], v[196:197], v[200:201]
	v_mov_b32_e32 v198, v203
	v_pk_add_f32 v[196:197], v[196:197], v[198:199]
	ds_bpermute_b32 v199, v175, v197
	ds_bpermute_b32 v198, v175, v196
	v_mul_f32_e32 v161, 0x4b800000, v194
	v_cndmask_b32_e32 v161, v194, v161, vcc
	v_rsq_f32_e32 v161, v161
	v_add_u32_e32 v194, 0x83, v160
	s_waitcnt lgkmcnt(0)
	v_pk_add_f32 v[196:197], v[196:197], v[198:199]
	ds_bpermute_b32 v199, v174, v197
	ds_bpermute_b32 v198, v174, v196
	v_mul_f32_e32 v192, 0x45800000, v161
	v_cndmask_b32_e32 v161, v161, v192, vcc
	v_ashrrev_i32_e32 v195, 31, v194
	v_mul_f32_e32 v192, v101, v161
	s_waitcnt lgkmcnt(0)
	v_pk_add_f32 v[196:197], v[196:197], v[198:199]
	ds_bpermute_b32 v199, v173, v197
	ds_bpermute_b32 v198, v173, v196
	v_lshlrev_b64 v[194:195], 12, v[194:195]
	v_mul_f32_e32 v192, v168, v192
	v_lshl_add_u64 v[194:195], v[158:159], 0, v[194:195]
	v_cvt_pk_bf16_f32 v192, v192, s0
	s_waitcnt lgkmcnt(0)
	v_pk_add_f32 v[196:197], v[196:197], v[198:199]
	ds_bpermute_b32 v199, v172, v197
	ds_bpermute_b32 v198, v172, v196
	global_store_short v[194:195], v192, off
	v_mul_f32_e32 v192, v73, v161
	v_mul_f32_e32 v192, v169, v192
	v_cvt_pk_bf16_f32 v192, v192, s0
	global_store_short v[194:195], v192, off offset:32
	v_mul_f32_e32 v192, v37, v161
	v_mul_f32_e32 v161, v17, v161
	v_mul_f32_e32 v161, v171, v161
	s_waitcnt lgkmcnt(0)
	v_pk_add_f32 v[196:197], v[196:197], v[198:199]
	v_cvt_pk_bf16_f32 v161, v161, s0
	v_pk_fma_f32 v[196:197], v[196:197], s[8:9], v[162:163] op_sel_hi:[1,0,0]
	global_store_short v[194:195], v161, off offset:96
	v_mul_f32_e32 v161, 0x4b800000, v197
	v_cmp_gt_f32_e64 s[46:47], s93, v197
	v_mul_f32_e32 v192, v170, v192
	v_cvt_pk_bf16_f32 v192, v192, s0
	v_cndmask_b32_e64 v161, v197, v161, s[46:47]
	v_rsq_f32_e32 v161, v161
	global_store_short v[194:195], v192, off offset:64
	v_add_u32_e32 v194, 0x90, v160
	v_ashrrev_i32_e32 v195, 31, v194
	v_mul_f32_e32 v192, 0x45800000, v161
	v_cndmask_b32_e64 v161, v161, v192, s[46:47]
	v_mul_f32_e32 v192, v90, v161
	v_lshlrev_b64 v[194:195], 12, v[194:195]
	v_mul_f32_e32 v192, v168, v192
	v_lshl_add_u64 v[194:195], v[158:159], 0, v[194:195]
	v_cvt_pk_bf16_f32 v192, v192, s0
	global_store_short v[194:195], v192, off
	v_mul_f32_e32 v192, v62, v161
	v_mul_f32_e32 v192, v169, v192
	v_cvt_pk_bf16_f32 v192, v192, s0
	global_store_short v[194:195], v192, off offset:32
	v_mul_f32_e32 v192, v26, v161
	v_mul_f32_e32 v161, v10, v161
	v_mul_f32_e32 v161, v171, v161
	v_cvt_pk_bf16_f32 v161, v161, s0
	v_cmp_gt_f32_e32 vcc, s93, v196
	global_store_short v[194:195], v161, off offset:96
	v_mul_f32_e32 v161, 0x4b800000, v196
	v_cndmask_b32_e32 v161, v196, v161, vcc
	v_rsq_f32_e32 v161, v161
	v_mul_f32_e32 v192, v170, v192
	v_cvt_pk_bf16_f32 v192, v192, s0
	global_store_short v[194:195], v192, off offset:64
	v_mul_f32_e32 v192, 0x45800000, v161
	v_cndmask_b32_e32 v161, v161, v192, vcc
	v_add_u32_e32 v194, 0x91, v160
	v_ashrrev_i32_e32 v195, 31, v194
	v_mul_f32_e32 v192, v91, v161
	v_lshlrev_b64 v[194:195], 12, v[194:195]
	v_mul_f32_e32 v192, v168, v192
	v_lshl_add_u64 v[194:195], v[158:159], 0, v[194:195]
	v_cvt_pk_bf16_f32 v192, v192, s0
	global_store_short v[194:195], v192, off
	v_mul_f32_e32 v192, v63, v161
	v_mul_f32_e32 v192, v169, v192
	v_cvt_pk_bf16_f32 v192, v192, s0
	global_store_short v[194:195], v192, off offset:32
	v_mul_f32_e32 v192, v27, v161
	v_mul_f32_e32 v161, v11, v161
	v_mul_f32_e32 v192, v170, v192
	v_mul_f32_e32 v161, v171, v161
	v_cvt_pk_bf16_f32 v192, v192, s0
	v_cvt_pk_bf16_f32 v161, v161, s0
	global_store_short v[194:195], v192, off offset:64
	global_store_short v[194:195], v161, off offset:96
	v_mov_b32_e32 v194, v92
	v_mov_b32_e32 v195, v64
	v_mov_b32_e32 v200, v93
	v_mov_b32_e32 v201, v65
	v_pk_mul_f32 v[194:195], v[194:195], v[194:195]
	v_mov_b32_e32 v196, v28
	v_mov_b32_e32 v197, v12
	v_pk_mul_f32 v[200:201], v[200:201], v[200:201]
	v_mov_b32_e32 v203, v13
	v_pk_mul_f32 v[196:197], v[196:197], v[196:197]
	v_pk_mul_f32 v[202:203], v[202:203], v[202:203]
	v_mov_b32_e32 v204, v200
	v_mov_b32_e32 v205, v194
	v_mov_b32_e32 v194, v201
	v_pk_add_f32 v[194:195], v[204:205], v[194:195]
	v_mov_b32_e32 v200, v202
	v_mov_b32_e32 v201, v196
	v_pk_add_f32 v[194:195], v[194:195], v[200:201]
	v_mov_b32_e32 v196, v203
	v_pk_add_f32 v[194:195], v[194:195], v[196:197]
	ds_bpermute_b32 v197, v175, v195
	ds_bpermute_b32 v196, v175, v194
	v_add_u32_e32 v198, 0x92, v160
	v_ashrrev_i32_e32 v199, 31, v198
	v_lshlrev_b64 v[198:199], 12, v[198:199]
	v_lshl_add_u64 v[198:199], v[158:159], 0, v[198:199]
	s_waitcnt lgkmcnt(0)
; __device__ __forceinline__ unsigned f2bf(float f) { const __bf16 b = (__bf16)f; return (unsigned)__builtin_bit_cast(unsigned short, b); }
;     __device__ __forceinline__ void operator()(Acc& acc, int pm, int pn, int wr, int wc, int fr, int fq) const {
;     ...
;                     float ss = acc[ai][0][m][0][j] * acc[ai][0][m][0][j] + acc[ai][0][m][1][j] * acc[ai][0][m][1][j] +
;                                acc[ai][1][m][0][j] * acc[ai][1][m][0][j] + acc[ai][1][m][1][j] * acc[ai][1][m][1][j];
;                     ss += __shfl_xor(ss, 1); ss += __shfl_xor(ss, 2); ss += __shfl_xor(ss, 4); ss += __shfl_xor(ss, 8);
;                     const float rs = rsqrtf(ss * (1.0f / 64.0f) + EPSV);
;                     bf16_t* rp = qk + (size_t)(pm * 256 + ai * 128 + wr * 64 + m * 16 + fq * 4 + j) * 2048 + head * 64 + fr;
; #pragma unroll
;                     for (int bj = 0; bj < 2; ++bj)
; #pragma unroll
;                         for (int n = 0; n < 2; ++n) rp[bj * 32 + n * 16] = (bf16_t)f2bf(acc[ai][bj][m][n][j] * rs * gv[bj][n]);
	v_pk_add_f32 v[194:195], v[194:195], v[196:197]
	ds_bpermute_b32 v197, v174, v195
	ds_bpermute_b32 v196, v174, v194
	v_mov_b32_e32 v200, v87
	v_mov_b32_e32 v201, v55
	v_pk_mul_f32 v[200:201], v[200:201], v[200:201]
	v_mov_b32_e32 v202, v23
	s_waitcnt lgkmcnt(0)
	v_pk_add_f32 v[194:195], v[194:195], v[196:197]
	ds_bpermute_b32 v197, v173, v195
	ds_bpermute_b32 v196, v173, v194
	v_mov_b32_e32 v203, v7
	v_pk_mul_f32 v[202:203], v[202:203], v[202:203]
	v_mov_b32_e32 v204, v200
	v_mov_b32_e32 v200, v202
	s_waitcnt lgkmcnt(0)
	v_pk_add_f32 v[194:195], v[194:195], v[196:197]
	ds_bpermute_b32 v197, v172, v195
	ds_bpermute_b32 v196, v172, v194
	v_mov_b32_e32 v202, v25
	s_waitcnt lgkmcnt(0)
	v_pk_add_f32 v[194:195], v[194:195], v[196:197]
	s_nop 0
	v_pk_fma_f32 v[194:195], v[194:195], s[8:9], v[162:163] op_sel_hi:[1,0,0]
	v_mov_b32_e32 v196, v86
	v_mul_f32_e32 v161, 0x4b800000, v195
	v_cmp_gt_f32_e64 s[46:47], s93, v195
	v_mov_b32_e32 v197, v54
	v_pk_mul_f32 v[196:197], v[196:197], v[196:197]
	v_cndmask_b32_e64 v161, v195, v161, s[46:47]
	v_rsq_f32_e32 v161, v161
	v_mov_b32_e32 v205, v196
	v_mov_b32_e32 v196, v201
	v_pk_add_f32 v[196:197], v[204:205], v[196:197]
	v_mul_f32_e32 v192, 0x45800000, v161
	v_cndmask_b32_e64 v161, v161, v192, s[46:47]
	v_mul_f32_e32 v192, v92, v161
	v_mul_f32_e32 v192, v168, v192
	v_cvt_pk_bf16_f32 v192, v192, s0
	global_store_short v[198:199], v192, off
	v_mul_f32_e32 v192, v64, v161
	v_mul_f32_e32 v192, v169, v192
	v_cvt_pk_bf16_f32 v192, v192, s0
	global_store_short v[198:199], v192, off offset:32
	v_mul_f32_e32 v192, v28, v161
	v_mul_f32_e32 v161, v12, v161
	v_mul_f32_e32 v192, v170, v192
	v_mul_f32_e32 v161, v171, v161
	v_cvt_pk_bf16_f32 v192, v192, s0
	v_cvt_pk_bf16_f32 v161, v161, s0
	global_store_short v[198:199], v192, off offset:64
	global_store_short v[198:199], v161, off offset:96
	v_mov_b32_e32 v198, v22
	v_mov_b32_e32 v199, v6
	v_pk_mul_f32 v[198:199], v[198:199], v[198:199]
	v_cmp_gt_f32_e32 vcc, s93, v194
	v_mov_b32_e32 v201, v198
	v_pk_add_f32 v[196:197], v[196:197], v[200:201]
	v_mov_b32_e32 v198, v203
	v_pk_add_f32 v[196:197], v[196:197], v[198:199]
	ds_bpermute_b32 v199, v175, v197
	ds_bpermute_b32 v198, v175, v196
	v_mul_f32_e32 v161, 0x4b800000, v194
	v_cndmask_b32_e32 v161, v194, v161, vcc
	v_rsq_f32_e32 v161, v161
	v_add_u32_e32 v194, 0x93, v160
	s_waitcnt lgkmcnt(0)
	v_pk_add_f32 v[196:197], v[196:197], v[198:199]
	ds_bpermute_b32 v199, v174, v197
	ds_bpermute_b32 v198, v174, v196
	v_mul_f32_e32 v192, 0x45800000, v161
	v_cndmask_b32_e32 v161, v161, v192, vcc
	v_ashrrev_i32_e32 v195, 31, v194
	v_mul_f32_e32 v192, v93, v161
	s_waitcnt lgkmcnt(0)
	v_pk_add_f32 v[196:197], v[196:197], v[198:199]
	ds_bpermute_b32 v199, v173, v197
	ds_bpermute_b32 v198, v173, v196
	v_lshlrev_b64 v[194:195], 12, v[194:195]
	v_mul_f32_e32 v192, v168, v192
	v_lshl_add_u64 v[194:195], v[158:159], 0, v[194:195]
	v_cvt_pk_bf16_f32 v192, v192, s0
	s_waitcnt lgkmcnt(0)
	v_pk_add_f32 v[196:197], v[196:197], v[198:199]
	ds_bpermute_b32 v199, v172, v197
	ds_bpermute_b32 v198, v172, v196
	global_store_short v[194:195], v192, off
	v_mul_f32_e32 v192, v65, v161
	v_mul_f32_e32 v192, v169, v192
	v_cvt_pk_bf16_f32 v192, v192, s0
	global_store_short v[194:195], v192, off offset:32
	v_mul_f32_e32 v192, v29, v161
	v_mul_f32_e32 v161, v13, v161
	v_mul_f32_e32 v161, v171, v161
	s_waitcnt lgkmcnt(0)
	v_pk_add_f32 v[196:197], v[196:197], v[198:199]
	v_cvt_pk_bf16_f32 v161, v161, s0
	v_pk_fma_f32 v[196:197], v[196:197], s[8:9], v[162:163] op_sel_hi:[1,0,0]
	global_store_short v[194:195], v161, off offset:96
	v_mul_f32_e32 v161, 0x4b800000, v197
	v_cmp_gt_f32_e64 s[46:47], s93, v197
	v_mul_f32_e32 v192, v170, v192
	v_cvt_pk_bf16_f32 v192, v192, s0
	v_cndmask_b32_e64 v161, v197, v161, s[46:47]
	v_rsq_f32_e32 v161, v161
	global_store_short v[194:195], v192, off offset:64
	v_add_u32_e32 v194, 0xa0, v160
	v_ashrrev_i32_e32 v195, 31, v194
	v_mul_f32_e32 v192, 0x45800000, v161
	v_cndmask_b32_e64 v161, v161, v192, s[46:47]
	v_mul_f32_e32 v192, v86, v161
	v_lshlrev_b64 v[194:195], 12, v[194:195]
	v_mul_f32_e32 v192, v168, v192
	v_lshl_add_u64 v[194:195], v[158:159], 0, v[194:195]
	v_cvt_pk_bf16_f32 v192, v192, s0
	global_store_short v[194:195], v192, off
	v_mul_f32_e32 v192, v54, v161
	v_mul_f32_e32 v192, v169, v192
	v_cvt_pk_bf16_f32 v192, v192, s0
	global_store_short v[194:195], v192, off offset:32
	v_mul_f32_e32 v192, v22, v161
	v_mul_f32_e32 v161, v6, v161
	v_mul_f32_e32 v161, v171, v161
	v_cvt_pk_bf16_f32 v161, v161, s0
	v_cmp_gt_f32_e32 vcc, s93, v196
	global_store_short v[194:195], v161, off offset:96
	v_mul_f32_e32 v161, 0x4b800000, v196
	v_cndmask_b32_e32 v161, v196, v161, vcc
	v_rsq_f32_e32 v161, v161
	v_mul_f32_e32 v192, v170, v192
	v_cvt_pk_bf16_f32 v192, v192, s0
	global_store_short v[194:195], v192, off offset:64
	v_mul_f32_e32 v192, 0x45800000, v161
	v_cndmask_b32_e32 v161, v161, v192, vcc
	v_add_u32_e32 v194, 0xa1, v160
	v_ashrrev_i32_e32 v195, 31, v194
	v_mul_f32_e32 v192, v87, v161
	v_lshlrev_b64 v[194:195], 12, v[194:195]
	v_mul_f32_e32 v192, v168, v192
	v_lshl_add_u64 v[194:195], v[158:159], 0, v[194:195]
	v_cvt_pk_bf16_f32 v192, v192, s0
	global_store_short v[194:195], v192, off
	v_mul_f32_e32 v192, v55, v161
	v_mul_f32_e32 v192, v169, v192
	v_cvt_pk_bf16_f32 v192, v192, s0
	global_store_short v[194:195], v192, off offset:32
	v_mul_f32_e32 v192, v23, v161
	v_mul_f32_e32 v161, v7, v161
	v_mul_f32_e32 v192, v170, v192
	v_mul_f32_e32 v161, v171, v161
	v_cvt_pk_bf16_f32 v192, v192, s0
	v_cvt_pk_bf16_f32 v161, v161, s0
	global_store_short v[194:195], v192, off offset:64
	global_store_short v[194:195], v161, off offset:96
	v_mov_b32_e32 v194, v88
	v_mov_b32_e32 v195, v56
	v_mov_b32_e32 v200, v89
	v_mov_b32_e32 v201, v57
	v_pk_mul_f32 v[194:195], v[194:195], v[194:195]
	v_mov_b32_e32 v196, v24
	v_mov_b32_e32 v197, v8
	v_pk_mul_f32 v[200:201], v[200:201], v[200:201]
	v_mov_b32_e32 v203, v9
	v_pk_mul_f32 v[196:197], v[196:197], v[196:197]
	v_pk_mul_f32 v[202:203], v[202:203], v[202:203]
	v_mov_b32_e32 v204, v200
	v_mov_b32_e32 v205, v194
	v_mov_b32_e32 v194, v201
	v_pk_add_f32 v[194:195], v[204:205], v[194:195]
	v_mov_b32_e32 v200, v202
	v_mov_b32_e32 v201, v196
	v_pk_add_f32 v[194:195], v[194:195], v[200:201]
	v_mov_b32_e32 v196, v203
	v_pk_add_f32 v[194:195], v[194:195], v[196:197]
	ds_bpermute_b32 v197, v175, v195
	ds_bpermute_b32 v196, v175, v194
	v_add_u32_e32 v198, 0xa2, v160
	v_ashrrev_i32_e32 v199, 31, v198
	v_lshlrev_b64 v[198:199], 12, v[198:199]
	v_lshl_add_u64 v[198:199], v[158:159], 0, v[198:199]
	s_waitcnt lgkmcnt(0)
; __device__ __forceinline__ unsigned f2bf(float f) { const __bf16 b = (__bf16)f; return (unsigned)__builtin_bit_cast(unsigned short, b); }
;     __device__ __forceinline__ void operator()(Acc& acc, int pm, int pn, int wr, int wc, int fr, int fq) const {
;     ...
;                     float ss = acc[ai][0][m][0][j] * acc[ai][0][m][0][j] + acc[ai][0][m][1][j] * acc[ai][0][m][1][j] +
;                                acc[ai][1][m][0][j] * acc[ai][1][m][0][j] + acc[ai][1][m][1][j] * acc[ai][1][m][1][j];
;                     ss += __shfl_xor(ss, 1); ss += __shfl_xor(ss, 2); ss += __shfl_xor(ss, 4); ss += __shfl_xor(ss, 8);
;                     const float rs = rsqrtf(ss * (1.0f / 64.0f) + EPSV);
;                     bf16_t* rp = qk + (size_t)(pm * 256 + ai * 128 + wr * 64 + m * 16 + fq * 4 + j) * 2048 + head * 64 + fr;
; #pragma unroll
;                     for (int bj = 0; bj < 2; ++bj)
; #pragma unroll
;                         for (int n = 0; n < 2; ++n) rp[bj * 32 + n * 16] = (bf16_t)f2bf(acc[ai][bj][m][n][j] * rs * gv[bj][n]);
	v_pk_add_f32 v[194:195], v[194:195], v[196:197]
	ds_bpermute_b32 v197, v174, v195
	ds_bpermute_b32 v196, v174, v194
	v_mov_b32_e32 v200, v79
	v_mov_b32_e32 v201, v47
	v_pk_mul_f32 v[200:201], v[200:201], v[200:201]
	v_mov_b32_e32 v202, v19
	s_waitcnt lgkmcnt(0)
	v_pk_add_f32 v[194:195], v[194:195], v[196:197]
	ds_bpermute_b32 v197, v173, v195
	ds_bpermute_b32 v196, v173, v194
	v_mov_b32_e32 v203, v3
	v_pk_mul_f32 v[202:203], v[202:203], v[202:203]
	v_mov_b32_e32 v204, v200
	v_mov_b32_e32 v200, v202
	s_waitcnt lgkmcnt(0)
	v_pk_add_f32 v[194:195], v[194:195], v[196:197]
	ds_bpermute_b32 v197, v172, v195
	ds_bpermute_b32 v196, v172, v194
	v_mov_b32_e32 v202, v21
	s_waitcnt lgkmcnt(0)
	v_pk_add_f32 v[194:195], v[194:195], v[196:197]
	s_nop 0
	v_pk_fma_f32 v[194:195], v[194:195], s[8:9], v[162:163] op_sel_hi:[1,0,0]
	v_mov_b32_e32 v196, v78
	v_mul_f32_e32 v161, 0x4b800000, v195
	v_cmp_gt_f32_e64 s[46:47], s93, v195
	v_mov_b32_e32 v197, v46
	v_pk_mul_f32 v[196:197], v[196:197], v[196:197]
	v_cndmask_b32_e64 v161, v195, v161, s[46:47]
	v_rsq_f32_e32 v161, v161
	v_mov_b32_e32 v205, v196
	v_mov_b32_e32 v196, v201
	v_pk_add_f32 v[196:197], v[204:205], v[196:197]
	v_mul_f32_e32 v192, 0x45800000, v161
	v_cndmask_b32_e64 v161, v161, v192, s[46:47]
	v_mul_f32_e32 v192, v88, v161
	v_mul_f32_e32 v192, v168, v192
	v_cvt_pk_bf16_f32 v192, v192, s0
	global_store_short v[198:199], v192, off
	v_mul_f32_e32 v192, v56, v161
	v_mul_f32_e32 v192, v169, v192
	v_cvt_pk_bf16_f32 v192, v192, s0
	global_store_short v[198:199], v192, off offset:32
	v_mul_f32_e32 v192, v24, v161
	v_mul_f32_e32 v161, v8, v161
	v_mul_f32_e32 v192, v170, v192
	v_mul_f32_e32 v161, v171, v161
	v_cvt_pk_bf16_f32 v192, v192, s0
	v_cvt_pk_bf16_f32 v161, v161, s0
	global_store_short v[198:199], v192, off offset:64
	global_store_short v[198:199], v161, off offset:96
	v_mov_b32_e32 v198, v18
	v_mov_b32_e32 v199, v2
	v_pk_mul_f32 v[198:199], v[198:199], v[198:199]
	v_cmp_gt_f32_e32 vcc, s93, v194
	v_mov_b32_e32 v201, v198
	v_pk_add_f32 v[196:197], v[196:197], v[200:201]
	v_mov_b32_e32 v198, v203
	v_pk_add_f32 v[196:197], v[196:197], v[198:199]
	ds_bpermute_b32 v199, v175, v197
	ds_bpermute_b32 v198, v175, v196
	v_mul_f32_e32 v161, 0x4b800000, v194
	v_cndmask_b32_e32 v161, v194, v161, vcc
	v_rsq_f32_e32 v161, v161
	v_add_u32_e32 v194, 0xa3, v160
	s_waitcnt lgkmcnt(0)
	v_pk_add_f32 v[196:197], v[196:197], v[198:199]
	ds_bpermute_b32 v199, v174, v197
	ds_bpermute_b32 v198, v174, v196
	v_mul_f32_e32 v192, 0x45800000, v161
	v_cndmask_b32_e32 v161, v161, v192, vcc
	v_ashrrev_i32_e32 v195, 31, v194
	v_mul_f32_e32 v192, v89, v161
	s_waitcnt lgkmcnt(0)
	v_pk_add_f32 v[196:197], v[196:197], v[198:199]
	ds_bpermute_b32 v199, v173, v197
	ds_bpermute_b32 v198, v173, v196
	v_lshlrev_b64 v[194:195], 12, v[194:195]
	v_mul_f32_e32 v192, v168, v192
	v_lshl_add_u64 v[194:195], v[158:159], 0, v[194:195]
	v_cvt_pk_bf16_f32 v192, v192, s0
	s_waitcnt lgkmcnt(0)
	v_pk_add_f32 v[196:197], v[196:197], v[198:199]
	ds_bpermute_b32 v199, v172, v197
	ds_bpermute_b32 v198, v172, v196
	global_store_short v[194:195], v192, off
	v_mul_f32_e32 v192, v57, v161
	v_mul_f32_e32 v192, v169, v192
	v_cvt_pk_bf16_f32 v192, v192, s0
	global_store_short v[194:195], v192, off offset:32
	v_mul_f32_e32 v192, v25, v161
	v_mul_f32_e32 v161, v9, v161
	v_mul_f32_e32 v161, v171, v161
	s_waitcnt lgkmcnt(0)
; __device__ __forceinline__ unsigned f2bf(float f) { const __bf16 b = (__bf16)f; return (unsigned)__builtin_bit_cast(unsigned short, b); }
;     __device__ __forceinline__ void operator()(Acc& acc, int pm, int pn, int wr, int wc, int fr, int fq) const {
;     ...
;                     float ss = acc[ai][0][m][0][j] * acc[ai][0][m][0][j] + acc[ai][0][m][1][j] * acc[ai][0][m][1][j] +
;                                acc[ai][1][m][0][j] * acc[ai][1][m][0][j] + acc[ai][1][m][1][j] * acc[ai][1][m][1][j];
;                     ss += __shfl_xor(ss, 1); ss += __shfl_xor(ss, 2); ss += __shfl_xor(ss, 4); ss += __shfl_xor(ss, 8);
;                     const float rs = rsqrtf(ss * (1.0f / 64.0f) + EPSV);
;                     bf16_t* rp = qk + (size_t)(pm * 256 + ai * 128 + wr * 64 + m * 16 + fq * 4 + j) * 2048 + head * 64 + fr;
; #pragma unroll
;                     for (int bj = 0; bj < 2; ++bj)
; #pragma unroll
;                         for (int n = 0; n < 2; ++n) rp[bj * 32 + n * 16] = (bf16_t)f2bf(acc[ai][bj][m][n][j] * rs * gv[bj][n]);
	v_pk_add_f32 v[196:197], v[196:197], v[198:199]
	v_cvt_pk_bf16_f32 v161, v161, s0
	v_pk_fma_f32 v[196:197], v[196:197], s[8:9], v[162:163] op_sel_hi:[1,0,0]
	global_store_short v[194:195], v161, off offset:96
	v_mul_f32_e32 v161, 0x4b800000, v197
	v_cmp_gt_f32_e64 s[46:47], s93, v197
	v_mul_f32_e32 v192, v170, v192
	v_cvt_pk_bf16_f32 v192, v192, s0
	v_cndmask_b32_e64 v161, v197, v161, s[46:47]
	v_rsq_f32_e32 v161, v161
	global_store_short v[194:195], v192, off offset:64
	v_add_u32_e32 v194, 0xb0, v160
	v_ashrrev_i32_e32 v195, 31, v194
	v_mul_f32_e32 v192, 0x45800000, v161
	v_cndmask_b32_e64 v161, v161, v192, s[46:47]
	v_mul_f32_e32 v192, v78, v161
	v_lshlrev_b64 v[194:195], 12, v[194:195]
	v_mul_f32_e32 v192, v168, v192
	v_lshl_add_u64 v[194:195], v[158:159], 0, v[194:195]
	v_cvt_pk_bf16_f32 v192, v192, s0
	global_store_short v[194:195], v192, off
	v_mul_f32_e32 v192, v46, v161
	v_mul_f32_e32 v192, v169, v192
	v_cvt_pk_bf16_f32 v192, v192, s0
	global_store_short v[194:195], v192, off offset:32
	v_mul_f32_e32 v192, v18, v161
	v_mul_f32_e32 v161, v2, v161
	v_mul_f32_e32 v161, v171, v161
	v_cvt_pk_bf16_f32 v161, v161, s0
	v_cmp_gt_f32_e32 vcc, s93, v196
	global_store_short v[194:195], v161, off offset:96
	v_mul_f32_e32 v161, 0x4b800000, v196
	v_cndmask_b32_e32 v161, v196, v161, vcc
	v_rsq_f32_e32 v161, v161
	v_mul_f32_e32 v192, v170, v192
	v_cvt_pk_bf16_f32 v192, v192, s0
	global_store_short v[194:195], v192, off offset:64
	v_mul_f32_e32 v192, 0x45800000, v161
	v_cndmask_b32_e32 v161, v161, v192, vcc
	v_add_u32_e32 v194, 0xb1, v160
	v_ashrrev_i32_e32 v195, 31, v194
	v_mul_f32_e32 v192, v79, v161
	v_lshlrev_b64 v[194:195], 12, v[194:195]
	v_mul_f32_e32 v192, v168, v192
	v_lshl_add_u64 v[194:195], v[158:159], 0, v[194:195]
	v_cvt_pk_bf16_f32 v192, v192, s0
	global_store_short v[194:195], v192, off
	v_mul_f32_e32 v192, v47, v161
	v_mul_f32_e32 v192, v169, v192
	v_cvt_pk_bf16_f32 v192, v192, s0
	global_store_short v[194:195], v192, off offset:32
	v_mul_f32_e32 v192, v19, v161
	v_mul_f32_e32 v161, v3, v161
	v_mul_f32_e32 v192, v170, v192
	v_mul_f32_e32 v161, v171, v161
	v_cvt_pk_bf16_f32 v192, v192, s0
	v_cvt_pk_bf16_f32 v161, v161, s0
	global_store_short v[194:195], v192, off offset:64
	global_store_short v[194:195], v161, off offset:96
	v_mov_b32_e32 v194, v80
	v_mov_b32_e32 v195, v48
	v_mov_b32_e32 v200, v81
	v_mov_b32_e32 v201, v49
	v_pk_mul_f32 v[194:195], v[194:195], v[194:195]
	v_mov_b32_e32 v196, v20
	v_mov_b32_e32 v197, v4
	v_pk_mul_f32 v[200:201], v[200:201], v[200:201]
	v_mov_b32_e32 v203, v5
	v_pk_mul_f32 v[196:197], v[196:197], v[196:197]
	v_pk_mul_f32 v[202:203], v[202:203], v[202:203]
	v_mov_b32_e32 v204, v200
	v_mov_b32_e32 v205, v194
	v_mov_b32_e32 v194, v201
	v_pk_add_f32 v[194:195], v[204:205], v[194:195]
	v_mov_b32_e32 v200, v202
	v_mov_b32_e32 v201, v196
	v_pk_add_f32 v[194:195], v[194:195], v[200:201]
	v_mov_b32_e32 v196, v203
	v_pk_add_f32 v[194:195], v[194:195], v[196:197]
	ds_bpermute_b32 v197, v175, v195
	ds_bpermute_b32 v196, v175, v194
	v_add_u32_e32 v198, 0xb2, v160
	v_ashrrev_i32_e32 v199, 31, v198
	v_lshlrev_b64 v[198:199], 12, v[198:199]
	v_lshl_add_u64 v[198:199], v[158:159], 0, v[198:199]
	s_waitcnt lgkmcnt(0)
	v_pk_add_f32 v[194:195], v[194:195], v[196:197]
	ds_bpermute_b32 v175, v174, v195
	ds_bpermute_b32 v174, v174, v194
	v_add_u32_e32 v160, 0xb3, v160
	s_waitcnt lgkmcnt(0)
	v_pk_add_f32 v[174:175], v[194:195], v[174:175]
	ds_bpermute_b32 v195, v173, v175
	ds_bpermute_b32 v194, v173, v174
	s_waitcnt lgkmcnt(0)
	v_pk_add_f32 v[174:175], v[174:175], v[194:195]
	ds_bpermute_b32 v173, v172, v175
	ds_bpermute_b32 v172, v172, v174
	s_waitcnt lgkmcnt(0)
	v_pk_add_f32 v[172:173], v[174:175], v[172:173]
	s_nop 0
	v_pk_fma_f32 v[162:163], v[172:173], s[8:9], v[162:163] op_sel_hi:[1,0,0]
	s_nop 0
	v_mul_f32_e32 v161, 0x4b800000, v163
	v_cmp_gt_f32_e64 s[46:47], s93, v163
	v_cmp_gt_f32_e32 vcc, s93, v162
	s_nop 0
	v_cndmask_b32_e64 v161, v163, v161, s[46:47]
	v_rsq_f32_e32 v161, v161
	s_nop 0
	v_mul_f32_e32 v163, 0x45800000, v161
	v_cndmask_b32_e64 v161, v161, v163, s[46:47]
	v_mul_f32_e32 v163, v80, v161
	v_mul_f32_e32 v163, v168, v163
	v_cvt_pk_bf16_f32 v163, v163, s0
	global_store_short v[198:199], v163, off
	v_mul_f32_e32 v163, v48, v161
	v_mul_f32_e32 v163, v169, v163
	v_cvt_pk_bf16_f32 v163, v163, s0
	global_store_short v[198:199], v163, off offset:32
	v_mul_f32_e32 v163, v20, v161
	v_mul_f32_e32 v161, v4, v161
	v_mul_f32_e32 v161, v171, v161
	v_cvt_pk_bf16_f32 v161, v161, s0
	global_store_short v[198:199], v161, off offset:96
	v_mul_f32_e32 v161, 0x4b800000, v162
	v_cndmask_b32_e32 v161, v162, v161, vcc
	v_rsq_f32_e32 v161, v161
	v_mul_f32_e32 v163, v170, v163
	v_cvt_pk_bf16_f32 v163, v163, s0
	global_store_short v[198:199], v163, off offset:64
	v_mul_f32_e32 v162, 0x45800000, v161
	v_cndmask_b32_e32 v162, v161, v162, vcc
	v_ashrrev_i32_e32 v161, 31, v160
	v_lshlrev_b64 v[160:161], 12, v[160:161]
	v_lshl_add_u64 v[158:159], v[158:159], 0, v[160:161]
	v_mul_f32_e32 v160, v81, v162
	v_mul_f32_e32 v160, v168, v160
	v_cvt_pk_bf16_f32 v160, v160, s0
	global_store_short v[158:159], v160, off
	v_mul_f32_e32 v160, v49, v162
	v_mul_f32_e32 v160, v169, v160
	v_cvt_pk_bf16_f32 v160, v160, s0
	global_store_short v[158:159], v160, off offset:32
	v_mul_f32_e32 v160, v21, v162
	v_mul_f32_e32 v160, v170, v160
	v_cvt_pk_bf16_f32 v160, v160, s0
	global_store_short v[158:159], v160, off offset:64
	v_mul_f32_e32 v160, v5, v162
	v_mul_f32_e32 v160, v171, v160
	v_cvt_pk_bf16_f32 v160, v160, s0
	global_store_short v[158:159], v160, off offset:96

; #define PG8_STAGE(bufoff, gbase) do { _Pragma("unroll") for (int _i = 0; _i < 2; ++_i) \
;         __builtin_amdgcn_global_load_lds((const unsigned*)((const char*)(gbase) + voff[_i]), (LAS unsigned*)(lds + (bufoff) + ldsw + _i * 8192), 16, 0, 0); } while (0)
; #define PG8_LDA(dst, b, h) do { _Pragma("unroll") for (int m = 0; m < 4; ++m) _Pragma("unroll") for (int k = 0; k < 2; ++k) dst[m][k] = *(const LAS bf16x8*)(lds + PG8_SA(b, h) + aoff + m * 2048 + k * 1024); } while (0)
; #define PG8_LDB(dst, b, h) do { _Pragma("unroll") for (int n = 0; n < 2; ++n) _Pragma("unroll") for (int k = 0; k < 2; ++k) dst[n][k] = *(const LAS bf16x8*)(lds + PG8_SB(b, h) + boff + n * 2048 + k * 1024); } while (0)
; #define PG8_WAIT_L(n) asm volatile("s_waitcnt lgkmcnt(" #n ")" ::: "memory")
; #define PG8_BAR __builtin_amdgcn_s_barrier()
; #define PG8_SCHED __builtin_amdgcn_sched_barrier(0)
;     ...
;             PG8_LDB(B0, 0, 0); PG8_SCHED; PG8_LDA(At, 0, 0); PG8_STAGE(PG8_SA(1, 1), a1 + hstep);
;             PG8_WAIT_L(8); PG8_BAR; PG8_WAIT_L(0); PG8_MMA(0, 0, At, B0); PG8_BAR; PG8_SCHED;
;             PG8_LDB(B1, 0, 1); PG8_STAGE(PG8_SB(0, 0), b2);
;             PG8_BAR; PG8_WAIT_L(0); PG8_MMA(0, 1, At, B1); PG8_BAR;
;             PG8_LDA(At, 0, 1); PG8_STAGE(PG8_SA(0, 0), a2);
;             PG8_BAR; PG8_WAIT_L(0); PG8_MMA(1, 0, At, B0); PG8_BAR; PG8_SCHED;
.LBB0_482:
	s_add_u32 s0, s10, 0xfffc0080
	s_addc_u32 s1, s11, -1
	s_add_i32 s29, 0, 0x10000
	v_add_u32_e32 v169, s29, v164
	ds_read_b128 v[156:159], v169
	ds_read_b128 v[160:163], v169 offset:1024
	ds_read_b128 v[170:173], v169 offset:2048
	ds_read_b128 v[194:197], v169 offset:3072
	s_cmp_eq_u32 s28, 12
	s_cselect_b32 s15, s4, s1
	s_cselect_b32 s14, s7, s0
	s_cselect_b32 s13, s18, s23
	s_cselect_b32 s12, s19, s22
	v_lshl_add_u64 v[174:175], s[10:11], 0, v[152:153]
	s_add_i32 m0, s41, 0xc000
	ds_read_b128 v[198:201], v168
	ds_read_b128 v[202:205], v168 offset:1024
	ds_read_b128 v[206:209], v168 offset:2048
	ds_read_b128 v[210:213], v168 offset:3072
	ds_read_b128 v[214:217], v168 offset:4096
	ds_read_b128 v[218:221], v168 offset:5120
	ds_read_b128 v[222:225], v168 offset:6144
	ds_read_b128 v[226:229], v168 offset:7168
	global_load_lds_dwordx4 v[174:175], off
	s_add_i32 m0, s41, 0xe000
	v_lshl_add_u64 v[174:175], s[10:11], 0, v[154:155]
	global_load_lds_dwordx4 v[174:175], off
	s_waitcnt lgkmcnt(8)
	s_barrier
	s_waitcnt lgkmcnt(0)
	s_setprio 1
	v_mfma_f32_16x16x32_bf16 v[126:129], v[198:201], v[156:159], v[126:129]
	v_mfma_f32_16x16x32_bf16 v[110:113], v[198:201], v[170:173], v[110:113]
	v_mfma_f32_16x16x32_bf16 v[122:125], v[206:209], v[156:159], v[122:125]
	v_mfma_f32_16x16x32_bf16 v[106:109], v[206:209], v[170:173], v[106:109]
	v_mfma_f32_16x16x32_bf16 v[118:121], v[214:217], v[156:159], v[118:121]
	v_mfma_f32_16x16x32_bf16 v[102:105], v[214:217], v[170:173], v[102:105]
	v_mfma_f32_16x16x32_bf16 v[114:117], v[222:225], v[156:159], v[114:117]
	v_mfma_f32_16x16x32_bf16 v[94:97], v[222:225], v[170:173], v[94:97]
	v_mfma_f32_16x16x32_bf16 v[126:129], v[202:205], v[160:163], v[126:129]
	v_mfma_f32_16x16x32_bf16 v[110:113], v[202:205], v[194:197], v[110:113]
	v_mfma_f32_16x16x32_bf16 v[122:125], v[210:213], v[160:163], v[122:125]
	v_mfma_f32_16x16x32_bf16 v[106:109], v[210:213], v[194:197], v[106:109]
	v_mfma_f32_16x16x32_bf16 v[118:121], v[218:221], v[160:163], v[118:121]
	v_mfma_f32_16x16x32_bf16 v[102:105], v[218:221], v[194:197], v[102:105]
	v_mfma_f32_16x16x32_bf16 v[114:117], v[226:229], v[160:163], v[114:117]
	v_mfma_f32_16x16x32_bf16 v[94:97], v[226:229], v[194:197], v[94:97]
	s_setprio 0
	s_barrier
	s_add_i32 s0, 0, 0x14000
	s_add_i32 s1, s29, s40
	v_add_u32_e32 v169, s0, v164
	v_lshl_add_u64 v[174:175], s[12:13], 0, v[132:133]
	s_mov_b32 m0, s1
	ds_read_b128 v[230:233], v169
	ds_read_b128 v[234:237], v169 offset:1024
	ds_read_b128 v[238:241], v169 offset:2048
	ds_read_b128 v[242:245], v169 offset:3072
	global_load_lds_dwordx4 v[174:175], off
	s_add_i32 m0, s1, 0x2000
	v_lshl_add_u64 v[192:193], s[12:13], 0, v[130:131]
	global_load_lds_dwordx4 v[192:193], off
	s_barrier
	s_waitcnt lgkmcnt(0)
	s_setprio 1
	v_mfma_f32_16x16x32_bf16 v[82:85], v[198:201], v[230:233], v[82:85]
	v_mfma_f32_16x16x32_bf16 v[50:53], v[198:201], v[238:241], v[50:53]
	v_mfma_f32_16x16x32_bf16 v[74:77], v[206:209], v[230:233], v[74:77]
	v_mfma_f32_16x16x32_bf16 v[42:45], v[206:209], v[238:241], v[42:45]
	v_mfma_f32_16x16x32_bf16 v[66:69], v[214:217], v[230:233], v[66:69]
	v_mfma_f32_16x16x32_bf16 v[38:41], v[214:217], v[238:241], v[38:41]
	v_mfma_f32_16x16x32_bf16 v[58:61], v[222:225], v[230:233], v[58:61]
	v_mfma_f32_16x16x32_bf16 v[30:33], v[222:225], v[238:241], v[30:33]
	v_mfma_f32_16x16x32_bf16 v[82:85], v[202:205], v[234:237], v[82:85]
	v_mfma_f32_16x16x32_bf16 v[50:53], v[202:205], v[242:245], v[50:53]
	v_mfma_f32_16x16x32_bf16 v[74:77], v[210:213], v[234:237], v[74:77]
	v_mfma_f32_16x16x32_bf16 v[42:45], v[210:213], v[242:245], v[42:45]
	v_mfma_f32_16x16x32_bf16 v[66:69], v[218:221], v[234:237], v[66:69]
	v_mfma_f32_16x16x32_bf16 v[38:41], v[218:221], v[242:245], v[38:41]
	v_mfma_f32_16x16x32_bf16 v[58:61], v[226:229], v[234:237], v[58:61]
	v_mfma_f32_16x16x32_bf16 v[30:33], v[226:229], v[242:245], v[30:33]
	s_setprio 0
	s_mov_b32 m0, s41
	v_lshl_add_u64 v[246:247], s[14:15], 0, v[132:133]
	s_barrier
	ds_read_b128 v[198:201], v168 offset:16384
	ds_read_b128 v[202:205], v168 offset:17408
	ds_read_b128 v[206:209], v168 offset:18432
	ds_read_b128 v[210:213], v168 offset:19456
	ds_read_b128 v[214:217], v168 offset:20480
	ds_read_b128 v[218:221], v168 offset:21504
	ds_read_b128 v[222:225], v168 offset:22528
	ds_read_b128 v[226:229], v168 offset:23552
	global_load_lds_dwordx4 v[246:247], off
	s_mov_b32 m0, s64
	v_lshl_add_u64 v[248:249], s[14:15], 0, v[130:131]
	global_load_lds_dwordx4 v[248:249], off
	s_barrier
	s_waitcnt lgkmcnt(0)
	s_setprio 1
	v_mfma_f32_16x16x32_bf16 v[98:101], v[198:201], v[156:159], v[98:101]
	v_mfma_f32_16x16x32_bf16 v[70:73], v[198:201], v[170:173], v[70:73]
	v_mfma_f32_16x16x32_bf16 v[90:93], v[206:209], v[156:159], v[90:93]
	v_mfma_f32_16x16x32_bf16 v[62:65], v[206:209], v[170:173], v[62:65]
	v_mfma_f32_16x16x32_bf16 v[86:89], v[214:217], v[156:159], v[86:89]
	v_mfma_f32_16x16x32_bf16 v[54:57], v[214:217], v[170:173], v[54:57]
	v_mfma_f32_16x16x32_bf16 v[78:81], v[222:225], v[156:159], v[78:81]
	v_mfma_f32_16x16x32_bf16 v[46:49], v[222:225], v[170:173], v[46:49]
	v_mfma_f32_16x16x32_bf16 v[98:101], v[202:205], v[160:163], v[98:101]
	v_mfma_f32_16x16x32_bf16 v[70:73], v[202:205], v[194:197], v[70:73]
	v_mfma_f32_16x16x32_bf16 v[90:93], v[210:213], v[160:163], v[90:93]
	v_mfma_f32_16x16x32_bf16 v[62:65], v[210:213], v[194:197], v[62:65]
	v_mfma_f32_16x16x32_bf16 v[86:89], v[218:221], v[160:163], v[86:89]
	v_mfma_f32_16x16x32_bf16 v[54:57], v[218:221], v[194:197], v[54:57]
	v_mfma_f32_16x16x32_bf16 v[78:81], v[226:229], v[160:163], v[78:81]
	v_mfma_f32_16x16x32_bf16 v[46:49], v[226:229], v[194:197], v[46:49]
	s_setprio 0
	s_barrier
; #define PG8_STAGE(bufoff, gbase) do { _Pragma("unroll") for (int _i = 0; _i < 2; ++_i) \
;         __builtin_amdgcn_global_load_lds((const unsigned*)((const char*)(gbase) + voff[_i]), (LAS unsigned*)(lds + (bufoff) + ldsw + _i * 8192), 16, 0, 0); } while (0)
; #define PG8_LDA(dst, b, h) do { _Pragma("unroll") for (int m = 0; m < 4; ++m) _Pragma("unroll") for (int k = 0; k < 2; ++k) dst[m][k] = *(const LAS bf16x8*)(lds + PG8_SA(b, h) + aoff + m * 2048 + k * 1024); } while (0)
; #define PG8_LDB(dst, b, h) do { _Pragma("unroll") for (int n = 0; n < 2; ++n) _Pragma("unroll") for (int k = 0; k < 2; ++k) dst[n][k] = *(const LAS bf16x8*)(lds + PG8_SB(b, h) + boff + n * 2048 + k * 1024); } while (0)
; #define PG8_WAIT_V(n) asm volatile("s_waitcnt vmcnt(" #n ")" ::: "memory")
; #define PG8_WAIT_L(n) asm volatile("s_waitcnt lgkmcnt(" #n ")" ::: "memory")
; #define PG8_BAR __builtin_amdgcn_s_barrier()
; #define PG8_SCHED __builtin_amdgcn_sched_barrier(0)
;     ...
;             PG8_STAGE(PG8_SB(0, 1), b2 + hstep);
;             PG8_WAIT_V(6); PG8_BAR; PG8_MMA(1, 1, At, B1); PG8_BAR;
;             PG8_LDB(B0, 1, 0); PG8_SCHED; PG8_LDA(At, 1, 0); PG8_STAGE(PG8_SA(0, 1), a2 + hstep);
;             PG8_WAIT_L(8); PG8_BAR; PG8_WAIT_L(0); PG8_MMA(0, 0, At, B0); PG8_BAR; PG8_SCHED;
;             PG8_LDB(B1, 1, 1); PG8_STAGE(PG8_SB(1, 0), b3);
;             PG8_BAR; PG8_WAIT_L(0); PG8_MMA(0, 1, At, B1); PG8_BAR;
;             PG8_LDA(At, 1, 1); PG8_STAGE(PG8_SA(1, 0), a3);
;             PG8_BAR; PG8_WAIT_L(0); PG8_MMA(1, 0, At, B0); PG8_BAR; PG8_SCHED;
	s_add_u32 s30, s12, 0x40000
	s_addc_u32 s31, s13, 0
	s_add_i32 s0, s0, s40
	s_mov_b32 m0, s0
	v_lshl_add_u64 v[156:157], s[30:31], 0, v[132:133]
	global_load_lds_dwordx4 v[156:157], off
	s_add_i32 m0, s0, 0x2000
	v_lshl_add_u64 v[156:157], s[30:31], 0, v[130:131]
	global_load_lds_dwordx4 v[156:157], off
	s_waitcnt vmcnt(6)
	s_barrier
	s_setprio 1
	v_mfma_f32_16x16x32_bf16 v[34:37], v[198:201], v[230:233], v[34:37]
	v_mfma_f32_16x16x32_bf16 v[14:17], v[198:201], v[238:241], v[14:17]
	v_mfma_f32_16x16x32_bf16 v[26:29], v[206:209], v[230:233], v[26:29]
	v_mfma_f32_16x16x32_bf16 v[10:13], v[206:209], v[238:241], v[10:13]
	v_mfma_f32_16x16x32_bf16 v[22:25], v[214:217], v[230:233], v[22:25]
	v_mfma_f32_16x16x32_bf16 v[6:9], v[214:217], v[238:241], v[6:9]
	v_mfma_f32_16x16x32_bf16 v[18:21], v[222:225], v[230:233], v[18:21]
	v_mfma_f32_16x16x32_bf16 v[2:5], v[222:225], v[238:241], v[2:5]
	v_mfma_f32_16x16x32_bf16 v[34:37], v[202:205], v[234:237], v[34:37]
	v_mfma_f32_16x16x32_bf16 v[14:17], v[202:205], v[242:245], v[14:17]
	v_mfma_f32_16x16x32_bf16 v[26:29], v[210:213], v[234:237], v[26:29]
	v_mfma_f32_16x16x32_bf16 v[10:13], v[210:213], v[242:245], v[10:13]
	v_mfma_f32_16x16x32_bf16 v[22:25], v[218:221], v[234:237], v[22:25]
	v_mfma_f32_16x16x32_bf16 v[6:9], v[218:221], v[242:245], v[6:9]
	v_mfma_f32_16x16x32_bf16 v[18:21], v[226:229], v[234:237], v[18:21]
	v_mfma_f32_16x16x32_bf16 v[2:5], v[226:229], v[242:245], v[2:5]
	s_setprio 0
	s_add_i32 s0, 0, 0x18000
	v_add_u32_e32 v169, s0, v164
	s_barrier
	ds_read_b128 v[156:159], v169
	ds_read_b128 v[160:163], v169 offset:1024
	ds_read_b128 v[170:173], v169 offset:2048
	ds_read_b128 v[194:197], v169 offset:3072
	s_add_u32 s14, s14, 0x40000
	s_addc_u32 s15, s15, 0
	s_mov_b32 m0, s65
	v_lshl_add_u64 v[230:231], s[14:15], 0, v[132:133]
	ds_read_b128 v[198:201], v168 offset:32768
	ds_read_b128 v[202:205], v168 offset:33792
	ds_read_b128 v[206:209], v168 offset:34816
	ds_read_b128 v[210:213], v168 offset:35840
	ds_read_b128 v[214:217], v168 offset:36864
	ds_read_b128 v[218:221], v168 offset:37888
	ds_read_b128 v[222:225], v168 offset:38912
	ds_read_b128 v[226:229], v168 offset:39936
	global_load_lds_dwordx4 v[230:231], off
	s_mov_b32 m0, s66
	v_lshl_add_u64 v[230:231], s[14:15], 0, v[130:131]
	global_load_lds_dwordx4 v[230:231], off
	s_waitcnt lgkmcnt(8)
	s_barrier
	s_waitcnt lgkmcnt(0)
	s_setprio 1
	v_mfma_f32_16x16x32_bf16 v[126:129], v[198:201], v[156:159], v[126:129]
	v_mfma_f32_16x16x32_bf16 v[110:113], v[198:201], v[170:173], v[110:113]
	v_mfma_f32_16x16x32_bf16 v[122:125], v[206:209], v[156:159], v[122:125]
	v_mfma_f32_16x16x32_bf16 v[106:109], v[206:209], v[170:173], v[106:109]
	v_mfma_f32_16x16x32_bf16 v[118:121], v[214:217], v[156:159], v[118:121]
	v_mfma_f32_16x16x32_bf16 v[102:105], v[214:217], v[170:173], v[102:105]
	v_mfma_f32_16x16x32_bf16 v[114:117], v[222:225], v[156:159], v[114:117]
	v_mfma_f32_16x16x32_bf16 v[94:97], v[222:225], v[170:173], v[94:97]
	v_mfma_f32_16x16x32_bf16 v[126:129], v[202:205], v[160:163], v[126:129]
	v_mfma_f32_16x16x32_bf16 v[110:113], v[202:205], v[194:197], v[110:113]
	v_mfma_f32_16x16x32_bf16 v[122:125], v[210:213], v[160:163], v[122:125]
	v_mfma_f32_16x16x32_bf16 v[106:109], v[210:213], v[194:197], v[106:109]
	v_mfma_f32_16x16x32_bf16 v[118:121], v[218:221], v[160:163], v[118:121]
	v_mfma_f32_16x16x32_bf16 v[102:105], v[218:221], v[194:197], v[102:105]
	v_mfma_f32_16x16x32_bf16 v[114:117], v[226:229], v[160:163], v[114:117]
	v_mfma_f32_16x16x32_bf16 v[94:97], v[226:229], v[194:197], v[94:97]
	s_setprio 0
	s_barrier
	s_add_i32 s1, 0, 0x1c000
	s_add_i32 s0, s0, s40
	v_add_u32_e32 v169, s1, v164
	v_lshl_add_u64 v[174:175], v[174:175], 0, s[88:89]
	s_mov_b32 m0, s0
	ds_read_b128 v[230:233], v169
	ds_read_b128 v[234:237], v169 offset:1024
	ds_read_b128 v[238:241], v169 offset:2048
	ds_read_b128 v[242:245], v169 offset:3072
	global_load_lds_dwordx4 v[174:175], off
	s_add_i32 m0, s0, 0x2000
	v_lshl_add_u64 v[174:175], v[192:193], 0, s[88:89]
	global_load_lds_dwordx4 v[174:175], off
	s_barrier
	s_waitcnt lgkmcnt(0)
	s_setprio 1
	v_mfma_f32_16x16x32_bf16 v[82:85], v[198:201], v[230:233], v[82:85]
	v_mfma_f32_16x16x32_bf16 v[50:53], v[198:201], v[238:241], v[50:53]
	v_mfma_f32_16x16x32_bf16 v[74:77], v[206:209], v[230:233], v[74:77]
	v_mfma_f32_16x16x32_bf16 v[42:45], v[206:209], v[238:241], v[42:45]
	v_mfma_f32_16x16x32_bf16 v[66:69], v[214:217], v[230:233], v[66:69]
	v_mfma_f32_16x16x32_bf16 v[38:41], v[214:217], v[238:241], v[38:41]
	v_mfma_f32_16x16x32_bf16 v[58:61], v[222:225], v[230:233], v[58:61]
	v_mfma_f32_16x16x32_bf16 v[30:33], v[222:225], v[238:241], v[30:33]
	v_mfma_f32_16x16x32_bf16 v[82:85], v[202:205], v[234:237], v[82:85]
	v_mfma_f32_16x16x32_bf16 v[50:53], v[202:205], v[242:245], v[50:53]
	v_mfma_f32_16x16x32_bf16 v[74:77], v[210:213], v[234:237], v[74:77]
	v_mfma_f32_16x16x32_bf16 v[42:45], v[210:213], v[242:245], v[42:45]
	v_mfma_f32_16x16x32_bf16 v[66:69], v[218:221], v[234:237], v[66:69]
	v_mfma_f32_16x16x32_bf16 v[38:41], v[218:221], v[242:245], v[38:41]
	v_mfma_f32_16x16x32_bf16 v[58:61], v[226:229], v[234:237], v[58:61]
	v_mfma_f32_16x16x32_bf16 v[30:33], v[226:229], v[242:245], v[30:33]
	s_setprio 0
	s_mov_b32 m0, s67
	v_lshl_add_u64 v[174:175], v[246:247], 0, s[88:89]
	s_barrier
	ds_read_b128 v[198:201], v168 offset:49152
	ds_read_b128 v[202:205], v168 offset:50176
	ds_read_b128 v[206:209], v168 offset:51200
	ds_read_b128 v[210:213], v168 offset:52224
	ds_read_b128 v[214:217], v168 offset:53248
	ds_read_b128 v[218:221], v168 offset:54272
	ds_read_b128 v[222:225], v168 offset:55296
	ds_read_b128 v[226:229], v168 offset:56320
	global_load_lds_dwordx4 v[174:175], off
	s_mov_b32 m0, s68
	v_lshl_add_u64 v[174:175], v[248:249], 0, s[88:89]
	global_load_lds_dwordx4 v[174:175], off
	s_barrier
; __device__ __forceinline__ float frcp(float x) { return __builtin_amdgcn_rcpf(x); }
; __device__ __forceinline__ float fexp(float x) { return __builtin_amdgcn_exp2f(x * 1.4426950408889634f); }
; #define PG8_STAGE(bufoff, gbase) do { _Pragma("unroll") for (int _i = 0; _i < 2; ++_i) \
;         __builtin_amdgcn_global_load_lds((const unsigned*)((const char*)(gbase) + voff[_i]), (LAS unsigned*)(lds + (bufoff) + ldsw + _i * 8192), 16, 0, 0); } while (0)
; #define PG8_WAIT_V(n) asm volatile("s_waitcnt vmcnt(" #n ")" ::: "memory")
; #define PG8_WAIT_L(n) asm volatile("s_waitcnt lgkmcnt(" #n ")" ::: "memory")
; #define PG8_BAR __builtin_amdgcn_s_barrier()
; #define PG8_SCHED __builtin_amdgcn_sched_barrier(0)
;     ...
;             PG8_BAR; PG8_WAIT_L(0); PG8_MMA(1, 0, At, B0); PG8_BAR; PG8_SCHED;
;             PG8_STAGE(PG8_SB(1, 1), b3 + hstep);
;             PG8_WAIT_V(6); PG8_BAR; PG8_MMA(1, 1, At, B1); PG8_BAR;
;     __device__ __forceinline__ void operator()(Acc& acc, int pm, int pn, int wr, int wc, int fr, int fq) const {
;         if (pn >= 8) { store_vT(acc, vT, (pn - 8) * 256, pm, wr, wc, fr, fq); return; }
;         const int chl = pn * 64 + wc * 16 + fr, chg = half * 512 + chl;
;         const float lb = lbv[chg], oml = 1.f - lb;
; #pragma unroll
;         for (int ai = 0; ai < 2; ++ai) {
;             const int row0 = pm * 256 + ai * 128 + wr * 64;
;             float totb = 1.f;
; #pragma unroll
;             for (int mt = 0; mt < 4; ++mt)
; #pragma unroll
;                 for (int j = 0; j < 4; ++j) {
;                     const float sb = frcp(1.f + fexp(-acc[ai][1][mt][0][j]));
;                     acc[ai][1][mt][0][j] = sb;
;                     totb *= lb + oml * sb;
	s_waitcnt lgkmcnt(0)
	s_setprio 1
	v_mfma_f32_16x16x32_bf16 v[98:101], v[198:201], v[156:159], v[98:101]
	v_mfma_f32_16x16x32_bf16 v[70:73], v[198:201], v[170:173], v[70:73]
	v_mfma_f32_16x16x32_bf16 v[90:93], v[206:209], v[156:159], v[90:93]
	v_mfma_f32_16x16x32_bf16 v[62:65], v[206:209], v[170:173], v[62:65]
	v_mfma_f32_16x16x32_bf16 v[86:89], v[214:217], v[156:159], v[86:89]
	v_mfma_f32_16x16x32_bf16 v[54:57], v[214:217], v[170:173], v[54:57]
	v_mfma_f32_16x16x32_bf16 v[78:81], v[222:225], v[156:159], v[78:81]
	v_mfma_f32_16x16x32_bf16 v[46:49], v[222:225], v[170:173], v[46:49]
	v_mfma_f32_16x16x32_bf16 v[98:101], v[202:205], v[160:163], v[98:101]
	v_mfma_f32_16x16x32_bf16 v[70:73], v[202:205], v[194:197], v[70:73]
	v_mfma_f32_16x16x32_bf16 v[90:93], v[210:213], v[160:163], v[90:93]
	v_mfma_f32_16x16x32_bf16 v[62:65], v[210:213], v[194:197], v[62:65]
	v_mfma_f32_16x16x32_bf16 v[86:89], v[218:221], v[160:163], v[86:89]
	v_mfma_f32_16x16x32_bf16 v[54:57], v[218:221], v[194:197], v[54:57]
	v_mfma_f32_16x16x32_bf16 v[78:81], v[226:229], v[160:163], v[78:81]
	v_mfma_f32_16x16x32_bf16 v[46:49], v[226:229], v[194:197], v[46:49]
	s_setprio 0
	s_barrier
	s_add_u32 s12, s12, 0x40080
	s_addc_u32 s13, s13, 0
	s_add_i32 s0, s1, s40
	s_mov_b32 m0, s0
	v_lshl_add_u64 v[156:157], s[12:13], 0, v[132:133]
	global_load_lds_dwordx4 v[156:157], off
	s_add_i32 m0, s0, 0x2000
	v_lshl_add_u64 v[156:157], s[12:13], 0, v[130:131]
	global_load_lds_dwordx4 v[156:157], off
	s_waitcnt vmcnt(6)
	s_barrier
	s_setprio 1
	v_mfma_f32_16x16x32_bf16 v[34:37], v[198:201], v[230:233], v[34:37]
	v_mfma_f32_16x16x32_bf16 v[14:17], v[198:201], v[238:241], v[14:17]
	v_mfma_f32_16x16x32_bf16 v[26:29], v[206:209], v[230:233], v[26:29]
	v_mfma_f32_16x16x32_bf16 v[10:13], v[206:209], v[238:241], v[10:13]
	v_mfma_f32_16x16x32_bf16 v[22:25], v[214:217], v[230:233], v[22:25]
	v_mfma_f32_16x16x32_bf16 v[6:9], v[214:217], v[238:241], v[6:9]
	v_mfma_f32_16x16x32_bf16 v[18:21], v[222:225], v[230:233], v[18:21]
	v_mfma_f32_16x16x32_bf16 v[2:5], v[222:225], v[238:241], v[2:5]
	v_mfma_f32_16x16x32_bf16 v[34:37], v[202:205], v[234:237], v[34:37]
	v_mfma_f32_16x16x32_bf16 v[14:17], v[202:205], v[242:245], v[14:17]
	v_mfma_f32_16x16x32_bf16 v[26:29], v[210:213], v[234:237], v[26:29]
	v_mfma_f32_16x16x32_bf16 v[10:13], v[210:213], v[242:245], v[10:13]
	v_mfma_f32_16x16x32_bf16 v[22:25], v[218:221], v[234:237], v[22:25]
	v_mfma_f32_16x16x32_bf16 v[6:9], v[218:221], v[242:245], v[6:9]
	v_mfma_f32_16x16x32_bf16 v[18:21], v[226:229], v[234:237], v[18:21]
	v_mfma_f32_16x16x32_bf16 v[2:5], v[226:229], v[242:245], v[2:5]
	s_setprio 0
	s_add_i32 s28, s28, 2
	s_add_u32 s10, s10, 0x100
	s_addc_u32 s11, s11, 0
	s_add_u32 s22, s22, 0x100
	s_addc_u32 s23, s23, 0
	s_cmp_gt_u32 s28, 13
	s_barrier
	s_cbranch_scc0 .LBB0_482
	s_cmp_lt_i32 s70, 8
	s_mov_b64 s[10:11], -1
	s_cbranch_scc0 .LBB0_489
	v_lshl_or_b32 v156, s70, 6, v167
	v_add_u32_e32 v158, s55, v156
	v_readlane_b32 s12, v253, 28
	v_ashrrev_i32_e32 v159, 31, v158
	v_readlane_b32 s13, v253, 29
	v_cmp_lt_i32_e32 vcc, v184, v182
	v_mul_f32_e32 v162, 0xbfb8aa3b, v84
	v_lshl_add_u64 v[160:161], v[158:159], 2, s[12:13]
	global_load_dword v169, v[160:161], off
	v_cndmask_b32_e32 v157, v180, v184, vcc
	v_mul_f32_e32 v160, 0xbfb8aa3b, v82
	v_mul_f32_e32 v161, 0xbfb8aa3b, v83
	v_lshlrev_b32_e32 v172, 2, v157
	v_exp_f32_e32 v157, v160
	v_exp_f32_e32 v160, v161
	v_mul_f32_e32 v163, 0xbfb8aa3b, v85
	v_exp_f32_e32 v161, v162
	v_mul_f32_e32 v170, 0xbfb8aa3b, v74
	v_mul_f32_e32 v171, 0xbfb8aa3b, v75
	v_exp_f32_e32 v162, v163
	v_mul_f32_e32 v173, 0xbfb8aa3b, v76
	v_mul_f32_e32 v174, 0xbfb8aa3b, v77
	v_mul_f32_e32 v175, 0xbfb8aa3b, v66
	v_mul_f32_e32 v192, 0xbfb8aa3b, v67
	v_mul_f32_e32 v193, 0xbfb8aa3b, v68
	v_exp_f32_e32 v163, v170
	v_exp_f32_e32 v170, v171
	v_exp_f32_e32 v171, v173
	v_exp_f32_e32 v173, v174
	v_exp_f32_e32 v174, v175
	v_exp_f32_e32 v175, v192
	v_exp_f32_e32 v192, v193
	v_add_f32_e32 v157, 1.0, v157
	v_add_f32_e32 v160, 1.0, v160
	v_add_f32_e32 v161, 1.0, v161
	v_rcp_f32_e32 v210, v157
	v_rcp_f32_e32 v211, v160
	v_add_f32_e32 v162, 1.0, v162
	v_rcp_f32_e32 v213, v161
	v_add_f32_e32 v163, 1.0, v163
	v_add_f32_e32 v170, 1.0, v170
	v_rcp_f32_e32 v214, v162
	v_add_f32_e32 v192, 1.0, v192
	v_rcp_f32_e32 v222, v163
	v_rcp_f32_e32 v223, v170
	v_mul_f32_e32 v194, 0xbfb8aa3b, v69
	v_add_f32_e32 v171, 1.0, v171
	v_rcp_f32_e32 v205, v192
	v_mul_f32_e32 v195, 0xbfb8aa3b, v58
	v_exp_f32_e32 v193, v194
	v_add_f32_e32 v173, 1.0, v173
	v_rcp_f32_e32 v224, v171
	v_mul_f32_e32 v196, 0xbfb8aa3b, v59
	v_exp_f32_e32 v194, v195
	v_add_f32_e32 v174, 1.0, v174
	v_rcp_f32_e32 v225, v173
	v_mul_f32_e32 v197, 0xbfb8aa3b, v60
	v_exp_f32_e32 v195, v196
	v_add_f32_e32 v175, 1.0, v175
	v_rcp_f32_e32 v207, v174
	v_mul_f32_e32 v198, 0xbfb8aa3b, v61
	v_exp_f32_e32 v196, v197
	v_rcp_f32_e32 v206, v175
	v_exp_f32_e32 v197, v198
	v_add_f32_e32 v193, 1.0, v193
	v_add_f32_e32 v194, 1.0, v194
	v_rcp_f32_e32 v204, v193
	v_add_f32_e32 v195, 1.0, v195
	v_rcp_f32_e32 v199, v194
	v_add_f32_e32 v198, 1.0, v196
	v_rcp_f32_e32 v196, v195
	v_rcp_f32_e32 v198, v198
	v_add_f32_e32 v160, 1.0, v197
	v_rcp_f32_e32 v197, v160
	v_mul_f32_e32 v216, 0xbfb8aa3b, v111
	v_exp_f32_e32 v216, v216
	v_cmp_lt_i32_e32 vcc, v183, v182
	s_lshl_b32 s4, s71, 8
	s_add_i32 s4, s4, s54
	v_add_f32_e32 v216, 1.0, v216
	v_rcp_f32_e32 v216, v216
	v_cndmask_b32_e32 v161, v180, v183, vcc
	v_lshlrev_b32_e32 v173, 2, v161
	v_or_b32_e32 v161, v181, v1
	v_lshlrev_b32_e32 v171, 2, v161
	s_mov_b64 s[10:11], 0x1100000
	v_lshl_add_u64 v[158:159], v[158:159], 1, s[8:9]
	v_readlane_b32 s14, v253, 30
	s_waitcnt vmcnt(0)
;     __device__ __forceinline__ void operator()(Acc& acc, int pm, int pn, int wr, int wc, int fr, int fq) const {
;     ...
;         const int chl = pn * 64 + wc * 16 + fr, chg = half * 512 + chl;
;         const float lb = lbv[chg], oml = 1.f - lb;
; #pragma unroll
;         for (int ai = 0; ai < 2; ++ai) {
;             const int row0 = pm * 256 + ai * 128 + wr * 64;
;             float totb = 1.f;
; #pragma unroll
;             for (int mt = 0; mt < 4; ++mt)
; #pragma unroll
;                 for (int j = 0; j < 4; ++j) {
;                     const float sb = frcp(1.f + fexp(-acc[ai][1][mt][0][j]));
;                     acc[ai][1][mt][0][j] = sb;
;                     totb *= lb + oml * sb;
;                 }
;             totb *= __shfl_xor(totb, 16);
;             totb *= __shfl_xor(totb, 32);
;             float offf = 1.f, offb = 1.f;
; #pragma unroll
;             for (int mt = 0; mt < 4; ++mt) {
;                 float cf[4], cb[4], kf[4], kb[4], fbw[4];
;                 float rf = 1.f, rb = 1.f;
; #pragma unroll
;                 for (int j = 0; j < 4; ++j) {
;                     const float sf = frcp(1.f + fexp(-acc[ai][0][mt][1][j])), sb = acc[ai][1][mt][0][j];
;                     const float ff = lb + oml * sf, fb = lb + oml * sb;
;                     kf[j] = oml * (1.f - sf); kb[j] = oml * (1.f - sb);
;                     rf *= ff; rb *= fb; cf[j] = rf; cb[j] = rb; fbw[j] = fb;
;                 }
;                 const float a0 = __shfl(rf, fr), a1 = __shfl(rf, fr + 16), a2 = __shfl(rf, fr + 32), a3 = __shfl(rf, fr + 48);
;                 const float b0 = __shfl(rb, fr), b1 = __shfl(rb, fr + 16), b2 = __shfl(rb, fr + 32), b3 = __shfl(rb, fr + 48);
;                 const float pf = offf * (fq > 0 ? a0 : 1.f) * (fq > 1 ? a1 : 1.f) * (fq > 2 ? a2 : 1.f);
;                 const float pb = offb * (fq > 0 ? b0 : 1.f) * (fq > 1 ? b1 : 1.f) * (fq > 2 ? b2 : 1.f);
;                 offf *= (a0 * a1) * (a2 * a3);
;                 offb *= (b0 * b1) * (b2 * b3);
; #pragma unroll
;                 for (int j = 0; j < 4; ++j) {
;                     const int row = row0 + mt * 16 + fq * 4 + j;
;                     const float Pf = pf * cf[j];
;                     const float Pb = totb * fbw[j] * frcp(pb * cb[j]);
;                     const float qs = siluf_(acc[ai][0][mt][0][j]);
	v_sub_f32_e32 v170, 1.0, v169
	v_fma_f32 v163, v210, v170, v169
	v_fma_f32 v192, v211, v170, v169
	v_fma_f32 v226, v213, v170, v169
	v_mul_f32_e32 v220, v163, v192
	v_fma_f32 v227, v214, v170, v169
	v_mul_f32_e32 v229, v226, v220
	v_fma_f32 v228, v222, v170, v169
	v_mul_f32_e32 v230, v227, v229
	v_fma_f32 v212, v223, v170, v169
	v_mul_f32_e32 v157, v228, v230
	v_fma_f32 v209, v224, v170, v169
	v_mul_f32_e32 v157, v212, v157
	v_fma_f32 v208, v225, v170, v169
	v_mul_f32_e32 v157, v209, v157
	v_fma_f32 v203, v207, v170, v169
	v_mul_f32_e32 v157, v208, v157
	v_fma_f32 v202, v206, v170, v169
	v_mul_f32_e32 v157, v203, v157
	v_fma_f32 v201, v205, v170, v169
	v_mul_f32_e32 v157, v202, v157
	v_fma_f32 v200, v204, v170, v169
	v_mul_f32_e32 v157, v201, v157
	v_fma_f32 v195, v199, v170, v169
	v_mul_f32_e32 v157, v200, v157
	v_fma_f32 v194, v196, v170, v169
	v_mul_f32_e32 v157, v195, v157
	v_mul_f32_e32 v157, v194, v157
	v_fma_f32 v193, v198, v170, v169
	v_mul_f32_e32 v157, v193, v157
	v_fma_f32 v175, v197, v170, v169
	v_mul_f32_e32 v157, v175, v157
	ds_bpermute_b32 v160, v172, v157
	v_sub_f32_e32 v210, 1.0, v210
	v_mul_f32_e32 v231, v210, v170
	v_fma_f32 v210, v216, v170, v169
	v_sub_f32_e32 v211, 1.0, v211
	s_waitcnt lgkmcnt(0)
	v_mul_f32_e32 v162, v157, v160
	v_mul_f32_e32 v160, 0xbfb8aa3b, v110
	v_exp_f32_e32 v215, v160
	v_mul_f32_e32 v233, v211, v170
	ds_bpermute_b32 v218, v171, v230 offset:64
	ds_bpermute_b32 v219, v171, v230 offset:128
	v_add_f32_e32 v215, 1.0, v215
	v_rcp_f32_e32 v215, v215
	ds_bpermute_b32 v240, v171, v230 offset:192
	s_waitcnt lgkmcnt(2)
	v_cndmask_b32_e64 v243, 1.0, v218, s[46:47]
	ds_bpermute_b32 v174, v173, v162
	v_fma_f32 v217, v215, v170, v169
	v_sub_f32_e32 v215, 1.0, v215
	v_mul_f32_e32 v221, v215, v170
	v_sub_f32_e32 v215, 1.0, v216
	v_mul_f32_e32 v216, 0xbfb8aa3b, v112
	v_exp_f32_e32 v216, v216
	v_mul_f32_e32 v234, v217, v210
	v_mul_f32_e32 v210, 0xbfb8aa3b, v113
	v_exp_f32_e32 v210, v210
	v_add_f32_e32 v211, 1.0, v216
	v_rcp_f32_e32 v211, v211
	v_mul_f32_e32 v232, v215, v170
	v_add_f32_e32 v210, 1.0, v210
	v_rcp_f32_e32 v210, v210
	v_fma_f32 v215, v211, v170, v169
	v_sub_f32_e32 v211, 1.0, v211
	v_mul_f32_e32 v235, v211, v170
	v_sub_f32_e32 v211, 1.0, v213
	v_mul_f32_e32 v213, v211, v170
	v_mul_f32_e32 v236, v215, v234
	v_fma_f32 v211, v210, v170, v169
	v_sub_f32_e32 v210, 1.0, v210
	v_mul_f32_e32 v237, v210, v170
	v_sub_f32_e32 v210, 1.0, v214
	v_mul_f32_e32 v239, v211, v236
	v_mul_f32_e32 v238, v210, v170
	ds_bpermute_b32 v210, v171, v239
	ds_bpermute_b32 v211, v171, v239 offset:64
	ds_bpermute_b32 v214, v171, v239 offset:128
	ds_bpermute_b32 v215, v171, v239 offset:192
	ds_bpermute_b32 v216, v171, v230
	s_waitcnt lgkmcnt(4)
	v_cndmask_b32_e64 v241, v210, 1.0, s[44:45]
	s_waitcnt lgkmcnt(3)
	v_cndmask_b32_e64 v242, 1.0, v211, s[46:47]
	v_mul_f32_e32 v241, v241, v242
	s_waitcnt lgkmcnt(2)
	v_cndmask_b32_e64 v242, 1.0, v214, s[48:49]
	v_mul_f32_e32 v210, v210, v211
	s_waitcnt lgkmcnt(1)
	v_mul_f32_e32 v211, v214, v215
	v_mul_f32_e32 v215, 0xbfb8aa3b, v126
	v_mul_f32_e32 v241, v241, v242
	s_waitcnt lgkmcnt(0)
	v_cndmask_b32_e64 v242, v216, 1.0, s[44:45]
	v_exp_f32_e32 v215, v215
	v_mul_f32_e32 v242, v242, v243
	v_cndmask_b32_e64 v243, 1.0, v219, s[48:49]
	v_mul_f32_e32 v242, v242, v243
	v_mul_f32_e32 v210, v210, v211
	v_mul_f32_e32 v211, v216, v218
	v_mul_f32_e32 v214, v219, v240
	v_mul_f32_e32 v211, v211, v214
	v_mul_f32_e32 v214, v163, v242
	v_rcp_f32_e32 v214, v214
	v_add_f32_e32 v215, 1.0, v215
	v_rcp_f32_e32 v215, v215
	v_mul_f32_e32 v174, v162, v174
	v_or_b32_e32 v162, s4, v165
	v_mul_f32_e32 v163, v163, v174
	v_mul_f32_e32 v243, v214, v163
	v_ashrrev_i32_e32 v163, 31, v162
	v_ashrrev_i32_e32 v157, 31, v156
	v_mul_f32_e32 v244, v126, v215
	v_lshlrev_b64 v[214:215], 9, v[162:163]
	v_mul_f32_e32 v240, v217, v241
	v_lshl_add_u64 v[216:217], v[214:215], 0, v[156:157]
	v_lshl_add_u64 v[160:161], v[156:157], 0, s[10:11]
	v_mul_f32_e32 v218, v244, v240
	v_lshlrev_b64 v[216:217], 1, v[216:217]
	v_rcp_f32_e32 v240, v240
	v_lshl_add_u64 v[214:215], v[214:215], 0, v[160:161]
	v_cvt_pk_bf16_f32 v245, v218, s0
	v_lshl_add_u64 v[218:219], s[26:27], 0, v[216:217]
	global_store_short v[218:219], v245, off
	v_mul_f32_e32 v218, v244, v243
	v_lshlrev_b64 v[214:215], 1, v[214:215]
	v_cvt_pk_bf16_f32 v244, v218, s0
	v_lshl_add_u64 v[218:219], s[26:27], 0, v[214:215]
	global_store_short v[218:219], v244, off
	v_mul_f32_e32 v218, v221, v240
	v_mul_f32_e32 v221, 0xbfb8aa3b, v50
	v_exp_f32_e32 v221, v221
	v_cvt_pk_bf16_f32 v218, v218, s0
	v_rcp_f32_e32 v219, v243
	v_lshl_add_u64 v[216:217], s[86:87], 0, v[216:217]
	global_store_short v[216:217], v218, off
	v_add_f32_e32 v217, 1.0, v221
	v_rcp_f32_e32 v217, v217
	v_mul_f32_e32 v216, v231, v219
	v_cvt_pk_bf16_f32 v216, v216, s0
	v_lshl_add_u64 v[214:215], s[86:87], 0, v[214:215]
	global_store_short v[214:215], v216, off
	v_mul_f32_e32 v214, v50, v217
	v_cvt_pk_bf16_f32 v216, v214, s0
	v_lshlrev_b64 v[214:215], 11, v[162:163]
	v_mul_f32_e32 v163, 0xbfb8aa3b, v127
	v_exp_f32_e32 v163, v163
	v_lshl_add_u64 v[214:215], v[158:159], 0, v[214:215]
	global_store_short v[214:215], v216, off
	v_mul_f32_e32 v215, v220, v242
	v_rcp_f32_e32 v215, v215
	v_add_f32_e32 v163, 1.0, v163
	v_rcp_f32_e32 v163, v163
	v_or_b32_e32 v214, 1, v162
	v_mul_f32_e32 v192, v192, v174
	v_mul_f32_e32 v192, v215, v192
	v_ashrrev_i32_e32 v215, 31, v214
	v_lshlrev_b64 v[216:217], 9, v[214:215]
	v_mul_f32_e32 v231, v234, v241
	v_mul_f32_e32 v163, v127, v163
	v_lshl_add_u64 v[218:219], v[216:217], 0, v[156:157]
	v_lshl_add_u64 v[216:217], v[216:217], 0, v[160:161]
	v_mul_f32_e32 v220, v163, v231
	v_lshlrev_b64 v[218:219], 1, v[218:219]
; __device__ __forceinline__ unsigned f2bf(float f) { const __bf16 b = (__bf16)f; return (unsigned)__builtin_bit_cast(unsigned short, b); }
; __device__ __forceinline__ float frcp(float x) { return __builtin_amdgcn_rcpf(x); }
; __device__ __forceinline__ float fexp(float x) { return __builtin_amdgcn_exp2f(x * 1.4426950408889634f); }
;     __device__ __forceinline__ void operator()(Acc& acc, int pm, int pn, int wr, int wc, int fr, int fq) const {
;     ...
;             for (int mt = 0; mt < 4; ++mt) {
;                 float cf[4], cb[4], kf[4], kb[4], fbw[4];
;                 float rf = 1.f, rb = 1.f;
; #pragma unroll
;                 for (int j = 0; j < 4; ++j) {
;                     const float sf = frcp(1.f + fexp(-acc[ai][0][mt][1][j])), sb = acc[ai][1][mt][0][j];
;                     const float ff = lb + oml * sf, fb = lb + oml * sb;
;                     kf[j] = oml * (1.f - sf); kb[j] = oml * (1.f - sb);
;                     rf *= ff; rb *= fb; cf[j] = rf; cb[j] = rb; fbw[j] = fb;
;                 }
;                 const float a0 = __shfl(rf, fr), a1 = __shfl(rf, fr + 16), a2 = __shfl(rf, fr + 32), a3 = __shfl(rf, fr + 48);
;                 const float b0 = __shfl(rb, fr), b1 = __shfl(rb, fr + 16), b2 = __shfl(rb, fr + 32), b3 = __shfl(rb, fr + 48);
;                 const float pf = offf * (fq > 0 ? a0 : 1.f) * (fq > 1 ? a1 : 1.f) * (fq > 2 ? a2 : 1.f);
;                 const float pb = offb * (fq > 0 ? b0 : 1.f) * (fq > 1 ? b1 : 1.f) * (fq > 2 ? b2 : 1.f);
;                 offf *= (a0 * a1) * (a2 * a3);
;                 offb *= (b0 * b1) * (b2 * b3);
; #pragma unroll
;                 for (int j = 0; j < 4; ++j) {
;                     const int row = row0 + mt * 16 + fq * 4 + j;
;                     const float Pf = pf * cf[j];
;                     const float Pb = totb * fbw[j] * frcp(pb * cb[j]);
;                     const float qs = siluf_(acc[ai][0][mt][0][j]);
;                     const size_t o0 = ((size_t)row) * 512 + chl, o1 = ((size_t)T_ALL + row) * 512 + chl;
;                     qt[o0] = (bf16_t)f2bf(qs * Pf);
;                     qt[o1] = (bf16_t)f2bf(qs * Pb);
;                     kt[o0] = (bf16_t)f2bf(kf[j] * frcp(Pf));
;                     kt[o1] = (bf16_t)f2bf(kb[j] * frcp(Pb));
;                     sg[(size_t)row * DM + chg] = (bf16_t)f2bf(siluf_(acc[ai][1][mt][1][j]));
	v_cvt_pk_bf16_f32 v234, v220, s0
	v_lshl_add_u64 v[220:221], s[26:27], 0, v[218:219]
	v_mul_f32_e32 v163, v163, v192
	v_lshlrev_b64 v[216:217], 1, v[216:217]
	global_store_short v[220:221], v234, off
	v_cvt_pk_bf16_f32 v163, v163, s0
	v_rcp_f32_e32 v231, v231
	v_lshl_add_u64 v[220:221], s[26:27], 0, v[216:217]
	global_store_short v[220:221], v163, off
	v_mul_f32_e32 v220, 0xbfb8aa3b, v51
	v_rcp_f32_e32 v192, v192
	v_exp_f32_e32 v220, v220
	v_mul_f32_e32 v163, v232, v231
	v_cvt_pk_bf16_f32 v163, v163, s0
	v_lshl_add_u64 v[218:219], s[86:87], 0, v[218:219]
	global_store_short v[218:219], v163, off
	v_mul_f32_e32 v163, v233, v192
	v_add_f32_e32 v192, 1.0, v220
	v_rcp_f32_e32 v192, v192
	v_cvt_pk_bf16_f32 v163, v163, s0
	v_lshl_add_u64 v[216:217], s[86:87], 0, v[216:217]
	global_store_short v[216:217], v163, off
	v_mul_f32_e32 v163, v51, v192
	v_lshlrev_b64 v[214:215], 11, v[214:215]
	v_cvt_pk_bf16_f32 v163, v163, s0
	v_lshl_add_u64 v[214:215], v[158:159], 0, v[214:215]
	global_store_short v[214:215], v163, off
	v_mul_f32_e32 v163, 0xbfb8aa3b, v128
	v_exp_f32_e32 v163, v163
	v_mul_f32_e32 v192, v229, v242
	v_rcp_f32_e32 v192, v192
	v_or_b32_e32 v214, 2, v162
	v_add_f32_e32 v163, 1.0, v163
	v_rcp_f32_e32 v163, v163
	v_mul_f32_e32 v215, v226, v174
	v_mul_f32_e32 v192, v192, v215
	v_ashrrev_i32_e32 v215, 31, v214
	v_lshlrev_b64 v[216:217], 9, v[214:215]
	v_mul_f32_e32 v229, v236, v241
	v_mul_f32_e32 v163, v128, v163
	v_lshl_add_u64 v[218:219], v[216:217], 0, v[156:157]
	v_lshl_add_u64 v[216:217], v[216:217], 0, v[160:161]
	v_mul_f32_e32 v220, v163, v229
	v_lshlrev_b64 v[218:219], 1, v[218:219]
	v_cvt_pk_bf16_f32 v226, v220, s0
	v_lshl_add_u64 v[220:221], s[26:27], 0, v[218:219]
	v_mul_f32_e32 v163, v163, v192
	v_lshlrev_b64 v[216:217], 1, v[216:217]
	global_store_short v[220:221], v226, off
	v_cvt_pk_bf16_f32 v163, v163, s0
	v_rcp_f32_e32 v226, v229
	v_lshl_add_u64 v[220:221], s[26:27], 0, v[216:217]
	global_store_short v[220:221], v163, off
	v_mul_f32_e32 v220, 0xbfb8aa3b, v52
	v_rcp_f32_e32 v192, v192
	v_exp_f32_e32 v220, v220
	v_mul_f32_e32 v163, v235, v226
	v_cvt_pk_bf16_f32 v163, v163, s0
	v_lshl_add_u64 v[218:219], s[86:87], 0, v[218:219]
	global_store_short v[218:219], v163, off
	v_mul_f32_e32 v163, v213, v192
	v_add_f32_e32 v192, 1.0, v220
	v_rcp_f32_e32 v192, v192
	v_cvt_pk_bf16_f32 v163, v163, s0
	v_lshl_add_u64 v[216:217], s[86:87], 0, v[216:217]
	global_store_short v[216:217], v163, off
	v_mul_f32_e32 v163, v52, v192
	v_lshlrev_b64 v[214:215], 11, v[214:215]
	v_cvt_pk_bf16_f32 v163, v163, s0
	v_lshl_add_u64 v[214:215], v[158:159], 0, v[214:215]
	global_store_short v[214:215], v163, off
	v_mul_f32_e32 v163, 0xbfb8aa3b, v129
	v_exp_f32_e32 v163, v163
	v_mul_f32_e32 v192, v230, v242
	v_rcp_f32_e32 v192, v192
	v_or_b32_e32 v214, 3, v162
	v_add_f32_e32 v163, 1.0, v163
	v_rcp_f32_e32 v163, v163
	v_mul_f32_e32 v215, v227, v174
	v_mul_f32_e32 v192, v192, v215
	v_ashrrev_i32_e32 v215, 31, v214
	v_mul_f32_e32 v213, v239, v241
	v_mul_f32_e32 v163, v129, v163
	v_lshlrev_b64 v[216:217], 9, v[214:215]
	v_lshl_add_u64 v[218:219], v[216:217], 0, v[156:157]
	v_mul_f32_e32 v220, v163, v213
	v_rcp_f32_e32 v213, v213
	v_lshl_add_u64 v[216:217], v[216:217], 0, v[160:161]
	v_lshlrev_b64 v[218:219], 1, v[218:219]
	v_cvt_pk_bf16_f32 v226, v220, s0
	v_lshl_add_u64 v[220:221], s[26:27], 0, v[218:219]
	v_mul_f32_e32 v163, v163, v192
	v_lshlrev_b64 v[216:217], 1, v[216:217]
	global_store_short v[220:221], v226, off
	v_cvt_pk_bf16_f32 v163, v163, s0
	v_lshl_add_u64 v[220:221], s[26:27], 0, v[216:217]
	global_store_short v[220:221], v163, off
	v_mul_f32_e32 v163, v237, v213
	v_mul_f32_e32 v213, 0xbfb8aa3b, v53
	v_rcp_f32_e32 v192, v192
	v_exp_f32_e32 v213, v213
	v_cvt_pk_bf16_f32 v163, v163, s0
	v_lshl_add_u64 v[218:219], s[86:87], 0, v[218:219]
	global_store_short v[218:219], v163, off
	v_mul_f32_e32 v163, v238, v192
	v_add_f32_e32 v192, 1.0, v213
	v_rcp_f32_e32 v192, v192
	v_cvt_pk_bf16_f32 v163, v163, s0
	v_lshl_add_u64 v[216:217], s[86:87], 0, v[216:217]
	global_store_short v[216:217], v163, off
	v_mul_f32_e32 v163, v53, v192
	v_lshlrev_b64 v[214:215], 11, v[214:215]
	v_mul_f32_e32 v213, 0xbfb8aa3b, v107
	v_mul_f32_e32 v192, 0xbfb8aa3b, v106
	v_cvt_pk_bf16_f32 v163, v163, s0
	v_lshl_add_u64 v[214:215], v[158:159], 0, v[214:215]
	v_exp_f32_e32 v213, v213
	v_exp_f32_e32 v192, v192
	global_store_short v[214:215], v163, off
	v_mul_f32_e32 v215, 0xbfb8aa3b, v108
	v_exp_f32_e32 v215, v215
	v_mul_f32_e32 v216, 0xbfb8aa3b, v109
	v_exp_f32_e32 v216, v216
	v_add_f32_e32 v213, 1.0, v213
	v_add_f32_e32 v192, 1.0, v192
	v_rcp_f32_e32 v213, v213
	v_rcp_f32_e32 v192, v192
	v_add_f32_e32 v215, 1.0, v215
	v_rcp_f32_e32 v215, v215
	v_add_f32_e32 v216, 1.0, v216
	v_sub_f32_e32 v214, 1.0, v222
	v_rcp_f32_e32 v216, v216
	v_mul_f32_e32 v222, v214, v170
	v_fma_f32 v214, v213, v170, v169
	v_sub_f32_e32 v213, 1.0, v213
	v_fma_f32 v163, v192, v170, v169
	v_mul_f32_e32 v226, v213, v170
	v_sub_f32_e32 v213, 1.0, v223
	v_mul_f32_e32 v223, v213, v170
	v_mul_f32_e32 v213, v163, v214
	v_fma_f32 v214, v215, v170, v169
	v_sub_f32_e32 v215, 1.0, v215
	v_mul_f32_e32 v229, v215, v170
	v_sub_f32_e32 v215, 1.0, v224
	v_mul_f32_e32 v230, v214, v213
	v_fma_f32 v214, v216, v170, v169
	v_mul_f32_e32 v224, v215, v170
	v_sub_f32_e32 v215, 1.0, v216
	v_mul_f32_e32 v233, v214, v230
	v_mul_f32_e32 v227, v228, v212
	v_mul_f32_e32 v232, v215, v170
	v_sub_f32_e32 v215, 1.0, v225
	ds_bpermute_b32 v214, v171, v233
	v_mul_f32_e32 v231, v209, v227
	v_mul_f32_e32 v225, v215, v170
	ds_bpermute_b32 v215, v171, v233 offset:64
	v_mul_f32_e32 v234, v208, v231
	ds_bpermute_b32 v216, v171, v233 offset:128
	ds_bpermute_b32 v218, v171, v234
	ds_bpermute_b32 v219, v171, v234 offset:64
	ds_bpermute_b32 v217, v171, v233 offset:192
	ds_bpermute_b32 v220, v171, v234 offset:128
	s_waitcnt lgkmcnt(6)
; __device__ __forceinline__ unsigned f2bf(float f) { const __bf16 b = (__bf16)f; return (unsigned)__builtin_bit_cast(unsigned short, b); }
; __device__ __forceinline__ float frcp(float x) { return __builtin_amdgcn_rcpf(x); }
; __device__ __forceinline__ float fexp(float x) { return __builtin_amdgcn_exp2f(x * 1.4426950408889634f); }
;     __device__ __forceinline__ void operator()(Acc& acc, int pm, int pn, int wr, int wc, int fr, int fq) const {
;     ...
;             for (int mt = 0; mt < 4; ++mt) {
;                 float cf[4], cb[4], kf[4], kb[4], fbw[4];
;                 float rf = 1.f, rb = 1.f;
; #pragma unroll
;                 for (int j = 0; j < 4; ++j) {
;                     const float sf = frcp(1.f + fexp(-acc[ai][0][mt][1][j])), sb = acc[ai][1][mt][0][j];
;                     const float ff = lb + oml * sf, fb = lb + oml * sb;
;                     kf[j] = oml * (1.f - sf); kb[j] = oml * (1.f - sb);
;                     rf *= ff; rb *= fb; cf[j] = rf; cb[j] = rb; fbw[j] = fb;
;                 }
;                 const float a0 = __shfl(rf, fr), a1 = __shfl(rf, fr + 16), a2 = __shfl(rf, fr + 32), a3 = __shfl(rf, fr + 48);
;                 const float b0 = __shfl(rb, fr), b1 = __shfl(rb, fr + 16), b2 = __shfl(rb, fr + 32), b3 = __shfl(rb, fr + 48);
;                 const float pf = offf * (fq > 0 ? a0 : 1.f) * (fq > 1 ? a1 : 1.f) * (fq > 2 ? a2 : 1.f);
;                 const float pb = offb * (fq > 0 ? b0 : 1.f) * (fq > 1 ? b1 : 1.f) * (fq > 2 ? b2 : 1.f);
;                 offf *= (a0 * a1) * (a2 * a3);
;                 offb *= (b0 * b1) * (b2 * b3);
; #pragma unroll
;                 for (int j = 0; j < 4; ++j) {
;                     const int row = row0 + mt * 16 + fq * 4 + j;
;                     const float Pf = pf * cf[j];
;                     const float Pb = totb * fbw[j] * frcp(pb * cb[j]);
;                     const float qs = siluf_(acc[ai][0][mt][0][j]);
;                     const size_t o0 = ((size_t)row) * 512 + chl, o1 = ((size_t)T_ALL + row) * 512 + chl;
;                     qt[o0] = (bf16_t)f2bf(qs * Pf);
;                     qt[o1] = (bf16_t)f2bf(qs * Pb);
;                     kt[o0] = (bf16_t)f2bf(kf[j] * frcp(Pf));
;                     kt[o1] = (bf16_t)f2bf(kb[j] * frcp(Pb));
;                     sg[(size_t)row * DM + chg] = (bf16_t)f2bf(siluf_(acc[ai][1][mt][1][j]));
	v_cndmask_b32_e64 v235, v214, 1.0, s[44:45]
	ds_bpermute_b32 v221, v171, v234 offset:192
	v_mul_f32_e32 v235, v210, v235
	s_waitcnt lgkmcnt(6)
	v_cndmask_b32_e64 v236, 1.0, v215, s[46:47]
	v_mul_f32_e32 v235, v235, v236
	s_waitcnt lgkmcnt(5)
	v_cndmask_b32_e64 v236, 1.0, v216, s[48:49]
	v_mul_f32_e32 v235, v235, v236
	s_waitcnt lgkmcnt(4)
	v_cndmask_b32_e64 v236, v218, 1.0, s[44:45]
	v_mul_f32_e32 v236, v211, v236
	s_waitcnt lgkmcnt(3)
	v_cndmask_b32_e64 v237, 1.0, v219, s[46:47]
	v_mul_f32_e32 v236, v236, v237
	s_waitcnt lgkmcnt(1)
	v_cndmask_b32_e64 v237, 1.0, v220, s[48:49]
	v_mul_f32_e32 v214, v214, v215
	v_mul_f32_e32 v215, v216, v217
	v_mul_f32_e32 v236, v236, v237
	v_mul_f32_e32 v237, v214, v215
	v_mul_f32_e32 v214, v218, v219
	s_waitcnt lgkmcnt(0)
	v_mul_f32_e32 v215, v220, v221
	v_mul_f32_e32 v238, v214, v215
	v_mul_f32_e32 v214, 0xbfb8aa3b, v122
	v_exp_f32_e32 v215, v214
	v_mul_f32_e32 v216, v228, v236
	v_rcp_f32_e32 v216, v216
	v_or_b32_e32 v214, 16, v162
	v_add_f32_e32 v215, 1.0, v215
	v_rcp_f32_e32 v215, v215
	v_mul_f32_e32 v217, v228, v174
	v_mul_f32_e32 v228, v217, v216
	v_mul_f32_e32 v163, v163, v235
	v_mul_f32_e32 v239, v122, v215
	v_ashrrev_i32_e32 v215, 31, v214
	v_lshlrev_b64 v[216:217], 9, v[214:215]
	v_lshl_add_u64 v[218:219], v[216:217], 0, v[156:157]
	v_mul_f32_e32 v220, v239, v163
	v_lshlrev_b64 v[218:219], 1, v[218:219]
	v_lshl_add_u64 v[216:217], v[216:217], 0, v[160:161]
	v_cvt_pk_bf16_f32 v240, v220, s0
	v_lshl_add_u64 v[220:221], s[26:27], 0, v[218:219]
	v_rcp_f32_e32 v163, v163
	global_store_short v[220:221], v240, off
	v_mul_f32_e32 v220, v239, v228
	v_lshlrev_b64 v[216:217], 1, v[216:217]
	v_sub_f32_e32 v192, 1.0, v192
	v_cvt_pk_bf16_f32 v239, v220, s0
	v_lshl_add_u64 v[220:221], s[26:27], 0, v[216:217]
	v_mul_f32_e32 v192, v192, v170
	global_store_short v[220:221], v239, off
	v_mul_f32_e32 v220, 0xbfb8aa3b, v42
	v_mul_f32_e32 v163, v192, v163
	v_rcp_f32_e32 v192, v228
	v_exp_f32_e32 v220, v220
	v_cvt_pk_bf16_f32 v163, v163, s0
	v_lshl_add_u64 v[218:219], s[86:87], 0, v[218:219]
	global_store_short v[218:219], v163, off
	v_mul_f32_e32 v163, v222, v192
	v_add_f32_e32 v192, 1.0, v220
	v_rcp_f32_e32 v192, v192
	v_cvt_pk_bf16_f32 v163, v163, s0
	v_lshl_add_u64 v[216:217], s[86:87], 0, v[216:217]
	global_store_short v[216:217], v163, off
	v_mul_f32_e32 v163, v42, v192
	v_lshlrev_b64 v[214:215], 11, v[214:215]
	v_cvt_pk_bf16_f32 v163, v163, s0
	v_lshl_add_u64 v[214:215], v[158:159], 0, v[214:215]
	global_store_short v[214:215], v163, off
	v_mul_f32_e32 v163, 0xbfb8aa3b, v123
	v_exp_f32_e32 v163, v163
	v_mul_f32_e32 v192, v227, v236
	v_rcp_f32_e32 v192, v192
	v_or_b32_e32 v214, 17, v162
	v_add_f32_e32 v163, 1.0, v163
	v_rcp_f32_e32 v163, v163
	v_mul_f32_e32 v212, v212, v174
	v_ashrrev_i32_e32 v215, 31, v214
	v_mul_f32_e32 v220, v213, v235
	v_mul_f32_e32 v192, v212, v192
	v_lshlrev_b64 v[212:213], 9, v[214:215]
	v_mul_f32_e32 v163, v123, v163
	v_lshl_add_u64 v[216:217], v[212:213], 0, v[156:157]
	v_lshl_add_u64 v[212:213], v[212:213], 0, v[160:161]
	v_mul_f32_e32 v218, v163, v220
	v_lshlrev_b64 v[216:217], 1, v[216:217]
	v_cvt_pk_bf16_f32 v221, v218, s0
	v_lshl_add_u64 v[218:219], s[26:27], 0, v[216:217]
	v_mul_f32_e32 v163, v163, v192
	v_lshlrev_b64 v[212:213], 1, v[212:213]
	global_store_short v[218:219], v221, off
	v_cvt_pk_bf16_f32 v163, v163, s0
	v_rcp_f32_e32 v220, v220
	v_lshl_add_u64 v[218:219], s[26:27], 0, v[212:213]
	global_store_short v[218:219], v163, off
	v_mul_f32_e32 v218, 0xbfb8aa3b, v43
	v_rcp_f32_e32 v192, v192
	v_exp_f32_e32 v218, v218
	v_mul_f32_e32 v163, v226, v220
	v_cvt_pk_bf16_f32 v163, v163, s0
	v_lshl_add_u64 v[216:217], s[86:87], 0, v[216:217]
	global_store_short v[216:217], v163, off
	v_mul_f32_e32 v163, v223, v192
	v_add_f32_e32 v192, 1.0, v218
	v_rcp_f32_e32 v192, v192
	v_cvt_pk_bf16_f32 v163, v163, s0
	v_lshl_add_u64 v[212:213], s[86:87], 0, v[212:213]
	global_store_short v[212:213], v163, off
	v_mul_f32_e32 v163, v43, v192
	v_lshlrev_b64 v[212:213], 11, v[214:215]
	v_cvt_pk_bf16_f32 v163, v163, s0
	v_lshl_add_u64 v[212:213], v[158:159], 0, v[212:213]
	global_store_short v[212:213], v163, off
	v_mul_f32_e32 v163, 0xbfb8aa3b, v124
	v_exp_f32_e32 v163, v163
	v_mul_f32_e32 v192, v231, v236
	v_or_b32_e32 v212, 18, v162
	v_rcp_f32_e32 v192, v192
	v_add_f32_e32 v163, 1.0, v163
	v_rcp_f32_e32 v163, v163
	v_ashrrev_i32_e32 v213, 31, v212
	v_lshlrev_b64 v[214:215], 9, v[212:213]
	v_mul_f32_e32 v220, v230, v235
	v_mul_f32_e32 v209, v209, v174
	v_mul_f32_e32 v163, v124, v163
	v_lshl_add_u64 v[216:217], v[214:215], 0, v[156:157]
	v_mul_f32_e32 v192, v209, v192
	v_mul_f32_e32 v209, v163, v220
	v_lshlrev_b64 v[216:217], 1, v[216:217]
	v_cvt_pk_bf16_f32 v209, v209, s0
	v_lshl_add_u64 v[218:219], s[26:27], 0, v[216:217]
	global_store_short v[218:219], v209, off
	v_rcp_f32_e32 v209, v220
	v_lshl_add_u64 v[214:215], v[214:215], 0, v[160:161]
	v_mul_f32_e32 v163, v163, v192
	v_lshlrev_b64 v[214:215], 1, v[214:215]
	v_cvt_pk_bf16_f32 v163, v163, s0
	v_lshl_add_u64 v[218:219], s[26:27], 0, v[214:215]
	global_store_short v[218:219], v163, off
	v_mul_f32_e32 v163, v229, v209
	v_mul_f32_e32 v209, 0xbfb8aa3b, v44
	v_rcp_f32_e32 v192, v192
	v_exp_f32_e32 v209, v209
	v_cvt_pk_bf16_f32 v163, v163, s0
	v_lshl_add_u64 v[216:217], s[86:87], 0, v[216:217]
	global_store_short v[216:217], v163, off
	v_mul_f32_e32 v163, v224, v192
	v_add_f32_e32 v192, 1.0, v209
	v_rcp_f32_e32 v192, v192
	v_cvt_pk_bf16_f32 v163, v163, s0
	v_lshl_add_u64 v[214:215], s[86:87], 0, v[214:215]
	global_store_short v[214:215], v163, off
	v_mul_f32_e32 v163, v44, v192
	v_lshlrev_b64 v[212:213], 11, v[212:213]
	v_cvt_pk_bf16_f32 v163, v163, s0
; __device__ __forceinline__ unsigned f2bf(float f) { const __bf16 b = (__bf16)f; return (unsigned)__builtin_bit_cast(unsigned short, b); }
; __device__ __forceinline__ float frcp(float x) { return __builtin_amdgcn_rcpf(x); }
; __device__ __forceinline__ float fexp(float x) { return __builtin_amdgcn_exp2f(x * 1.4426950408889634f); }
;     __device__ __forceinline__ void operator()(Acc& acc, int pm, int pn, int wr, int wc, int fr, int fq) const {
;     ...
;             for (int mt = 0; mt < 4; ++mt) {
;                 float cf[4], cb[4], kf[4], kb[4], fbw[4];
;                 float rf = 1.f, rb = 1.f;
; #pragma unroll
;                 for (int j = 0; j < 4; ++j) {
;                     const float sf = frcp(1.f + fexp(-acc[ai][0][mt][1][j])), sb = acc[ai][1][mt][0][j];
;                     const float ff = lb + oml * sf, fb = lb + oml * sb;
;                     kf[j] = oml * (1.f - sf); kb[j] = oml * (1.f - sb);
;                     rf *= ff; rb *= fb; cf[j] = rf; cb[j] = rb; fbw[j] = fb;
;                 }
;                 const float a0 = __shfl(rf, fr), a1 = __shfl(rf, fr + 16), a2 = __shfl(rf, fr + 32), a3 = __shfl(rf, fr + 48);
;                 const float b0 = __shfl(rb, fr), b1 = __shfl(rb, fr + 16), b2 = __shfl(rb, fr + 32), b3 = __shfl(rb, fr + 48);
;                 const float pf = offf * (fq > 0 ? a0 : 1.f) * (fq > 1 ? a1 : 1.f) * (fq > 2 ? a2 : 1.f);
;                 const float pb = offb * (fq > 0 ? b0 : 1.f) * (fq > 1 ? b1 : 1.f) * (fq > 2 ? b2 : 1.f);
;                 offf *= (a0 * a1) * (a2 * a3);
;                 offb *= (b0 * b1) * (b2 * b3);
; #pragma unroll
;                 for (int j = 0; j < 4; ++j) {
;                     const int row = row0 + mt * 16 + fq * 4 + j;
;                     const float Pf = pf * cf[j];
;                     const float Pb = totb * fbw[j] * frcp(pb * cb[j]);
;                     const float qs = siluf_(acc[ai][0][mt][0][j]);
;                     const size_t o0 = ((size_t)row) * 512 + chl, o1 = ((size_t)T_ALL + row) * 512 + chl;
;                     qt[o0] = (bf16_t)f2bf(qs * Pf);
;                     qt[o1] = (bf16_t)f2bf(qs * Pb);
;                     kt[o0] = (bf16_t)f2bf(kf[j] * frcp(Pf));
;                     kt[o1] = (bf16_t)f2bf(kb[j] * frcp(Pb));
;                     sg[(size_t)row * DM + chg] = (bf16_t)f2bf(siluf_(acc[ai][1][mt][1][j]));
	v_lshl_add_u64 v[212:213], v[158:159], 0, v[212:213]
	global_store_short v[212:213], v163, off
	v_mul_f32_e32 v163, 0xbfb8aa3b, v125
	v_exp_f32_e32 v163, v163
	v_mul_f32_e32 v192, v234, v236
	v_rcp_f32_e32 v192, v192
	v_or_b32_e32 v212, 19, v162
	v_add_f32_e32 v163, 1.0, v163
	v_rcp_f32_e32 v163, v163
	v_mul_f32_e32 v208, v208, v174
	v_ashrrev_i32_e32 v213, 31, v212
	v_mul_f32_e32 v192, v208, v192
	v_lshlrev_b64 v[208:209], 9, v[212:213]
	v_mul_f32_e32 v218, v233, v235
	v_mul_f32_e32 v163, v125, v163
	v_lshl_add_u64 v[214:215], v[208:209], 0, v[156:157]
	v_lshl_add_u64 v[208:209], v[208:209], 0, v[160:161]
	v_mul_f32_e32 v216, v163, v218
	v_lshlrev_b64 v[214:215], 1, v[214:215]
	v_cvt_pk_bf16_f32 v219, v216, s0
	v_lshl_add_u64 v[216:217], s[26:27], 0, v[214:215]
	v_mul_f32_e32 v163, v163, v192
	v_lshlrev_b64 v[208:209], 1, v[208:209]
	global_store_short v[216:217], v219, off
	v_cvt_pk_bf16_f32 v163, v163, s0
	v_rcp_f32_e32 v218, v218
	v_lshl_add_u64 v[216:217], s[26:27], 0, v[208:209]
	global_store_short v[216:217], v163, off
	v_mul_f32_e32 v216, 0xbfb8aa3b, v45
	v_rcp_f32_e32 v192, v192
	v_exp_f32_e32 v216, v216
	v_mul_f32_e32 v163, v232, v218
	v_cvt_pk_bf16_f32 v163, v163, s0
	v_lshl_add_u64 v[214:215], s[86:87], 0, v[214:215]
	global_store_short v[214:215], v163, off
	v_mul_f32_e32 v163, v225, v192
	v_add_f32_e32 v192, 1.0, v216
	v_rcp_f32_e32 v192, v192
	v_cvt_pk_bf16_f32 v163, v163, s0
	v_lshl_add_u64 v[208:209], s[86:87], 0, v[208:209]
	global_store_short v[208:209], v163, off
	v_mul_f32_e32 v163, v45, v192
	v_lshlrev_b64 v[208:209], 11, v[212:213]
	v_cvt_pk_bf16_f32 v163, v163, s0
	v_lshl_add_u64 v[208:209], v[158:159], 0, v[208:209]
	v_mul_f32_e32 v192, 0xbfb8aa3b, v102
	global_store_short v[208:209], v163, off
	v_mul_f32_e32 v208, 0xbfb8aa3b, v103
	v_exp_f32_e32 v192, v192
	v_exp_f32_e32 v208, v208
	v_sub_f32_e32 v207, 1.0, v207
	v_mul_f32_e32 v163, v210, v237
	v_add_f32_e32 v192, 1.0, v192
	v_add_f32_e32 v208, 1.0, v208
	v_rcp_f32_e32 v192, v192
	v_rcp_f32_e32 v208, v208
	v_mul_f32_e32 v213, v207, v170
	v_mul_f32_e32 v210, 0xbfb8aa3b, v104
	v_fma_f32 v209, v192, v170, v169
	v_fma_f32 v207, v208, v170, v169
	v_exp_f32_e32 v210, v210
	v_mul_f32_e32 v216, v209, v207
	v_mul_f32_e32 v207, 0xbfb8aa3b, v105
	v_exp_f32_e32 v207, v207
	v_sub_f32_e32 v208, 1.0, v208
	v_mul_f32_e32 v214, v208, v170
	v_add_f32_e32 v208, 1.0, v210
	v_rcp_f32_e32 v208, v208
	v_add_f32_e32 v207, 1.0, v207
	v_rcp_f32_e32 v207, v207
	v_sub_f32_e32 v206, 1.0, v206
	v_mul_f32_e32 v215, v206, v170
	v_fma_f32 v206, v208, v170, v169
	v_sub_f32_e32 v205, 1.0, v205
	v_mul_f32_e32 v219, v205, v170
	v_mul_f32_e32 v220, v206, v216
	v_fma_f32 v205, v207, v170, v169
	v_sub_f32_e32 v204, 1.0, v204
	v_mul_f32_e32 v224, v205, v220
	v_mul_f32_e32 v217, v203, v202
	v_mul_f32_e32 v223, v204, v170
	ds_bpermute_b32 v204, v171, v224
	v_mul_f32_e32 v221, v201, v217
	v_sub_f32_e32 v206, 1.0, v207
	ds_bpermute_b32 v205, v171, v224 offset:64
	v_sub_f32_e32 v208, 1.0, v208
	v_mul_f32_e32 v222, v206, v170
	v_mul_f32_e32 v225, v200, v221
	ds_bpermute_b32 v206, v171, v224 offset:128
	v_mul_f32_e32 v218, v208, v170
	ds_bpermute_b32 v208, v171, v225
	ds_bpermute_b32 v210, v171, v225 offset:64
	v_mul_f32_e32 v212, v211, v238
	ds_bpermute_b32 v207, v171, v224 offset:192
	ds_bpermute_b32 v211, v171, v225 offset:128
	s_waitcnt lgkmcnt(6)
	v_cndmask_b32_e64 v227, v204, 1.0, s[44:45]
	ds_bpermute_b32 v226, v171, v225 offset:192
	v_mul_f32_e32 v227, v163, v227
	s_waitcnt lgkmcnt(6)
	v_cndmask_b32_e64 v228, 1.0, v205, s[46:47]
	v_mul_f32_e32 v227, v227, v228
	s_waitcnt lgkmcnt(5)
	v_cndmask_b32_e64 v228, 1.0, v206, s[48:49]
	v_mul_f32_e32 v227, v227, v228
	s_waitcnt lgkmcnt(4)
	v_cndmask_b32_e64 v228, v208, 1.0, s[44:45]
	v_mul_f32_e32 v228, v212, v228
	s_waitcnt lgkmcnt(3)
	v_cndmask_b32_e64 v229, 1.0, v210, s[46:47]
	v_mul_f32_e32 v228, v228, v229
	s_waitcnt lgkmcnt(1)
	v_cndmask_b32_e64 v229, 1.0, v211, s[48:49]
	v_mul_f32_e32 v204, v204, v205
	v_mul_f32_e32 v205, v206, v207
	v_mul_f32_e32 v228, v228, v229
	v_mul_f32_e32 v229, v204, v205
	v_mul_f32_e32 v204, v208, v210
	s_waitcnt lgkmcnt(0)
	v_mul_f32_e32 v205, v211, v226
	v_mul_f32_e32 v226, v204, v205
	v_mul_f32_e32 v204, 0xbfb8aa3b, v118
	v_exp_f32_e32 v205, v204
	v_mul_f32_e32 v206, v203, v228
	v_rcp_f32_e32 v206, v206
	v_or_b32_e32 v204, 32, v162
	v_add_f32_e32 v205, 1.0, v205
	v_rcp_f32_e32 v205, v205
	v_mul_f32_e32 v203, v203, v174
	v_mul_f32_e32 v203, v203, v206
	v_mul_f32_e32 v230, v209, v227
	v_mul_f32_e32 v231, v118, v205
	v_ashrrev_i32_e32 v205, 31, v204
	v_lshlrev_b64 v[206:207], 9, v[204:205]
	v_lshl_add_u64 v[208:209], v[206:207], 0, v[156:157]
	v_mul_f32_e32 v210, v231, v230
	v_lshlrev_b64 v[208:209], 1, v[208:209]
	v_lshl_add_u64 v[206:207], v[206:207], 0, v[160:161]
	v_cvt_pk_bf16_f32 v232, v210, s0
	v_lshl_add_u64 v[210:211], s[26:27], 0, v[208:209]
	global_store_short v[210:211], v232, off
	v_mul_f32_e32 v210, v231, v203
	v_lshlrev_b64 v[206:207], 1, v[206:207]
	v_cvt_pk_bf16_f32 v231, v210, s0
	v_rcp_f32_e32 v230, v230
	v_lshl_add_u64 v[210:211], s[26:27], 0, v[206:207]
	global_store_short v[210:211], v231, off
	v_mul_f32_e32 v210, 0xbfb8aa3b, v38
	v_sub_f32_e32 v192, 1.0, v192
	v_rcp_f32_e32 v203, v203
	v_exp_f32_e32 v210, v210
	v_mul_f32_e32 v192, v192, v170
	v_mul_f32_e32 v192, v192, v230
	v_cvt_pk_bf16_f32 v192, v192, s0
	v_lshl_add_u64 v[208:209], s[86:87], 0, v[208:209]
	global_store_short v[208:209], v192, off
	v_mul_f32_e32 v192, v213, v203
	v_add_f32_e32 v203, 1.0, v210
	v_rcp_f32_e32 v203, v203
	v_cvt_pk_bf16_f32 v192, v192, s0
	v_lshl_add_u64 v[206:207], s[86:87], 0, v[206:207]
	global_store_short v[206:207], v192, off
; __device__ __forceinline__ unsigned f2bf(float f) { const __bf16 b = (__bf16)f; return (unsigned)__builtin_bit_cast(unsigned short, b); }
; __device__ __forceinline__ float frcp(float x) { return __builtin_amdgcn_rcpf(x); }
; __device__ __forceinline__ float fexp(float x) { return __builtin_amdgcn_exp2f(x * 1.4426950408889634f); }
;     __device__ __forceinline__ void operator()(Acc& acc, int pm, int pn, int wr, int wc, int fr, int fq) const {
;     ...
;             for (int mt = 0; mt < 4; ++mt) {
;                 float cf[4], cb[4], kf[4], kb[4], fbw[4];
;                 float rf = 1.f, rb = 1.f;
; #pragma unroll
;                 for (int j = 0; j < 4; ++j) {
;                     const float sf = frcp(1.f + fexp(-acc[ai][0][mt][1][j])), sb = acc[ai][1][mt][0][j];
;                     const float ff = lb + oml * sf, fb = lb + oml * sb;
;                     kf[j] = oml * (1.f - sf); kb[j] = oml * (1.f - sb);
;                     rf *= ff; rb *= fb; cf[j] = rf; cb[j] = rb; fbw[j] = fb;
;                 }
;                 const float a0 = __shfl(rf, fr), a1 = __shfl(rf, fr + 16), a2 = __shfl(rf, fr + 32), a3 = __shfl(rf, fr + 48);
;                 const float b0 = __shfl(rb, fr), b1 = __shfl(rb, fr + 16), b2 = __shfl(rb, fr + 32), b3 = __shfl(rb, fr + 48);
;                 const float pf = offf * (fq > 0 ? a0 : 1.f) * (fq > 1 ? a1 : 1.f) * (fq > 2 ? a2 : 1.f);
;                 const float pb = offb * (fq > 0 ? b0 : 1.f) * (fq > 1 ? b1 : 1.f) * (fq > 2 ? b2 : 1.f);
;                 offf *= (a0 * a1) * (a2 * a3);
;                 offb *= (b0 * b1) * (b2 * b3);
; #pragma unroll
;                 for (int j = 0; j < 4; ++j) {
;                     const int row = row0 + mt * 16 + fq * 4 + j;
;                     const float Pf = pf * cf[j];
;                     const float Pb = totb * fbw[j] * frcp(pb * cb[j]);
;                     const float qs = siluf_(acc[ai][0][mt][0][j]);
;                     const size_t o0 = ((size_t)row) * 512 + chl, o1 = ((size_t)T_ALL + row) * 512 + chl;
;                     qt[o0] = (bf16_t)f2bf(qs * Pf);
;                     qt[o1] = (bf16_t)f2bf(qs * Pb);
;                     kt[o0] = (bf16_t)f2bf(kf[j] * frcp(Pf));
;                     kt[o1] = (bf16_t)f2bf(kb[j] * frcp(Pb));
;                     sg[(size_t)row * DM + chg] = (bf16_t)f2bf(siluf_(acc[ai][1][mt][1][j]));
	v_mul_f32_e32 v192, v38, v203
	v_lshlrev_b64 v[204:205], 11, v[204:205]
	v_cvt_pk_bf16_f32 v192, v192, s0
	v_lshl_add_u64 v[204:205], v[158:159], 0, v[204:205]
	global_store_short v[204:205], v192, off
	v_mul_f32_e32 v192, 0xbfb8aa3b, v119
	v_exp_f32_e32 v192, v192
	v_mul_f32_e32 v203, v217, v228
	v_rcp_f32_e32 v203, v203
	v_or_b32_e32 v204, 33, v162
	v_add_f32_e32 v192, 1.0, v192
	v_rcp_f32_e32 v192, v192
	v_mul_f32_e32 v202, v202, v174
	v_ashrrev_i32_e32 v205, 31, v204
	v_mul_f32_e32 v211, v202, v203
	v_lshlrev_b64 v[202:203], 9, v[204:205]
	v_mul_f32_e32 v210, v216, v227
	v_mul_f32_e32 v192, v119, v192
	v_lshl_add_u64 v[206:207], v[202:203], 0, v[156:157]
	v_lshl_add_u64 v[202:203], v[202:203], 0, v[160:161]
	v_mul_f32_e32 v208, v192, v210
	v_lshlrev_b64 v[206:207], 1, v[206:207]
	v_cvt_pk_bf16_f32 v213, v208, s0
	v_lshl_add_u64 v[208:209], s[26:27], 0, v[206:207]
	v_mul_f32_e32 v192, v192, v211
	v_lshlrev_b64 v[202:203], 1, v[202:203]
	global_store_short v[208:209], v213, off
	v_cvt_pk_bf16_f32 v192, v192, s0
	v_rcp_f32_e32 v210, v210
	v_lshl_add_u64 v[208:209], s[26:27], 0, v[202:203]
	global_store_short v[208:209], v192, off
	v_mul_f32_e32 v209, 0xbfb8aa3b, v39
	v_exp_f32_e32 v209, v209
	v_mul_f32_e32 v192, v214, v210
	v_cvt_pk_bf16_f32 v192, v192, s0
	v_rcp_f32_e32 v208, v211
	v_lshl_add_u64 v[206:207], s[86:87], 0, v[206:207]
	global_store_short v[206:207], v192, off
	v_add_f32_e32 v206, 1.0, v209
	v_rcp_f32_e32 v206, v206
	v_mul_f32_e32 v192, v215, v208
	v_cvt_pk_bf16_f32 v192, v192, s0
	v_lshl_add_u64 v[202:203], s[86:87], 0, v[202:203]
	global_store_short v[202:203], v192, off
	v_mul_f32_e32 v192, v39, v206
	v_lshlrev_b64 v[202:203], 11, v[204:205]
	v_cvt_pk_bf16_f32 v192, v192, s0
	v_lshl_add_u64 v[202:203], v[158:159], 0, v[202:203]
	global_store_short v[202:203], v192, off
	v_mul_f32_e32 v192, 0xbfb8aa3b, v120
	v_exp_f32_e32 v192, v192
	v_mul_f32_e32 v203, v221, v228
	v_rcp_f32_e32 v203, v203
	v_or_b32_e32 v202, 34, v162
	v_add_f32_e32 v192, 1.0, v192
	v_rcp_f32_e32 v192, v192
	v_mul_f32_e32 v201, v201, v174
	v_mul_f32_e32 v201, v201, v203
	v_ashrrev_i32_e32 v203, 31, v202
	v_lshlrev_b64 v[204:205], 9, v[202:203]
	v_mul_f32_e32 v210, v220, v227
	v_mul_f32_e32 v192, v120, v192
	v_lshl_add_u64 v[206:207], v[204:205], 0, v[156:157]
	v_lshl_add_u64 v[204:205], v[204:205], 0, v[160:161]
	v_mul_f32_e32 v208, v192, v210
	v_lshlrev_b64 v[206:207], 1, v[206:207]
	v_cvt_pk_bf16_f32 v211, v208, s0
	v_lshl_add_u64 v[208:209], s[26:27], 0, v[206:207]
	v_mul_f32_e32 v192, v192, v201
	v_lshlrev_b64 v[204:205], 1, v[204:205]
	global_store_short v[208:209], v211, off
	v_cvt_pk_bf16_f32 v192, v192, s0
	v_rcp_f32_e32 v210, v210
	v_lshl_add_u64 v[208:209], s[26:27], 0, v[204:205]
	global_store_short v[208:209], v192, off
	v_mul_f32_e32 v208, 0xbfb8aa3b, v40
	v_rcp_f32_e32 v201, v201
	v_exp_f32_e32 v208, v208
	v_mul_f32_e32 v192, v218, v210
	v_cvt_pk_bf16_f32 v192, v192, s0
	v_lshl_add_u64 v[206:207], s[86:87], 0, v[206:207]
	global_store_short v[206:207], v192, off
	v_mul_f32_e32 v192, v219, v201
	v_add_f32_e32 v201, 1.0, v208
	v_rcp_f32_e32 v201, v201
	v_cvt_pk_bf16_f32 v192, v192, s0
	v_lshl_add_u64 v[204:205], s[86:87], 0, v[204:205]
	global_store_short v[204:205], v192, off
	v_mul_f32_e32 v192, v40, v201
	v_lshlrev_b64 v[202:203], 11, v[202:203]
	v_cvt_pk_bf16_f32 v192, v192, s0
	v_lshl_add_u64 v[202:203], v[158:159], 0, v[202:203]
	global_store_short v[202:203], v192, off
	v_mul_f32_e32 v192, 0xbfb8aa3b, v121
	v_exp_f32_e32 v192, v192
	v_mul_f32_e32 v201, v225, v228
	v_rcp_f32_e32 v201, v201
	v_or_b32_e32 v202, 35, v162
	v_add_f32_e32 v192, 1.0, v192
	v_rcp_f32_e32 v192, v192
	v_mul_f32_e32 v200, v200, v174
	v_ashrrev_i32_e32 v203, 31, v202
	v_mul_f32_e32 v209, v200, v201
	v_lshlrev_b64 v[200:201], 9, v[202:203]
	v_mul_f32_e32 v208, v224, v227
	v_mul_f32_e32 v192, v121, v192
	v_lshl_add_u64 v[204:205], v[200:201], 0, v[156:157]
	v_lshl_add_u64 v[200:201], v[200:201], 0, v[160:161]
	v_mul_f32_e32 v206, v192, v208
	v_lshlrev_b64 v[204:205], 1, v[204:205]
	v_cvt_pk_bf16_f32 v210, v206, s0
	v_lshl_add_u64 v[206:207], s[26:27], 0, v[204:205]
	v_mul_f32_e32 v192, v192, v209
	v_lshlrev_b64 v[200:201], 1, v[200:201]
	global_store_short v[206:207], v210, off
	v_cvt_pk_bf16_f32 v192, v192, s0
	v_rcp_f32_e32 v208, v208
	v_lshl_add_u64 v[206:207], s[26:27], 0, v[200:201]
	global_store_short v[206:207], v192, off
	v_mul_f32_e32 v207, 0xbfb8aa3b, v41
	v_exp_f32_e32 v207, v207
	v_mul_f32_e32 v192, v222, v208
	v_cvt_pk_bf16_f32 v192, v192, s0
	v_rcp_f32_e32 v206, v209
	v_lshl_add_u64 v[204:205], s[86:87], 0, v[204:205]
	global_store_short v[204:205], v192, off
	v_add_f32_e32 v204, 1.0, v207
	v_rcp_f32_e32 v204, v204
	v_mul_f32_e32 v192, v223, v206
	v_cvt_pk_bf16_f32 v192, v192, s0
	v_lshl_add_u64 v[200:201], s[86:87], 0, v[200:201]
	global_store_short v[200:201], v192, off
	v_mul_f32_e32 v192, v41, v204
	v_lshlrev_b64 v[200:201], 11, v[202:203]
	v_cvt_pk_bf16_f32 v192, v192, s0
	v_lshl_add_u64 v[200:201], v[158:159], 0, v[200:201]
	global_store_short v[200:201], v192, off
	v_mul_f32_e32 v200, 0xbfb8aa3b, v95
	v_exp_f32_e32 v200, v200
	v_mul_f32_e32 v202, 0xbfb8aa3b, v94
	v_exp_f32_e32 v202, v202
	v_mul_f32_e32 v203, 0xbfb8aa3b, v96
	v_add_f32_e32 v200, 1.0, v200
	v_rcp_f32_e32 v200, v200
	v_exp_f32_e32 v203, v203
	v_add_f32_e32 v192, 1.0, v202
	v_sub_f32_e32 v199, 1.0, v199
	v_rcp_f32_e32 v192, v192
	v_mul_f32_e32 v208, v199, v170
	v_fma_f32 v199, v200, v170, v169
	v_sub_f32_e32 v200, 1.0, v200
	v_mul_f32_e32 v209, v200, v170
	v_add_f32_e32 v200, 1.0, v203
	v_rcp_f32_e32 v200, v200
	v_mul_f32_e32 v201, v212, v226
	v_fma_f32 v202, v192, v170, v169
	v_mul_f32_e32 v212, v195, v194
	v_sub_f32_e32 v196, 1.0, v196
	v_mul_f32_e32 v211, v202, v199
	v_mul_f32_e32 v199, 0xbfb8aa3b, v97
	v_mul_f32_e32 v216, v193, v212
	v_mul_f32_e32 v210, v196, v170
	v_fma_f32 v196, v200, v170, v169
	v_exp_f32_e32 v199, v199
	v_sub_f32_e32 v200, 1.0, v200
	v_mul_f32_e32 v220, v175, v216
	v_mul_f32_e32 v213, v200, v170
	ds_bpermute_b32 v200, v171, v220
	ds_bpermute_b32 v203, v171, v220 offset:64
	ds_bpermute_b32 v204, v171, v220 offset:128
	v_add_f32_e32 v199, 1.0, v199
	v_rcp_f32_e32 v199, v199
	s_waitcnt lgkmcnt(2)
; __device__ __forceinline__ unsigned f2bf(float f) { const __bf16 b = (__bf16)f; return (unsigned)__builtin_bit_cast(unsigned short, b); }
; __device__ __forceinline__ float frcp(float x) { return __builtin_amdgcn_rcpf(x); }
; __device__ __forceinline__ float fexp(float x) { return __builtin_amdgcn_exp2f(x * 1.4426950408889634f); }
;     __device__ __forceinline__ void operator()(Acc& acc, int pm, int pn, int wr, int wc, int fr, int fq) const {
;     ...
;             for (int mt = 0; mt < 4; ++mt) {
;                 float cf[4], cb[4], kf[4], kb[4], fbw[4];
;                 float rf = 1.f, rb = 1.f;
; #pragma unroll
;                 for (int j = 0; j < 4; ++j) {
;                     const float sf = frcp(1.f + fexp(-acc[ai][0][mt][1][j])), sb = acc[ai][1][mt][0][j];
;                     const float ff = lb + oml * sf, fb = lb + oml * sb;
;                     kf[j] = oml * (1.f - sf); kb[j] = oml * (1.f - sb);
;                     rf *= ff; rb *= fb; cf[j] = rf; cb[j] = rb; fbw[j] = fb;
;                 }
;                 const float a0 = __shfl(rf, fr), a1 = __shfl(rf, fr + 16), a2 = __shfl(rf, fr + 32), a3 = __shfl(rf, fr + 48);
;                 const float b0 = __shfl(rb, fr), b1 = __shfl(rb, fr + 16), b2 = __shfl(rb, fr + 32), b3 = __shfl(rb, fr + 48);
;                 const float pf = offf * (fq > 0 ? a0 : 1.f) * (fq > 1 ? a1 : 1.f) * (fq > 2 ? a2 : 1.f);
;                 const float pb = offb * (fq > 0 ? b0 : 1.f) * (fq > 1 ? b1 : 1.f) * (fq > 2 ? b2 : 1.f);
;                 offf *= (a0 * a1) * (a2 * a3);
;                 offb *= (b0 * b1) * (b2 * b3);
; #pragma unroll
;                 for (int j = 0; j < 4; ++j) {
;                     const int row = row0 + mt * 16 + fq * 4 + j;
;                     const float Pf = pf * cf[j];
;                     const float Pb = totb * fbw[j] * frcp(pb * cb[j]);
;                     const float qs = siluf_(acc[ai][0][mt][0][j]);
;                     const size_t o0 = ((size_t)row) * 512 + chl, o1 = ((size_t)T_ALL + row) * 512 + chl;
;                     qt[o0] = (bf16_t)f2bf(qs * Pf);
;                     qt[o1] = (bf16_t)f2bf(qs * Pb);
;                     kt[o0] = (bf16_t)f2bf(kf[j] * frcp(Pf));
;                     kt[o1] = (bf16_t)f2bf(kb[j] * frcp(Pb));
;                     sg[(size_t)row * DM + chg] = (bf16_t)f2bf(siluf_(acc[ai][1][mt][1][j]));
	v_cndmask_b32_e64 v200, v200, 1.0, s[44:45]
	v_mul_f32_e32 v200, v201, v200
	s_waitcnt lgkmcnt(1)
	v_cndmask_b32_e64 v201, 1.0, v203, s[46:47]
	v_mul_f32_e32 v200, v200, v201
	s_waitcnt lgkmcnt(0)
	v_cndmask_b32_e64 v201, 1.0, v204, s[48:49]
	v_mul_f32_e32 v215, v196, v211
	v_fma_f32 v196, v199, v170, v169
	v_mul_f32_e32 v222, v200, v201
	v_mul_f32_e32 v200, 0xbfb8aa3b, v114
	v_mul_f32_e32 v219, v196, v215
	v_exp_f32_e32 v201, v200
	v_sub_f32_e32 v198, 1.0, v198
	v_sub_f32_e32 v197, 1.0, v197
	ds_bpermute_b32 v196, v171, v219
	v_mul_f32_e32 v214, v198, v170
	v_sub_f32_e32 v198, 1.0, v199
	v_mul_f32_e32 v218, v197, v170
	ds_bpermute_b32 v197, v171, v219 offset:64
	v_mul_f32_e32 v217, v198, v170
	ds_bpermute_b32 v198, v171, v219 offset:128
	v_add_f32_e32 v201, 1.0, v201
	v_mul_f32_e32 v203, v195, v222
	v_rcp_f32_e32 v201, v201
	v_mul_f32_e32 v163, v163, v229
	s_waitcnt lgkmcnt(2)
	v_cndmask_b32_e64 v205, v196, 1.0, s[44:45]
	v_rcp_f32_e32 v203, v203
	v_mul_f32_e32 v205, v163, v205
	s_waitcnt lgkmcnt(1)
	v_cndmask_b32_e64 v206, 1.0, v197, s[46:47]
	v_mul_f32_e32 v205, v205, v206
	s_waitcnt lgkmcnt(0)
	v_cndmask_b32_e64 v206, 1.0, v198, s[48:49]
	v_or_b32_e32 v200, 48, v162
	v_mul_f32_e32 v221, v205, v206
	v_mul_f32_e32 v195, v195, v174
	v_mul_f32_e32 v224, v114, v201
	v_ashrrev_i32_e32 v201, 31, v200
	v_mul_f32_e32 v223, v202, v221
	v_mul_f32_e32 v195, v195, v203
	v_lshlrev_b64 v[202:203], 9, v[200:201]
	v_lshl_add_u64 v[204:205], v[202:203], 0, v[156:157]
	v_mul_f32_e32 v206, v224, v223
	v_lshlrev_b64 v[204:205], 1, v[204:205]
	v_lshl_add_u64 v[202:203], v[202:203], 0, v[160:161]
	v_cvt_pk_bf16_f32 v225, v206, s0
	v_lshl_add_u64 v[206:207], s[26:27], 0, v[204:205]
	global_store_short v[206:207], v225, off
	v_mul_f32_e32 v206, v224, v195
	v_lshlrev_b64 v[202:203], 1, v[202:203]
	v_cvt_pk_bf16_f32 v224, v206, s0
	v_rcp_f32_e32 v223, v223
	v_lshl_add_u64 v[206:207], s[26:27], 0, v[202:203]
	global_store_short v[206:207], v224, off
	v_mul_f32_e32 v206, 0xbfb8aa3b, v30
	v_sub_f32_e32 v192, 1.0, v192
	v_rcp_f32_e32 v195, v195
	v_exp_f32_e32 v206, v206
	v_mul_f32_e32 v192, v192, v170
	v_mul_f32_e32 v192, v192, v223
	v_cvt_pk_bf16_f32 v192, v192, s0
	v_lshl_add_u64 v[204:205], s[86:87], 0, v[204:205]
	global_store_short v[204:205], v192, off
	v_mul_f32_e32 v192, v208, v195
	v_add_f32_e32 v195, 1.0, v206
	v_rcp_f32_e32 v195, v195
	v_cvt_pk_bf16_f32 v192, v192, s0
	v_lshl_add_u64 v[202:203], s[86:87], 0, v[202:203]
	global_store_short v[202:203], v192, off
	v_mul_f32_e32 v192, v30, v195
	v_lshlrev_b64 v[200:201], 11, v[200:201]
	v_cvt_pk_bf16_f32 v192, v192, s0
	v_lshl_add_u64 v[200:201], v[158:159], 0, v[200:201]
	global_store_short v[200:201], v192, off
	v_mul_f32_e32 v192, 0xbfb8aa3b, v115
	v_exp_f32_e32 v192, v192
	v_mul_f32_e32 v195, v212, v222
	v_rcp_f32_e32 v195, v195
	v_or_b32_e32 v200, 49, v162
	v_add_f32_e32 v192, 1.0, v192
	v_rcp_f32_e32 v192, v192
	v_mul_f32_e32 v194, v194, v174
	v_ashrrev_i32_e32 v201, 31, v200
	v_mul_f32_e32 v207, v194, v195
	v_lshlrev_b64 v[194:195], 9, v[200:201]
	v_mul_f32_e32 v206, v211, v221
	v_mul_f32_e32 v192, v115, v192
	v_lshl_add_u64 v[202:203], v[194:195], 0, v[156:157]
	v_lshl_add_u64 v[194:195], v[194:195], 0, v[160:161]
	v_mul_f32_e32 v204, v192, v206
	v_lshlrev_b64 v[202:203], 1, v[202:203]
	v_cvt_pk_bf16_f32 v208, v204, s0
	v_lshl_add_u64 v[204:205], s[26:27], 0, v[202:203]
	v_mul_f32_e32 v192, v192, v207
	v_lshlrev_b64 v[194:195], 1, v[194:195]
	global_store_short v[204:205], v208, off
	v_cvt_pk_bf16_f32 v192, v192, s0
	v_rcp_f32_e32 v206, v206
	v_lshl_add_u64 v[204:205], s[26:27], 0, v[194:195]
	global_store_short v[204:205], v192, off
	v_mul_f32_e32 v205, 0xbfb8aa3b, v31
	v_exp_f32_e32 v205, v205
	v_mul_f32_e32 v192, v209, v206
	v_cvt_pk_bf16_f32 v192, v192, s0
	v_rcp_f32_e32 v204, v207
	v_lshl_add_u64 v[202:203], s[86:87], 0, v[202:203]
	global_store_short v[202:203], v192, off
	v_add_f32_e32 v202, 1.0, v205
	v_rcp_f32_e32 v202, v202
	v_mul_f32_e32 v192, v210, v204
	v_cvt_pk_bf16_f32 v192, v192, s0
	v_lshl_add_u64 v[194:195], s[86:87], 0, v[194:195]
	global_store_short v[194:195], v192, off
	v_mul_f32_e32 v192, v31, v202
	v_lshlrev_b64 v[194:195], 11, v[200:201]
; __device__ __forceinline__ float frcp(float x) { return __builtin_amdgcn_rcpf(x); }
;     __device__ __forceinline__ void operator()(Acc& acc, int pm, int pn, int wr, int wc, int fr, int fq) const {
;     ...
;             for (int mt = 0; mt < 4; ++mt) {
;                 float cf[4], cb[4], kf[4], kb[4], fbw[4];
;                 float rf = 1.f, rb = 1.f;
; #pragma unroll
;                 for (int j = 0; j < 4; ++j) {
;                     const float sf = frcp(1.f + fexp(-acc[ai][0][mt][1][j])), sb = acc[ai][1][mt][0][j];
;                     const float ff = lb + oml * sf, fb = lb + oml * sb;
;                     kf[j] = oml * (1.f - sf); kb[j] = oml * (1.f - sb);
;                     rf *= ff; rb *= fb; cf[j] = rf; cb[j] = rb; fbw[j] = fb;
;                 }
;                 const float a0 = __shfl(rf, fr), a1 = __shfl(rf, fr + 16), a2 = __shfl(rf, fr + 32), a3 = __shfl(rf, fr + 48);
;                 const float b0 = __shfl(rb, fr), b1 = __shfl(rb, fr + 16), b2 = __shfl(rb, fr + 32), b3 = __shfl(rb, fr + 48);
;                 const float pf = offf * (fq > 0 ? a0 : 1.f) * (fq > 1 ? a1 : 1.f) * (fq > 2 ? a2 : 1.f);
;                 const float pb = offb * (fq > 0 ? b0 : 1.f) * (fq > 1 ? b1 : 1.f) * (fq > 2 ? b2 : 1.f);
;                 offf *= (a0 * a1) * (a2 * a3);
;                 offb *= (b0 * b1) * (b2 * b3);
; #pragma unroll
;                 for (int j = 0; j < 4; ++j) {
;                     const int row = row0 + mt * 16 + fq * 4 + j;
;                     const float Pf = pf * cf[j];
;                     const float Pb = totb * fbw[j] * frcp(pb * cb[j]);
;                     const float qs = siluf_(acc[ai][0][mt][0][j]);
;                     const size_t o0 = ((size_t)row) * 512 + chl, o1 = ((size_t)T_ALL + row) * 512 + chl;
;                     qt[o0] = (bf16_t)f2bf(qs * Pf);
;                     qt[o1] = (bf16_t)f2bf(qs * Pb);
;                     kt[o0] = (bf16_t)f2bf(kf[j] * frcp(Pf));
;                     kt[o1] = (bf16_t)f2bf(kb[j] * frcp(Pb));
;                     sg[(size_t)row * DM + chg] = (bf16_t)f2bf(siluf_(acc[ai][1][mt][1][j]));
;                 }
;             }
;             const int chunk = row0 >> 6;
;             if (fq == 0) {
;                 dend[((size_t)0 * 544 + chunk) * 512 + chl] = offf;
;                 dend[((size_t)1 * 544 + chunk) * 512 + chl] = totb;
;             }
	v_cvt_pk_bf16_f32 v192, v192, s0
	v_lshl_add_u64 v[194:195], v[158:159], 0, v[194:195]
	global_store_short v[194:195], v192, off
	v_mul_f32_e32 v192, 0xbfb8aa3b, v116
	v_exp_f32_e32 v194, v192
	v_mul_f32_e32 v195, v216, v222
	v_rcp_f32_e32 v195, v195
	v_or_b32_e32 v192, 50, v162
	v_add_f32_e32 v194, 1.0, v194
	v_rcp_f32_e32 v194, v194
	v_mul_f32_e32 v193, v193, v174
	v_mul_f32_e32 v205, v193, v195
	v_ashrrev_i32_e32 v193, 31, v192
	v_mul_f32_e32 v206, v116, v194
	v_lshlrev_b64 v[194:195], 9, v[192:193]
	v_mul_f32_e32 v204, v215, v221
	v_lshl_add_u64 v[200:201], v[194:195], 0, v[156:157]
	v_mul_f32_e32 v202, v206, v204
	v_lshlrev_b64 v[200:201], 1, v[200:201]
	v_rcp_f32_e32 v204, v204
	v_lshl_add_u64 v[194:195], v[194:195], 0, v[160:161]
	v_cvt_pk_bf16_f32 v207, v202, s0
	v_lshl_add_u64 v[202:203], s[26:27], 0, v[200:201]
	global_store_short v[202:203], v207, off
	v_mul_f32_e32 v202, v206, v205
	v_lshlrev_b64 v[194:195], 1, v[194:195]
	v_cvt_pk_bf16_f32 v206, v202, s0
	v_lshl_add_u64 v[202:203], s[26:27], 0, v[194:195]
	global_store_short v[202:203], v206, off
	v_mul_f32_e32 v202, v213, v204
	v_mul_f32_e32 v204, 0xbfb8aa3b, v32
	v_exp_f32_e32 v204, v204
	v_cvt_pk_bf16_f32 v202, v202, s0
	v_rcp_f32_e32 v203, v205
	v_lshl_add_u64 v[200:201], s[86:87], 0, v[200:201]
	global_store_short v[200:201], v202, off
	v_add_f32_e32 v201, 1.0, v204
	v_rcp_f32_e32 v201, v201
	v_mul_f32_e32 v200, v214, v203
	v_cvt_pk_bf16_f32 v200, v200, s0
	v_lshl_add_u64 v[194:195], s[86:87], 0, v[194:195]
	global_store_short v[194:195], v200, off
	v_mul_f32_e32 v194, v32, v201
	v_lshlrev_b64 v[192:193], 11, v[192:193]
	v_cvt_pk_bf16_f32 v194, v194, s0
	v_lshl_add_u64 v[192:193], v[158:159], 0, v[192:193]
	global_store_short v[192:193], v194, off
	v_mul_f32_e32 v192, 0xbfb8aa3b, v117
	v_exp_f32_e32 v193, v192
	v_or_b32_e32 v192, 51, v162
	v_mul_f32_e32 v162, v220, v222
	v_rcp_f32_e32 v162, v162
	v_add_f32_e32 v193, 1.0, v193
	v_rcp_f32_e32 v193, v193
	v_mul_f32_e32 v175, v175, v174
	v_mul_f32_e32 v162, v175, v162
	v_mul_f32_e32 v204, v219, v221
	v_mul_f32_e32 v175, v117, v193
	v_ashrrev_i32_e32 v193, 31, v192
	v_lshlrev_b64 v[194:195], 9, v[192:193]
	v_lshl_add_u64 v[200:201], v[194:195], 0, v[156:157]
	v_lshl_add_u64 v[194:195], v[194:195], 0, v[160:161]
	v_mul_f32_e32 v202, v175, v204
	v_lshlrev_b64 v[200:201], 1, v[200:201]
	v_cvt_pk_bf16_f32 v205, v202, s0
	v_lshl_add_u64 v[202:203], s[26:27], 0, v[200:201]
	v_mul_f32_e32 v175, v175, v162
	v_lshlrev_b64 v[194:195], 1, v[194:195]
	global_store_short v[202:203], v205, off
	v_cvt_pk_bf16_f32 v175, v175, s0
	v_rcp_f32_e32 v204, v204
	v_lshl_add_u64 v[202:203], s[26:27], 0, v[194:195]
	global_store_short v[202:203], v175, off
	v_mul_f32_e32 v202, 0xbfb8aa3b, v33
	v_exp_f32_e32 v202, v202
	v_mul_f32_e32 v175, v217, v204
	v_cvt_pk_bf16_f32 v175, v175, s0
	v_rcp_f32_e32 v162, v162
	v_lshl_add_u64 v[200:201], s[86:87], 0, v[200:201]
	global_store_short v[200:201], v175, off
	v_add_f32_e32 v175, 1.0, v202
	v_rcp_f32_e32 v175, v175
	ds_bpermute_b32 v199, v171, v219 offset:192
	v_mul_f32_e32 v162, v218, v162
	v_cvt_pk_bf16_f32 v162, v162, s0
	v_lshl_add_u64 v[194:195], s[86:87], 0, v[194:195]
	global_store_short v[194:195], v162, off
	v_mul_f32_e32 v162, v33, v175
	v_lshlrev_b64 v[192:193], 11, v[192:193]
	v_cvt_pk_bf16_f32 v162, v162, s0
	v_lshl_add_u64 v[192:193], v[158:159], 0, v[192:193]
	v_readlane_b32 s15, v253, 31
	global_store_short v[192:193], v162, off
	s_and_saveexec_b64 s[10:11], s[44:45]
	s_cbranch_execz .LBB0_486
	s_ashr_i32 s12, s4, 6
	s_ashr_i32 s13, s12, 31
	v_readlane_b32 s28, v253, 28
	s_lshl_b64 s[12:13], s[12:13], 11
	v_readlane_b32 s30, v253, 30
	v_mul_f32_e32 v162, v196, v197
	s_waitcnt lgkmcnt(0)
	v_mul_f32_e32 v175, v198, v199
	v_readlane_b32 s31, v253, 31
	s_add_u32 s12, s30, s12
	v_mul_f32_e32 v162, v162, v175
	s_addc_u32 s13, s31, s13
	v_mul_f32_e32 v175, v163, v162
	v_lshl_add_u64 v[162:163], v[156:157], 2, s[12:13]
	global_store_dword v[162:163], v175, off
	v_add_co_u32_e32 v162, vcc, 0x110000, v162
	v_readlane_b32 s29, v253, 29
	s_nop 0
	v_addc_co_u32_e32 v163, vcc, 0, v163, vcc
	global_store_dword v[162:163], v174, off

; #define PG8_STAGE(bufoff, gbase) do { _Pragma("unroll") for (int _i = 0; _i < 2; ++_i) \
;         __builtin_amdgcn_global_load_lds((const unsigned*)((const char*)(gbase) + voff[_i]), (LAS unsigned*)(lds + (bufoff) + ldsw + _i * 8192), 16, 0, 0); } while (0)
; #define PG8_LDA(dst, b, h) do { _Pragma("unroll") for (int m = 0; m < 4; ++m) _Pragma("unroll") for (int k = 0; k < 2; ++k) dst[m][k] = *(const LAS bf16x8*)(lds + PG8_SA(b, h) + aoff + m * 2048 + k * 1024); } while (0)
; #define PG8_LDB(dst, b, h) do { _Pragma("unroll") for (int n = 0; n < 2; ++n) _Pragma("unroll") for (int k = 0; k < 2; ++k) dst[n][k] = *(const LAS bf16x8*)(lds + PG8_SB(b, h) + boff + n * 2048 + k * 1024); } while (0)
; #define PG8_WAIT_L(n) asm volatile("s_waitcnt lgkmcnt(" #n ")" ::: "memory")
; #define PG8_BAR __builtin_amdgcn_s_barrier()
; #define PG8_SCHED __builtin_amdgcn_sched_barrier(0)
;     ...
;         for (int t = 0; t < nt; t += 2) {
;             const bool last = (t == nt - 2);
;             const char* a1 = cA + (size_t)(t + 1) * kstep;
;             const char* a2 = last ? nA : cA + (size_t)(t + 2) * kstep; const char* b2 = last ? nB : cB + (size_t)(t + 2) * kstep;
;             const char* a3 = a2 + kstep; const char* b3 = b2 + kstep;
;             PG8_LDB(B0, 0, 0); PG8_SCHED; PG8_LDA(At, 0, 0); PG8_STAGE(PG8_SA(1, 1), a1 + hstep);
;             PG8_WAIT_L(8); PG8_BAR; PG8_WAIT_L(0); PG8_MMA(0, 0, At, B0); PG8_BAR; PG8_SCHED;
;             PG8_LDB(B1, 0, 1); PG8_STAGE(PG8_SB(0, 0), b2);
;             PG8_BAR; PG8_WAIT_L(0); PG8_MMA(0, 1, At, B1); PG8_BAR;
;             PG8_LDA(At, 0, 1); PG8_STAGE(PG8_SA(0, 0), a2);
;             PG8_BAR; PG8_WAIT_L(0); PG8_MMA(1, 0, At, B0); PG8_BAR; PG8_SCHED;
.LBB0_759:
	s_add_u32 s0, s10, 0xfffc0080
	s_addc_u32 s1, s11, -1
	s_add_i32 s31, 0, 0x10000
	v_add_u32_e32 v161, s31, v158
	ds_read_b128 v[154:157], v161
	ds_read_b128 v[162:165], v161 offset:1024
	ds_read_b128 v[166:169], v161 offset:2048
	ds_read_b128 v[170:173], v161 offset:3072
	s_cmp_eq_u32 s30, 12
	s_cselect_b32 s15, s18, s1
	s_cselect_b32 s14, s19, s0
	s_cselect_b32 s13, s22, s29
	s_cselect_b32 s12, s23, s28
	v_lshl_add_u64 v[174:175], s[10:11], 0, v[150:151]
	s_add_i32 m0, s17, 0xc000
	ds_read_b128 v[194:197], v160
	ds_read_b128 v[198:201], v160 offset:1024
	ds_read_b128 v[202:205], v160 offset:2048
	ds_read_b128 v[206:209], v160 offset:3072
	ds_read_b128 v[210:213], v160 offset:4096
	ds_read_b128 v[214:217], v160 offset:5120
	ds_read_b128 v[218:221], v160 offset:6144
	ds_read_b128 v[222:225], v160 offset:7168
	global_load_lds_dwordx4 v[174:175], off
	s_add_i32 m0, s17, 0xe000
	v_lshl_add_u64 v[174:175], s[10:11], 0, v[152:153]
	global_load_lds_dwordx4 v[174:175], off
	s_waitcnt lgkmcnt(8)
	s_barrier
	s_waitcnt lgkmcnt(0)
	s_setprio 1
	v_mfma_f32_16x16x32_bf16 v[126:129], v[154:157], v[194:197], v[126:129]
	v_mfma_f32_16x16x32_bf16 v[122:125], v[166:169], v[194:197], v[122:125]
	v_mfma_f32_16x16x32_bf16 v[110:113], v[154:157], v[202:205], v[110:113]
	v_mfma_f32_16x16x32_bf16 v[106:109], v[166:169], v[202:205], v[106:109]
	v_mfma_f32_16x16x32_bf16 v[94:97], v[154:157], v[210:213], v[94:97]
	v_mfma_f32_16x16x32_bf16 v[90:93], v[166:169], v[210:213], v[90:93]
	v_mfma_f32_16x16x32_bf16 v[78:81], v[154:157], v[218:221], v[78:81]
	v_mfma_f32_16x16x32_bf16 v[74:77], v[166:169], v[218:221], v[74:77]
	v_mfma_f32_16x16x32_bf16 v[126:129], v[162:165], v[198:201], v[126:129]
	v_mfma_f32_16x16x32_bf16 v[122:125], v[170:173], v[198:201], v[122:125]
	v_mfma_f32_16x16x32_bf16 v[110:113], v[162:165], v[206:209], v[110:113]
	v_mfma_f32_16x16x32_bf16 v[106:109], v[170:173], v[206:209], v[106:109]
	v_mfma_f32_16x16x32_bf16 v[94:97], v[162:165], v[214:217], v[94:97]
	v_mfma_f32_16x16x32_bf16 v[90:93], v[170:173], v[214:217], v[90:93]
	v_mfma_f32_16x16x32_bf16 v[78:81], v[162:165], v[222:225], v[78:81]
	v_mfma_f32_16x16x32_bf16 v[74:77], v[170:173], v[222:225], v[74:77]
	s_setprio 0
	s_barrier
	s_add_i32 s0, 0, 0x14000
	s_add_i32 s1, s31, s16
	v_add_u32_e32 v161, s0, v158
	v_lshl_add_u64 v[174:175], s[12:13], 0, v[132:133]
	s_mov_b32 m0, s1
	ds_read_b128 v[226:229], v161
	ds_read_b128 v[230:233], v161 offset:1024
	ds_read_b128 v[234:237], v161 offset:2048
	ds_read_b128 v[238:241], v161 offset:3072
	global_load_lds_dwordx4 v[174:175], off
	s_add_i32 m0, s1, 0x2000
	v_lshl_add_u64 v[242:243], s[12:13], 0, v[130:131]
	global_load_lds_dwordx4 v[242:243], off
	s_barrier
	s_waitcnt lgkmcnt(0)
	s_setprio 1
	v_mfma_f32_16x16x32_bf16 v[118:121], v[226:229], v[194:197], v[118:121]
	v_mfma_f32_16x16x32_bf16 v[114:117], v[234:237], v[194:197], v[114:117]
	v_mfma_f32_16x16x32_bf16 v[102:105], v[226:229], v[202:205], v[102:105]
	v_mfma_f32_16x16x32_bf16 v[98:101], v[234:237], v[202:205], v[98:101]
	v_mfma_f32_16x16x32_bf16 v[86:89], v[226:229], v[210:213], v[86:89]
	v_mfma_f32_16x16x32_bf16 v[82:85], v[234:237], v[210:213], v[82:85]
	v_mfma_f32_16x16x32_bf16 v[70:73], v[226:229], v[218:221], v[70:73]
	v_mfma_f32_16x16x32_bf16 v[66:69], v[234:237], v[218:221], v[66:69]
	v_mfma_f32_16x16x32_bf16 v[118:121], v[230:233], v[198:201], v[118:121]
	v_mfma_f32_16x16x32_bf16 v[114:117], v[238:241], v[198:201], v[114:117]
	v_mfma_f32_16x16x32_bf16 v[102:105], v[230:233], v[206:209], v[102:105]
	v_mfma_f32_16x16x32_bf16 v[98:101], v[238:241], v[206:209], v[98:101]
	v_mfma_f32_16x16x32_bf16 v[86:89], v[230:233], v[214:217], v[86:89]
	v_mfma_f32_16x16x32_bf16 v[82:85], v[238:241], v[214:217], v[82:85]
	v_mfma_f32_16x16x32_bf16 v[70:73], v[230:233], v[222:225], v[70:73]
	v_mfma_f32_16x16x32_bf16 v[66:69], v[238:241], v[222:225], v[66:69]
	s_setprio 0
	s_mov_b32 m0, s17
	v_lshl_add_u64 v[244:245], s[14:15], 0, v[132:133]
	s_barrier
	ds_read_b128 v[194:197], v160 offset:16384
	ds_read_b128 v[198:201], v160 offset:17408
	ds_read_b128 v[202:205], v160 offset:18432
	ds_read_b128 v[206:209], v160 offset:19456
	ds_read_b128 v[210:213], v160 offset:20480
	ds_read_b128 v[214:217], v160 offset:21504
	ds_read_b128 v[218:221], v160 offset:22528
	ds_read_b128 v[222:225], v160 offset:23552
	global_load_lds_dwordx4 v[244:245], off
	s_mov_b32 m0, s20
	v_lshl_add_u64 v[246:247], s[14:15], 0, v[130:131]
	global_load_lds_dwordx4 v[246:247], off
	s_barrier
	s_waitcnt lgkmcnt(0)
	s_setprio 1
	v_mfma_f32_16x16x32_bf16 v[62:65], v[154:157], v[194:197], v[62:65]
	v_mfma_f32_16x16x32_bf16 v[58:61], v[166:169], v[194:197], v[58:61]
	v_mfma_f32_16x16x32_bf16 v[46:49], v[154:157], v[202:205], v[46:49]
	v_mfma_f32_16x16x32_bf16 v[42:45], v[166:169], v[202:205], v[42:45]
	v_mfma_f32_16x16x32_bf16 v[30:33], v[154:157], v[210:213], v[30:33]
	v_mfma_f32_16x16x32_bf16 v[26:29], v[166:169], v[210:213], v[26:29]
	v_mfma_f32_16x16x32_bf16 v[14:17], v[154:157], v[218:221], v[14:17]
	v_mfma_f32_16x16x32_bf16 v[10:13], v[166:169], v[218:221], v[10:13]
	v_mfma_f32_16x16x32_bf16 v[62:65], v[162:165], v[198:201], v[62:65]
	v_mfma_f32_16x16x32_bf16 v[58:61], v[170:173], v[198:201], v[58:61]
	v_mfma_f32_16x16x32_bf16 v[46:49], v[162:165], v[206:209], v[46:49]
	v_mfma_f32_16x16x32_bf16 v[42:45], v[170:173], v[206:209], v[42:45]
	v_mfma_f32_16x16x32_bf16 v[30:33], v[162:165], v[214:217], v[30:33]
	v_mfma_f32_16x16x32_bf16 v[26:29], v[170:173], v[214:217], v[26:29]
	v_mfma_f32_16x16x32_bf16 v[14:17], v[162:165], v[222:225], v[14:17]
	v_mfma_f32_16x16x32_bf16 v[10:13], v[170:173], v[222:225], v[10:13]
	s_setprio 0
	s_barrier
; #define PG8_STAGE(bufoff, gbase) do { _Pragma("unroll") for (int _i = 0; _i < 2; ++_i) \
;         __builtin_amdgcn_global_load_lds((const unsigned*)((const char*)(gbase) + voff[_i]), (LAS unsigned*)(lds + (bufoff) + ldsw + _i * 8192), 16, 0, 0); } while (0)
; #define PG8_LDA(dst, b, h) do { _Pragma("unroll") for (int m = 0; m < 4; ++m) _Pragma("unroll") for (int k = 0; k < 2; ++k) dst[m][k] = *(const LAS bf16x8*)(lds + PG8_SA(b, h) + aoff + m * 2048 + k * 1024); } while (0)
; #define PG8_LDB(dst, b, h) do { _Pragma("unroll") for (int n = 0; n < 2; ++n) _Pragma("unroll") for (int k = 0; k < 2; ++k) dst[n][k] = *(const LAS bf16x8*)(lds + PG8_SB(b, h) + boff + n * 2048 + k * 1024); } while (0)
; #define PG8_WAIT_V(n) asm volatile("s_waitcnt vmcnt(" #n ")" ::: "memory")
; #define PG8_WAIT_L(n) asm volatile("s_waitcnt lgkmcnt(" #n ")" ::: "memory")
; #define PG8_BAR __builtin_amdgcn_s_barrier()
; #define PG8_SCHED __builtin_amdgcn_sched_barrier(0)
;     ...
;             PG8_STAGE(PG8_SB(0, 1), b2 + hstep);
;             PG8_WAIT_V(6); PG8_BAR; PG8_MMA(1, 1, At, B1); PG8_BAR;
;             PG8_LDB(B0, 1, 0); PG8_SCHED; PG8_LDA(At, 1, 0); PG8_STAGE(PG8_SA(0, 1), a2 + hstep);
;             PG8_WAIT_L(8); PG8_BAR; PG8_WAIT_L(0); PG8_MMA(0, 0, At, B0); PG8_BAR; PG8_SCHED;
;             PG8_LDB(B1, 1, 1); PG8_STAGE(PG8_SB(1, 0), b3);
;             PG8_BAR; PG8_WAIT_L(0); PG8_MMA(0, 1, At, B1); PG8_BAR;
;             PG8_LDA(At, 1, 1); PG8_STAGE(PG8_SA(1, 0), a3);
	s_add_u32 s46, s12, 0x40000
	s_addc_u32 s47, s13, 0
	s_add_i32 s0, s0, s16
	s_mov_b32 m0, s0
	v_lshl_add_u64 v[154:155], s[46:47], 0, v[132:133]
	global_load_lds_dwordx4 v[154:155], off
	s_add_i32 m0, s0, 0x2000
	v_lshl_add_u64 v[154:155], s[46:47], 0, v[130:131]
	global_load_lds_dwordx4 v[154:155], off
	s_waitcnt vmcnt(6)
	s_barrier
	s_setprio 1
	v_mfma_f32_16x16x32_bf16 v[54:57], v[226:229], v[194:197], v[54:57]
	v_mfma_f32_16x16x32_bf16 v[50:53], v[234:237], v[194:197], v[50:53]
	v_mfma_f32_16x16x32_bf16 v[38:41], v[226:229], v[202:205], v[38:41]
	v_mfma_f32_16x16x32_bf16 v[34:37], v[234:237], v[202:205], v[34:37]
	v_mfma_f32_16x16x32_bf16 v[22:25], v[226:229], v[210:213], v[22:25]
	v_mfma_f32_16x16x32_bf16 v[18:21], v[234:237], v[210:213], v[18:21]
	v_mfma_f32_16x16x32_bf16 v[6:9], v[226:229], v[218:221], v[6:9]
	v_mfma_f32_16x16x32_bf16 v[2:5], v[234:237], v[218:221], v[2:5]
	v_mfma_f32_16x16x32_bf16 v[54:57], v[230:233], v[198:201], v[54:57]
	v_mfma_f32_16x16x32_bf16 v[50:53], v[238:241], v[198:201], v[50:53]
	v_mfma_f32_16x16x32_bf16 v[38:41], v[230:233], v[206:209], v[38:41]
	v_mfma_f32_16x16x32_bf16 v[34:37], v[238:241], v[206:209], v[34:37]
	v_mfma_f32_16x16x32_bf16 v[22:25], v[230:233], v[214:217], v[22:25]
	v_mfma_f32_16x16x32_bf16 v[18:21], v[238:241], v[214:217], v[18:21]
	v_mfma_f32_16x16x32_bf16 v[6:9], v[230:233], v[222:225], v[6:9]
	v_mfma_f32_16x16x32_bf16 v[2:5], v[238:241], v[222:225], v[2:5]
	s_setprio 0
	s_add_i32 s0, 0, 0x18000
	v_add_u32_e32 v161, s0, v158
	s_barrier
	ds_read_b128 v[154:157], v161
	ds_read_b128 v[162:165], v161 offset:1024
	ds_read_b128 v[166:169], v161 offset:2048
	ds_read_b128 v[170:173], v161 offset:3072
	s_add_u32 s14, s14, 0x40000
	s_addc_u32 s15, s15, 0
	s_mov_b32 m0, s40
	v_lshl_add_u64 v[226:227], s[14:15], 0, v[132:133]
	ds_read_b128 v[194:197], v160 offset:32768
	ds_read_b128 v[198:201], v160 offset:33792
	ds_read_b128 v[202:205], v160 offset:34816
	ds_read_b128 v[206:209], v160 offset:35840
	ds_read_b128 v[210:213], v160 offset:36864
	ds_read_b128 v[214:217], v160 offset:37888
	ds_read_b128 v[218:221], v160 offset:38912
	ds_read_b128 v[222:225], v160 offset:39936
	global_load_lds_dwordx4 v[226:227], off
	s_mov_b32 m0, s41
	v_lshl_add_u64 v[226:227], s[14:15], 0, v[130:131]
	global_load_lds_dwordx4 v[226:227], off
	s_waitcnt lgkmcnt(8)
	s_barrier
	s_waitcnt lgkmcnt(0)
	s_setprio 1
	v_mfma_f32_16x16x32_bf16 v[126:129], v[154:157], v[194:197], v[126:129]
	v_mfma_f32_16x16x32_bf16 v[122:125], v[166:169], v[194:197], v[122:125]
	v_mfma_f32_16x16x32_bf16 v[110:113], v[154:157], v[202:205], v[110:113]
	v_mfma_f32_16x16x32_bf16 v[106:109], v[166:169], v[202:205], v[106:109]
	v_mfma_f32_16x16x32_bf16 v[94:97], v[154:157], v[210:213], v[94:97]
	v_mfma_f32_16x16x32_bf16 v[90:93], v[166:169], v[210:213], v[90:93]
	v_mfma_f32_16x16x32_bf16 v[78:81], v[154:157], v[218:221], v[78:81]
	v_mfma_f32_16x16x32_bf16 v[74:77], v[166:169], v[218:221], v[74:77]
	v_mfma_f32_16x16x32_bf16 v[126:129], v[162:165], v[198:201], v[126:129]
	v_mfma_f32_16x16x32_bf16 v[122:125], v[170:173], v[198:201], v[122:125]
	v_mfma_f32_16x16x32_bf16 v[110:113], v[162:165], v[206:209], v[110:113]
	v_mfma_f32_16x16x32_bf16 v[106:109], v[170:173], v[206:209], v[106:109]
	v_mfma_f32_16x16x32_bf16 v[94:97], v[162:165], v[214:217], v[94:97]
	v_mfma_f32_16x16x32_bf16 v[90:93], v[170:173], v[214:217], v[90:93]
	v_mfma_f32_16x16x32_bf16 v[78:81], v[162:165], v[222:225], v[78:81]
	v_mfma_f32_16x16x32_bf16 v[74:77], v[170:173], v[222:225], v[74:77]
	s_setprio 0
	s_barrier
	s_add_i32 s1, 0, 0x1c000
	s_add_i32 s0, s0, s16
	v_add_u32_e32 v161, s1, v158
	v_lshl_add_u64 v[174:175], v[174:175], 0, s[88:89]
	s_mov_b32 m0, s0
	ds_read_b128 v[226:229], v161
	ds_read_b128 v[230:233], v161 offset:1024
	ds_read_b128 v[234:237], v161 offset:2048
	ds_read_b128 v[238:241], v161 offset:3072
	global_load_lds_dwordx4 v[174:175], off
	s_add_i32 m0, s0, 0x2000
	v_lshl_add_u64 v[174:175], v[242:243], 0, s[88:89]
	global_load_lds_dwordx4 v[174:175], off
	s_barrier
	s_waitcnt lgkmcnt(0)
	s_setprio 1
	v_mfma_f32_16x16x32_bf16 v[118:121], v[226:229], v[194:197], v[118:121]
	v_mfma_f32_16x16x32_bf16 v[114:117], v[234:237], v[194:197], v[114:117]
	v_mfma_f32_16x16x32_bf16 v[102:105], v[226:229], v[202:205], v[102:105]
	v_mfma_f32_16x16x32_bf16 v[98:101], v[234:237], v[202:205], v[98:101]
	v_mfma_f32_16x16x32_bf16 v[86:89], v[226:229], v[210:213], v[86:89]
	v_mfma_f32_16x16x32_bf16 v[82:85], v[234:237], v[210:213], v[82:85]
	v_mfma_f32_16x16x32_bf16 v[70:73], v[226:229], v[218:221], v[70:73]
	v_mfma_f32_16x16x32_bf16 v[66:69], v[234:237], v[218:221], v[66:69]
	v_mfma_f32_16x16x32_bf16 v[118:121], v[230:233], v[198:201], v[118:121]
	v_mfma_f32_16x16x32_bf16 v[114:117], v[238:241], v[198:201], v[114:117]
	v_mfma_f32_16x16x32_bf16 v[102:105], v[230:233], v[206:209], v[102:105]
	v_mfma_f32_16x16x32_bf16 v[98:101], v[238:241], v[206:209], v[98:101]
	v_mfma_f32_16x16x32_bf16 v[86:89], v[230:233], v[214:217], v[86:89]
	v_mfma_f32_16x16x32_bf16 v[82:85], v[238:241], v[214:217], v[82:85]
	v_mfma_f32_16x16x32_bf16 v[70:73], v[230:233], v[222:225], v[70:73]
	v_mfma_f32_16x16x32_bf16 v[66:69], v[238:241], v[222:225], v[66:69]
	s_setprio 0
	s_mov_b32 m0, s70
	v_lshl_add_u64 v[174:175], v[244:245], 0, s[88:89]
	s_barrier
; #define PG8_STAGE(bufoff, gbase) do { _Pragma("unroll") for (int _i = 0; _i < 2; ++_i) \
;         __builtin_amdgcn_global_load_lds((const unsigned*)((const char*)(gbase) + voff[_i]), (LAS unsigned*)(lds + (bufoff) + ldsw + _i * 8192), 16, 0, 0); } while (0)
; #define PG8_LDA(dst, b, h) do { _Pragma("unroll") for (int m = 0; m < 4; ++m) _Pragma("unroll") for (int k = 0; k < 2; ++k) dst[m][k] = *(const LAS bf16x8*)(lds + PG8_SA(b, h) + aoff + m * 2048 + k * 1024); } while (0)
; #define PG8_WAIT_V(n) asm volatile("s_waitcnt vmcnt(" #n ")" ::: "memory")
; #define PG8_WAIT_L(n) asm volatile("s_waitcnt lgkmcnt(" #n ")" ::: "memory")
; #define PG8_BAR __builtin_amdgcn_s_barrier()
; #define PG8_SCHED __builtin_amdgcn_sched_barrier(0)
;     ...
;             PG8_LDA(At, 1, 1); PG8_STAGE(PG8_SA(1, 0), a3);
;             PG8_BAR; PG8_WAIT_L(0); PG8_MMA(1, 0, At, B0); PG8_BAR; PG8_SCHED;
;             PG8_STAGE(PG8_SB(1, 1), b3 + hstep);
;             PG8_WAIT_V(6); PG8_BAR; PG8_MMA(1, 1, At, B1); PG8_BAR;
;     __device__ __forceinline__ void operator()(Acc& acc, int pm, int pn, int wr, int wc, int fr, int fq) const {
;         const bool isg = mode == 0 ? (pn < 5) : (mode == 1);
;         bf16_t* base = isg ? gbuf : upre;
;         const int cb = ((mode == 0 && !isg) ? pn * 256 - DRNN : pn * 256) + wc * 32 + fq * 4;
; #pragma unroll
;         for (int ai = 0; ai < 2; ++ai)
; #pragma unroll
;             for (int m = 0; m < 4; ++m) {
;                 const size_t ro = (size_t)(pm * 256 + ai * 128 + wr * 64 + m * 16 + fr) * DRNN + cb;
; #pragma unroll
;                 for (int bj = 0; bj < 2; ++bj)
; #pragma unroll
;                     for (int n = 0; n < 2; ++n) {
;                         f32x4 v = acc[ai][bj][m][n];
;                         if (isg) { v[0] = gelu_tanh(v[0]); v[1] = gelu_tanh(v[1]); v[2] = gelu_tanh(v[2]); v[3] = gelu_tanh(v[3]); }
;                         u32x2 o = {pack2(v[0], v[1]), pack2(v[2], v[3])};
;                         *reinterpret_cast<u32x2*>(base + ro + bj * 128 + n * 16) = o;
	ds_read_b128 v[194:197], v160 offset:49152
	ds_read_b128 v[198:201], v160 offset:50176
	ds_read_b128 v[202:205], v160 offset:51200
	ds_read_b128 v[206:209], v160 offset:52224
	ds_read_b128 v[210:213], v160 offset:53248
	ds_read_b128 v[214:217], v160 offset:54272
	ds_read_b128 v[218:221], v160 offset:55296
	ds_read_b128 v[222:225], v160 offset:56320
	global_load_lds_dwordx4 v[174:175], off
	s_mov_b32 m0, s71
	v_lshl_add_u64 v[174:175], v[246:247], 0, s[88:89]
	global_load_lds_dwordx4 v[174:175], off
	s_barrier
	s_waitcnt lgkmcnt(0)
	s_setprio 1
	v_mfma_f32_16x16x32_bf16 v[62:65], v[154:157], v[194:197], v[62:65]
	v_mfma_f32_16x16x32_bf16 v[58:61], v[166:169], v[194:197], v[58:61]
	v_mfma_f32_16x16x32_bf16 v[46:49], v[154:157], v[202:205], v[46:49]
	v_mfma_f32_16x16x32_bf16 v[42:45], v[166:169], v[202:205], v[42:45]
	v_mfma_f32_16x16x32_bf16 v[30:33], v[154:157], v[210:213], v[30:33]
	v_mfma_f32_16x16x32_bf16 v[26:29], v[166:169], v[210:213], v[26:29]
	v_mfma_f32_16x16x32_bf16 v[14:17], v[154:157], v[218:221], v[14:17]
	v_mfma_f32_16x16x32_bf16 v[10:13], v[166:169], v[218:221], v[10:13]
	v_mfma_f32_16x16x32_bf16 v[62:65], v[162:165], v[198:201], v[62:65]
	v_mfma_f32_16x16x32_bf16 v[58:61], v[170:173], v[198:201], v[58:61]
	v_mfma_f32_16x16x32_bf16 v[46:49], v[162:165], v[206:209], v[46:49]
	v_mfma_f32_16x16x32_bf16 v[42:45], v[170:173], v[206:209], v[42:45]
	v_mfma_f32_16x16x32_bf16 v[30:33], v[162:165], v[214:217], v[30:33]
	v_mfma_f32_16x16x32_bf16 v[26:29], v[170:173], v[214:217], v[26:29]
	v_mfma_f32_16x16x32_bf16 v[14:17], v[162:165], v[222:225], v[14:17]
	v_mfma_f32_16x16x32_bf16 v[10:13], v[170:173], v[222:225], v[10:13]
	s_setprio 0
	s_barrier
	s_add_u32 s12, s12, 0x40080
	s_addc_u32 s13, s13, 0
	s_add_i32 s0, s1, s16
	s_mov_b32 m0, s0
	v_lshl_add_u64 v[154:155], s[12:13], 0, v[132:133]
	global_load_lds_dwordx4 v[154:155], off
	s_add_i32 m0, s0, 0x2000
	v_lshl_add_u64 v[154:155], s[12:13], 0, v[130:131]
	global_load_lds_dwordx4 v[154:155], off
	s_waitcnt vmcnt(6)
	s_barrier
	s_setprio 1
	v_mfma_f32_16x16x32_bf16 v[54:57], v[226:229], v[194:197], v[54:57]
	v_mfma_f32_16x16x32_bf16 v[50:53], v[234:237], v[194:197], v[50:53]
	v_mfma_f32_16x16x32_bf16 v[38:41], v[226:229], v[202:205], v[38:41]
	v_mfma_f32_16x16x32_bf16 v[34:37], v[234:237], v[202:205], v[34:37]
	v_mfma_f32_16x16x32_bf16 v[22:25], v[226:229], v[210:213], v[22:25]
	v_mfma_f32_16x16x32_bf16 v[18:21], v[234:237], v[210:213], v[18:21]
	v_mfma_f32_16x16x32_bf16 v[6:9], v[226:229], v[218:221], v[6:9]
	v_mfma_f32_16x16x32_bf16 v[2:5], v[234:237], v[218:221], v[2:5]
	v_mfma_f32_16x16x32_bf16 v[54:57], v[230:233], v[198:201], v[54:57]
	v_mfma_f32_16x16x32_bf16 v[50:53], v[238:241], v[198:201], v[50:53]
	v_mfma_f32_16x16x32_bf16 v[38:41], v[230:233], v[206:209], v[38:41]
	v_mfma_f32_16x16x32_bf16 v[34:37], v[238:241], v[206:209], v[34:37]
	v_mfma_f32_16x16x32_bf16 v[22:25], v[230:233], v[214:217], v[22:25]
	v_mfma_f32_16x16x32_bf16 v[18:21], v[238:241], v[214:217], v[18:21]
	v_mfma_f32_16x16x32_bf16 v[6:9], v[230:233], v[222:225], v[6:9]
	v_mfma_f32_16x16x32_bf16 v[2:5], v[238:241], v[222:225], v[2:5]
	s_setprio 0
	s_add_i32 s30, s30, 2
	s_add_u32 s10, s10, 0x100
	s_addc_u32 s11, s11, 0
	s_add_u32 s28, s28, 0x100
	s_addc_u32 s29, s29, 0
	s_cmp_gt_u32 s30, 13
	s_barrier
	s_cbranch_scc0 .LBB0_759
	s_cmp_lt_i32 s7, 5
	s_cselect_b64 s[10:11], -1, 0
	s_cmp_gt_i32 s7, 4
	s_cbranch_scc1 .LBB0_762
	v_mul_f32_e32 v154, 0x3d372713, v126
	v_mul_f32_e32 v155, 0x3d372713, v127
	v_mul_f32_e32 v156, 0x3d372713, v128
	v_mul_f32_e32 v157, 0x3d372713, v129
	v_mul_f32_e32 v154, v126, v154
	v_mul_f32_e32 v155, v127, v155
	v_mul_f32_e32 v156, v128, v156
	v_mul_f32_e32 v157, v129, v157
	v_fma_f32 v154, v126, v154, v126
	v_fma_f32 v155, v127, v155, v127
	v_fma_f32 v156, v128, v156, v128
	v_fma_f32 v157, v129, v157, v129
	v_mul_f32_e32 v154, 0xbfcc422a, v154
	v_mul_f32_e32 v155, 0xbfcc422a, v155
	v_mul_f32_e32 v156, 0xbfcc422a, v156
	v_mul_f32_e32 v157, 0xbfcc422a, v157
	v_mul_f32_e32 v154, 0x3fb8aa3b, v154
	v_mul_f32_e32 v155, 0x3fb8aa3b, v155
	v_mul_f32_e32 v156, 0x3fb8aa3b, v156
	v_mul_f32_e32 v157, 0x3fb8aa3b, v157
	v_exp_f32_e32 v154, v154
	v_exp_f32_e32 v155, v155
	v_exp_f32_e32 v156, v156
	v_exp_f32_e32 v157, v157
	v_add_f32_e32 v154, 1.0, v154
	v_add_f32_e32 v155, 1.0, v155
	v_add_f32_e32 v156, 1.0, v156
	v_add_f32_e32 v157, 1.0, v157
	v_rcp_f32_e32 v154, v154
	v_rcp_f32_e32 v156, v156
	v_rcp_f32_e32 v157, v157
	v_rcp_f32_e32 v155, v155
	v_pk_mul_f32 v[128:129], v[128:129], v[156:157]
	v_pk_mul_f32 v[126:127], v[126:127], v[154:155]

; #define PG8_STAGE(bufoff, gbase) do { _Pragma("unroll") for (int _i = 0; _i < 2; ++_i) \
;         __builtin_amdgcn_global_load_lds((const unsigned*)((const char*)(gbase) + voff[_i]), (LAS unsigned*)(lds + (bufoff) + ldsw + _i * 8192), 16, 0, 0); } while (0)
; #define PG8_LDA(dst, b, h) do { _Pragma("unroll") for (int m = 0; m < 4; ++m) _Pragma("unroll") for (int k = 0; k < 2; ++k) dst[m][k] = *(const LAS bf16x8*)(lds + PG8_SA(b, h) + aoff + m * 2048 + k * 1024); } while (0)
; #define PG8_LDB(dst, b, h) do { _Pragma("unroll") for (int n = 0; n < 2; ++n) _Pragma("unroll") for (int k = 0; k < 2; ++k) dst[n][k] = *(const LAS bf16x8*)(lds + PG8_SB(b, h) + boff + n * 2048 + k * 1024); } while (0)
; #define PG8_WAIT_L(n) asm volatile("s_waitcnt lgkmcnt(" #n ")" ::: "memory")
; #define PG8_BAR __builtin_amdgcn_s_barrier()
; #define PG8_SCHED __builtin_amdgcn_sched_barrier(0)
;     ...
;         for (int t = 0; t < nt; t += 2) {
;             const bool last = (t == nt - 2);
;             const char* a1 = cA + (size_t)(t + 1) * kstep;
;             const char* a2 = last ? nA : cA + (size_t)(t + 2) * kstep; const char* b2 = last ? nB : cB + (size_t)(t + 2) * kstep;
;             const char* a3 = a2 + kstep; const char* b3 = b2 + kstep;
;             PG8_LDB(B0, 0, 0); PG8_SCHED; PG8_LDA(At, 0, 0); PG8_STAGE(PG8_SA(1, 1), a1 + hstep);
;             PG8_WAIT_L(8); PG8_BAR; PG8_WAIT_L(0); PG8_MMA(0, 0, At, B0); PG8_BAR; PG8_SCHED;
;             PG8_LDB(B1, 0, 1); PG8_STAGE(PG8_SB(0, 0), b2);
;             PG8_BAR; PG8_WAIT_L(0); PG8_MMA(0, 1, At, B1); PG8_BAR;
;             PG8_LDA(At, 0, 1); PG8_STAGE(PG8_SA(0, 0), a2);
;             PG8_BAR; PG8_WAIT_L(0); PG8_MMA(1, 0, At, B0); PG8_BAR; PG8_SCHED;
.LBB0_904:
	s_add_u32 s0, s54, 0xfffc0080
	s_addc_u32 s1, s55, -1
	s_add_i32 s63, 0, 0x10000
	v_add_u32_e32 v157, s63, v154
	ds_read_b128 v[158:161], v157
	ds_read_b128 v[162:165], v157 offset:1024
	ds_read_b128 v[166:169], v157 offset:2048
	ds_read_b128 v[170:173], v157 offset:3072
	s_cmp_eq_u32 s62, 12
	s_cselect_b32 s59, s15, s1
	s_cselect_b32 s58, s31, s0
	s_cselect_b32 s57, s13, s61
	s_cselect_b32 s56, s36, s60
	v_lshl_add_u64 v[174:175], s[54:55], 0, v[150:151]
	s_add_i32 m0, s17, 0xc000
	ds_read_b128 v[194:197], v156
	ds_read_b128 v[198:201], v156 offset:1024
	ds_read_b128 v[202:205], v156 offset:2048
	ds_read_b128 v[206:209], v156 offset:3072
	ds_read_b128 v[210:213], v156 offset:4096
	ds_read_b128 v[214:217], v156 offset:5120
	ds_read_b128 v[218:221], v156 offset:6144
	ds_read_b128 v[222:225], v156 offset:7168
	global_load_lds_dwordx4 v[174:175], off
	s_add_i32 m0, s17, 0xe000
	v_lshl_add_u64 v[174:175], s[54:55], 0, v[152:153]
	global_load_lds_dwordx4 v[174:175], off
	s_waitcnt lgkmcnt(8)
	s_barrier
	s_waitcnt lgkmcnt(0)
	s_setprio 1
	v_mfma_f32_16x16x32_bf16 v[126:129], v[158:161], v[194:197], v[126:129]
	v_mfma_f32_16x16x32_bf16 v[122:125], v[166:169], v[194:197], v[122:125]
	v_mfma_f32_16x16x32_bf16 v[118:121], v[158:161], v[202:205], v[118:121]
	v_mfma_f32_16x16x32_bf16 v[114:117], v[166:169], v[202:205], v[114:117]
	v_mfma_f32_16x16x32_bf16 v[102:105], v[158:161], v[210:213], v[102:105]
	v_mfma_f32_16x16x32_bf16 v[98:101], v[166:169], v[210:213], v[98:101]
	v_mfma_f32_16x16x32_bf16 v[86:89], v[158:161], v[218:221], v[86:89]
	v_mfma_f32_16x16x32_bf16 v[82:85], v[166:169], v[218:221], v[82:85]
	v_mfma_f32_16x16x32_bf16 v[126:129], v[162:165], v[198:201], v[126:129]
	v_mfma_f32_16x16x32_bf16 v[122:125], v[170:173], v[198:201], v[122:125]
	v_mfma_f32_16x16x32_bf16 v[118:121], v[162:165], v[206:209], v[118:121]
	v_mfma_f32_16x16x32_bf16 v[114:117], v[170:173], v[206:209], v[114:117]
	v_mfma_f32_16x16x32_bf16 v[102:105], v[162:165], v[214:217], v[102:105]
	v_mfma_f32_16x16x32_bf16 v[98:101], v[170:173], v[214:217], v[98:101]
	v_mfma_f32_16x16x32_bf16 v[86:89], v[162:165], v[222:225], v[86:89]
	v_mfma_f32_16x16x32_bf16 v[82:85], v[170:173], v[222:225], v[82:85]
	s_setprio 0
	s_barrier
	s_add_i32 s0, 0, 0x14000
	s_add_i32 s1, s63, s16
	v_add_u32_e32 v157, s0, v154
	v_lshl_add_u64 v[174:175], s[56:57], 0, v[132:133]
	s_mov_b32 m0, s1
	ds_read_b128 v[226:229], v157
	ds_read_b128 v[230:233], v157 offset:1024
	ds_read_b128 v[234:237], v157 offset:2048
	ds_read_b128 v[238:241], v157 offset:3072
	global_load_lds_dwordx4 v[174:175], off
	s_add_i32 m0, s1, 0x2000
	v_lshl_add_u64 v[242:243], s[56:57], 0, v[130:131]
	global_load_lds_dwordx4 v[242:243], off
	s_barrier
	s_waitcnt lgkmcnt(0)
	s_setprio 1
	v_mfma_f32_16x16x32_bf16 v[110:113], v[226:229], v[194:197], v[110:113]
	v_mfma_f32_16x16x32_bf16 v[106:109], v[234:237], v[194:197], v[106:109]
	v_mfma_f32_16x16x32_bf16 v[94:97], v[226:229], v[202:205], v[94:97]
	v_mfma_f32_16x16x32_bf16 v[90:93], v[234:237], v[202:205], v[90:93]
	v_mfma_f32_16x16x32_bf16 v[78:81], v[226:229], v[210:213], v[78:81]
	v_mfma_f32_16x16x32_bf16 v[74:77], v[234:237], v[210:213], v[74:77]
	v_mfma_f32_16x16x32_bf16 v[70:73], v[226:229], v[218:221], v[70:73]
	v_mfma_f32_16x16x32_bf16 v[66:69], v[234:237], v[218:221], v[66:69]
	v_mfma_f32_16x16x32_bf16 v[110:113], v[230:233], v[198:201], v[110:113]
	v_mfma_f32_16x16x32_bf16 v[106:109], v[238:241], v[198:201], v[106:109]
	v_mfma_f32_16x16x32_bf16 v[94:97], v[230:233], v[206:209], v[94:97]
	v_mfma_f32_16x16x32_bf16 v[90:93], v[238:241], v[206:209], v[90:93]
	v_mfma_f32_16x16x32_bf16 v[78:81], v[230:233], v[214:217], v[78:81]
	v_mfma_f32_16x16x32_bf16 v[74:77], v[238:241], v[214:217], v[74:77]
	v_mfma_f32_16x16x32_bf16 v[70:73], v[230:233], v[222:225], v[70:73]
	v_mfma_f32_16x16x32_bf16 v[66:69], v[238:241], v[222:225], v[66:69]
	s_setprio 0
	s_mov_b32 m0, s17
	v_lshl_add_u64 v[244:245], s[58:59], 0, v[132:133]
	s_barrier
	ds_read_b128 v[194:197], v156 offset:16384
	ds_read_b128 v[198:201], v156 offset:17408
	ds_read_b128 v[202:205], v156 offset:18432
	ds_read_b128 v[206:209], v156 offset:19456
	ds_read_b128 v[210:213], v156 offset:20480
	ds_read_b128 v[214:217], v156 offset:21504
	ds_read_b128 v[218:221], v156 offset:22528
	ds_read_b128 v[222:225], v156 offset:23552
	global_load_lds_dwordx4 v[244:245], off
	s_mov_b32 m0, s18
	v_lshl_add_u64 v[246:247], s[58:59], 0, v[130:131]
	global_load_lds_dwordx4 v[246:247], off
	s_barrier
	s_waitcnt lgkmcnt(0)
	s_setprio 1
	v_mfma_f32_16x16x32_bf16 v[62:65], v[158:161], v[194:197], v[62:65]
	v_mfma_f32_16x16x32_bf16 v[58:61], v[166:169], v[194:197], v[58:61]
	v_mfma_f32_16x16x32_bf16 v[54:57], v[158:161], v[202:205], v[54:57]
	v_mfma_f32_16x16x32_bf16 v[50:53], v[166:169], v[202:205], v[50:53]
	v_mfma_f32_16x16x32_bf16 v[38:41], v[158:161], v[210:213], v[38:41]
	v_mfma_f32_16x16x32_bf16 v[34:37], v[166:169], v[210:213], v[34:37]
	v_mfma_f32_16x16x32_bf16 v[22:25], v[158:161], v[218:221], v[22:25]
	v_mfma_f32_16x16x32_bf16 v[18:21], v[166:169], v[218:221], v[18:21]
	v_mfma_f32_16x16x32_bf16 v[62:65], v[162:165], v[198:201], v[62:65]
	v_mfma_f32_16x16x32_bf16 v[58:61], v[170:173], v[198:201], v[58:61]
	v_mfma_f32_16x16x32_bf16 v[54:57], v[162:165], v[206:209], v[54:57]
	v_mfma_f32_16x16x32_bf16 v[50:53], v[170:173], v[206:209], v[50:53]
	v_mfma_f32_16x16x32_bf16 v[38:41], v[162:165], v[214:217], v[38:41]
	v_mfma_f32_16x16x32_bf16 v[34:37], v[170:173], v[214:217], v[34:37]
	v_mfma_f32_16x16x32_bf16 v[22:25], v[162:165], v[222:225], v[22:25]
	v_mfma_f32_16x16x32_bf16 v[18:21], v[170:173], v[222:225], v[18:21]
	s_setprio 0
	s_barrier
; #define PG8_STAGE(bufoff, gbase) do { _Pragma("unroll") for (int _i = 0; _i < 2; ++_i) \
;         __builtin_amdgcn_global_load_lds((const unsigned*)((const char*)(gbase) + voff[_i]), (LAS unsigned*)(lds + (bufoff) + ldsw + _i * 8192), 16, 0, 0); } while (0)
; #define PG8_LDA(dst, b, h) do { _Pragma("unroll") for (int m = 0; m < 4; ++m) _Pragma("unroll") for (int k = 0; k < 2; ++k) dst[m][k] = *(const LAS bf16x8*)(lds + PG8_SA(b, h) + aoff + m * 2048 + k * 1024); } while (0)
; #define PG8_LDB(dst, b, h) do { _Pragma("unroll") for (int n = 0; n < 2; ++n) _Pragma("unroll") for (int k = 0; k < 2; ++k) dst[n][k] = *(const LAS bf16x8*)(lds + PG8_SB(b, h) + boff + n * 2048 + k * 1024); } while (0)
; #define PG8_WAIT_V(n) asm volatile("s_waitcnt vmcnt(" #n ")" ::: "memory")
; #define PG8_WAIT_L(n) asm volatile("s_waitcnt lgkmcnt(" #n ")" ::: "memory")
; #define PG8_BAR __builtin_amdgcn_s_barrier()
; #define PG8_SCHED __builtin_amdgcn_sched_barrier(0)
;     ...
;             PG8_STAGE(PG8_SB(0, 1), b2 + hstep);
;             PG8_WAIT_V(6); PG8_BAR; PG8_MMA(1, 1, At, B1); PG8_BAR;
;             PG8_LDB(B0, 1, 0); PG8_SCHED; PG8_LDA(At, 1, 0); PG8_STAGE(PG8_SA(0, 1), a2 + hstep);
;             PG8_WAIT_L(8); PG8_BAR; PG8_WAIT_L(0); PG8_MMA(0, 0, At, B0); PG8_BAR; PG8_SCHED;
;             PG8_LDB(B1, 1, 1); PG8_STAGE(PG8_SB(1, 0), b3);
;             PG8_BAR; PG8_WAIT_L(0); PG8_MMA(0, 1, At, B1); PG8_BAR;
;             PG8_LDA(At, 1, 1); PG8_STAGE(PG8_SA(1, 0), a3);
	s_add_u32 s64, s56, 0x40000
	s_addc_u32 s65, s57, 0
	s_add_i32 s0, s0, s16
	s_mov_b32 m0, s0
	v_lshl_add_u64 v[158:159], s[64:65], 0, v[132:133]
	global_load_lds_dwordx4 v[158:159], off
	s_add_i32 m0, s0, 0x2000
	v_lshl_add_u64 v[158:159], s[64:65], 0, v[130:131]
	global_load_lds_dwordx4 v[158:159], off
	s_waitcnt vmcnt(6)
	s_barrier
	s_setprio 1
	v_mfma_f32_16x16x32_bf16 v[46:49], v[226:229], v[194:197], v[46:49]
	v_mfma_f32_16x16x32_bf16 v[42:45], v[234:237], v[194:197], v[42:45]
	v_mfma_f32_16x16x32_bf16 v[30:33], v[226:229], v[202:205], v[30:33]
	v_mfma_f32_16x16x32_bf16 v[26:29], v[234:237], v[202:205], v[26:29]
	v_mfma_f32_16x16x32_bf16 v[14:17], v[226:229], v[210:213], v[14:17]
	v_mfma_f32_16x16x32_bf16 v[10:13], v[234:237], v[210:213], v[10:13]
	v_mfma_f32_16x16x32_bf16 v[6:9], v[226:229], v[218:221], v[6:9]
	v_mfma_f32_16x16x32_bf16 v[2:5], v[234:237], v[218:221], v[2:5]
	v_mfma_f32_16x16x32_bf16 v[46:49], v[230:233], v[198:201], v[46:49]
	v_mfma_f32_16x16x32_bf16 v[42:45], v[238:241], v[198:201], v[42:45]
	v_mfma_f32_16x16x32_bf16 v[30:33], v[230:233], v[206:209], v[30:33]
	v_mfma_f32_16x16x32_bf16 v[26:29], v[238:241], v[206:209], v[26:29]
	v_mfma_f32_16x16x32_bf16 v[14:17], v[230:233], v[214:217], v[14:17]
	v_mfma_f32_16x16x32_bf16 v[10:13], v[238:241], v[214:217], v[10:13]
	v_mfma_f32_16x16x32_bf16 v[6:9], v[230:233], v[222:225], v[6:9]
	v_mfma_f32_16x16x32_bf16 v[2:5], v[238:241], v[222:225], v[2:5]
	s_setprio 0
	s_add_i32 s0, 0, 0x18000
	v_add_u32_e32 v157, s0, v154
	s_barrier
	ds_read_b128 v[158:161], v157
	ds_read_b128 v[162:165], v157 offset:1024
	ds_read_b128 v[166:169], v157 offset:2048
	ds_read_b128 v[170:173], v157 offset:3072
	s_add_u32 s58, s58, 0x40000
	s_addc_u32 s59, s59, 0
	s_mov_b32 m0, s19
	v_lshl_add_u64 v[226:227], s[58:59], 0, v[132:133]
	ds_read_b128 v[194:197], v156 offset:32768
	ds_read_b128 v[198:201], v156 offset:33792
	ds_read_b128 v[202:205], v156 offset:34816
	ds_read_b128 v[206:209], v156 offset:35840
	ds_read_b128 v[210:213], v156 offset:36864
	ds_read_b128 v[214:217], v156 offset:37888
	ds_read_b128 v[218:221], v156 offset:38912
	ds_read_b128 v[222:225], v156 offset:39936
	global_load_lds_dwordx4 v[226:227], off
	s_mov_b32 m0, s20
	v_lshl_add_u64 v[226:227], s[58:59], 0, v[130:131]
	global_load_lds_dwordx4 v[226:227], off
	s_waitcnt lgkmcnt(8)
	s_barrier
	s_waitcnt lgkmcnt(0)
	s_setprio 1
	v_mfma_f32_16x16x32_bf16 v[126:129], v[158:161], v[194:197], v[126:129]
	v_mfma_f32_16x16x32_bf16 v[122:125], v[166:169], v[194:197], v[122:125]
	v_mfma_f32_16x16x32_bf16 v[118:121], v[158:161], v[202:205], v[118:121]
	v_mfma_f32_16x16x32_bf16 v[114:117], v[166:169], v[202:205], v[114:117]
	v_mfma_f32_16x16x32_bf16 v[102:105], v[158:161], v[210:213], v[102:105]
	v_mfma_f32_16x16x32_bf16 v[98:101], v[166:169], v[210:213], v[98:101]
	v_mfma_f32_16x16x32_bf16 v[86:89], v[158:161], v[218:221], v[86:89]
	v_mfma_f32_16x16x32_bf16 v[82:85], v[166:169], v[218:221], v[82:85]
	v_mfma_f32_16x16x32_bf16 v[126:129], v[162:165], v[198:201], v[126:129]
	v_mfma_f32_16x16x32_bf16 v[122:125], v[170:173], v[198:201], v[122:125]
	v_mfma_f32_16x16x32_bf16 v[118:121], v[162:165], v[206:209], v[118:121]
	v_mfma_f32_16x16x32_bf16 v[114:117], v[170:173], v[206:209], v[114:117]
	v_mfma_f32_16x16x32_bf16 v[102:105], v[162:165], v[214:217], v[102:105]
	v_mfma_f32_16x16x32_bf16 v[98:101], v[170:173], v[214:217], v[98:101]
	v_mfma_f32_16x16x32_bf16 v[86:89], v[162:165], v[222:225], v[86:89]
	v_mfma_f32_16x16x32_bf16 v[82:85], v[170:173], v[222:225], v[82:85]
	s_setprio 0
	s_barrier
	s_add_i32 s1, 0, 0x1c000
	s_add_i32 s0, s0, s16
	v_add_u32_e32 v157, s1, v154
	v_lshl_add_u64 v[174:175], v[174:175], 0, s[88:89]
	s_mov_b32 m0, s0
	ds_read_b128 v[226:229], v157
	ds_read_b128 v[230:233], v157 offset:1024
	ds_read_b128 v[234:237], v157 offset:2048
	ds_read_b128 v[238:241], v157 offset:3072
	global_load_lds_dwordx4 v[174:175], off
	s_add_i32 m0, s0, 0x2000
	v_lshl_add_u64 v[174:175], v[242:243], 0, s[88:89]
	global_load_lds_dwordx4 v[174:175], off
	s_barrier
	s_waitcnt lgkmcnt(0)
	s_setprio 1
	v_mfma_f32_16x16x32_bf16 v[110:113], v[226:229], v[194:197], v[110:113]
	v_mfma_f32_16x16x32_bf16 v[106:109], v[234:237], v[194:197], v[106:109]
	v_mfma_f32_16x16x32_bf16 v[94:97], v[226:229], v[202:205], v[94:97]
	v_mfma_f32_16x16x32_bf16 v[90:93], v[234:237], v[202:205], v[90:93]
	v_mfma_f32_16x16x32_bf16 v[78:81], v[226:229], v[210:213], v[78:81]
	v_mfma_f32_16x16x32_bf16 v[74:77], v[234:237], v[210:213], v[74:77]
	v_mfma_f32_16x16x32_bf16 v[70:73], v[226:229], v[218:221], v[70:73]
	v_mfma_f32_16x16x32_bf16 v[66:69], v[234:237], v[218:221], v[66:69]
	v_mfma_f32_16x16x32_bf16 v[110:113], v[230:233], v[198:201], v[110:113]
	v_mfma_f32_16x16x32_bf16 v[106:109], v[238:241], v[198:201], v[106:109]
	v_mfma_f32_16x16x32_bf16 v[94:97], v[230:233], v[206:209], v[94:97]
	v_mfma_f32_16x16x32_bf16 v[90:93], v[238:241], v[206:209], v[90:93]
	v_mfma_f32_16x16x32_bf16 v[78:81], v[230:233], v[214:217], v[78:81]
	v_mfma_f32_16x16x32_bf16 v[74:77], v[238:241], v[214:217], v[74:77]
	v_mfma_f32_16x16x32_bf16 v[70:73], v[230:233], v[222:225], v[70:73]
	v_mfma_f32_16x16x32_bf16 v[66:69], v[238:241], v[222:225], v[66:69]
	s_setprio 0
	s_mov_b32 m0, s22
	v_lshl_add_u64 v[174:175], v[244:245], 0, s[88:89]
	s_barrier
	ds_read_b128 v[194:197], v156 offset:49152
	ds_read_b128 v[198:201], v156 offset:50176
	ds_read_b128 v[202:205], v156 offset:51200
	ds_read_b128 v[206:209], v156 offset:52224
	ds_read_b128 v[210:213], v156 offset:53248
	ds_read_b128 v[214:217], v156 offset:54272
	ds_read_b128 v[218:221], v156 offset:55296
	ds_read_b128 v[222:225], v156 offset:56320
	global_load_lds_dwordx4 v[174:175], off
	s_mov_b32 m0, s23
	v_lshl_add_u64 v[174:175], v[246:247], 0, s[88:89]
	global_load_lds_dwordx4 v[174:175], off
	s_barrier
; #define PG8_STAGE(bufoff, gbase) do { _Pragma("unroll") for (int _i = 0; _i < 2; ++_i) \
;         __builtin_amdgcn_global_load_lds((const unsigned*)((const char*)(gbase) + voff[_i]), (LAS unsigned*)(lds + (bufoff) + ldsw + _i * 8192), 16, 0, 0); } while (0)
; #define PG8_WAIT_V(n) asm volatile("s_waitcnt vmcnt(" #n ")" ::: "memory")
; #define PG8_WAIT_L(n) asm volatile("s_waitcnt lgkmcnt(" #n ")" ::: "memory")
; #define PG8_BAR __builtin_amdgcn_s_barrier()
; #define PG8_SCHED __builtin_amdgcn_sched_barrier(0)
;     ...
;             PG8_BAR; PG8_WAIT_L(0); PG8_MMA(1, 0, At, B0); PG8_BAR; PG8_SCHED;
;             PG8_STAGE(PG8_SB(1, 1), b3 + hstep);
;             PG8_WAIT_V(6); PG8_BAR; PG8_MMA(1, 1, At, B1); PG8_BAR;
	s_waitcnt lgkmcnt(0)
	s_setprio 1
	v_mfma_f32_16x16x32_bf16 v[62:65], v[158:161], v[194:197], v[62:65]
	v_mfma_f32_16x16x32_bf16 v[58:61], v[166:169], v[194:197], v[58:61]
	v_mfma_f32_16x16x32_bf16 v[54:57], v[158:161], v[202:205], v[54:57]
	v_mfma_f32_16x16x32_bf16 v[50:53], v[166:169], v[202:205], v[50:53]
	v_mfma_f32_16x16x32_bf16 v[38:41], v[158:161], v[210:213], v[38:41]
	v_mfma_f32_16x16x32_bf16 v[34:37], v[166:169], v[210:213], v[34:37]
	v_mfma_f32_16x16x32_bf16 v[22:25], v[158:161], v[218:221], v[22:25]
	v_mfma_f32_16x16x32_bf16 v[18:21], v[166:169], v[218:221], v[18:21]
	v_mfma_f32_16x16x32_bf16 v[62:65], v[162:165], v[198:201], v[62:65]
	v_mfma_f32_16x16x32_bf16 v[58:61], v[170:173], v[198:201], v[58:61]
	v_mfma_f32_16x16x32_bf16 v[54:57], v[162:165], v[206:209], v[54:57]
	v_mfma_f32_16x16x32_bf16 v[50:53], v[170:173], v[206:209], v[50:53]
	v_mfma_f32_16x16x32_bf16 v[38:41], v[162:165], v[214:217], v[38:41]
	v_mfma_f32_16x16x32_bf16 v[34:37], v[170:173], v[214:217], v[34:37]
	v_mfma_f32_16x16x32_bf16 v[22:25], v[162:165], v[222:225], v[22:25]
	v_mfma_f32_16x16x32_bf16 v[18:21], v[170:173], v[222:225], v[18:21]
	s_setprio 0
	s_barrier
	s_add_u32 s56, s56, 0x40080
	s_addc_u32 s57, s57, 0
	s_add_i32 s0, s1, s16
	s_mov_b32 m0, s0
	v_lshl_add_u64 v[158:159], s[56:57], 0, v[132:133]
	global_load_lds_dwordx4 v[158:159], off
	s_add_i32 m0, s0, 0x2000
	v_lshl_add_u64 v[158:159], s[56:57], 0, v[130:131]
	global_load_lds_dwordx4 v[158:159], off
	s_waitcnt vmcnt(6)
	s_barrier
	s_setprio 1
	v_mfma_f32_16x16x32_bf16 v[46:49], v[226:229], v[194:197], v[46:49]
	v_mfma_f32_16x16x32_bf16 v[42:45], v[234:237], v[194:197], v[42:45]
	v_mfma_f32_16x16x32_bf16 v[30:33], v[226:229], v[202:205], v[30:33]
	v_mfma_f32_16x16x32_bf16 v[26:29], v[234:237], v[202:205], v[26:29]
	v_mfma_f32_16x16x32_bf16 v[14:17], v[226:229], v[210:213], v[14:17]
	v_mfma_f32_16x16x32_bf16 v[10:13], v[234:237], v[210:213], v[10:13]
	v_mfma_f32_16x16x32_bf16 v[6:9], v[226:229], v[218:221], v[6:9]
	v_mfma_f32_16x16x32_bf16 v[2:5], v[234:237], v[218:221], v[2:5]
	v_mfma_f32_16x16x32_bf16 v[46:49], v[230:233], v[198:201], v[46:49]
	v_mfma_f32_16x16x32_bf16 v[42:45], v[238:241], v[198:201], v[42:45]
	v_mfma_f32_16x16x32_bf16 v[30:33], v[230:233], v[206:209], v[30:33]
	v_mfma_f32_16x16x32_bf16 v[26:29], v[238:241], v[206:209], v[26:29]
	v_mfma_f32_16x16x32_bf16 v[14:17], v[230:233], v[214:217], v[14:17]
	v_mfma_f32_16x16x32_bf16 v[10:13], v[238:241], v[214:217], v[10:13]
	v_mfma_f32_16x16x32_bf16 v[6:9], v[230:233], v[222:225], v[6:9]
	v_mfma_f32_16x16x32_bf16 v[2:5], v[238:241], v[222:225], v[2:5]
	s_setprio 0
	s_add_i32 s62, s62, 2
	s_add_u32 s54, s54, 0x100
	s_addc_u32 s55, s55, 0
	s_add_u32 s60, s60, 0x100
	s_addc_u32 s61, s61, 0
	s_cmp_gt_u32 s62, 13
	s_barrier
	s_cbranch_scc0 .LBB0_904
; #define PG8_WAIT_V(n) asm volatile("s_waitcnt vmcnt(" #n ")" ::: "memory")
; #define PG8_BAR __builtin_amdgcn_s_barrier()
;     ...
;         cur = nxt; cA = nA; cB = nB; ++ui;
;     }
;     PG8_WAIT_V(0);
;     if (wr == 0) PG8_BAR;
;     __device__ __forceinline__ void operator()(Acc& acc, int pm, int pn, int wr, int wc, int fr, int fq) const {
;         const bool isg = mode == 0 ? (pn < 5) : (mode == 1);
;         bf16_t* base = isg ? gbuf : upre;
;         const int cb = ((mode == 0 && !isg) ? pn * 256 - DRNN : pn * 256) + wc * 32 + fq * 4;
; #pragma unroll
;         for (int ai = 0; ai < 2; ++ai)
; #pragma unroll
;             for (int m = 0; m < 4; ++m) {
;                 const size_t ro = (size_t)(pm * 256 + ai * 128 + wr * 64 + m * 16 + fr) * DRNN + cb;
; #pragma unroll
;                 for (int bj = 0; bj < 2; ++bj)
; #pragma unroll
;                     for (int n = 0; n < 2; ++n) {
;                         f32x4 v = acc[ai][bj][m][n];
;                         if (isg) { v[0] = gelu_tanh(v[0]); v[1] = gelu_tanh(v[1]); v[2] = gelu_tanh(v[2]); v[3] = gelu_tanh(v[3]); }
;                         u32x2 o = {pack2(v[0], v[1]), pack2(v[2], v[3])};
;                         *reinterpret_cast<u32x2*>(base + ro + bj * 128 + n * 16) = o;
;                     }
	v_lshl_or_b32 v158, s29, 8, v155
	v_ashrrev_i32_e32 v159, 31, v158
	v_lshl_add_u32 v157, s30, 8, v1
	v_lshl_add_u64 v[158:159], v[158:159], 1, s[48:49]
	v_mad_i64_i32 v[160:161], s[30:31], v157, s73, v[158:159]
	v_cvt_pk_bf16_f32 v106, v106, v107
	v_cvt_pk_bf16_f32 v107, v108, v109
	global_store_dwordx2 v[160:161], v[106:107], off offset:288
	v_or_b32_e32 v106, 16, v157
	v_mad_i64_i32 v[106:107], s[30:31], v106, s73, v[158:159]
	v_cvt_pk_bf16_f32 v90, v90, v91
	v_cvt_pk_bf16_f32 v91, v92, v93
	global_store_dwordx2 v[106:107], v[90:91], off offset:288
	v_or_b32_e32 v90, 32, v157
	v_mad_i64_i32 v[90:91], s[30:31], v90, s73, v[158:159]
	v_cvt_pk_bf16_f32 v74, v74, v75
	v_cvt_pk_bf16_f32 v75, v76, v77
	global_store_dwordx2 v[90:91], v[74:75], off offset:288
	v_or_b32_e32 v74, 48, v157
	v_mad_i64_i32 v[74:75], s[30:31], v74, s73, v[158:159]
	v_cvt_pk_bf16_f32 v66, v66, v67
	v_cvt_pk_bf16_f32 v67, v68, v69
	global_store_dwordx2 v[74:75], v[66:67], off offset:288
	v_add_u32_e32 v66, 0x80, v157
	v_mad_i64_i32 v[66:67], s[30:31], v66, s73, v[158:159]
	v_cvt_pk_bf16_f32 v42, v42, v43
	v_cvt_pk_bf16_f32 v43, v44, v45
	global_store_dwordx2 v[66:67], v[42:43], off offset:288
	v_add_u32_e32 v42, 0x90, v157
	v_mad_i64_i32 v[42:43], s[30:31], v42, s73, v[158:159]
	v_cvt_pk_bf16_f32 v26, v26, v27
	v_cvt_pk_bf16_f32 v27, v28, v29
	global_store_dwordx2 v[42:43], v[26:27], off offset:288
	v_add_u32_e32 v26, 0xa0, v157
	v_mad_i64_i32 v[26:27], s[30:31], v26, s73, v[158:159]
	v_cvt_pk_bf16_f32 v10, v10, v11
	v_cvt_pk_bf16_f32 v11, v12, v13
	global_store_dwordx2 v[26:27], v[10:11], off offset:288
	v_add_u32_e32 v10, 0xb0, v157
	v_cvt_pk_bf16_f32 v108, v118, v119
	v_cvt_pk_bf16_f32 v109, v120, v121
	v_cvt_pk_bf16_f32 v92, v102, v103
	v_cvt_pk_bf16_f32 v93, v104, v105
	v_cvt_pk_bf16_f32 v76, v86, v87
	v_cvt_pk_bf16_f32 v77, v88, v89
	v_cvt_pk_bf16_f32 v44, v54, v55
	v_cvt_pk_bf16_f32 v45, v56, v57
	v_cvt_pk_bf16_f32 v28, v38, v39
	v_cvt_pk_bf16_f32 v29, v40, v41
	v_mad_i64_i32 v[10:11], s[30:31], v10, s73, v[158:159]
	v_cvt_pk_bf16_f32 v12, v22, v23
	v_cvt_pk_bf16_f32 v13, v24, v25
	v_cvt_pk_bf16_f32 v126, v126, v127
	v_cvt_pk_bf16_f32 v127, v128, v129
	v_cvt_pk_bf16_f32 v122, v122, v123
	v_cvt_pk_bf16_f32 v123, v124, v125
	v_cvt_pk_bf16_f32 v110, v110, v111
	v_cvt_pk_bf16_f32 v111, v112, v113
	global_store_dwordx2 v[106:107], v[108:109], off
	v_cvt_pk_bf16_f32 v108, v114, v115
	v_cvt_pk_bf16_f32 v109, v116, v117
	v_cvt_pk_bf16_f32 v94, v94, v95
	v_cvt_pk_bf16_f32 v95, v96, v97
	global_store_dwordx2 v[90:91], v[92:93], off
	v_cvt_pk_bf16_f32 v92, v98, v99
	v_cvt_pk_bf16_f32 v93, v100, v101
	v_cvt_pk_bf16_f32 v78, v78, v79
	v_cvt_pk_bf16_f32 v79, v80, v81
	global_store_dwordx2 v[74:75], v[76:77], off
	v_cvt_pk_bf16_f32 v76, v82, v83
	v_cvt_pk_bf16_f32 v77, v84, v85
	v_cvt_pk_bf16_f32 v70, v70, v71
	v_cvt_pk_bf16_f32 v71, v72, v73
	v_cvt_pk_bf16_f32 v62, v62, v63
	v_cvt_pk_bf16_f32 v63, v64, v65
	v_cvt_pk_bf16_f32 v58, v58, v59
	v_cvt_pk_bf16_f32 v59, v60, v61
	v_cvt_pk_bf16_f32 v46, v46, v47
	v_cvt_pk_bf16_f32 v47, v48, v49
	global_store_dwordx2 v[42:43], v[44:45], off
	v_cvt_pk_bf16_f32 v44, v50, v51
	v_cvt_pk_bf16_f32 v45, v52, v53
	v_cvt_pk_bf16_f32 v30, v30, v31
	v_cvt_pk_bf16_f32 v31, v32, v33
	global_store_dwordx2 v[26:27], v[28:29], off
	v_cvt_pk_bf16_f32 v28, v34, v35
	v_cvt_pk_bf16_f32 v29, v36, v37
	v_cvt_pk_bf16_f32 v14, v14, v15
	v_cvt_pk_bf16_f32 v15, v16, v17
	global_store_dwordx2 v[10:11], v[12:13], off
	v_cvt_pk_bf16_f32 v12, v18, v19
	v_cvt_pk_bf16_f32 v13, v20, v21
	v_cvt_pk_bf16_f32 v6, v6, v7
	v_cvt_pk_bf16_f32 v7, v8, v9
	v_cvt_pk_bf16_f32 v2, v2, v3
	v_cvt_pk_bf16_f32 v3, v4, v5
	s_and_b64 vcc, exec, s[44:45]
	s_mov_b32 s29, s12
	s_mov_b32 s30, s14
	s_mov_b64 s[56:57], s[46:47]
	s_mov_b64 s[54:55], s[40:41]
	global_store_dwordx2 v[160:161], v[126:127], off
	global_store_dwordx2 v[160:161], v[122:123], off offset:32
	global_store_dwordx2 v[160:161], v[110:111], off offset:256
	global_store_dwordx2 v[106:107], v[108:109], off offset:32
	global_store_dwordx2 v[106:107], v[94:95], off offset:256
	global_store_dwordx2 v[90:91], v[92:93], off offset:32
	global_store_dwordx2 v[90:91], v[78:79], off offset:256
	global_store_dwordx2 v[74:75], v[76:77], off offset:32
	global_store_dwordx2 v[74:75], v[70:71], off offset:256
	global_store_dwordx2 v[66:67], v[62:63], off
	global_store_dwordx2 v[66:67], v[58:59], off offset:32
	global_store_dwordx2 v[66:67], v[46:47], off offset:256
	global_store_dwordx2 v[42:43], v[44:45], off offset:32
	global_store_dwordx2 v[42:43], v[30:31], off offset:256
	global_store_dwordx2 v[26:27], v[28:29], off offset:32
	global_store_dwordx2 v[26:27], v[14:15], off offset:256
	global_store_dwordx2 v[10:11], v[12:13], off offset:32
	global_store_dwordx2 v[10:11], v[6:7], off offset:256
	global_store_dwordx2 v[10:11], v[2:3], off offset:288
	s_cbranch_vccz .LBB0_901
	s_waitcnt vmcnt(0)
	s_cmpk_gt_u32 s4, 0xff
	s_cbranch_scc1 .LBB0_908
	s_barrier

; #define PG8_STAGE(bufoff, gbase) do { _Pragma("unroll") for (int _i = 0; _i < 2; ++_i) \
;         __builtin_amdgcn_global_load_lds((const unsigned*)((const char*)(gbase) + voff[_i]), (LAS unsigned*)(lds + (bufoff) + ldsw + _i * 8192), 16, 0, 0); } while (0)
; #define PG8_LDA(dst, b, h) do { _Pragma("unroll") for (int m = 0; m < 4; ++m) _Pragma("unroll") for (int k = 0; k < 2; ++k) dst[m][k] = *(const LAS bf16x8*)(lds + PG8_SA(b, h) + aoff + m * 2048 + k * 1024); } while (0)
; #define PG8_LDB(dst, b, h) do { _Pragma("unroll") for (int n = 0; n < 2; ++n) _Pragma("unroll") for (int k = 0; k < 2; ++k) dst[n][k] = *(const LAS bf16x8*)(lds + PG8_SB(b, h) + boff + n * 2048 + k * 1024); } while (0)
; #define PG8_WAIT_L(n) asm volatile("s_waitcnt lgkmcnt(" #n ")" ::: "memory")
; #define PG8_BAR __builtin_amdgcn_s_barrier()
; #define PG8_SCHED __builtin_amdgcn_sched_barrier(0)
;     ...
;         for (int t = 0; t < nt; t += 2) {
;             const bool last = (t == nt - 2);
;             const char* a1 = cA + (size_t)(t + 1) * kstep;
;             const char* a2 = last ? nA : cA + (size_t)(t + 2) * kstep; const char* b2 = last ? nB : cB + (size_t)(t + 2) * kstep;
;             const char* a3 = a2 + kstep; const char* b3 = b2 + kstep;
;             PG8_LDB(B0, 0, 0); PG8_SCHED; PG8_LDA(At, 0, 0); PG8_STAGE(PG8_SA(1, 1), a1 + hstep);
;             PG8_WAIT_L(8); PG8_BAR; PG8_WAIT_L(0); PG8_MMA(0, 0, At, B0); PG8_BAR; PG8_SCHED;
;             PG8_LDB(B1, 0, 1); PG8_STAGE(PG8_SB(0, 0), b2);
;             PG8_BAR; PG8_WAIT_L(0); PG8_MMA(0, 1, At, B1); PG8_BAR;
;             PG8_LDA(At, 0, 1); PG8_STAGE(PG8_SA(0, 0), a2);
;             PG8_BAR; PG8_WAIT_L(0); PG8_MMA(1, 0, At, B0); PG8_BAR; PG8_SCHED;
.LBB0_1051:
	s_add_u32 s0, s10, 0xfffc0080
	s_addc_u32 s1, s11, -1
	s_add_i32 s31, 0, 0x10000
	v_add_u32_e32 v161, s31, v158
	ds_read_b128 v[154:157], v161
	ds_read_b128 v[162:165], v161 offset:1024
	ds_read_b128 v[166:169], v161 offset:2048
	ds_read_b128 v[170:173], v161 offset:3072
	s_cmp_eq_u32 s30, 12
	s_cselect_b32 s15, s18, s1
	s_cselect_b32 s14, s19, s0
	s_cselect_b32 s13, s22, s29
	s_cselect_b32 s12, s23, s28
	v_lshl_add_u64 v[174:175], s[10:11], 0, v[150:151]
	s_add_i32 m0, s17, 0xc000
	ds_read_b128 v[194:197], v160
	ds_read_b128 v[198:201], v160 offset:1024
	ds_read_b128 v[202:205], v160 offset:2048
	ds_read_b128 v[206:209], v160 offset:3072
	ds_read_b128 v[210:213], v160 offset:4096
	ds_read_b128 v[214:217], v160 offset:5120
	ds_read_b128 v[218:221], v160 offset:6144
	ds_read_b128 v[222:225], v160 offset:7168
	global_load_lds_dwordx4 v[174:175], off
	s_add_i32 m0, s17, 0xe000
	v_lshl_add_u64 v[174:175], s[10:11], 0, v[152:153]
	global_load_lds_dwordx4 v[174:175], off
	s_waitcnt lgkmcnt(8)
	s_barrier
	s_waitcnt lgkmcnt(0)
	s_setprio 1
	v_mfma_f32_16x16x32_bf16 v[126:129], v[154:157], v[194:197], v[126:129]
	v_mfma_f32_16x16x32_bf16 v[122:125], v[166:169], v[194:197], v[122:125]
	v_mfma_f32_16x16x32_bf16 v[110:113], v[154:157], v[202:205], v[110:113]
	v_mfma_f32_16x16x32_bf16 v[106:109], v[166:169], v[202:205], v[106:109]
	v_mfma_f32_16x16x32_bf16 v[94:97], v[154:157], v[210:213], v[94:97]
	v_mfma_f32_16x16x32_bf16 v[90:93], v[166:169], v[210:213], v[90:93]
	v_mfma_f32_16x16x32_bf16 v[78:81], v[154:157], v[218:221], v[78:81]
	v_mfma_f32_16x16x32_bf16 v[74:77], v[166:169], v[218:221], v[74:77]
	v_mfma_f32_16x16x32_bf16 v[126:129], v[162:165], v[198:201], v[126:129]
	v_mfma_f32_16x16x32_bf16 v[122:125], v[170:173], v[198:201], v[122:125]
	v_mfma_f32_16x16x32_bf16 v[110:113], v[162:165], v[206:209], v[110:113]
	v_mfma_f32_16x16x32_bf16 v[106:109], v[170:173], v[206:209], v[106:109]
	v_mfma_f32_16x16x32_bf16 v[94:97], v[162:165], v[214:217], v[94:97]
	v_mfma_f32_16x16x32_bf16 v[90:93], v[170:173], v[214:217], v[90:93]
	v_mfma_f32_16x16x32_bf16 v[78:81], v[162:165], v[222:225], v[78:81]
	v_mfma_f32_16x16x32_bf16 v[74:77], v[170:173], v[222:225], v[74:77]
	s_setprio 0
	s_barrier
	s_add_i32 s0, 0, 0x14000
	s_add_i32 s1, s31, s16
	v_add_u32_e32 v161, s0, v158
	v_lshl_add_u64 v[174:175], s[12:13], 0, v[132:133]
	s_mov_b32 m0, s1
	ds_read_b128 v[226:229], v161
	ds_read_b128 v[230:233], v161 offset:1024
	ds_read_b128 v[234:237], v161 offset:2048
	ds_read_b128 v[238:241], v161 offset:3072
	global_load_lds_dwordx4 v[174:175], off
	s_add_i32 m0, s1, 0x2000
	v_lshl_add_u64 v[242:243], s[12:13], 0, v[130:131]
	global_load_lds_dwordx4 v[242:243], off
	s_barrier
	s_waitcnt lgkmcnt(0)
	s_setprio 1
	v_mfma_f32_16x16x32_bf16 v[118:121], v[226:229], v[194:197], v[118:121]
	v_mfma_f32_16x16x32_bf16 v[114:117], v[234:237], v[194:197], v[114:117]
	v_mfma_f32_16x16x32_bf16 v[102:105], v[226:229], v[202:205], v[102:105]
	v_mfma_f32_16x16x32_bf16 v[98:101], v[234:237], v[202:205], v[98:101]
	v_mfma_f32_16x16x32_bf16 v[86:89], v[226:229], v[210:213], v[86:89]
	v_mfma_f32_16x16x32_bf16 v[82:85], v[234:237], v[210:213], v[82:85]
	v_mfma_f32_16x16x32_bf16 v[70:73], v[226:229], v[218:221], v[70:73]
	v_mfma_f32_16x16x32_bf16 v[66:69], v[234:237], v[218:221], v[66:69]
	v_mfma_f32_16x16x32_bf16 v[118:121], v[230:233], v[198:201], v[118:121]
	v_mfma_f32_16x16x32_bf16 v[114:117], v[238:241], v[198:201], v[114:117]
	v_mfma_f32_16x16x32_bf16 v[102:105], v[230:233], v[206:209], v[102:105]
	v_mfma_f32_16x16x32_bf16 v[98:101], v[238:241], v[206:209], v[98:101]
	v_mfma_f32_16x16x32_bf16 v[86:89], v[230:233], v[214:217], v[86:89]
	v_mfma_f32_16x16x32_bf16 v[82:85], v[238:241], v[214:217], v[82:85]
	v_mfma_f32_16x16x32_bf16 v[70:73], v[230:233], v[222:225], v[70:73]
	v_mfma_f32_16x16x32_bf16 v[66:69], v[238:241], v[222:225], v[66:69]
	s_setprio 0
	s_mov_b32 m0, s17
	v_lshl_add_u64 v[244:245], s[14:15], 0, v[132:133]
	s_barrier
	ds_read_b128 v[194:197], v160 offset:16384
	ds_read_b128 v[198:201], v160 offset:17408
	ds_read_b128 v[202:205], v160 offset:18432
	ds_read_b128 v[206:209], v160 offset:19456
	ds_read_b128 v[210:213], v160 offset:20480
	ds_read_b128 v[214:217], v160 offset:21504
	ds_read_b128 v[218:221], v160 offset:22528
	ds_read_b128 v[222:225], v160 offset:23552
	global_load_lds_dwordx4 v[244:245], off
	s_mov_b32 m0, s40
	v_lshl_add_u64 v[246:247], s[14:15], 0, v[130:131]
	global_load_lds_dwordx4 v[246:247], off
	s_barrier
	s_waitcnt lgkmcnt(0)
	s_setprio 1
	v_mfma_f32_16x16x32_bf16 v[62:65], v[154:157], v[194:197], v[62:65]
	v_mfma_f32_16x16x32_bf16 v[58:61], v[166:169], v[194:197], v[58:61]
	v_mfma_f32_16x16x32_bf16 v[46:49], v[154:157], v[202:205], v[46:49]
	v_mfma_f32_16x16x32_bf16 v[42:45], v[166:169], v[202:205], v[42:45]
	v_mfma_f32_16x16x32_bf16 v[30:33], v[154:157], v[210:213], v[30:33]
	v_mfma_f32_16x16x32_bf16 v[26:29], v[166:169], v[210:213], v[26:29]
	v_mfma_f32_16x16x32_bf16 v[14:17], v[154:157], v[218:221], v[14:17]
	v_mfma_f32_16x16x32_bf16 v[10:13], v[166:169], v[218:221], v[10:13]
	v_mfma_f32_16x16x32_bf16 v[62:65], v[162:165], v[198:201], v[62:65]
	v_mfma_f32_16x16x32_bf16 v[58:61], v[170:173], v[198:201], v[58:61]
	v_mfma_f32_16x16x32_bf16 v[46:49], v[162:165], v[206:209], v[46:49]
	v_mfma_f32_16x16x32_bf16 v[42:45], v[170:173], v[206:209], v[42:45]
	v_mfma_f32_16x16x32_bf16 v[30:33], v[162:165], v[214:217], v[30:33]
	v_mfma_f32_16x16x32_bf16 v[26:29], v[170:173], v[214:217], v[26:29]
	v_mfma_f32_16x16x32_bf16 v[14:17], v[162:165], v[222:225], v[14:17]
	v_mfma_f32_16x16x32_bf16 v[10:13], v[170:173], v[222:225], v[10:13]
	s_setprio 0
	s_barrier
; #define PG8_STAGE(bufoff, gbase) do { _Pragma("unroll") for (int _i = 0; _i < 2; ++_i) \
;         __builtin_amdgcn_global_load_lds((const unsigned*)((const char*)(gbase) + voff[_i]), (LAS unsigned*)(lds + (bufoff) + ldsw + _i * 8192), 16, 0, 0); } while (0)
; #define PG8_LDA(dst, b, h) do { _Pragma("unroll") for (int m = 0; m < 4; ++m) _Pragma("unroll") for (int k = 0; k < 2; ++k) dst[m][k] = *(const LAS bf16x8*)(lds + PG8_SA(b, h) + aoff + m * 2048 + k * 1024); } while (0)
; #define PG8_LDB(dst, b, h) do { _Pragma("unroll") for (int n = 0; n < 2; ++n) _Pragma("unroll") for (int k = 0; k < 2; ++k) dst[n][k] = *(const LAS bf16x8*)(lds + PG8_SB(b, h) + boff + n * 2048 + k * 1024); } while (0)
; #define PG8_WAIT_V(n) asm volatile("s_waitcnt vmcnt(" #n ")" ::: "memory")
; #define PG8_WAIT_L(n) asm volatile("s_waitcnt lgkmcnt(" #n ")" ::: "memory")
; #define PG8_BAR __builtin_amdgcn_s_barrier()
; #define PG8_SCHED __builtin_amdgcn_sched_barrier(0)
;     ...
;             PG8_STAGE(PG8_SB(0, 1), b2 + hstep);
;             PG8_WAIT_V(6); PG8_BAR; PG8_MMA(1, 1, At, B1); PG8_BAR;
;             PG8_LDB(B0, 1, 0); PG8_SCHED; PG8_LDA(At, 1, 0); PG8_STAGE(PG8_SA(0, 1), a2 + hstep);
;             PG8_WAIT_L(8); PG8_BAR; PG8_WAIT_L(0); PG8_MMA(0, 0, At, B0); PG8_BAR; PG8_SCHED;
;             PG8_LDB(B1, 1, 1); PG8_STAGE(PG8_SB(1, 0), b3);
;             PG8_BAR; PG8_WAIT_L(0); PG8_MMA(0, 1, At, B1); PG8_BAR;
;             PG8_LDA(At, 1, 1); PG8_STAGE(PG8_SA(1, 0), a3);
	s_add_u32 s70, s12, 0x40000
	s_addc_u32 s71, s13, 0
	s_add_i32 s0, s0, s16
	s_mov_b32 m0, s0
	v_lshl_add_u64 v[154:155], s[70:71], 0, v[132:133]
	global_load_lds_dwordx4 v[154:155], off
	s_add_i32 m0, s0, 0x2000
	v_lshl_add_u64 v[154:155], s[70:71], 0, v[130:131]
	global_load_lds_dwordx4 v[154:155], off
	s_waitcnt vmcnt(6)
	s_barrier
	s_setprio 1
	v_mfma_f32_16x16x32_bf16 v[54:57], v[226:229], v[194:197], v[54:57]
	v_mfma_f32_16x16x32_bf16 v[50:53], v[234:237], v[194:197], v[50:53]
	v_mfma_f32_16x16x32_bf16 v[38:41], v[226:229], v[202:205], v[38:41]
	v_mfma_f32_16x16x32_bf16 v[34:37], v[234:237], v[202:205], v[34:37]
	v_mfma_f32_16x16x32_bf16 v[22:25], v[226:229], v[210:213], v[22:25]
	v_mfma_f32_16x16x32_bf16 v[18:21], v[234:237], v[210:213], v[18:21]
	v_mfma_f32_16x16x32_bf16 v[6:9], v[226:229], v[218:221], v[6:9]
	v_mfma_f32_16x16x32_bf16 v[2:5], v[234:237], v[218:221], v[2:5]
	v_mfma_f32_16x16x32_bf16 v[54:57], v[230:233], v[198:201], v[54:57]
	v_mfma_f32_16x16x32_bf16 v[50:53], v[238:241], v[198:201], v[50:53]
	v_mfma_f32_16x16x32_bf16 v[38:41], v[230:233], v[206:209], v[38:41]
	v_mfma_f32_16x16x32_bf16 v[34:37], v[238:241], v[206:209], v[34:37]
	v_mfma_f32_16x16x32_bf16 v[22:25], v[230:233], v[214:217], v[22:25]
	v_mfma_f32_16x16x32_bf16 v[18:21], v[238:241], v[214:217], v[18:21]
	v_mfma_f32_16x16x32_bf16 v[6:9], v[230:233], v[222:225], v[6:9]
	v_mfma_f32_16x16x32_bf16 v[2:5], v[238:241], v[222:225], v[2:5]
	s_setprio 0
	s_add_i32 s0, 0, 0x18000
	v_add_u32_e32 v161, s0, v158
	s_barrier
	ds_read_b128 v[154:157], v161
	ds_read_b128 v[162:165], v161 offset:1024
	ds_read_b128 v[166:169], v161 offset:2048
	ds_read_b128 v[170:173], v161 offset:3072
	s_add_u32 s14, s14, 0x40000
	s_addc_u32 s15, s15, 0
	s_mov_b32 m0, s41
	v_lshl_add_u64 v[226:227], s[14:15], 0, v[132:133]
	ds_read_b128 v[194:197], v160 offset:32768
	ds_read_b128 v[198:201], v160 offset:33792
	ds_read_b128 v[202:205], v160 offset:34816
	ds_read_b128 v[206:209], v160 offset:35840
	ds_read_b128 v[210:213], v160 offset:36864
	ds_read_b128 v[214:217], v160 offset:37888
	ds_read_b128 v[218:221], v160 offset:38912
	ds_read_b128 v[222:225], v160 offset:39936
	global_load_lds_dwordx4 v[226:227], off
	s_mov_b32 m0, s66
	v_lshl_add_u64 v[226:227], s[14:15], 0, v[130:131]
	global_load_lds_dwordx4 v[226:227], off
	s_waitcnt lgkmcnt(8)
	s_barrier
	s_waitcnt lgkmcnt(0)
	s_setprio 1
	v_mfma_f32_16x16x32_bf16 v[126:129], v[154:157], v[194:197], v[126:129]
	v_mfma_f32_16x16x32_bf16 v[122:125], v[166:169], v[194:197], v[122:125]
	v_mfma_f32_16x16x32_bf16 v[110:113], v[154:157], v[202:205], v[110:113]
	v_mfma_f32_16x16x32_bf16 v[106:109], v[166:169], v[202:205], v[106:109]
	v_mfma_f32_16x16x32_bf16 v[94:97], v[154:157], v[210:213], v[94:97]
	v_mfma_f32_16x16x32_bf16 v[90:93], v[166:169], v[210:213], v[90:93]
	v_mfma_f32_16x16x32_bf16 v[78:81], v[154:157], v[218:221], v[78:81]
	v_mfma_f32_16x16x32_bf16 v[74:77], v[166:169], v[218:221], v[74:77]
	v_mfma_f32_16x16x32_bf16 v[126:129], v[162:165], v[198:201], v[126:129]
	v_mfma_f32_16x16x32_bf16 v[122:125], v[170:173], v[198:201], v[122:125]
	v_mfma_f32_16x16x32_bf16 v[110:113], v[162:165], v[206:209], v[110:113]
	v_mfma_f32_16x16x32_bf16 v[106:109], v[170:173], v[206:209], v[106:109]
	v_mfma_f32_16x16x32_bf16 v[94:97], v[162:165], v[214:217], v[94:97]
	v_mfma_f32_16x16x32_bf16 v[90:93], v[170:173], v[214:217], v[90:93]
	v_mfma_f32_16x16x32_bf16 v[78:81], v[162:165], v[222:225], v[78:81]
	v_mfma_f32_16x16x32_bf16 v[74:77], v[170:173], v[222:225], v[74:77]
	s_setprio 0
	s_barrier
	s_add_i32 s1, 0, 0x1c000
	s_add_i32 s0, s0, s16
	v_add_u32_e32 v161, s1, v158
	v_lshl_add_u64 v[174:175], v[174:175], 0, s[88:89]
	s_mov_b32 m0, s0
	ds_read_b128 v[226:229], v161
	ds_read_b128 v[230:233], v161 offset:1024
	ds_read_b128 v[234:237], v161 offset:2048
	ds_read_b128 v[238:241], v161 offset:3072
	global_load_lds_dwordx4 v[174:175], off
	s_add_i32 m0, s0, 0x2000
	v_lshl_add_u64 v[174:175], v[242:243], 0, s[88:89]
	global_load_lds_dwordx4 v[174:175], off
	s_barrier
	s_waitcnt lgkmcnt(0)
	s_setprio 1
	v_mfma_f32_16x16x32_bf16 v[118:121], v[226:229], v[194:197], v[118:121]
	v_mfma_f32_16x16x32_bf16 v[114:117], v[234:237], v[194:197], v[114:117]
	v_mfma_f32_16x16x32_bf16 v[102:105], v[226:229], v[202:205], v[102:105]
	v_mfma_f32_16x16x32_bf16 v[98:101], v[234:237], v[202:205], v[98:101]
	v_mfma_f32_16x16x32_bf16 v[86:89], v[226:229], v[210:213], v[86:89]
	v_mfma_f32_16x16x32_bf16 v[82:85], v[234:237], v[210:213], v[82:85]
	v_mfma_f32_16x16x32_bf16 v[70:73], v[226:229], v[218:221], v[70:73]
	v_mfma_f32_16x16x32_bf16 v[66:69], v[234:237], v[218:221], v[66:69]
	v_mfma_f32_16x16x32_bf16 v[118:121], v[230:233], v[198:201], v[118:121]
	v_mfma_f32_16x16x32_bf16 v[114:117], v[238:241], v[198:201], v[114:117]
	v_mfma_f32_16x16x32_bf16 v[102:105], v[230:233], v[206:209], v[102:105]
	v_mfma_f32_16x16x32_bf16 v[98:101], v[238:241], v[206:209], v[98:101]
	v_mfma_f32_16x16x32_bf16 v[86:89], v[230:233], v[214:217], v[86:89]
	v_mfma_f32_16x16x32_bf16 v[82:85], v[238:241], v[214:217], v[82:85]
	v_mfma_f32_16x16x32_bf16 v[70:73], v[230:233], v[222:225], v[70:73]
	v_mfma_f32_16x16x32_bf16 v[66:69], v[238:241], v[222:225], v[66:69]
	s_setprio 0
	s_mov_b32 m0, s67
	v_lshl_add_u64 v[174:175], v[244:245], 0, s[88:89]
	s_barrier
	ds_read_b128 v[194:197], v160 offset:49152
	ds_read_b128 v[198:201], v160 offset:50176
	ds_read_b128 v[202:205], v160 offset:51200
	ds_read_b128 v[206:209], v160 offset:52224
	ds_read_b128 v[210:213], v160 offset:53248
	ds_read_b128 v[214:217], v160 offset:54272
	ds_read_b128 v[218:221], v160 offset:55296
	ds_read_b128 v[222:225], v160 offset:56320
	global_load_lds_dwordx4 v[174:175], off
	s_mov_b32 m0, s68
	v_lshl_add_u64 v[174:175], v[246:247], 0, s[88:89]
	global_load_lds_dwordx4 v[174:175], off
	s_barrier
; #define PG8_STAGE(bufoff, gbase) do { _Pragma("unroll") for (int _i = 0; _i < 2; ++_i) \
;         __builtin_amdgcn_global_load_lds((const unsigned*)((const char*)(gbase) + voff[_i]), (LAS unsigned*)(lds + (bufoff) + ldsw + _i * 8192), 16, 0, 0); } while (0)
; #define PG8_WAIT_V(n) asm volatile("s_waitcnt vmcnt(" #n ")" ::: "memory")
; #define PG8_WAIT_L(n) asm volatile("s_waitcnt lgkmcnt(" #n ")" ::: "memory")
; #define PG8_BAR __builtin_amdgcn_s_barrier()
; #define PG8_SCHED __builtin_amdgcn_sched_barrier(0)
;     ...
;             PG8_BAR; PG8_WAIT_L(0); PG8_MMA(1, 0, At, B0); PG8_BAR; PG8_SCHED;
;             PG8_STAGE(PG8_SB(1, 1), b3 + hstep);
;             PG8_WAIT_V(6); PG8_BAR; PG8_MMA(1, 1, At, B1); PG8_BAR;
;     __device__ __forceinline__ void operator()(Acc& acc, int pm, int pn, int wr, int wc, int fr, int fq) const {
;         const bool isg = mode == 0 ? (pn < 5) : (mode == 1);
;         bf16_t* base = isg ? gbuf : upre;
;         const int cb = ((mode == 0 && !isg) ? pn * 256 - DRNN : pn * 256) + wc * 32 + fq * 4;
; #pragma unroll
;         for (int ai = 0; ai < 2; ++ai)
; #pragma unroll
;             for (int m = 0; m < 4; ++m) {
;                 const size_t ro = (size_t)(pm * 256 + ai * 128 + wr * 64 + m * 16 + fr) * DRNN + cb;
; #pragma unroll
;                 for (int bj = 0; bj < 2; ++bj)
; #pragma unroll
;                     for (int n = 0; n < 2; ++n) {
;                         f32x4 v = acc[ai][bj][m][n];
;                         if (isg) { v[0] = gelu_tanh(v[0]); v[1] = gelu_tanh(v[1]); v[2] = gelu_tanh(v[2]); v[3] = gelu_tanh(v[3]); }
;                         u32x2 o = {pack2(v[0], v[1]), pack2(v[2], v[3])};
;                         *reinterpret_cast<u32x2*>(base + ro + bj * 128 + n * 16) = o;
	s_waitcnt lgkmcnt(0)
	s_setprio 1
	v_mfma_f32_16x16x32_bf16 v[62:65], v[154:157], v[194:197], v[62:65]
	v_mfma_f32_16x16x32_bf16 v[58:61], v[166:169], v[194:197], v[58:61]
	v_mfma_f32_16x16x32_bf16 v[46:49], v[154:157], v[202:205], v[46:49]
	v_mfma_f32_16x16x32_bf16 v[42:45], v[166:169], v[202:205], v[42:45]
	v_mfma_f32_16x16x32_bf16 v[30:33], v[154:157], v[210:213], v[30:33]
	v_mfma_f32_16x16x32_bf16 v[26:29], v[166:169], v[210:213], v[26:29]
	v_mfma_f32_16x16x32_bf16 v[14:17], v[154:157], v[218:221], v[14:17]
	v_mfma_f32_16x16x32_bf16 v[10:13], v[166:169], v[218:221], v[10:13]
	v_mfma_f32_16x16x32_bf16 v[62:65], v[162:165], v[198:201], v[62:65]
	v_mfma_f32_16x16x32_bf16 v[58:61], v[170:173], v[198:201], v[58:61]
	v_mfma_f32_16x16x32_bf16 v[46:49], v[162:165], v[206:209], v[46:49]
	v_mfma_f32_16x16x32_bf16 v[42:45], v[170:173], v[206:209], v[42:45]
	v_mfma_f32_16x16x32_bf16 v[30:33], v[162:165], v[214:217], v[30:33]
	v_mfma_f32_16x16x32_bf16 v[26:29], v[170:173], v[214:217], v[26:29]
	v_mfma_f32_16x16x32_bf16 v[14:17], v[162:165], v[222:225], v[14:17]
	v_mfma_f32_16x16x32_bf16 v[10:13], v[170:173], v[222:225], v[10:13]
	s_setprio 0
	s_barrier
	s_add_u32 s12, s12, 0x40080
	s_addc_u32 s13, s13, 0
	s_add_i32 s0, s1, s16
	s_mov_b32 m0, s0
	v_lshl_add_u64 v[154:155], s[12:13], 0, v[132:133]
	global_load_lds_dwordx4 v[154:155], off
	s_add_i32 m0, s0, 0x2000
	v_lshl_add_u64 v[154:155], s[12:13], 0, v[130:131]
	global_load_lds_dwordx4 v[154:155], off
	s_waitcnt vmcnt(6)
	s_barrier
	s_setprio 1
	v_mfma_f32_16x16x32_bf16 v[54:57], v[226:229], v[194:197], v[54:57]
	v_mfma_f32_16x16x32_bf16 v[50:53], v[234:237], v[194:197], v[50:53]
	v_mfma_f32_16x16x32_bf16 v[38:41], v[226:229], v[202:205], v[38:41]
	v_mfma_f32_16x16x32_bf16 v[34:37], v[234:237], v[202:205], v[34:37]
	v_mfma_f32_16x16x32_bf16 v[22:25], v[226:229], v[210:213], v[22:25]
	v_mfma_f32_16x16x32_bf16 v[18:21], v[234:237], v[210:213], v[18:21]
	v_mfma_f32_16x16x32_bf16 v[6:9], v[226:229], v[218:221], v[6:9]
	v_mfma_f32_16x16x32_bf16 v[2:5], v[234:237], v[218:221], v[2:5]
	v_mfma_f32_16x16x32_bf16 v[54:57], v[230:233], v[198:201], v[54:57]
	v_mfma_f32_16x16x32_bf16 v[50:53], v[238:241], v[198:201], v[50:53]
	v_mfma_f32_16x16x32_bf16 v[38:41], v[230:233], v[206:209], v[38:41]
	v_mfma_f32_16x16x32_bf16 v[34:37], v[238:241], v[206:209], v[34:37]
	v_mfma_f32_16x16x32_bf16 v[22:25], v[230:233], v[214:217], v[22:25]
	v_mfma_f32_16x16x32_bf16 v[18:21], v[238:241], v[214:217], v[18:21]
	v_mfma_f32_16x16x32_bf16 v[6:9], v[230:233], v[222:225], v[6:9]
	v_mfma_f32_16x16x32_bf16 v[2:5], v[238:241], v[222:225], v[2:5]
	s_setprio 0
	s_add_i32 s30, s30, 2
	s_add_u32 s10, s10, 0x100
	s_addc_u32 s11, s11, 0
	s_add_u32 s28, s28, 0x100
	s_addc_u32 s29, s29, 0
	s_cmp_gt_u32 s30, 13
	s_barrier
	s_cbranch_scc0 .LBB0_1051
	v_mul_f32_e32 v162, 0x3d372713, v126
	v_mul_f32_e32 v162, v126, v162
	v_fma_f32 v162, v126, v162, v126
	v_mul_f32_e32 v162, 0xbfcc422a, v162
	v_mul_f32_e32 v162, 0x3fb8aa3b, v162
	v_exp_f32_e32 v162, v162
	v_lshl_or_b32 v154, s4, 8, v159
	v_ashrrev_i32_e32 v155, 31, v154
	v_lshl_add_u32 v161, s7, 8, v1
	v_add_f32_e32 v162, 1.0, v162
	v_rcp_f32_e32 v162, v162
	v_lshl_add_u64 v[154:155], v[154:155], 1, s[50:51]
	v_mad_i64_i32 v[156:157], s[10:11], v161, s73, v[154:155]
	v_mul_f32_e32 v126, v126, v162
	v_mul_f32_e32 v162, 0x3d372713, v127
	v_mul_f32_e32 v162, v127, v162
	v_fma_f32 v162, v127, v162, v127
	v_mul_f32_e32 v162, 0xbfcc422a, v162
	v_mul_f32_e32 v162, 0x3fb8aa3b, v162
	v_exp_f32_e32 v162, v162
	s_and_b64 vcc, exec, s[44:45]
	s_mov_b32 s4, s48
	s_mov_b32 s7, s60
	v_add_f32_e32 v162, 1.0, v162
	v_rcp_f32_e32 v162, v162
	s_mov_b64 s[12:13], s[64:65]
	v_mul_f32_e32 v127, v127, v162
	v_mul_f32_e32 v162, 0x3d372713, v128
	v_mul_f32_e32 v162, v128, v162
	v_fma_f32 v162, v128, v162, v128
	v_mul_f32_e32 v162, 0xbfcc422a, v162
	v_mul_f32_e32 v162, 0x3fb8aa3b, v162
	v_exp_f32_e32 v162, v162
	v_cvt_pk_bf16_f32 v126, v126, v127
	v_add_f32_e32 v162, 1.0, v162
	v_rcp_f32_e32 v162, v162
	s_nop 0
	v_mul_f32_e32 v128, v128, v162
	v_mul_f32_e32 v162, 0x3d372713, v129
	v_mul_f32_e32 v162, v129, v162
	v_fma_f32 v162, v129, v162, v129
	v_mul_f32_e32 v162, 0xbfcc422a, v162
	v_mul_f32_e32 v162, 0x3fb8aa3b, v162
	v_exp_f32_e32 v162, v162
	s_nop 0
	v_add_f32_e32 v162, 1.0, v162
	v_rcp_f32_e32 v162, v162
	s_nop 0
	v_mul_f32_e32 v129, v129, v162
	v_cvt_pk_bf16_f32 v127, v128, v129
	global_store_dwordx2 v[156:157], v[126:127], off
	v_mul_f32_e32 v126, 0x3d372713, v122
	v_mul_f32_e32 v126, v122, v126
	v_fma_f32 v126, v122, v126, v122
	v_mul_f32_e32 v126, 0xbfcc422a, v126
	v_mul_f32_e32 v126, 0x3fb8aa3b, v126
	v_exp_f32_e32 v126, v126
	s_nop 0
	v_add_f32_e32 v126, 1.0, v126
	v_rcp_f32_e32 v126, v126
	s_nop 0
	v_mul_f32_e32 v122, v122, v126
	v_mul_f32_e32 v126, 0x3d372713, v123
	v_mul_f32_e32 v126, v123, v126
	v_fma_f32 v126, v123, v126, v123
	v_mul_f32_e32 v126, 0xbfcc422a, v126
	v_mul_f32_e32 v126, 0x3fb8aa3b, v126
	v_exp_f32_e32 v126, v126
	s_nop 0
	v_add_f32_e32 v126, 1.0, v126
	v_rcp_f32_e32 v126, v126
	s_nop 0
	v_mul_f32_e32 v123, v123, v126
	v_mul_f32_e32 v126, 0x3d372713, v124
	v_mul_f32_e32 v126, v124, v126
	v_fma_f32 v126, v124, v126, v124
	v_mul_f32_e32 v126, 0xbfcc422a, v126
	v_mul_f32_e32 v126, 0x3fb8aa3b, v126
	v_exp_f32_e32 v126, v126
	v_cvt_pk_bf16_f32 v122, v122, v123
	v_add_f32_e32 v126, 1.0, v126
	v_rcp_f32_e32 v126, v126
	s_nop 0
	v_mul_f32_e32 v124, v124, v126
	v_mul_f32_e32 v126, 0x3d372713, v125
	v_mul_f32_e32 v126, v125, v126
	v_fma_f32 v126, v125, v126, v125
	v_mul_f32_e32 v126, 0xbfcc422a, v126
	v_mul_f32_e32 v126, 0x3fb8aa3b, v126
	v_exp_f32_e32 v126, v126
	s_nop 0
	v_add_f32_e32 v126, 1.0, v126
;     __device__ __forceinline__ void operator()(Acc& acc, int pm, int pn, int wr, int wc, int fr, int fq) const {
;     ...
;         for (int ai = 0; ai < 2; ++ai)
; #pragma unroll
;             for (int m = 0; m < 4; ++m) {
;                 const size_t ro = (size_t)(pm * 256 + ai * 128 + wr * 64 + m * 16 + fr) * DRNN + cb;
; #pragma unroll
;                 for (int bj = 0; bj < 2; ++bj)
; #pragma unroll
;                     for (int n = 0; n < 2; ++n) {
;                         f32x4 v = acc[ai][bj][m][n];
;                         if (isg) { v[0] = gelu_tanh(v[0]); v[1] = gelu_tanh(v[1]); v[2] = gelu_tanh(v[2]); v[3] = gelu_tanh(v[3]); }
;                         u32x2 o = {pack2(v[0], v[1]), pack2(v[2], v[3])};
;                         *reinterpret_cast<u32x2*>(base + ro + bj * 128 + n * 16) = o;
;                     }
	v_rcp_f32_e32 v126, v126
	s_nop 0
	v_mul_f32_e32 v125, v125, v126
	v_cvt_pk_bf16_f32 v123, v124, v125
	global_store_dwordx2 v[156:157], v[122:123], off offset:32
	v_mul_f32_e32 v122, 0x3d372713, v118
	v_mul_f32_e32 v122, v118, v122
	v_fma_f32 v122, v118, v122, v118
	v_mul_f32_e32 v122, 0xbfcc422a, v122
	v_mul_f32_e32 v122, 0x3fb8aa3b, v122
	v_exp_f32_e32 v122, v122
	s_nop 0
	v_add_f32_e32 v122, 1.0, v122
	v_rcp_f32_e32 v122, v122
	s_nop 0
	v_mul_f32_e32 v118, v118, v122
	v_mul_f32_e32 v122, 0x3d372713, v119
	v_mul_f32_e32 v122, v119, v122
	v_fma_f32 v122, v119, v122, v119
	v_mul_f32_e32 v122, 0xbfcc422a, v122
	v_mul_f32_e32 v122, 0x3fb8aa3b, v122
	v_exp_f32_e32 v122, v122
	s_nop 0
	v_add_f32_e32 v122, 1.0, v122
	v_rcp_f32_e32 v122, v122
	s_nop 0
	v_mul_f32_e32 v119, v119, v122
	v_mul_f32_e32 v122, 0x3d372713, v120
	v_mul_f32_e32 v122, v120, v122
	v_fma_f32 v122, v120, v122, v120
	v_mul_f32_e32 v122, 0xbfcc422a, v122
	v_mul_f32_e32 v122, 0x3fb8aa3b, v122
	v_exp_f32_e32 v122, v122
	v_cvt_pk_bf16_f32 v118, v118, v119
	v_add_f32_e32 v122, 1.0, v122
	v_rcp_f32_e32 v122, v122
	s_nop 0
	v_mul_f32_e32 v120, v120, v122
	v_mul_f32_e32 v122, 0x3d372713, v121
	v_mul_f32_e32 v122, v121, v122
	v_fma_f32 v122, v121, v122, v121
	v_mul_f32_e32 v122, 0xbfcc422a, v122
	v_mul_f32_e32 v122, 0x3fb8aa3b, v122
	v_exp_f32_e32 v122, v122
	s_nop 0
	v_add_f32_e32 v122, 1.0, v122
	v_rcp_f32_e32 v122, v122
	s_nop 0
	v_mul_f32_e32 v121, v121, v122
	v_cvt_pk_bf16_f32 v119, v120, v121
	global_store_dwordx2 v[156:157], v[118:119], off offset:256
	v_mul_f32_e32 v118, 0x3d372713, v114
	v_mul_f32_e32 v118, v114, v118
	v_fma_f32 v118, v114, v118, v114
	v_mul_f32_e32 v118, 0xbfcc422a, v118
	v_mul_f32_e32 v118, 0x3fb8aa3b, v118
	v_exp_f32_e32 v118, v118
	s_nop 0
	v_add_f32_e32 v118, 1.0, v118
	v_rcp_f32_e32 v118, v118
	s_nop 0
	v_mul_f32_e32 v114, v114, v118
	v_mul_f32_e32 v118, 0x3d372713, v115
	v_mul_f32_e32 v118, v115, v118
	v_fma_f32 v118, v115, v118, v115
	v_mul_f32_e32 v118, 0xbfcc422a, v118
	v_mul_f32_e32 v118, 0x3fb8aa3b, v118
	v_exp_f32_e32 v118, v118
	s_nop 0
	v_add_f32_e32 v118, 1.0, v118
	v_rcp_f32_e32 v118, v118
	s_nop 0
	v_mul_f32_e32 v115, v115, v118
	v_mul_f32_e32 v118, 0x3d372713, v116
	v_mul_f32_e32 v118, v116, v118
	v_fma_f32 v118, v116, v118, v116
	v_mul_f32_e32 v118, 0xbfcc422a, v118
	v_mul_f32_e32 v118, 0x3fb8aa3b, v118
	v_exp_f32_e32 v118, v118
	v_cvt_pk_bf16_f32 v114, v114, v115
	v_add_f32_e32 v118, 1.0, v118
	v_rcp_f32_e32 v118, v118
	s_nop 0
	v_mul_f32_e32 v116, v116, v118
	v_mul_f32_e32 v118, 0x3d372713, v117
	v_mul_f32_e32 v118, v117, v118
	v_fma_f32 v118, v117, v118, v117
	v_mul_f32_e32 v118, 0xbfcc422a, v118
	v_mul_f32_e32 v118, 0x3fb8aa3b, v118
	v_exp_f32_e32 v118, v118
	s_nop 0
	v_add_f32_e32 v118, 1.0, v118
	v_rcp_f32_e32 v118, v118
	s_nop 0
	v_mul_f32_e32 v117, v117, v118
	v_cvt_pk_bf16_f32 v115, v116, v117
	v_mul_f32_e32 v116, 0x3d372713, v110
	v_mul_f32_e32 v116, v110, v116
	v_fma_f32 v116, v110, v116, v110
	v_mul_f32_e32 v116, 0xbfcc422a, v116
	v_mul_f32_e32 v116, 0x3fb8aa3b, v116
	v_exp_f32_e32 v116, v116
	global_store_dwordx2 v[156:157], v[114:115], off offset:288
	v_or_b32_e32 v114, 16, v161
	v_mad_i64_i32 v[114:115], s[10:11], v114, s73, v[154:155]
	v_add_f32_e32 v116, 1.0, v116
	v_rcp_f32_e32 v116, v116
	s_nop 0
	v_mul_f32_e32 v110, v110, v116
	v_mul_f32_e32 v116, 0x3d372713, v111
	v_mul_f32_e32 v116, v111, v116
	v_fma_f32 v116, v111, v116, v111
	v_mul_f32_e32 v116, 0xbfcc422a, v116
	v_mul_f32_e32 v116, 0x3fb8aa3b, v116
	v_exp_f32_e32 v116, v116
	s_nop 0
	v_add_f32_e32 v116, 1.0, v116
	v_rcp_f32_e32 v116, v116
	s_nop 0
	v_mul_f32_e32 v111, v111, v116
	v_mul_f32_e32 v116, 0x3d372713, v112
	v_mul_f32_e32 v116, v112, v116
	v_fma_f32 v116, v112, v116, v112
	v_mul_f32_e32 v116, 0xbfcc422a, v116
	v_mul_f32_e32 v116, 0x3fb8aa3b, v116
	v_exp_f32_e32 v116, v116
	v_cvt_pk_bf16_f32 v110, v110, v111
	v_add_f32_e32 v116, 1.0, v116
	v_rcp_f32_e32 v116, v116
	s_nop 0
	v_mul_f32_e32 v112, v112, v116
	v_mul_f32_e32 v116, 0x3d372713, v113
	v_mul_f32_e32 v116, v113, v116
	v_fma_f32 v116, v113, v116, v113
	v_mul_f32_e32 v116, 0xbfcc422a, v116
	v_mul_f32_e32 v116, 0x3fb8aa3b, v116
	v_exp_f32_e32 v116, v116
	s_nop 0
	v_add_f32_e32 v116, 1.0, v116
	v_rcp_f32_e32 v116, v116
	s_nop 0
	v_mul_f32_e32 v113, v113, v116
	v_cvt_pk_bf16_f32 v111, v112, v113
	global_store_dwordx2 v[114:115], v[110:111], off
	v_mul_f32_e32 v110, 0x3d372713, v106
	v_mul_f32_e32 v110, v106, v110
	v_fma_f32 v110, v106, v110, v106
	v_mul_f32_e32 v110, 0xbfcc422a, v110
	v_mul_f32_e32 v110, 0x3fb8aa3b, v110
	v_exp_f32_e32 v110, v110
	s_nop 0
	v_add_f32_e32 v110, 1.0, v110
	v_rcp_f32_e32 v110, v110
	s_nop 0
	v_mul_f32_e32 v106, v106, v110
	v_mul_f32_e32 v110, 0x3d372713, v107
	v_mul_f32_e32 v110, v107, v110
	v_fma_f32 v110, v107, v110, v107
	v_mul_f32_e32 v110, 0xbfcc422a, v110
	v_mul_f32_e32 v110, 0x3fb8aa3b, v110
	v_exp_f32_e32 v110, v110
	s_nop 0
	v_add_f32_e32 v110, 1.0, v110
	v_rcp_f32_e32 v110, v110
	s_nop 0
	v_mul_f32_e32 v107, v107, v110
	v_mul_f32_e32 v110, 0x3d372713, v108
	v_mul_f32_e32 v110, v108, v110
	v_fma_f32 v110, v108, v110, v108
	v_mul_f32_e32 v110, 0xbfcc422a, v110
	v_mul_f32_e32 v110, 0x3fb8aa3b, v110
	v_exp_f32_e32 v110, v110
	v_cvt_pk_bf16_f32 v106, v106, v107
	v_add_f32_e32 v110, 1.0, v110
	v_rcp_f32_e32 v110, v110
	s_nop 0
	v_mul_f32_e32 v108, v108, v110
	v_mul_f32_e32 v110, 0x3d372713, v109
	v_mul_f32_e32 v110, v109, v110
	v_fma_f32 v110, v109, v110, v109
	v_mul_f32_e32 v110, 0xbfcc422a, v110
	v_mul_f32_e32 v110, 0x3fb8aa3b, v110
	v_exp_f32_e32 v110, v110
	s_nop 0
	v_add_f32_e32 v110, 1.0, v110
	v_rcp_f32_e32 v110, v110
	s_nop 0
	v_mul_f32_e32 v109, v109, v110
;     __device__ __forceinline__ void operator()(Acc& acc, int pm, int pn, int wr, int wc, int fr, int fq) const {
;     ...
;         for (int ai = 0; ai < 2; ++ai)
; #pragma unroll
;             for (int m = 0; m < 4; ++m) {
;                 const size_t ro = (size_t)(pm * 256 + ai * 128 + wr * 64 + m * 16 + fr) * DRNN + cb;
; #pragma unroll
;                 for (int bj = 0; bj < 2; ++bj)
; #pragma unroll
;                     for (int n = 0; n < 2; ++n) {
;                         f32x4 v = acc[ai][bj][m][n];
;                         if (isg) { v[0] = gelu_tanh(v[0]); v[1] = gelu_tanh(v[1]); v[2] = gelu_tanh(v[2]); v[3] = gelu_tanh(v[3]); }
;                         u32x2 o = {pack2(v[0], v[1]), pack2(v[2], v[3])};
;                         *reinterpret_cast<u32x2*>(base + ro + bj * 128 + n * 16) = o;
;                     }
	v_cvt_pk_bf16_f32 v107, v108, v109
	global_store_dwordx2 v[114:115], v[106:107], off offset:32
	v_mul_f32_e32 v106, 0x3d372713, v102
	v_mul_f32_e32 v106, v102, v106
	v_fma_f32 v106, v102, v106, v102
	v_mul_f32_e32 v106, 0xbfcc422a, v106
	v_mul_f32_e32 v106, 0x3fb8aa3b, v106
	v_exp_f32_e32 v106, v106
	s_nop 0
	v_add_f32_e32 v106, 1.0, v106
	v_rcp_f32_e32 v106, v106
	s_nop 0
	v_mul_f32_e32 v102, v102, v106
	v_mul_f32_e32 v106, 0x3d372713, v103
	v_mul_f32_e32 v106, v103, v106
	v_fma_f32 v106, v103, v106, v103
	v_mul_f32_e32 v106, 0xbfcc422a, v106
	v_mul_f32_e32 v106, 0x3fb8aa3b, v106
	v_exp_f32_e32 v106, v106
	s_nop 0
	v_add_f32_e32 v106, 1.0, v106
	v_rcp_f32_e32 v106, v106
	s_nop 0
	v_mul_f32_e32 v103, v103, v106
	v_mul_f32_e32 v106, 0x3d372713, v104
	v_mul_f32_e32 v106, v104, v106
	v_fma_f32 v106, v104, v106, v104
	v_mul_f32_e32 v106, 0xbfcc422a, v106
	v_mul_f32_e32 v106, 0x3fb8aa3b, v106
	v_exp_f32_e32 v106, v106
	v_cvt_pk_bf16_f32 v102, v102, v103
	v_add_f32_e32 v106, 1.0, v106
	v_rcp_f32_e32 v106, v106
	s_nop 0
	v_mul_f32_e32 v104, v104, v106
	v_mul_f32_e32 v106, 0x3d372713, v105
	v_mul_f32_e32 v106, v105, v106
	v_fma_f32 v106, v105, v106, v105
	v_mul_f32_e32 v106, 0xbfcc422a, v106
	v_mul_f32_e32 v106, 0x3fb8aa3b, v106
	v_exp_f32_e32 v106, v106
	s_nop 0
	v_add_f32_e32 v106, 1.0, v106
	v_rcp_f32_e32 v106, v106
	s_nop 0
	v_mul_f32_e32 v105, v105, v106
	v_cvt_pk_bf16_f32 v103, v104, v105
	global_store_dwordx2 v[114:115], v[102:103], off offset:256
	v_mul_f32_e32 v102, 0x3d372713, v98
	v_mul_f32_e32 v102, v98, v102
	v_fma_f32 v102, v98, v102, v98
	v_mul_f32_e32 v102, 0xbfcc422a, v102
	v_mul_f32_e32 v102, 0x3fb8aa3b, v102
	v_exp_f32_e32 v102, v102
	s_nop 0
	v_add_f32_e32 v102, 1.0, v102
	v_rcp_f32_e32 v102, v102
	s_nop 0
	v_mul_f32_e32 v98, v98, v102
	v_mul_f32_e32 v102, 0x3d372713, v99
	v_mul_f32_e32 v102, v99, v102
	v_fma_f32 v102, v99, v102, v99
	v_mul_f32_e32 v102, 0xbfcc422a, v102
	v_mul_f32_e32 v102, 0x3fb8aa3b, v102
	v_exp_f32_e32 v102, v102
	s_nop 0
	v_add_f32_e32 v102, 1.0, v102
	v_rcp_f32_e32 v102, v102
	s_nop 0
	v_mul_f32_e32 v99, v99, v102
	v_mul_f32_e32 v102, 0x3d372713, v100
	v_mul_f32_e32 v102, v100, v102
	v_fma_f32 v102, v100, v102, v100
	v_mul_f32_e32 v102, 0xbfcc422a, v102
	v_mul_f32_e32 v102, 0x3fb8aa3b, v102
	v_exp_f32_e32 v102, v102
	v_cvt_pk_bf16_f32 v98, v98, v99
	v_add_f32_e32 v102, 1.0, v102
	v_rcp_f32_e32 v102, v102
	s_nop 0
	v_mul_f32_e32 v100, v100, v102
	v_mul_f32_e32 v102, 0x3d372713, v101
	v_mul_f32_e32 v102, v101, v102
	v_fma_f32 v102, v101, v102, v101
	v_mul_f32_e32 v102, 0xbfcc422a, v102
	v_mul_f32_e32 v102, 0x3fb8aa3b, v102
	v_exp_f32_e32 v102, v102
	s_nop 0
	v_add_f32_e32 v102, 1.0, v102
	v_rcp_f32_e32 v102, v102
	s_nop 0
	v_mul_f32_e32 v101, v101, v102
	v_cvt_pk_bf16_f32 v99, v100, v101
	v_mul_f32_e32 v100, 0x3d372713, v94
	v_mul_f32_e32 v100, v94, v100
	v_fma_f32 v100, v94, v100, v94
	v_mul_f32_e32 v100, 0xbfcc422a, v100
	v_mul_f32_e32 v100, 0x3fb8aa3b, v100
	v_exp_f32_e32 v100, v100
	global_store_dwordx2 v[114:115], v[98:99], off offset:288
	v_or_b32_e32 v98, 32, v161
	v_mad_i64_i32 v[98:99], s[10:11], v98, s73, v[154:155]
	v_add_f32_e32 v100, 1.0, v100
	v_rcp_f32_e32 v100, v100
	s_nop 0
	v_mul_f32_e32 v94, v94, v100
	v_mul_f32_e32 v100, 0x3d372713, v95
	v_mul_f32_e32 v100, v95, v100
	v_fma_f32 v100, v95, v100, v95
	v_mul_f32_e32 v100, 0xbfcc422a, v100
	v_mul_f32_e32 v100, 0x3fb8aa3b, v100
	v_exp_f32_e32 v100, v100
	s_nop 0
	v_add_f32_e32 v100, 1.0, v100
	v_rcp_f32_e32 v100, v100
	s_nop 0
	v_mul_f32_e32 v95, v95, v100
	v_mul_f32_e32 v100, 0x3d372713, v96
	v_mul_f32_e32 v100, v96, v100
	v_fma_f32 v100, v96, v100, v96
	v_mul_f32_e32 v100, 0xbfcc422a, v100
	v_mul_f32_e32 v100, 0x3fb8aa3b, v100
	v_exp_f32_e32 v100, v100
	v_cvt_pk_bf16_f32 v94, v94, v95
	v_add_f32_e32 v100, 1.0, v100
	v_rcp_f32_e32 v100, v100
	s_nop 0
	v_mul_f32_e32 v96, v96, v100
	v_mul_f32_e32 v100, 0x3d372713, v97
	v_mul_f32_e32 v100, v97, v100
	v_fma_f32 v100, v97, v100, v97
	v_mul_f32_e32 v100, 0xbfcc422a, v100
	v_mul_f32_e32 v100, 0x3fb8aa3b, v100
	v_exp_f32_e32 v100, v100
	s_nop 0
	v_add_f32_e32 v100, 1.0, v100
	v_rcp_f32_e32 v100, v100
	s_nop 0
	v_mul_f32_e32 v97, v97, v100
	v_cvt_pk_bf16_f32 v95, v96, v97
	global_store_dwordx2 v[98:99], v[94:95], off
	v_mul_f32_e32 v94, 0x3d372713, v90
	v_mul_f32_e32 v94, v90, v94
	v_fma_f32 v94, v90, v94, v90
	v_mul_f32_e32 v94, 0xbfcc422a, v94
	v_mul_f32_e32 v94, 0x3fb8aa3b, v94
	v_exp_f32_e32 v94, v94
	s_nop 0
	v_add_f32_e32 v94, 1.0, v94
	v_rcp_f32_e32 v94, v94
	s_nop 0
	v_mul_f32_e32 v90, v90, v94
	v_mul_f32_e32 v94, 0x3d372713, v91
	v_mul_f32_e32 v94, v91, v94
	v_fma_f32 v94, v91, v94, v91
	v_mul_f32_e32 v94, 0xbfcc422a, v94
	v_mul_f32_e32 v94, 0x3fb8aa3b, v94
	v_exp_f32_e32 v94, v94
	s_nop 0
	v_add_f32_e32 v94, 1.0, v94
	v_rcp_f32_e32 v94, v94
	s_nop 0
	v_mul_f32_e32 v91, v91, v94
	v_mul_f32_e32 v94, 0x3d372713, v92
	v_mul_f32_e32 v94, v92, v94
	v_fma_f32 v94, v92, v94, v92
	v_mul_f32_e32 v94, 0xbfcc422a, v94
	v_mul_f32_e32 v94, 0x3fb8aa3b, v94
	v_exp_f32_e32 v94, v94
	v_cvt_pk_bf16_f32 v90, v90, v91
	v_add_f32_e32 v94, 1.0, v94
	v_rcp_f32_e32 v94, v94
	s_nop 0
	v_mul_f32_e32 v92, v92, v94
	v_mul_f32_e32 v94, 0x3d372713, v93
	v_mul_f32_e32 v94, v93, v94
	v_fma_f32 v94, v93, v94, v93
	v_mul_f32_e32 v94, 0xbfcc422a, v94
	v_mul_f32_e32 v94, 0x3fb8aa3b, v94
	v_exp_f32_e32 v94, v94
	s_nop 0
	v_add_f32_e32 v94, 1.0, v94
	v_rcp_f32_e32 v94, v94
	s_nop 0
	v_mul_f32_e32 v93, v93, v94
	v_cvt_pk_bf16_f32 v91, v92, v93
	global_store_dwordx2 v[98:99], v[90:91], off offset:32
	v_mul_f32_e32 v90, 0x3d372713, v86
	v_mul_f32_e32 v90, v86, v90
	v_fma_f32 v90, v86, v90, v86
	v_mul_f32_e32 v90, 0xbfcc422a, v90
;     __device__ __forceinline__ void operator()(Acc& acc, int pm, int pn, int wr, int wc, int fr, int fq) const {
;     ...
;         for (int ai = 0; ai < 2; ++ai)
; #pragma unroll
;             for (int m = 0; m < 4; ++m) {
;                 const size_t ro = (size_t)(pm * 256 + ai * 128 + wr * 64 + m * 16 + fr) * DRNN + cb;
; #pragma unroll
;                 for (int bj = 0; bj < 2; ++bj)
; #pragma unroll
;                     for (int n = 0; n < 2; ++n) {
;                         f32x4 v = acc[ai][bj][m][n];
;                         if (isg) { v[0] = gelu_tanh(v[0]); v[1] = gelu_tanh(v[1]); v[2] = gelu_tanh(v[2]); v[3] = gelu_tanh(v[3]); }
;                         u32x2 o = {pack2(v[0], v[1]), pack2(v[2], v[3])};
;                         *reinterpret_cast<u32x2*>(base + ro + bj * 128 + n * 16) = o;
;                     }
	v_mul_f32_e32 v90, 0x3fb8aa3b, v90
	v_exp_f32_e32 v90, v90
	s_nop 0
	v_add_f32_e32 v90, 1.0, v90
	v_rcp_f32_e32 v90, v90
	s_nop 0
	v_mul_f32_e32 v86, v86, v90
	v_mul_f32_e32 v90, 0x3d372713, v87
	v_mul_f32_e32 v90, v87, v90
	v_fma_f32 v90, v87, v90, v87
	v_mul_f32_e32 v90, 0xbfcc422a, v90
	v_mul_f32_e32 v90, 0x3fb8aa3b, v90
	v_exp_f32_e32 v90, v90
	s_nop 0
	v_add_f32_e32 v90, 1.0, v90
	v_rcp_f32_e32 v90, v90
	s_nop 0
	v_mul_f32_e32 v87, v87, v90
	v_mul_f32_e32 v90, 0x3d372713, v88
	v_mul_f32_e32 v90, v88, v90
	v_fma_f32 v90, v88, v90, v88
	v_mul_f32_e32 v90, 0xbfcc422a, v90
	v_mul_f32_e32 v90, 0x3fb8aa3b, v90
	v_exp_f32_e32 v90, v90
	v_cvt_pk_bf16_f32 v86, v86, v87
	v_add_f32_e32 v90, 1.0, v90
	v_rcp_f32_e32 v90, v90
	s_nop 0
	v_mul_f32_e32 v88, v88, v90
	v_mul_f32_e32 v90, 0x3d372713, v89
	v_mul_f32_e32 v90, v89, v90
	v_fma_f32 v90, v89, v90, v89
	v_mul_f32_e32 v90, 0xbfcc422a, v90
	v_mul_f32_e32 v90, 0x3fb8aa3b, v90
	v_exp_f32_e32 v90, v90
	s_nop 0
	v_add_f32_e32 v90, 1.0, v90
	v_rcp_f32_e32 v90, v90
	s_nop 0
	v_mul_f32_e32 v89, v89, v90
	v_cvt_pk_bf16_f32 v87, v88, v89
	global_store_dwordx2 v[98:99], v[86:87], off offset:256
	v_mul_f32_e32 v86, 0x3d372713, v82
	v_mul_f32_e32 v86, v82, v86
	v_fma_f32 v86, v82, v86, v82
	v_mul_f32_e32 v86, 0xbfcc422a, v86
	v_mul_f32_e32 v86, 0x3fb8aa3b, v86
	v_exp_f32_e32 v86, v86
	s_nop 0
	v_add_f32_e32 v86, 1.0, v86
	v_rcp_f32_e32 v86, v86
	s_nop 0
	v_mul_f32_e32 v82, v82, v86
	v_mul_f32_e32 v86, 0x3d372713, v83
	v_mul_f32_e32 v86, v83, v86
	v_fma_f32 v86, v83, v86, v83
	v_mul_f32_e32 v86, 0xbfcc422a, v86
	v_mul_f32_e32 v86, 0x3fb8aa3b, v86
	v_exp_f32_e32 v86, v86
	s_nop 0
	v_add_f32_e32 v86, 1.0, v86
	v_rcp_f32_e32 v86, v86
	s_nop 0
	v_mul_f32_e32 v83, v83, v86
	v_mul_f32_e32 v86, 0x3d372713, v84
	v_mul_f32_e32 v86, v84, v86
	v_fma_f32 v86, v84, v86, v84
	v_mul_f32_e32 v86, 0xbfcc422a, v86
	v_mul_f32_e32 v86, 0x3fb8aa3b, v86
	v_exp_f32_e32 v86, v86
	v_cvt_pk_bf16_f32 v82, v82, v83
	v_add_f32_e32 v86, 1.0, v86
	v_rcp_f32_e32 v86, v86
	s_nop 0
	v_mul_f32_e32 v84, v84, v86
	v_mul_f32_e32 v86, 0x3d372713, v85
	v_mul_f32_e32 v86, v85, v86
	v_fma_f32 v86, v85, v86, v85
	v_mul_f32_e32 v86, 0xbfcc422a, v86
	v_mul_f32_e32 v86, 0x3fb8aa3b, v86
	v_exp_f32_e32 v86, v86
	s_nop 0
	v_add_f32_e32 v86, 1.0, v86
	v_rcp_f32_e32 v86, v86
	s_nop 0
	v_mul_f32_e32 v85, v85, v86
	v_cvt_pk_bf16_f32 v83, v84, v85
	v_mul_f32_e32 v84, 0x3d372713, v78
	v_mul_f32_e32 v84, v78, v84
	v_fma_f32 v84, v78, v84, v78
	v_mul_f32_e32 v84, 0xbfcc422a, v84
	v_mul_f32_e32 v84, 0x3fb8aa3b, v84
	v_exp_f32_e32 v84, v84
	global_store_dwordx2 v[98:99], v[82:83], off offset:288
	v_or_b32_e32 v82, 48, v161
	v_mad_i64_i32 v[82:83], s[10:11], v82, s73, v[154:155]
	v_add_f32_e32 v84, 1.0, v84
	v_rcp_f32_e32 v84, v84
	s_nop 0
	v_mul_f32_e32 v78, v78, v84
	v_mul_f32_e32 v84, 0x3d372713, v79
	v_mul_f32_e32 v84, v79, v84
	v_fma_f32 v84, v79, v84, v79
	v_mul_f32_e32 v84, 0xbfcc422a, v84
	v_mul_f32_e32 v84, 0x3fb8aa3b, v84
	v_exp_f32_e32 v84, v84
	s_nop 0
	v_add_f32_e32 v84, 1.0, v84
	v_rcp_f32_e32 v84, v84
	s_nop 0
	v_mul_f32_e32 v79, v79, v84
	v_mul_f32_e32 v84, 0x3d372713, v80
	v_mul_f32_e32 v84, v80, v84
	v_fma_f32 v84, v80, v84, v80
	v_mul_f32_e32 v84, 0xbfcc422a, v84
	v_mul_f32_e32 v84, 0x3fb8aa3b, v84
	v_exp_f32_e32 v84, v84
	v_cvt_pk_bf16_f32 v78, v78, v79
	v_add_f32_e32 v84, 1.0, v84
	v_rcp_f32_e32 v84, v84
	s_nop 0
	v_mul_f32_e32 v80, v80, v84
	v_mul_f32_e32 v84, 0x3d372713, v81
	v_mul_f32_e32 v84, v81, v84
	v_fma_f32 v84, v81, v84, v81
	v_mul_f32_e32 v84, 0xbfcc422a, v84
	v_mul_f32_e32 v84, 0x3fb8aa3b, v84
	v_exp_f32_e32 v84, v84
	s_nop 0
	v_add_f32_e32 v84, 1.0, v84
	v_rcp_f32_e32 v84, v84
	s_nop 0
	v_mul_f32_e32 v81, v81, v84
	v_cvt_pk_bf16_f32 v79, v80, v81
	global_store_dwordx2 v[82:83], v[78:79], off
	v_mul_f32_e32 v78, 0x3d372713, v74
	v_mul_f32_e32 v78, v74, v78
	v_fma_f32 v78, v74, v78, v74
	v_mul_f32_e32 v78, 0xbfcc422a, v78
	v_mul_f32_e32 v78, 0x3fb8aa3b, v78
	v_exp_f32_e32 v78, v78
	s_nop 0
	v_add_f32_e32 v78, 1.0, v78
	v_rcp_f32_e32 v78, v78
	s_nop 0
	v_mul_f32_e32 v74, v74, v78
	v_mul_f32_e32 v78, 0x3d372713, v75
	v_mul_f32_e32 v78, v75, v78
	v_fma_f32 v78, v75, v78, v75
	v_mul_f32_e32 v78, 0xbfcc422a, v78
	v_mul_f32_e32 v78, 0x3fb8aa3b, v78
	v_exp_f32_e32 v78, v78
	s_nop 0
	v_add_f32_e32 v78, 1.0, v78
	v_rcp_f32_e32 v78, v78
	s_nop 0
	v_mul_f32_e32 v75, v75, v78
	v_mul_f32_e32 v78, 0x3d372713, v76
	v_mul_f32_e32 v78, v76, v78
	v_fma_f32 v78, v76, v78, v76
	v_mul_f32_e32 v78, 0xbfcc422a, v78
	v_mul_f32_e32 v78, 0x3fb8aa3b, v78
	v_exp_f32_e32 v78, v78
	v_cvt_pk_bf16_f32 v74, v74, v75
	v_add_f32_e32 v78, 1.0, v78
	v_rcp_f32_e32 v78, v78
	s_nop 0
	v_mul_f32_e32 v76, v76, v78
	v_mul_f32_e32 v78, 0x3d372713, v77
	v_mul_f32_e32 v78, v77, v78
	v_fma_f32 v78, v77, v78, v77
	v_mul_f32_e32 v78, 0xbfcc422a, v78
	v_mul_f32_e32 v78, 0x3fb8aa3b, v78
	v_exp_f32_e32 v78, v78
	s_nop 0
	v_add_f32_e32 v78, 1.0, v78
	v_rcp_f32_e32 v78, v78
	s_nop 0
	v_mul_f32_e32 v77, v77, v78
	v_cvt_pk_bf16_f32 v75, v76, v77
	global_store_dwordx2 v[82:83], v[74:75], off offset:32
	v_mul_f32_e32 v74, 0x3d372713, v70
	v_mul_f32_e32 v74, v70, v74
	v_fma_f32 v74, v70, v74, v70
	v_mul_f32_e32 v74, 0xbfcc422a, v74
	v_mul_f32_e32 v74, 0x3fb8aa3b, v74
	v_exp_f32_e32 v74, v74
	s_nop 0
	v_add_f32_e32 v74, 1.0, v74
	v_rcp_f32_e32 v74, v74
	s_nop 0
	v_mul_f32_e32 v70, v70, v74
	v_mul_f32_e32 v74, 0x3d372713, v71
	v_mul_f32_e32 v74, v71, v74
	v_fma_f32 v74, v71, v74, v71
	v_mul_f32_e32 v74, 0xbfcc422a, v74
	v_mul_f32_e32 v74, 0x3fb8aa3b, v74
	v_exp_f32_e32 v74, v74
	s_nop 0
	v_add_f32_e32 v74, 1.0, v74
	v_rcp_f32_e32 v74, v74
	s_nop 0
	v_mul_f32_e32 v71, v71, v74
;     __device__ __forceinline__ void operator()(Acc& acc, int pm, int pn, int wr, int wc, int fr, int fq) const {
;     ...
;         for (int ai = 0; ai < 2; ++ai)
; #pragma unroll
;             for (int m = 0; m < 4; ++m) {
;                 const size_t ro = (size_t)(pm * 256 + ai * 128 + wr * 64 + m * 16 + fr) * DRNN + cb;
; #pragma unroll
;                 for (int bj = 0; bj < 2; ++bj)
; #pragma unroll
;                     for (int n = 0; n < 2; ++n) {
;                         f32x4 v = acc[ai][bj][m][n];
;                         if (isg) { v[0] = gelu_tanh(v[0]); v[1] = gelu_tanh(v[1]); v[2] = gelu_tanh(v[2]); v[3] = gelu_tanh(v[3]); }
;                         u32x2 o = {pack2(v[0], v[1]), pack2(v[2], v[3])};
;                         *reinterpret_cast<u32x2*>(base + ro + bj * 128 + n * 16) = o;
;                     }
	v_mul_f32_e32 v74, 0x3d372713, v72
	v_mul_f32_e32 v74, v72, v74
	v_fma_f32 v74, v72, v74, v72
	v_mul_f32_e32 v74, 0xbfcc422a, v74
	v_mul_f32_e32 v74, 0x3fb8aa3b, v74
	v_exp_f32_e32 v74, v74
	v_cvt_pk_bf16_f32 v70, v70, v71
	v_add_f32_e32 v74, 1.0, v74
	v_rcp_f32_e32 v74, v74
	s_nop 0
	v_mul_f32_e32 v72, v72, v74
	v_mul_f32_e32 v74, 0x3d372713, v73
	v_mul_f32_e32 v74, v73, v74
	v_fma_f32 v74, v73, v74, v73
	v_mul_f32_e32 v74, 0xbfcc422a, v74
	v_mul_f32_e32 v74, 0x3fb8aa3b, v74
	v_exp_f32_e32 v74, v74
	s_nop 0
	v_add_f32_e32 v74, 1.0, v74
	v_rcp_f32_e32 v74, v74
	s_nop 0
	v_mul_f32_e32 v73, v73, v74
	v_cvt_pk_bf16_f32 v71, v72, v73
	global_store_dwordx2 v[82:83], v[70:71], off offset:256
	v_mul_f32_e32 v70, 0x3d372713, v66
	v_mul_f32_e32 v70, v66, v70
	v_fma_f32 v70, v66, v70, v66
	v_mul_f32_e32 v70, 0xbfcc422a, v70
	v_mul_f32_e32 v70, 0x3fb8aa3b, v70
	v_exp_f32_e32 v70, v70
	s_nop 0
	v_add_f32_e32 v70, 1.0, v70
	v_rcp_f32_e32 v70, v70
	s_nop 0
	v_mul_f32_e32 v66, v66, v70
	v_mul_f32_e32 v70, 0x3d372713, v67
	v_mul_f32_e32 v70, v67, v70
	v_fma_f32 v70, v67, v70, v67
	v_mul_f32_e32 v70, 0xbfcc422a, v70
	v_mul_f32_e32 v70, 0x3fb8aa3b, v70
	v_exp_f32_e32 v70, v70
	s_nop 0
	v_add_f32_e32 v70, 1.0, v70
	v_rcp_f32_e32 v70, v70
	s_nop 0
	v_mul_f32_e32 v67, v67, v70
	v_mul_f32_e32 v70, 0x3d372713, v68
	v_mul_f32_e32 v70, v68, v70
	v_fma_f32 v70, v68, v70, v68
	v_mul_f32_e32 v70, 0xbfcc422a, v70
	v_mul_f32_e32 v70, 0x3fb8aa3b, v70
	v_exp_f32_e32 v70, v70
	v_cvt_pk_bf16_f32 v66, v66, v67
	v_add_f32_e32 v70, 1.0, v70
	v_rcp_f32_e32 v70, v70
	s_nop 0
	v_mul_f32_e32 v68, v68, v70
	v_mul_f32_e32 v70, 0x3d372713, v69
	v_mul_f32_e32 v70, v69, v70
	v_fma_f32 v70, v69, v70, v69
	v_mul_f32_e32 v70, 0xbfcc422a, v70
	v_mul_f32_e32 v70, 0x3fb8aa3b, v70
	v_exp_f32_e32 v70, v70
	s_nop 0
	v_add_f32_e32 v70, 1.0, v70
	v_rcp_f32_e32 v70, v70
	s_nop 0
	v_mul_f32_e32 v69, v69, v70
	v_cvt_pk_bf16_f32 v67, v68, v69
	v_mul_f32_e32 v68, 0x3d372713, v62
	v_mul_f32_e32 v68, v62, v68
	v_fma_f32 v68, v62, v68, v62
	v_mul_f32_e32 v68, 0xbfcc422a, v68
	v_mul_f32_e32 v68, 0x3fb8aa3b, v68
	v_exp_f32_e32 v68, v68
	global_store_dwordx2 v[82:83], v[66:67], off offset:288
	v_add_u32_e32 v66, 0x80, v161
	v_mad_i64_i32 v[66:67], s[10:11], v66, s73, v[154:155]
	v_add_f32_e32 v68, 1.0, v68
	v_rcp_f32_e32 v68, v68
	s_nop 0
	v_mul_f32_e32 v62, v62, v68
	v_mul_f32_e32 v68, 0x3d372713, v63
	v_mul_f32_e32 v68, v63, v68
	v_fma_f32 v68, v63, v68, v63
	v_mul_f32_e32 v68, 0xbfcc422a, v68
	v_mul_f32_e32 v68, 0x3fb8aa3b, v68
	v_exp_f32_e32 v68, v68
	s_nop 0
	v_add_f32_e32 v68, 1.0, v68
	v_rcp_f32_e32 v68, v68
	s_nop 0
	v_mul_f32_e32 v63, v63, v68
	v_mul_f32_e32 v68, 0x3d372713, v64
	v_mul_f32_e32 v68, v64, v68
	v_fma_f32 v68, v64, v68, v64
	v_mul_f32_e32 v68, 0xbfcc422a, v68
	v_mul_f32_e32 v68, 0x3fb8aa3b, v68
	v_exp_f32_e32 v68, v68
	v_cvt_pk_bf16_f32 v62, v62, v63
	v_add_f32_e32 v68, 1.0, v68
	v_rcp_f32_e32 v68, v68
	s_nop 0
	v_mul_f32_e32 v64, v64, v68
	v_mul_f32_e32 v68, 0x3d372713, v65
	v_mul_f32_e32 v68, v65, v68
	v_fma_f32 v68, v65, v68, v65
	v_mul_f32_e32 v68, 0xbfcc422a, v68
	v_mul_f32_e32 v68, 0x3fb8aa3b, v68
	v_exp_f32_e32 v68, v68
	s_nop 0
	v_add_f32_e32 v68, 1.0, v68
	v_rcp_f32_e32 v68, v68
	s_nop 0
	v_mul_f32_e32 v65, v65, v68
	v_cvt_pk_bf16_f32 v63, v64, v65
	global_store_dwordx2 v[66:67], v[62:63], off
	v_mul_f32_e32 v62, 0x3d372713, v58
	v_mul_f32_e32 v62, v58, v62
	v_fma_f32 v62, v58, v62, v58
	v_mul_f32_e32 v62, 0xbfcc422a, v62
	v_mul_f32_e32 v62, 0x3fb8aa3b, v62
	v_exp_f32_e32 v62, v62
	s_nop 0
	v_add_f32_e32 v62, 1.0, v62
	v_rcp_f32_e32 v62, v62
	s_nop 0
	v_mul_f32_e32 v58, v58, v62
	v_mul_f32_e32 v62, 0x3d372713, v59
	v_mul_f32_e32 v62, v59, v62
	v_fma_f32 v62, v59, v62, v59
	v_mul_f32_e32 v62, 0xbfcc422a, v62
	v_mul_f32_e32 v62, 0x3fb8aa3b, v62
	v_exp_f32_e32 v62, v62
	s_nop 0
	v_add_f32_e32 v62, 1.0, v62
	v_rcp_f32_e32 v62, v62
	s_nop 0
	v_mul_f32_e32 v59, v59, v62
	v_mul_f32_e32 v62, 0x3d372713, v60
	v_mul_f32_e32 v62, v60, v62
	v_fma_f32 v62, v60, v62, v60
	v_mul_f32_e32 v62, 0xbfcc422a, v62
	v_mul_f32_e32 v62, 0x3fb8aa3b, v62
	v_exp_f32_e32 v62, v62
	v_cvt_pk_bf16_f32 v58, v58, v59
	v_add_f32_e32 v62, 1.0, v62
	v_rcp_f32_e32 v62, v62
	s_nop 0
	v_mul_f32_e32 v60, v60, v62
	v_mul_f32_e32 v62, 0x3d372713, v61
	v_mul_f32_e32 v62, v61, v62
	v_fma_f32 v62, v61, v62, v61
	v_mul_f32_e32 v62, 0xbfcc422a, v62
	v_mul_f32_e32 v62, 0x3fb8aa3b, v62
	v_exp_f32_e32 v62, v62
	s_nop 0
	v_add_f32_e32 v62, 1.0, v62
	v_rcp_f32_e32 v62, v62
	s_nop 0
	v_mul_f32_e32 v61, v61, v62
	v_cvt_pk_bf16_f32 v59, v60, v61
	global_store_dwordx2 v[66:67], v[58:59], off offset:32
	v_mul_f32_e32 v58, 0x3d372713, v54
	v_mul_f32_e32 v58, v54, v58
	v_fma_f32 v58, v54, v58, v54
	v_mul_f32_e32 v58, 0xbfcc422a, v58
	v_mul_f32_e32 v58, 0x3fb8aa3b, v58
	v_exp_f32_e32 v58, v58
	s_nop 0
	v_add_f32_e32 v58, 1.0, v58
	v_rcp_f32_e32 v58, v58
	s_nop 0
	v_mul_f32_e32 v54, v54, v58
	v_mul_f32_e32 v58, 0x3d372713, v55
	v_mul_f32_e32 v58, v55, v58
	v_fma_f32 v58, v55, v58, v55
	v_mul_f32_e32 v58, 0xbfcc422a, v58
	v_mul_f32_e32 v58, 0x3fb8aa3b, v58
	v_exp_f32_e32 v58, v58
	s_nop 0
	v_add_f32_e32 v58, 1.0, v58
	v_rcp_f32_e32 v58, v58
	s_nop 0
	v_mul_f32_e32 v55, v55, v58
	v_mul_f32_e32 v58, 0x3d372713, v56
	v_mul_f32_e32 v58, v56, v58
	v_fma_f32 v58, v56, v58, v56
	v_mul_f32_e32 v58, 0xbfcc422a, v58
	v_mul_f32_e32 v58, 0x3fb8aa3b, v58
	v_exp_f32_e32 v58, v58
	v_cvt_pk_bf16_f32 v54, v54, v55
	v_add_f32_e32 v58, 1.0, v58
	v_rcp_f32_e32 v58, v58
	s_nop 0
	v_mul_f32_e32 v56, v56, v58
	v_mul_f32_e32 v58, 0x3d372713, v57
	v_mul_f32_e32 v58, v57, v58
	v_fma_f32 v58, v57, v58, v57
	v_mul_f32_e32 v58, 0xbfcc422a, v58
;     __device__ __forceinline__ void operator()(Acc& acc, int pm, int pn, int wr, int wc, int fr, int fq) const {
;     ...
;         for (int ai = 0; ai < 2; ++ai)
; #pragma unroll
;             for (int m = 0; m < 4; ++m) {
;                 const size_t ro = (size_t)(pm * 256 + ai * 128 + wr * 64 + m * 16 + fr) * DRNN + cb;
; #pragma unroll
;                 for (int bj = 0; bj < 2; ++bj)
; #pragma unroll
;                     for (int n = 0; n < 2; ++n) {
;                         f32x4 v = acc[ai][bj][m][n];
;                         if (isg) { v[0] = gelu_tanh(v[0]); v[1] = gelu_tanh(v[1]); v[2] = gelu_tanh(v[2]); v[3] = gelu_tanh(v[3]); }
;                         u32x2 o = {pack2(v[0], v[1]), pack2(v[2], v[3])};
;                         *reinterpret_cast<u32x2*>(base + ro + bj * 128 + n * 16) = o;
;                     }
	v_mul_f32_e32 v58, 0x3fb8aa3b, v58
	v_exp_f32_e32 v58, v58
	s_nop 0
	v_add_f32_e32 v58, 1.0, v58
	v_rcp_f32_e32 v58, v58
	s_nop 0
	v_mul_f32_e32 v57, v57, v58
	v_cvt_pk_bf16_f32 v55, v56, v57
	global_store_dwordx2 v[66:67], v[54:55], off offset:256
	v_mul_f32_e32 v54, 0x3d372713, v50
	v_mul_f32_e32 v54, v50, v54
	v_fma_f32 v54, v50, v54, v50
	v_mul_f32_e32 v54, 0xbfcc422a, v54
	v_mul_f32_e32 v54, 0x3fb8aa3b, v54
	v_exp_f32_e32 v54, v54
	s_nop 0
	v_add_f32_e32 v54, 1.0, v54
	v_rcp_f32_e32 v54, v54
	s_nop 0
	v_mul_f32_e32 v50, v50, v54
	v_mul_f32_e32 v54, 0x3d372713, v51
	v_mul_f32_e32 v54, v51, v54
	v_fma_f32 v54, v51, v54, v51
	v_mul_f32_e32 v54, 0xbfcc422a, v54
	v_mul_f32_e32 v54, 0x3fb8aa3b, v54
	v_exp_f32_e32 v54, v54
	s_nop 0
	v_add_f32_e32 v54, 1.0, v54
	v_rcp_f32_e32 v54, v54
	s_nop 0
	v_mul_f32_e32 v51, v51, v54
	v_mul_f32_e32 v54, 0x3d372713, v52
	v_mul_f32_e32 v54, v52, v54
	v_fma_f32 v54, v52, v54, v52
	v_mul_f32_e32 v54, 0xbfcc422a, v54
	v_mul_f32_e32 v54, 0x3fb8aa3b, v54
	v_exp_f32_e32 v54, v54
	v_cvt_pk_bf16_f32 v50, v50, v51
	v_add_f32_e32 v54, 1.0, v54
	v_rcp_f32_e32 v54, v54
	s_nop 0
	v_mul_f32_e32 v52, v52, v54
	v_mul_f32_e32 v54, 0x3d372713, v53
	v_mul_f32_e32 v54, v53, v54
	v_fma_f32 v54, v53, v54, v53
	v_mul_f32_e32 v54, 0xbfcc422a, v54
	v_mul_f32_e32 v54, 0x3fb8aa3b, v54
	v_exp_f32_e32 v54, v54
	s_nop 0
	v_add_f32_e32 v54, 1.0, v54
	v_rcp_f32_e32 v54, v54
	s_nop 0
	v_mul_f32_e32 v53, v53, v54
	v_cvt_pk_bf16_f32 v51, v52, v53
	v_mul_f32_e32 v52, 0x3d372713, v46
	v_mul_f32_e32 v52, v46, v52
	v_fma_f32 v52, v46, v52, v46
	v_mul_f32_e32 v52, 0xbfcc422a, v52
	v_mul_f32_e32 v52, 0x3fb8aa3b, v52
	v_exp_f32_e32 v52, v52
	global_store_dwordx2 v[66:67], v[50:51], off offset:288
	v_add_u32_e32 v50, 0x90, v161
	v_mad_i64_i32 v[50:51], s[10:11], v50, s73, v[154:155]
	v_add_f32_e32 v52, 1.0, v52
	v_rcp_f32_e32 v52, v52
	s_nop 0
	v_mul_f32_e32 v46, v46, v52
	v_mul_f32_e32 v52, 0x3d372713, v47
	v_mul_f32_e32 v52, v47, v52
	v_fma_f32 v52, v47, v52, v47
	v_mul_f32_e32 v52, 0xbfcc422a, v52
	v_mul_f32_e32 v52, 0x3fb8aa3b, v52
	v_exp_f32_e32 v52, v52
	s_nop 0
	v_add_f32_e32 v52, 1.0, v52
	v_rcp_f32_e32 v52, v52
	s_nop 0
	v_mul_f32_e32 v47, v47, v52
	v_mul_f32_e32 v52, 0x3d372713, v48
	v_mul_f32_e32 v52, v48, v52
	v_fma_f32 v52, v48, v52, v48
	v_mul_f32_e32 v52, 0xbfcc422a, v52
	v_mul_f32_e32 v52, 0x3fb8aa3b, v52
	v_exp_f32_e32 v52, v52
	v_cvt_pk_bf16_f32 v46, v46, v47
	v_add_f32_e32 v52, 1.0, v52
	v_rcp_f32_e32 v52, v52
	s_nop 0
	v_mul_f32_e32 v48, v48, v52
	v_mul_f32_e32 v52, 0x3d372713, v49
	v_mul_f32_e32 v52, v49, v52
	v_fma_f32 v52, v49, v52, v49
	v_mul_f32_e32 v52, 0xbfcc422a, v52
	v_mul_f32_e32 v52, 0x3fb8aa3b, v52
	v_exp_f32_e32 v52, v52
	s_nop 0
	v_add_f32_e32 v52, 1.0, v52
	v_rcp_f32_e32 v52, v52
	s_nop 0
	v_mul_f32_e32 v49, v49, v52
	v_cvt_pk_bf16_f32 v47, v48, v49
	global_store_dwordx2 v[50:51], v[46:47], off
	v_mul_f32_e32 v46, 0x3d372713, v42
	v_mul_f32_e32 v46, v42, v46
	v_fma_f32 v46, v42, v46, v42
	v_mul_f32_e32 v46, 0xbfcc422a, v46
	v_mul_f32_e32 v46, 0x3fb8aa3b, v46
	v_exp_f32_e32 v46, v46
	s_nop 0
	v_add_f32_e32 v46, 1.0, v46
	v_rcp_f32_e32 v46, v46
	s_nop 0
	v_mul_f32_e32 v42, v42, v46
	v_mul_f32_e32 v46, 0x3d372713, v43
	v_mul_f32_e32 v46, v43, v46
	v_fma_f32 v46, v43, v46, v43
	v_mul_f32_e32 v46, 0xbfcc422a, v46
	v_mul_f32_e32 v46, 0x3fb8aa3b, v46
	v_exp_f32_e32 v46, v46
	s_nop 0
	v_add_f32_e32 v46, 1.0, v46
	v_rcp_f32_e32 v46, v46
	s_nop 0
	v_mul_f32_e32 v43, v43, v46
	v_mul_f32_e32 v46, 0x3d372713, v44
	v_mul_f32_e32 v46, v44, v46
	v_fma_f32 v46, v44, v46, v44
	v_mul_f32_e32 v46, 0xbfcc422a, v46
	v_mul_f32_e32 v46, 0x3fb8aa3b, v46
	v_exp_f32_e32 v46, v46
	v_cvt_pk_bf16_f32 v42, v42, v43
	v_add_f32_e32 v46, 1.0, v46
	v_rcp_f32_e32 v46, v46
	s_nop 0
	v_mul_f32_e32 v44, v44, v46
	v_mul_f32_e32 v46, 0x3d372713, v45
	v_mul_f32_e32 v46, v45, v46
	v_fma_f32 v46, v45, v46, v45
	v_mul_f32_e32 v46, 0xbfcc422a, v46
	v_mul_f32_e32 v46, 0x3fb8aa3b, v46
	v_exp_f32_e32 v46, v46
	s_nop 0
	v_add_f32_e32 v46, 1.0, v46
	v_rcp_f32_e32 v46, v46
	s_nop 0
	v_mul_f32_e32 v45, v45, v46
	v_cvt_pk_bf16_f32 v43, v44, v45
	global_store_dwordx2 v[50:51], v[42:43], off offset:32
	v_mul_f32_e32 v42, 0x3d372713, v38
	v_mul_f32_e32 v42, v38, v42
	v_fma_f32 v42, v38, v42, v38
	v_mul_f32_e32 v42, 0xbfcc422a, v42
	v_mul_f32_e32 v42, 0x3fb8aa3b, v42
	v_exp_f32_e32 v42, v42
	s_nop 0
	v_add_f32_e32 v42, 1.0, v42
	v_rcp_f32_e32 v42, v42
	s_nop 0
	v_mul_f32_e32 v38, v38, v42
	v_mul_f32_e32 v42, 0x3d372713, v39
	v_mul_f32_e32 v42, v39, v42
	v_fma_f32 v42, v39, v42, v39
	v_mul_f32_e32 v42, 0xbfcc422a, v42
	v_mul_f32_e32 v42, 0x3fb8aa3b, v42
	v_exp_f32_e32 v42, v42
	s_nop 0
	v_add_f32_e32 v42, 1.0, v42
	v_rcp_f32_e32 v42, v42
	s_nop 0
	v_mul_f32_e32 v39, v39, v42
	v_mul_f32_e32 v42, 0x3d372713, v40
	v_mul_f32_e32 v42, v40, v42
	v_fma_f32 v42, v40, v42, v40
	v_mul_f32_e32 v42, 0xbfcc422a, v42
	v_mul_f32_e32 v42, 0x3fb8aa3b, v42
	v_exp_f32_e32 v42, v42
	v_cvt_pk_bf16_f32 v38, v38, v39
	v_add_f32_e32 v42, 1.0, v42
	v_rcp_f32_e32 v42, v42
	s_nop 0
	v_mul_f32_e32 v40, v40, v42
	v_mul_f32_e32 v42, 0x3d372713, v41
	v_mul_f32_e32 v42, v41, v42
	v_fma_f32 v42, v41, v42, v41
	v_mul_f32_e32 v42, 0xbfcc422a, v42
	v_mul_f32_e32 v42, 0x3fb8aa3b, v42
	v_exp_f32_e32 v42, v42
	s_nop 0
	v_add_f32_e32 v42, 1.0, v42
	v_rcp_f32_e32 v42, v42
	s_nop 0
	v_mul_f32_e32 v41, v41, v42
	v_cvt_pk_bf16_f32 v39, v40, v41
	global_store_dwordx2 v[50:51], v[38:39], off offset:256
	v_mul_f32_e32 v38, 0x3d372713, v34
	v_mul_f32_e32 v38, v34, v38
	v_fma_f32 v38, v34, v38, v34
	v_mul_f32_e32 v38, 0xbfcc422a, v38
	v_mul_f32_e32 v38, 0x3fb8aa3b, v38
	v_exp_f32_e32 v38, v38
	s_nop 0
;     __device__ __forceinline__ void operator()(Acc& acc, int pm, int pn, int wr, int wc, int fr, int fq) const {
;     ...
;         for (int ai = 0; ai < 2; ++ai)
; #pragma unroll
;             for (int m = 0; m < 4; ++m) {
;                 const size_t ro = (size_t)(pm * 256 + ai * 128 + wr * 64 + m * 16 + fr) * DRNN + cb;
; #pragma unroll
;                 for (int bj = 0; bj < 2; ++bj)
; #pragma unroll
;                     for (int n = 0; n < 2; ++n) {
;                         f32x4 v = acc[ai][bj][m][n];
;                         if (isg) { v[0] = gelu_tanh(v[0]); v[1] = gelu_tanh(v[1]); v[2] = gelu_tanh(v[2]); v[3] = gelu_tanh(v[3]); }
;                         u32x2 o = {pack2(v[0], v[1]), pack2(v[2], v[3])};
;                         *reinterpret_cast<u32x2*>(base + ro + bj * 128 + n * 16) = o;
;                     }
	v_add_f32_e32 v38, 1.0, v38
	v_rcp_f32_e32 v38, v38
	s_nop 0
	v_mul_f32_e32 v34, v34, v38
	v_mul_f32_e32 v38, 0x3d372713, v35
	v_mul_f32_e32 v38, v35, v38
	v_fma_f32 v38, v35, v38, v35
	v_mul_f32_e32 v38, 0xbfcc422a, v38
	v_mul_f32_e32 v38, 0x3fb8aa3b, v38
	v_exp_f32_e32 v38, v38
	s_nop 0
	v_add_f32_e32 v38, 1.0, v38
	v_rcp_f32_e32 v38, v38
	s_nop 0
	v_mul_f32_e32 v35, v35, v38
	v_mul_f32_e32 v38, 0x3d372713, v36
	v_mul_f32_e32 v38, v36, v38
	v_fma_f32 v38, v36, v38, v36
	v_mul_f32_e32 v38, 0xbfcc422a, v38
	v_mul_f32_e32 v38, 0x3fb8aa3b, v38
	v_exp_f32_e32 v38, v38
	v_cvt_pk_bf16_f32 v34, v34, v35
	v_add_f32_e32 v38, 1.0, v38
	v_rcp_f32_e32 v38, v38
	s_nop 0
	v_mul_f32_e32 v36, v36, v38
	v_mul_f32_e32 v38, 0x3d372713, v37
	v_mul_f32_e32 v38, v37, v38
	v_fma_f32 v38, v37, v38, v37
	v_mul_f32_e32 v38, 0xbfcc422a, v38
	v_mul_f32_e32 v38, 0x3fb8aa3b, v38
	v_exp_f32_e32 v38, v38
	s_nop 0
	v_add_f32_e32 v38, 1.0, v38
	v_rcp_f32_e32 v38, v38
	s_nop 0
	v_mul_f32_e32 v37, v37, v38
	v_cvt_pk_bf16_f32 v35, v36, v37
	v_mul_f32_e32 v36, 0x3d372713, v30
	v_mul_f32_e32 v36, v30, v36
	v_fma_f32 v36, v30, v36, v30
	v_mul_f32_e32 v36, 0xbfcc422a, v36
	v_mul_f32_e32 v36, 0x3fb8aa3b, v36
	v_exp_f32_e32 v36, v36
	global_store_dwordx2 v[50:51], v[34:35], off offset:288
	v_add_u32_e32 v34, 0xa0, v161
	v_mad_i64_i32 v[34:35], s[10:11], v34, s73, v[154:155]
	v_add_f32_e32 v36, 1.0, v36
	v_rcp_f32_e32 v36, v36
	s_nop 0
	v_mul_f32_e32 v30, v30, v36
	v_mul_f32_e32 v36, 0x3d372713, v31
	v_mul_f32_e32 v36, v31, v36
	v_fma_f32 v36, v31, v36, v31
	v_mul_f32_e32 v36, 0xbfcc422a, v36
	v_mul_f32_e32 v36, 0x3fb8aa3b, v36
	v_exp_f32_e32 v36, v36
	s_nop 0
	v_add_f32_e32 v36, 1.0, v36
	v_rcp_f32_e32 v36, v36
	s_nop 0
	v_mul_f32_e32 v31, v31, v36
	v_mul_f32_e32 v36, 0x3d372713, v32
	v_mul_f32_e32 v36, v32, v36
	v_fma_f32 v36, v32, v36, v32
	v_mul_f32_e32 v36, 0xbfcc422a, v36
	v_mul_f32_e32 v36, 0x3fb8aa3b, v36
	v_exp_f32_e32 v36, v36
	v_cvt_pk_bf16_f32 v30, v30, v31
	v_add_f32_e32 v36, 1.0, v36
	v_rcp_f32_e32 v36, v36
	s_nop 0
	v_mul_f32_e32 v32, v32, v36
	v_mul_f32_e32 v36, 0x3d372713, v33
	v_mul_f32_e32 v36, v33, v36
	v_fma_f32 v36, v33, v36, v33
	v_mul_f32_e32 v36, 0xbfcc422a, v36
	v_mul_f32_e32 v36, 0x3fb8aa3b, v36
	v_exp_f32_e32 v36, v36
	s_nop 0
	v_add_f32_e32 v36, 1.0, v36
	v_rcp_f32_e32 v36, v36
	s_nop 0
	v_mul_f32_e32 v33, v33, v36
	v_cvt_pk_bf16_f32 v31, v32, v33
	global_store_dwordx2 v[34:35], v[30:31], off
	v_mul_f32_e32 v30, 0x3d372713, v26
	v_mul_f32_e32 v30, v26, v30
	v_fma_f32 v30, v26, v30, v26
	v_mul_f32_e32 v30, 0xbfcc422a, v30
	v_mul_f32_e32 v30, 0x3fb8aa3b, v30
	v_exp_f32_e32 v30, v30
	s_nop 0
	v_add_f32_e32 v30, 1.0, v30
	v_rcp_f32_e32 v30, v30
	s_nop 0
	v_mul_f32_e32 v26, v26, v30
	v_mul_f32_e32 v30, 0x3d372713, v27
	v_mul_f32_e32 v30, v27, v30
	v_fma_f32 v30, v27, v30, v27
	v_mul_f32_e32 v30, 0xbfcc422a, v30
	v_mul_f32_e32 v30, 0x3fb8aa3b, v30
	v_exp_f32_e32 v30, v30
	s_nop 0
	v_add_f32_e32 v30, 1.0, v30
	v_rcp_f32_e32 v30, v30
	s_nop 0
	v_mul_f32_e32 v27, v27, v30
	v_mul_f32_e32 v30, 0x3d372713, v28
	v_mul_f32_e32 v30, v28, v30
	v_fma_f32 v30, v28, v30, v28
	v_mul_f32_e32 v30, 0xbfcc422a, v30
	v_mul_f32_e32 v30, 0x3fb8aa3b, v30
	v_exp_f32_e32 v30, v30
	v_cvt_pk_bf16_f32 v26, v26, v27
	v_add_f32_e32 v30, 1.0, v30
	v_rcp_f32_e32 v30, v30
	s_nop 0
	v_mul_f32_e32 v28, v28, v30
	v_mul_f32_e32 v30, 0x3d372713, v29
	v_mul_f32_e32 v30, v29, v30
	v_fma_f32 v30, v29, v30, v29
	v_mul_f32_e32 v30, 0xbfcc422a, v30
	v_mul_f32_e32 v30, 0x3fb8aa3b, v30
	v_exp_f32_e32 v30, v30
	s_nop 0
	v_add_f32_e32 v30, 1.0, v30
	v_rcp_f32_e32 v30, v30
	s_nop 0
	v_mul_f32_e32 v29, v29, v30
	v_cvt_pk_bf16_f32 v27, v28, v29
	global_store_dwordx2 v[34:35], v[26:27], off offset:32
	v_mul_f32_e32 v26, 0x3d372713, v22
	v_mul_f32_e32 v26, v22, v26
	v_fma_f32 v26, v22, v26, v22
	v_mul_f32_e32 v26, 0xbfcc422a, v26
	v_mul_f32_e32 v26, 0x3fb8aa3b, v26
	v_exp_f32_e32 v26, v26
	s_nop 0
	v_add_f32_e32 v26, 1.0, v26
	v_rcp_f32_e32 v26, v26
	s_nop 0
	v_mul_f32_e32 v22, v22, v26
	v_mul_f32_e32 v26, 0x3d372713, v23
	v_mul_f32_e32 v26, v23, v26
	v_fma_f32 v26, v23, v26, v23
	v_mul_f32_e32 v26, 0xbfcc422a, v26
	v_mul_f32_e32 v26, 0x3fb8aa3b, v26
	v_exp_f32_e32 v26, v26
	s_nop 0
	v_add_f32_e32 v26, 1.0, v26
	v_rcp_f32_e32 v26, v26
	s_nop 0
	v_mul_f32_e32 v23, v23, v26
	v_mul_f32_e32 v26, 0x3d372713, v24
	v_mul_f32_e32 v26, v24, v26
	v_fma_f32 v26, v24, v26, v24
	v_mul_f32_e32 v26, 0xbfcc422a, v26
	v_mul_f32_e32 v26, 0x3fb8aa3b, v26
	v_exp_f32_e32 v26, v26
	v_cvt_pk_bf16_f32 v22, v22, v23
	v_add_f32_e32 v26, 1.0, v26
	v_rcp_f32_e32 v26, v26
	s_nop 0
	v_mul_f32_e32 v24, v24, v26
	v_mul_f32_e32 v26, 0x3d372713, v25
	v_mul_f32_e32 v26, v25, v26
	v_fma_f32 v26, v25, v26, v25
	v_mul_f32_e32 v26, 0xbfcc422a, v26
	v_mul_f32_e32 v26, 0x3fb8aa3b, v26
	v_exp_f32_e32 v26, v26
	s_nop 0
	v_add_f32_e32 v26, 1.0, v26
	v_rcp_f32_e32 v26, v26
	s_nop 0
	v_mul_f32_e32 v25, v25, v26
	v_cvt_pk_bf16_f32 v23, v24, v25
	global_store_dwordx2 v[34:35], v[22:23], off offset:256
	v_mul_f32_e32 v22, 0x3d372713, v18
	v_mul_f32_e32 v22, v18, v22
	v_fma_f32 v22, v18, v22, v18
	v_mul_f32_e32 v22, 0xbfcc422a, v22
	v_mul_f32_e32 v22, 0x3fb8aa3b, v22
	v_exp_f32_e32 v22, v22
	s_nop 0
	v_add_f32_e32 v22, 1.0, v22
	v_rcp_f32_e32 v22, v22
	s_nop 0
	v_mul_f32_e32 v18, v18, v22
	v_mul_f32_e32 v22, 0x3d372713, v19
	v_mul_f32_e32 v22, v19, v22
	v_fma_f32 v22, v19, v22, v19
	v_mul_f32_e32 v22, 0xbfcc422a, v22
	v_mul_f32_e32 v22, 0x3fb8aa3b, v22
	v_exp_f32_e32 v22, v22
	s_nop 0
	v_add_f32_e32 v22, 1.0, v22
	v_rcp_f32_e32 v22, v22
	s_nop 0
	v_mul_f32_e32 v19, v19, v22
	v_mul_f32_e32 v22, 0x3d372713, v20
	v_mul_f32_e32 v22, v20, v22
; #define PG8_WAIT_V(n) asm volatile("s_waitcnt vmcnt(" #n ")" ::: "memory")
; #define PG8_BAR __builtin_amdgcn_s_barrier()
;     ...
;         if (!has_next) break;
;     ...
;     PG8_WAIT_V(0);
;     if (wr == 0) PG8_BAR;
;     PG8_BAR;
;     __device__ __forceinline__ void operator()(Acc& acc, int pm, int pn, int wr, int wc, int fr, int fq) const {
;     ...
;         for (int ai = 0; ai < 2; ++ai)
; #pragma unroll
;             for (int m = 0; m < 4; ++m) {
;                 const size_t ro = (size_t)(pm * 256 + ai * 128 + wr * 64 + m * 16 + fr) * DRNN + cb;
; #pragma unroll
;                 for (int bj = 0; bj < 2; ++bj)
; #pragma unroll
;                     for (int n = 0; n < 2; ++n) {
;                         f32x4 v = acc[ai][bj][m][n];
;                         if (isg) { v[0] = gelu_tanh(v[0]); v[1] = gelu_tanh(v[1]); v[2] = gelu_tanh(v[2]); v[3] = gelu_tanh(v[3]); }
;                         u32x2 o = {pack2(v[0], v[1]), pack2(v[2], v[3])};
;                         *reinterpret_cast<u32x2*>(base + ro + bj * 128 + n * 16) = o;
;                     }
	v_fma_f32 v22, v20, v22, v20
	v_mul_f32_e32 v22, 0xbfcc422a, v22
	v_mul_f32_e32 v22, 0x3fb8aa3b, v22
	v_exp_f32_e32 v22, v22
	v_cvt_pk_bf16_f32 v18, v18, v19
	v_add_f32_e32 v22, 1.0, v22
	v_rcp_f32_e32 v22, v22
	s_nop 0
	v_mul_f32_e32 v20, v20, v22
	v_mul_f32_e32 v22, 0x3d372713, v21
	v_mul_f32_e32 v22, v21, v22
	v_fma_f32 v22, v21, v22, v21
	v_mul_f32_e32 v22, 0xbfcc422a, v22
	v_mul_f32_e32 v22, 0x3fb8aa3b, v22
	v_exp_f32_e32 v22, v22
	s_nop 0
	v_add_f32_e32 v22, 1.0, v22
	v_rcp_f32_e32 v22, v22
	s_nop 0
	v_mul_f32_e32 v21, v21, v22
	v_cvt_pk_bf16_f32 v19, v20, v21
	v_mul_f32_e32 v20, 0x3d372713, v14
	v_mul_f32_e32 v20, v14, v20
	v_fma_f32 v20, v14, v20, v14
	v_mul_f32_e32 v20, 0xbfcc422a, v20
	v_mul_f32_e32 v20, 0x3fb8aa3b, v20
	v_exp_f32_e32 v20, v20
	global_store_dwordx2 v[34:35], v[18:19], off offset:288
	v_add_u32_e32 v18, 0xb0, v161
	v_mad_i64_i32 v[18:19], s[10:11], v18, s73, v[154:155]
	v_add_f32_e32 v20, 1.0, v20
	v_rcp_f32_e32 v20, v20
	s_mov_b64 s[10:11], s[62:63]
	v_mul_f32_e32 v14, v14, v20
	v_mul_f32_e32 v20, 0x3d372713, v15
	v_mul_f32_e32 v20, v15, v20
	v_fma_f32 v20, v15, v20, v15
	v_mul_f32_e32 v20, 0xbfcc422a, v20
	v_mul_f32_e32 v20, 0x3fb8aa3b, v20
	v_exp_f32_e32 v20, v20
	s_nop 0
	v_add_f32_e32 v20, 1.0, v20
	v_rcp_f32_e32 v20, v20
	s_nop 0
	v_mul_f32_e32 v15, v15, v20
	v_mul_f32_e32 v20, 0x3d372713, v16
	v_mul_f32_e32 v20, v16, v20
	v_fma_f32 v20, v16, v20, v16
	v_mul_f32_e32 v20, 0xbfcc422a, v20
	v_mul_f32_e32 v20, 0x3fb8aa3b, v20
	v_exp_f32_e32 v20, v20
	v_cvt_pk_bf16_f32 v14, v14, v15
	v_add_f32_e32 v20, 1.0, v20
	v_rcp_f32_e32 v20, v20
	s_nop 0
	v_mul_f32_e32 v16, v16, v20
	v_mul_f32_e32 v20, 0x3d372713, v17
	v_mul_f32_e32 v20, v17, v20
	v_fma_f32 v20, v17, v20, v17
	v_mul_f32_e32 v20, 0xbfcc422a, v20
	v_mul_f32_e32 v20, 0x3fb8aa3b, v20
	v_exp_f32_e32 v20, v20
	s_nop 0
	v_add_f32_e32 v20, 1.0, v20
	v_rcp_f32_e32 v20, v20
	s_nop 0
	v_mul_f32_e32 v17, v17, v20
	v_cvt_pk_bf16_f32 v15, v16, v17
	global_store_dwordx2 v[18:19], v[14:15], off
	v_mul_f32_e32 v14, 0x3d372713, v10
	v_mul_f32_e32 v14, v10, v14
	v_fma_f32 v14, v10, v14, v10
	v_mul_f32_e32 v14, 0xbfcc422a, v14
	v_mul_f32_e32 v14, 0x3fb8aa3b, v14
	v_exp_f32_e32 v14, v14
	s_nop 0
	v_add_f32_e32 v14, 1.0, v14
	v_rcp_f32_e32 v14, v14
	s_nop 0
	v_mul_f32_e32 v10, v10, v14
	v_mul_f32_e32 v14, 0x3d372713, v11
	v_mul_f32_e32 v14, v11, v14
	v_fma_f32 v14, v11, v14, v11
	v_mul_f32_e32 v14, 0xbfcc422a, v14
	v_mul_f32_e32 v14, 0x3fb8aa3b, v14
	v_exp_f32_e32 v14, v14
	s_nop 0
	v_add_f32_e32 v14, 1.0, v14
	v_rcp_f32_e32 v14, v14
	s_nop 0
	v_mul_f32_e32 v11, v11, v14
	v_mul_f32_e32 v14, 0x3d372713, v12
	v_mul_f32_e32 v14, v12, v14
	v_fma_f32 v14, v12, v14, v12
	v_mul_f32_e32 v14, 0xbfcc422a, v14
	v_mul_f32_e32 v14, 0x3fb8aa3b, v14
	v_exp_f32_e32 v14, v14
	v_cvt_pk_bf16_f32 v10, v10, v11
	v_add_f32_e32 v14, 1.0, v14
	v_rcp_f32_e32 v14, v14
	s_nop 0
	v_mul_f32_e32 v12, v12, v14
	v_mul_f32_e32 v14, 0x3d372713, v13
	v_mul_f32_e32 v14, v13, v14
	v_fma_f32 v14, v13, v14, v13
	v_mul_f32_e32 v14, 0xbfcc422a, v14
	v_mul_f32_e32 v14, 0x3fb8aa3b, v14
	v_exp_f32_e32 v14, v14
	s_nop 0
	v_add_f32_e32 v14, 1.0, v14
	v_rcp_f32_e32 v14, v14
	s_nop 0
	v_mul_f32_e32 v13, v13, v14
	v_cvt_pk_bf16_f32 v11, v12, v13
	global_store_dwordx2 v[18:19], v[10:11], off offset:32
	v_mul_f32_e32 v10, 0x3d372713, v6
	v_mul_f32_e32 v10, v6, v10
	v_fma_f32 v10, v6, v10, v6
	v_mul_f32_e32 v10, 0xbfcc422a, v10
	v_mul_f32_e32 v10, 0x3fb8aa3b, v10
	v_exp_f32_e32 v10, v10
	s_nop 0
	v_add_f32_e32 v10, 1.0, v10
	v_rcp_f32_e32 v10, v10
	s_nop 0
	v_mul_f32_e32 v6, v6, v10
	v_mul_f32_e32 v10, 0x3d372713, v7
	v_mul_f32_e32 v10, v7, v10
	v_fma_f32 v10, v7, v10, v7
	v_mul_f32_e32 v10, 0xbfcc422a, v10
	v_mul_f32_e32 v10, 0x3fb8aa3b, v10
	v_exp_f32_e32 v10, v10
	s_nop 0
	v_add_f32_e32 v10, 1.0, v10
	v_rcp_f32_e32 v10, v10
	s_nop 0
	v_mul_f32_e32 v7, v7, v10
	v_mul_f32_e32 v10, 0x3d372713, v8
	v_mul_f32_e32 v10, v8, v10
	v_fma_f32 v10, v8, v10, v8
	v_mul_f32_e32 v10, 0xbfcc422a, v10
	v_mul_f32_e32 v10, 0x3fb8aa3b, v10
	v_exp_f32_e32 v10, v10
	v_cvt_pk_bf16_f32 v6, v6, v7
	v_add_f32_e32 v10, 1.0, v10
	v_rcp_f32_e32 v10, v10
	s_nop 0
	v_mul_f32_e32 v8, v8, v10
	v_mul_f32_e32 v10, 0x3d372713, v9
	v_mul_f32_e32 v10, v9, v10
	v_fma_f32 v10, v9, v10, v9
	v_mul_f32_e32 v10, 0xbfcc422a, v10
	v_mul_f32_e32 v10, 0x3fb8aa3b, v10
	v_exp_f32_e32 v10, v10
	s_nop 0
	v_add_f32_e32 v10, 1.0, v10
	v_rcp_f32_e32 v10, v10
	s_nop 0
	v_mul_f32_e32 v9, v9, v10
	v_cvt_pk_bf16_f32 v7, v8, v9
	global_store_dwordx2 v[18:19], v[6:7], off offset:256
	v_mul_f32_e32 v6, 0x3d372713, v2
	v_mul_f32_e32 v6, v2, v6
	v_fma_f32 v6, v2, v6, v2
	v_mul_f32_e32 v6, 0xbfcc422a, v6
	v_mul_f32_e32 v6, 0x3fb8aa3b, v6
	v_exp_f32_e32 v6, v6
	s_nop 0
	v_add_f32_e32 v6, 1.0, v6
	v_rcp_f32_e32 v6, v6
	s_nop 0
	v_mul_f32_e32 v2, v2, v6
	v_mul_f32_e32 v6, 0x3d372713, v3
	v_mul_f32_e32 v6, v3, v6
	v_fma_f32 v6, v3, v6, v3
	v_mul_f32_e32 v6, 0xbfcc422a, v6
	v_mul_f32_e32 v6, 0x3fb8aa3b, v6
	v_exp_f32_e32 v6, v6
	s_nop 0
	v_add_f32_e32 v6, 1.0, v6
	v_rcp_f32_e32 v6, v6
	s_nop 0
	v_mul_f32_e32 v3, v3, v6
	v_mul_f32_e32 v6, 0x3d372713, v4
	v_mul_f32_e32 v6, v4, v6
	v_fma_f32 v6, v4, v6, v4
	v_mul_f32_e32 v6, 0xbfcc422a, v6
	v_mul_f32_e32 v6, 0x3fb8aa3b, v6
	v_exp_f32_e32 v6, v6
	v_cvt_pk_bf16_f32 v2, v2, v3
	v_add_f32_e32 v6, 1.0, v6
	v_rcp_f32_e32 v6, v6
	s_nop 0
	v_mul_f32_e32 v4, v4, v6
	v_mul_f32_e32 v6, 0x3d372713, v5
	v_mul_f32_e32 v6, v5, v6
	v_fma_f32 v6, v5, v6, v5
	v_mul_f32_e32 v6, 0xbfcc422a, v6
	v_mul_f32_e32 v6, 0x3fb8aa3b, v6
	v_exp_f32_e32 v6, v6
	s_nop 0
	v_add_f32_e32 v6, 1.0, v6
	v_rcp_f32_e32 v6, v6
	s_nop 0
	v_mul_f32_e32 v5, v5, v6
	v_cvt_pk_bf16_f32 v3, v4, v5
	global_store_dwordx2 v[18:19], v[2:3], off offset:288
	s_cbranch_vccz .LBB0_1048
	s_waitcnt vmcnt(0)
	s_cmpk_gt_u32 s5, 0xff
	s_cbranch_scc1 .LBB0_1055
	s_barrier

; #define PG8_STAGE(bufoff, gbase) do { _Pragma("unroll") for (int _i = 0; _i < 2; ++_i) \
;         __builtin_amdgcn_global_load_lds((const unsigned*)((const char*)(gbase) + voff[_i]), (LAS unsigned*)(lds + (bufoff) + ldsw + _i * 8192), 16, 0, 0); } while (0)
; #define PG8_LDA(dst, b, h) do { _Pragma("unroll") for (int m = 0; m < 4; ++m) _Pragma("unroll") for (int k = 0; k < 2; ++k) dst[m][k] = *(const LAS bf16x8*)(lds + PG8_SA(b, h) + aoff + m * 2048 + k * 1024); } while (0)
; #define PG8_WAIT_V(n) asm volatile("s_waitcnt vmcnt(" #n ")" ::: "memory")
; #define PG8_WAIT_L(n) asm volatile("s_waitcnt lgkmcnt(" #n ")" ::: "memory")
;     ...
;         const bool has_next = S.next(ui + 1, nxt);
;         const char* nA = has_next ? (const char*)gA + (size_t)nxt.pm * tstep : cA; const char* nB = has_next ? (const char*)gBt + (size_t)nxt.pn * tstep : cB;
;         for (int t = 0; t < nt; t += 2) {
;             const bool last = (t == nt - 2);
;             const char* a1 = cA + (size_t)(t + 1) * kstep;
;             const char* a2 = last ? nA : cA + (size_t)(t + 2) * kstep; const char* b2 = last ? nB : cB + (size_t)(t + 2) * kstep;
;             const char* a3 = a2 + kstep; const char* b3 = b2 + kstep;
;             PG8_LDB(B0, 0, 0); PG8_SCHED; PG8_LDA(At, 0, 0); PG8_STAGE(PG8_SA(1, 1), a1 + hstep);
;             PG8_WAIT_L(8); PG8_BAR; PG8_WAIT_L(0); PG8_MMA(0, 0, At, B0); PG8_BAR; PG8_SCHED;
;             PG8_LDB(B1, 0, 1); PG8_STAGE(PG8_SB(0, 0), b2);
;             PG8_BAR; PG8_WAIT_L(0); PG8_MMA(0, 1, At, B1); PG8_BAR;
;             PG8_LDA(At, 0, 1); PG8_STAGE(PG8_SA(0, 0), a2);
;             PG8_BAR; PG8_WAIT_L(0); PG8_MMA(1, 0, At, B0); PG8_BAR; PG8_SCHED;
;             PG8_STAGE(PG8_SB(0, 1), b2 + hstep);
;             PG8_WAIT_V(6); PG8_BAR; PG8_MMA(1, 1, At, B1); PG8_BAR;
;             PG8_LDB(B0, 1, 0); PG8_SCHED; PG8_LDA(At, 1, 0); PG8_STAGE(PG8_SA(0, 1), a2 + hstep);
;             PG8_WAIT_L(8); PG8_BAR; PG8_WAIT_L(0); PG8_MMA(0, 0, At, B0); PG8_BAR; PG8_SCHED;
;             PG8_LDB(B1, 1, 1); PG8_STAGE(PG8_SB(1, 0), b3);
;             PG8_BAR; PG8_WAIT_L(0); PG8_MMA(0, 1, At, B1); PG8_BAR;
;             PG8_LDA(At, 1, 1); PG8_STAGE(PG8_SA(1, 0), a3);
;             PG8_BAR; PG8_WAIT_L(0); PG8_MMA(1, 0, At, B0); PG8_BAR; PG8_SCHED;
;             PG8_STAGE(PG8_SB(1, 1), b3 + hstep);
;             PG8_WAIT_V(6); PG8_BAR; PG8_MMA(1, 1, At, B1); PG8_BAR;
.LBB0_1245:
	s_add_i32 s67, s46, 2
	s_add_u32 s0, s40, 0x80
	s_addc_u32 s1, s41, 0
	s_add_i32 s68, 0, 0x10000
	v_add_u32_e32 v169, s68, v166
	ds_read_b128 v[130:133], v169
	ds_read_b128 v[158:161], v169 offset:1024
	ds_read_b128 v[162:165], v169 offset:2048
	ds_read_b128 v[170:173], v169 offset:3072
	s_cmp_eq_u32 s30, s46
	s_cselect_b32 s46, s12, s0
	s_cselect_b32 s47, s13, s1
	s_cselect_b32 s49, s15, s59
	s_cselect_b32 s48, s14, s58
	v_lshl_add_u64 v[174:175], s[40:41], 0, v[154:155]
	s_add_i32 m0, s23, 0xc000
	ds_read_b128 v[194:197], v168
	ds_read_b128 v[198:201], v168 offset:1024
	ds_read_b128 v[202:205], v168 offset:2048
	ds_read_b128 v[206:209], v168 offset:3072
	ds_read_b128 v[210:213], v168 offset:4096
	ds_read_b128 v[214:217], v168 offset:5120
	ds_read_b128 v[218:221], v168 offset:6144
	ds_read_b128 v[222:225], v168 offset:7168
	global_load_lds_dwordx4 v[174:175], off
	s_add_i32 m0, s23, 0xe000
	v_lshl_add_u64 v[174:175], s[40:41], 0, v[156:157]
	global_load_lds_dwordx4 v[174:175], off
	s_waitcnt lgkmcnt(8)
	s_barrier
	s_waitcnt lgkmcnt(0)
	s_setprio 1
	v_mfma_f32_16x16x32_bf16 v[126:129], v[130:133], v[194:197], v[126:129]
	v_mfma_f32_16x16x32_bf16 v[98:101], v[162:165], v[194:197], v[98:101]
	v_mfma_f32_16x16x32_bf16 v[122:125], v[130:133], v[202:205], v[122:125]
	v_mfma_f32_16x16x32_bf16 v[94:97], v[162:165], v[202:205], v[94:97]
	v_mfma_f32_16x16x32_bf16 v[118:121], v[130:133], v[210:213], v[118:121]
	v_mfma_f32_16x16x32_bf16 v[90:93], v[162:165], v[210:213], v[90:93]
	v_mfma_f32_16x16x32_bf16 v[114:117], v[130:133], v[218:221], v[114:117]
	v_mfma_f32_16x16x32_bf16 v[82:85], v[162:165], v[218:221], v[82:85]
	v_mfma_f32_16x16x32_bf16 v[126:129], v[158:161], v[198:201], v[126:129]
	v_mfma_f32_16x16x32_bf16 v[98:101], v[170:173], v[198:201], v[98:101]
	v_mfma_f32_16x16x32_bf16 v[122:125], v[158:161], v[206:209], v[122:125]
	v_mfma_f32_16x16x32_bf16 v[94:97], v[170:173], v[206:209], v[94:97]
	v_mfma_f32_16x16x32_bf16 v[118:121], v[158:161], v[214:217], v[118:121]
	v_mfma_f32_16x16x32_bf16 v[90:93], v[170:173], v[214:217], v[90:93]
	v_mfma_f32_16x16x32_bf16 v[114:117], v[158:161], v[222:225], v[114:117]
	v_mfma_f32_16x16x32_bf16 v[82:85], v[170:173], v[222:225], v[82:85]
	s_setprio 0
	s_barrier
	s_add_i32 s69, 0, 0x14000
	s_add_i32 s0, s68, s18
	v_add_u32_e32 v169, s69, v166
	v_lshl_add_u64 v[174:175], s[48:49], 0, v[152:153]
	s_mov_b32 m0, s0
	ds_read_b128 v[226:229], v169
	ds_read_b128 v[230:233], v169 offset:1024
	ds_read_b128 v[234:237], v169 offset:2048
	ds_read_b128 v[238:241], v169 offset:3072
	global_load_lds_dwordx4 v[174:175], off
	s_add_i32 m0, s0, 0x2000
	v_lshl_add_u64 v[192:193], s[48:49], 0, v[150:151]
	global_load_lds_dwordx4 v[192:193], off
	s_barrier
	s_waitcnt lgkmcnt(0)
	s_setprio 1
	v_mfma_f32_16x16x32_bf16 v[74:77], v[226:229], v[194:197], v[74:77]
	v_mfma_f32_16x16x32_bf16 v[46:49], v[234:237], v[194:197], v[46:49]
	v_mfma_f32_16x16x32_bf16 v[66:69], v[226:229], v[202:205], v[66:69]
	v_mfma_f32_16x16x32_bf16 v[38:41], v[234:237], v[202:205], v[38:41]
	v_mfma_f32_16x16x32_bf16 v[58:61], v[226:229], v[210:213], v[58:61]
	v_mfma_f32_16x16x32_bf16 v[30:33], v[234:237], v[210:213], v[30:33]
	v_mfma_f32_16x16x32_bf16 v[50:53], v[226:229], v[218:221], v[50:53]
	v_mfma_f32_16x16x32_bf16 v[22:25], v[234:237], v[218:221], v[22:25]
	v_mfma_f32_16x16x32_bf16 v[74:77], v[230:233], v[198:201], v[74:77]
	v_mfma_f32_16x16x32_bf16 v[46:49], v[238:241], v[198:201], v[46:49]
	v_mfma_f32_16x16x32_bf16 v[66:69], v[230:233], v[206:209], v[66:69]
	v_mfma_f32_16x16x32_bf16 v[38:41], v[238:241], v[206:209], v[38:41]
	v_mfma_f32_16x16x32_bf16 v[58:61], v[230:233], v[214:217], v[58:61]
	v_mfma_f32_16x16x32_bf16 v[30:33], v[238:241], v[214:217], v[30:33]
	v_mfma_f32_16x16x32_bf16 v[50:53], v[230:233], v[222:225], v[50:53]
	v_mfma_f32_16x16x32_bf16 v[22:25], v[238:241], v[222:225], v[22:25]
	s_setprio 0
	s_mov_b32 m0, s23
	v_lshl_add_u64 v[242:243], s[46:47], 0, v[152:153]
	s_barrier
	ds_read_b128 v[194:197], v168 offset:16384
	ds_read_b128 v[198:201], v168 offset:17408
	ds_read_b128 v[202:205], v168 offset:18432
	ds_read_b128 v[206:209], v168 offset:19456
	ds_read_b128 v[210:213], v168 offset:20480
	ds_read_b128 v[214:217], v168 offset:21504
	ds_read_b128 v[218:221], v168 offset:22528
	ds_read_b128 v[222:225], v168 offset:23552
	global_load_lds_dwordx4 v[242:243], off
	s_mov_b32 m0, s36
	v_lshl_add_u64 v[244:245], s[46:47], 0, v[150:151]
	global_load_lds_dwordx4 v[244:245], off
	s_barrier
	s_waitcnt lgkmcnt(0)
	s_setprio 1
	v_mfma_f32_16x16x32_bf16 v[110:113], v[130:133], v[194:197], v[110:113]
	v_mfma_f32_16x16x32_bf16 v[78:81], v[162:165], v[194:197], v[78:81]
	v_mfma_f32_16x16x32_bf16 v[106:109], v[130:133], v[202:205], v[106:109]
	v_mfma_f32_16x16x32_bf16 v[70:73], v[162:165], v[202:205], v[70:73]
	v_mfma_f32_16x16x32_bf16 v[102:105], v[130:133], v[210:213], v[102:105]
	v_mfma_f32_16x16x32_bf16 v[62:65], v[162:165], v[210:213], v[62:65]
	v_mfma_f32_16x16x32_bf16 v[86:89], v[130:133], v[218:221], v[86:89]
	v_mfma_f32_16x16x32_bf16 v[54:57], v[162:165], v[218:221], v[54:57]
	v_mfma_f32_16x16x32_bf16 v[110:113], v[158:161], v[198:201], v[110:113]
	v_mfma_f32_16x16x32_bf16 v[78:81], v[170:173], v[198:201], v[78:81]
	v_mfma_f32_16x16x32_bf16 v[106:109], v[158:161], v[206:209], v[106:109]
	v_mfma_f32_16x16x32_bf16 v[70:73], v[170:173], v[206:209], v[70:73]
	v_mfma_f32_16x16x32_bf16 v[102:105], v[158:161], v[214:217], v[102:105]
	v_mfma_f32_16x16x32_bf16 v[62:65], v[170:173], v[214:217], v[62:65]
	v_mfma_f32_16x16x32_bf16 v[86:89], v[158:161], v[222:225], v[86:89]
	v_mfma_f32_16x16x32_bf16 v[54:57], v[170:173], v[222:225], v[54:57]
	s_setprio 0
	s_barrier
; #define PG8_STAGE(bufoff, gbase) do { _Pragma("unroll") for (int _i = 0; _i < 2; ++_i) \
;         __builtin_amdgcn_global_load_lds((const unsigned*)((const char*)(gbase) + voff[_i]), (LAS unsigned*)(lds + (bufoff) + ldsw + _i * 8192), 16, 0, 0); } while (0)
; #define PG8_LDA(dst, b, h) do { _Pragma("unroll") for (int m = 0; m < 4; ++m) _Pragma("unroll") for (int k = 0; k < 2; ++k) dst[m][k] = *(const LAS bf16x8*)(lds + PG8_SA(b, h) + aoff + m * 2048 + k * 1024); } while (0)
; #define PG8_LDB(dst, b, h) do { _Pragma("unroll") for (int n = 0; n < 2; ++n) _Pragma("unroll") for (int k = 0; k < 2; ++k) dst[n][k] = *(const LAS bf16x8*)(lds + PG8_SB(b, h) + boff + n * 2048 + k * 1024); } while (0)
; #define PG8_WAIT_V(n) asm volatile("s_waitcnt vmcnt(" #n ")" ::: "memory")
; #define PG8_WAIT_L(n) asm volatile("s_waitcnt lgkmcnt(" #n ")" ::: "memory")
; #define PG8_BAR __builtin_amdgcn_s_barrier()
; #define PG8_SCHED __builtin_amdgcn_sched_barrier(0)
;     ...
;             PG8_STAGE(PG8_SB(0, 1), b2 + hstep);
;             PG8_WAIT_V(6); PG8_BAR; PG8_MMA(1, 1, At, B1); PG8_BAR;
;             PG8_LDB(B0, 1, 0); PG8_SCHED; PG8_LDA(At, 1, 0); PG8_STAGE(PG8_SA(0, 1), a2 + hstep);
;             PG8_WAIT_L(8); PG8_BAR; PG8_WAIT_L(0); PG8_MMA(0, 0, At, B0); PG8_BAR; PG8_SCHED;
;             PG8_LDB(B1, 1, 1); PG8_STAGE(PG8_SB(1, 0), b3);
;             PG8_BAR; PG8_WAIT_L(0); PG8_MMA(0, 1, At, B1); PG8_BAR;
;             PG8_LDA(At, 1, 1); PG8_STAGE(PG8_SA(1, 0), a3);
;             PG8_BAR; PG8_WAIT_L(0); PG8_MMA(1, 0, At, B0); PG8_BAR; PG8_SCHED;
;             PG8_STAGE(PG8_SB(1, 1), b3 + hstep);
;             PG8_WAIT_V(6); PG8_BAR; PG8_MMA(1, 1, At, B1); PG8_BAR;
	s_add_u32 s0, s48, s20
	s_addc_u32 s1, s49, 0
	s_add_i32 s48, s69, s18
	v_lshl_add_u64 v[246:247], s[0:1], 0, v[152:153]
	s_mov_b32 m0, s48
	v_lshl_add_u64 v[248:249], s[0:1], 0, v[150:151]
	global_load_lds_dwordx4 v[246:247], off
	s_add_i32 m0, s48, 0x2000
	s_nop 0
	global_load_lds_dwordx4 v[248:249], off
	s_waitcnt vmcnt(6)
	s_barrier
	s_setprio 1
	v_mfma_f32_16x16x32_bf16 v[42:45], v[226:229], v[194:197], v[42:45]
	v_mfma_f32_16x16x32_bf16 v[14:17], v[234:237], v[194:197], v[14:17]
	v_mfma_f32_16x16x32_bf16 v[34:37], v[226:229], v[202:205], v[34:37]
	v_mfma_f32_16x16x32_bf16 v[10:13], v[234:237], v[202:205], v[10:13]
	v_mfma_f32_16x16x32_bf16 v[26:29], v[226:229], v[210:213], v[26:29]
	v_mfma_f32_16x16x32_bf16 v[6:9], v[234:237], v[210:213], v[6:9]
	v_mfma_f32_16x16x32_bf16 v[18:21], v[226:229], v[218:221], v[18:21]
	v_mfma_f32_16x16x32_bf16 v[2:5], v[234:237], v[218:221], v[2:5]
	v_mfma_f32_16x16x32_bf16 v[42:45], v[230:233], v[198:201], v[42:45]
	v_mfma_f32_16x16x32_bf16 v[14:17], v[238:241], v[198:201], v[14:17]
	v_mfma_f32_16x16x32_bf16 v[34:37], v[230:233], v[206:209], v[34:37]
	v_mfma_f32_16x16x32_bf16 v[10:13], v[238:241], v[206:209], v[10:13]
	v_mfma_f32_16x16x32_bf16 v[26:29], v[230:233], v[214:217], v[26:29]
	v_mfma_f32_16x16x32_bf16 v[6:9], v[238:241], v[214:217], v[6:9]
	v_mfma_f32_16x16x32_bf16 v[18:21], v[230:233], v[222:225], v[18:21]
	v_mfma_f32_16x16x32_bf16 v[2:5], v[238:241], v[222:225], v[2:5]
	s_setprio 0
	s_add_i32 s48, 0, 0x18000
	v_add_u32_e32 v169, s48, v166
	s_barrier
	ds_read_b128 v[130:133], v169
	ds_read_b128 v[158:161], v169 offset:1024
	ds_read_b128 v[162:165], v169 offset:2048
	ds_read_b128 v[170:173], v169 offset:3072
	s_add_u32 s0, s46, s20
	s_addc_u32 s1, s47, 0
	s_mov_b32 m0, s60
	v_lshl_add_u64 v[226:227], s[0:1], 0, v[152:153]
	ds_read_b128 v[194:197], v168 offset:32768
	ds_read_b128 v[198:201], v168 offset:33792
	ds_read_b128 v[202:205], v168 offset:34816
	ds_read_b128 v[206:209], v168 offset:35840
	ds_read_b128 v[210:213], v168 offset:36864
	ds_read_b128 v[214:217], v168 offset:37888
	ds_read_b128 v[218:221], v168 offset:38912
	ds_read_b128 v[222:225], v168 offset:39936
	global_load_lds_dwordx4 v[226:227], off
	s_mov_b32 m0, s61
	v_lshl_add_u64 v[226:227], s[0:1], 0, v[150:151]
	global_load_lds_dwordx4 v[226:227], off
	s_waitcnt lgkmcnt(8)
	s_barrier
	s_waitcnt lgkmcnt(0)
	s_setprio 1
	v_mfma_f32_16x16x32_bf16 v[126:129], v[130:133], v[194:197], v[126:129]
	v_mfma_f32_16x16x32_bf16 v[98:101], v[162:165], v[194:197], v[98:101]
	v_mfma_f32_16x16x32_bf16 v[122:125], v[130:133], v[202:205], v[122:125]
	v_mfma_f32_16x16x32_bf16 v[94:97], v[162:165], v[202:205], v[94:97]
	v_mfma_f32_16x16x32_bf16 v[118:121], v[130:133], v[210:213], v[118:121]
	v_mfma_f32_16x16x32_bf16 v[90:93], v[162:165], v[210:213], v[90:93]
	v_mfma_f32_16x16x32_bf16 v[114:117], v[130:133], v[218:221], v[114:117]
	v_mfma_f32_16x16x32_bf16 v[82:85], v[162:165], v[218:221], v[82:85]
	v_mfma_f32_16x16x32_bf16 v[126:129], v[158:161], v[198:201], v[126:129]
	v_mfma_f32_16x16x32_bf16 v[98:101], v[170:173], v[198:201], v[98:101]
	v_mfma_f32_16x16x32_bf16 v[122:125], v[158:161], v[206:209], v[122:125]
	v_mfma_f32_16x16x32_bf16 v[94:97], v[170:173], v[206:209], v[94:97]
	v_mfma_f32_16x16x32_bf16 v[118:121], v[158:161], v[214:217], v[118:121]
	v_mfma_f32_16x16x32_bf16 v[90:93], v[170:173], v[214:217], v[90:93]
	v_mfma_f32_16x16x32_bf16 v[114:117], v[158:161], v[222:225], v[114:117]
	v_mfma_f32_16x16x32_bf16 v[82:85], v[170:173], v[222:225], v[82:85]
	s_setprio 0
	s_barrier
	s_add_i32 s0, 0, 0x1c000
	s_add_i32 s1, s48, s18
	v_add_u32_e32 v169, s0, v166
	v_lshl_add_u64 v[174:175], v[174:175], 0, s[88:89]
	s_mov_b32 m0, s1
	ds_read_b128 v[226:229], v169
	ds_read_b128 v[230:233], v169 offset:1024
	ds_read_b128 v[234:237], v169 offset:2048
	ds_read_b128 v[238:241], v169 offset:3072
	global_load_lds_dwordx4 v[174:175], off
	s_add_i32 m0, s1, 0x2000
	v_lshl_add_u64 v[174:175], v[192:193], 0, s[88:89]
	global_load_lds_dwordx4 v[174:175], off
	s_barrier
	s_waitcnt lgkmcnt(0)
	s_setprio 1
	v_mfma_f32_16x16x32_bf16 v[74:77], v[226:229], v[194:197], v[74:77]
	v_mfma_f32_16x16x32_bf16 v[46:49], v[234:237], v[194:197], v[46:49]
	v_mfma_f32_16x16x32_bf16 v[66:69], v[226:229], v[202:205], v[66:69]
	v_mfma_f32_16x16x32_bf16 v[38:41], v[234:237], v[202:205], v[38:41]
	v_mfma_f32_16x16x32_bf16 v[58:61], v[226:229], v[210:213], v[58:61]
	v_mfma_f32_16x16x32_bf16 v[30:33], v[234:237], v[210:213], v[30:33]
	v_mfma_f32_16x16x32_bf16 v[50:53], v[226:229], v[218:221], v[50:53]
	v_mfma_f32_16x16x32_bf16 v[22:25], v[234:237], v[218:221], v[22:25]
	v_mfma_f32_16x16x32_bf16 v[74:77], v[230:233], v[198:201], v[74:77]
	v_mfma_f32_16x16x32_bf16 v[46:49], v[238:241], v[198:201], v[46:49]
	v_mfma_f32_16x16x32_bf16 v[66:69], v[230:233], v[206:209], v[66:69]
	v_mfma_f32_16x16x32_bf16 v[38:41], v[238:241], v[206:209], v[38:41]
	v_mfma_f32_16x16x32_bf16 v[58:61], v[230:233], v[214:217], v[58:61]
	v_mfma_f32_16x16x32_bf16 v[30:33], v[238:241], v[214:217], v[30:33]
	v_mfma_f32_16x16x32_bf16 v[50:53], v[230:233], v[222:225], v[50:53]
	v_mfma_f32_16x16x32_bf16 v[22:25], v[238:241], v[222:225], v[22:25]
	s_setprio 0
	s_mov_b32 m0, s28
	v_lshl_add_u64 v[174:175], v[242:243], 0, s[88:89]
	s_barrier
	ds_read_b128 v[194:197], v168 offset:49152
	ds_read_b128 v[198:201], v168 offset:50176
	ds_read_b128 v[202:205], v168 offset:51200
	ds_read_b128 v[206:209], v168 offset:52224
	ds_read_b128 v[210:213], v168 offset:53248
	ds_read_b128 v[214:217], v168 offset:54272
	ds_read_b128 v[218:221], v168 offset:55296
	ds_read_b128 v[222:225], v168 offset:56320
	global_load_lds_dwordx4 v[174:175], off
	s_mov_b32 m0, s29
	v_lshl_add_u64 v[174:175], v[244:245], 0, s[88:89]
	global_load_lds_dwordx4 v[174:175], off
	s_barrier
; #define PG8_STAGE(bufoff, gbase) do { _Pragma("unroll") for (int _i = 0; _i < 2; ++_i) \
;         __builtin_amdgcn_global_load_lds((const unsigned*)((const char*)(gbase) + voff[_i]), (LAS unsigned*)(lds + (bufoff) + ldsw + _i * 8192), 16, 0, 0); } while (0)
; #define PG8_WAIT_V(n) asm volatile("s_waitcnt vmcnt(" #n ")" ::: "memory")
;     ...
;             PG8_WAIT_V(6); PG8_BAR; PG8_MMA(1, 1, At, B1); PG8_BAR;
;             PG8_LDB(B0, 1, 0); PG8_SCHED; PG8_LDA(At, 1, 0); PG8_STAGE(PG8_SA(0, 1), a2 + hstep);
;             PG8_WAIT_L(8); PG8_BAR; PG8_WAIT_L(0); PG8_MMA(0, 0, At, B0); PG8_BAR; PG8_SCHED;
;             PG8_LDB(B1, 1, 1); PG8_STAGE(PG8_SB(1, 0), b3);
;             PG8_BAR; PG8_WAIT_L(0); PG8_MMA(0, 1, At, B1); PG8_BAR;
;             PG8_LDA(At, 1, 1); PG8_STAGE(PG8_SA(1, 0), a3);
;             PG8_BAR; PG8_WAIT_L(0); PG8_MMA(1, 0, At, B0); PG8_BAR; PG8_SCHED;
;             PG8_STAGE(PG8_SB(1, 1), b3 + hstep);
;             PG8_WAIT_V(6); PG8_BAR; PG8_MMA(1, 1, At, B1); PG8_BAR;
;     __device__ __forceinline__ void operator()(Acc& acc, int pm, int pn, int wr, int wc, int fr, int fq) const {
;         const int brow = pm * 256;
;         const bool lat = brow < T_LAT;
;         const float* xin = lat ? xin_lat : xin_ctx;
;         float* xout = lat ? xout_lat : xout_ctx;
;         const int rsub = lat ? 0 : T_LAT;
;         const int mi = lat ? (brow >> 12) : 8;
;         const int c0 = pn * 256 + wc * 32 + fq * 4;
;         const float* gp = modv_l + (size_t)mi * 6144 + gate_i * 1024 + c0;
; #pragma unroll
;         for (int bj = 0; bj < 2; ++bj)
; #pragma unroll
;             for (int n = 0; n < 2; ++n) {
;                 const f32x4 gv = *reinterpret_cast<const f32x4*>(gp + bj * 128 + n * 16);
; #pragma unroll
;                 for (int ai = 0; ai < 2; ++ai)
; #pragma unroll
;                     for (int m = 0; m < 4; ++m) {
;                         const size_t o = (size_t)(brow + ai * 128 + wr * 64 + m * 16 + fr - rsub) * DM + c0 + bj * 128 + n * 16;
;                         const f32x4 xi = *reinterpret_cast<const f32x4*>(xin + o);
;                         const f32x4 a = acc[ai][bj][m][n];
;                         f32x4 r = {xi[0] + gv[0] * a[0], xi[1] + gv[1] * a[1], xi[2] + gv[2] * a[2], xi[3] + gv[3] * a[3]};
;                         *reinterpret_cast<f32x4*>(xout + o) = r;
;                     }
;             }
	s_waitcnt lgkmcnt(0)
	s_setprio 1
	v_mfma_f32_16x16x32_bf16 v[110:113], v[130:133], v[194:197], v[110:113]
	v_mfma_f32_16x16x32_bf16 v[78:81], v[162:165], v[194:197], v[78:81]
	v_mfma_f32_16x16x32_bf16 v[106:109], v[130:133], v[202:205], v[106:109]
	v_mfma_f32_16x16x32_bf16 v[70:73], v[162:165], v[202:205], v[70:73]
	v_mfma_f32_16x16x32_bf16 v[102:105], v[130:133], v[210:213], v[102:105]
	v_mfma_f32_16x16x32_bf16 v[62:65], v[162:165], v[210:213], v[62:65]
	v_mfma_f32_16x16x32_bf16 v[86:89], v[130:133], v[218:221], v[86:89]
	v_mfma_f32_16x16x32_bf16 v[54:57], v[162:165], v[218:221], v[54:57]
	v_mfma_f32_16x16x32_bf16 v[110:113], v[158:161], v[198:201], v[110:113]
	v_mfma_f32_16x16x32_bf16 v[78:81], v[170:173], v[198:201], v[78:81]
	v_mfma_f32_16x16x32_bf16 v[106:109], v[158:161], v[206:209], v[106:109]
	v_mfma_f32_16x16x32_bf16 v[70:73], v[170:173], v[206:209], v[70:73]
	v_mfma_f32_16x16x32_bf16 v[102:105], v[158:161], v[214:217], v[102:105]
	v_mfma_f32_16x16x32_bf16 v[62:65], v[170:173], v[214:217], v[62:65]
	v_mfma_f32_16x16x32_bf16 v[86:89], v[158:161], v[222:225], v[86:89]
	v_mfma_f32_16x16x32_bf16 v[54:57], v[170:173], v[222:225], v[54:57]
	s_setprio 0
	s_barrier
	s_add_i32 s0, s0, s18
	s_mov_b32 m0, s0
	v_lshl_add_u64 v[130:131], v[246:247], 0, s[88:89]
	global_load_lds_dwordx4 v[130:131], off
	s_add_i32 m0, s0, 0x2000
	v_lshl_add_u64 v[130:131], v[248:249], 0, s[88:89]
	global_load_lds_dwordx4 v[130:131], off
	s_waitcnt vmcnt(6)
	s_barrier
	s_setprio 1
	v_mfma_f32_16x16x32_bf16 v[42:45], v[226:229], v[194:197], v[42:45]
	v_mfma_f32_16x16x32_bf16 v[14:17], v[234:237], v[194:197], v[14:17]
	v_mfma_f32_16x16x32_bf16 v[34:37], v[226:229], v[202:205], v[34:37]
	v_mfma_f32_16x16x32_bf16 v[10:13], v[234:237], v[202:205], v[10:13]
	v_mfma_f32_16x16x32_bf16 v[26:29], v[226:229], v[210:213], v[26:29]
	v_mfma_f32_16x16x32_bf16 v[6:9], v[234:237], v[210:213], v[6:9]
	v_mfma_f32_16x16x32_bf16 v[18:21], v[226:229], v[218:221], v[18:21]
	v_mfma_f32_16x16x32_bf16 v[2:5], v[234:237], v[218:221], v[2:5]
	v_mfma_f32_16x16x32_bf16 v[42:45], v[230:233], v[198:201], v[42:45]
	v_mfma_f32_16x16x32_bf16 v[14:17], v[238:241], v[198:201], v[14:17]
	v_mfma_f32_16x16x32_bf16 v[34:37], v[230:233], v[206:209], v[34:37]
	v_mfma_f32_16x16x32_bf16 v[10:13], v[238:241], v[206:209], v[10:13]
	v_mfma_f32_16x16x32_bf16 v[26:29], v[230:233], v[214:217], v[26:29]
	v_mfma_f32_16x16x32_bf16 v[6:9], v[238:241], v[214:217], v[6:9]
	v_mfma_f32_16x16x32_bf16 v[18:21], v[230:233], v[222:225], v[18:21]
	v_mfma_f32_16x16x32_bf16 v[2:5], v[238:241], v[222:225], v[2:5]
	s_setprio 0
	s_add_u32 s40, s40, 0x100
	s_addc_u32 s41, s41, 0
	s_add_u32 s58, s58, 0x100
	s_addc_u32 s59, s59, 0
	s_cmp_ge_u32 s67, s7
	s_mov_b32 s46, s67
	s_barrier
	s_cbranch_scc0 .LBB0_1245
	s_lshl_b32 s48, s65, 8
	v_readlane_b32 s0, v255, 26
	v_readlane_b32 s40, v255, 24
	v_readlane_b32 s68, v254, 6
	s_cmpk_lt_i32 s65, 0x80
	v_readlane_b32 s1, v255, 27
	v_readlane_b32 s41, v255, 25
	v_readlane_b32 s70, v254, 8
	v_readlane_b32 s71, v254, 9
	v_readlane_b32 s72, v254, 10
	v_readlane_b32 s73, v254, 11
	s_cselect_b32 s47, s41, s1
	s_cselect_b32 s46, s40, s0
	s_cselect_b32 s49, 0, 0xffff8000
	s_cselect_b32 s41, s71, s73
	s_cselect_b32 s40, s70, s72
	s_min_i32 s0, s65, 0x80
	s_ashr_i32 s0, s0, 4
	s_mul_hi_i32 s1, s0, 0x6000
	s_mulk_i32 s0, 0x6000
	s_add_u32 s0, s50, s0
	s_addc_u32 s1, s51, s1
	s_add_i32 s49, s49, s48
	s_add_u32 s0, s0, 0x2000
	s_addc_u32 s1, s1, 0
	v_lshl_or_b32 v162, s66, 8, v167
	v_add_u32_e32 v164, s49, v1
	v_ashrrev_i32_e32 v163, 31, v162
	v_lshl_add_u64 v[174:175], v[162:163], 2, s[0:1]
	global_load_dwordx4 v[130:133], v[174:175], off
	global_load_dwordx4 v[158:161], v[174:175], off offset:64
	global_load_dwordx4 v[170:173], v[174:175], off offset:512
	global_load_dwordx4 v[192:195], v[174:175], off offset:576
	v_lshl_add_u32 v165, v164, 10, v162
	v_lshlrev_b32_e32 v165, 2, v165
	v_add_u32_e32 v169, 0x10000, v165
	v_add_u32_e32 v248, 0x20000, v165
	v_add_u32_e32 v162, 0x30000, v165
	v_add_u32_e32 v163, 0x80000, v165
	v_add_u32_e32 v164, 0x90000, v165
	v_add_u32_e32 v174, 0xa0000, v165
	v_add_u32_e32 v175, 0xb0000, v165
	global_load_dwordx4 v[196:199], v165, s[46:47]
	global_load_dwordx4 v[200:203], v165, s[46:47] offset:64
	global_load_dwordx4 v[204:207], v169, s[46:47]
	global_load_dwordx4 v[208:211], v169, s[46:47] offset:64
	global_load_dwordx4 v[212:215], v248, s[46:47]
	global_load_dwordx4 v[216:219], v248, s[46:47] offset:64
	global_load_dwordx4 v[220:223], v162, s[46:47]
	global_load_dwordx4 v[224:227], v162, s[46:47] offset:64
	global_load_dwordx4 v[228:231], v163, s[46:47]
	global_load_dwordx4 v[232:235], v163, s[46:47] offset:64
	global_load_dwordx4 v[236:239], v164, s[46:47]
	global_load_dwordx4 v[240:243], v164, s[46:47] offset:64
	global_load_dwordx4 v[244:247], v174, s[46:47]
	v_readlane_b32 s74, v254, 12
	v_readlane_b32 s75, v254, 13
	v_readlane_b32 s74, v255, 22
	s_and_b64 vcc, exec, s[44:45]
	s_mov_b32 s66, s62
	s_mov_b32 s65, s64
	s_mov_b64 s[58:59], s[14:15]
	s_mov_b32 s94, 0x87ff
	v_readlane_b32 s75, v255, 23
	v_readlane_b32 s69, v254, 7
	s_waitcnt vmcnt(12)
	v_pk_fma_f32 v[126:127], v[126:127], v[130:131], v[196:197]
	v_pk_fma_f32 v[128:129], v[128:129], v[132:133], v[198:199]
	global_store_dwordx4 v165, v[126:129], s[40:41] sc1
	global_load_dwordx4 v[196:199], v174, s[46:47] offset:64
	s_waitcnt vmcnt(13)
	v_pk_fma_f32 v[98:99], v[98:99], v[158:159], v[200:201]
	v_pk_fma_f32 v[100:101], v[100:101], v[160:161], v[202:203]
	global_store_dwordx4 v165, v[98:101], s[40:41] offset:64 sc1
	global_load_dwordx4 v[200:203], v175, s[46:47]
	s_waitcnt vmcnt(14)
; #define PG8_WAIT_V(n) asm volatile("s_waitcnt vmcnt(" #n ")" ::: "memory")
; #define PG8_BAR __builtin_amdgcn_s_barrier()
;     ...
;         if (!has_next) break;
;     ...
;     PG8_WAIT_V(0);
;     if (wr == 0) PG8_BAR;
;     PG8_BAR;
;     __device__ __forceinline__ void operator()(Acc& acc, int pm, int pn, int wr, int wc, int fr, int fq) const {
;     ...
; #pragma unroll
;         for (int bj = 0; bj < 2; ++bj)
; #pragma unroll
;             for (int n = 0; n < 2; ++n) {
;                 const f32x4 gv = *reinterpret_cast<const f32x4*>(gp + bj * 128 + n * 16);
; #pragma unroll
;                 for (int ai = 0; ai < 2; ++ai)
; #pragma unroll
;                     for (int m = 0; m < 4; ++m) {
;                         const size_t o = (size_t)(brow + ai * 128 + wr * 64 + m * 16 + fr - rsub) * DM + c0 + bj * 128 + n * 16;
;                         const f32x4 xi = *reinterpret_cast<const f32x4*>(xin + o);
;                         const f32x4 a = acc[ai][bj][m][n];
;                         f32x4 r = {xi[0] + gv[0] * a[0], xi[1] + gv[1] * a[1], xi[2] + gv[2] * a[2], xi[3] + gv[3] * a[3]};
;                         *reinterpret_cast<f32x4*>(xout + o) = r;
;                     }
;             }
	v_pk_fma_f32 v[122:123], v[122:123], v[130:131], v[204:205]
	v_pk_fma_f32 v[124:125], v[124:125], v[132:133], v[206:207]
	global_store_dwordx4 v169, v[122:125], s[40:41] sc1
	global_load_dwordx4 v[204:207], v175, s[46:47] offset:64
	s_waitcnt vmcnt(15)
	v_pk_fma_f32 v[94:95], v[94:95], v[158:159], v[208:209]
	v_pk_fma_f32 v[96:97], v[96:97], v[160:161], v[210:211]
	global_store_dwordx4 v169, v[94:97], s[40:41] offset:64 sc1
	global_load_dwordx4 v[208:211], v165, s[46:47] offset:512
	s_waitcnt vmcnt(16)
	v_pk_fma_f32 v[118:119], v[118:119], v[130:131], v[212:213]
	v_pk_fma_f32 v[120:121], v[120:121], v[132:133], v[214:215]
	global_store_dwordx4 v248, v[118:121], s[40:41] sc1
	global_load_dwordx4 v[212:215], v165, s[46:47] offset:576
	s_waitcnt vmcnt(17)
	v_pk_fma_f32 v[90:91], v[90:91], v[158:159], v[216:217]
	v_pk_fma_f32 v[92:93], v[92:93], v[160:161], v[218:219]
	global_store_dwordx4 v248, v[90:93], s[40:41] offset:64 sc1
	global_load_dwordx4 v[216:219], v169, s[46:47] offset:512
	s_waitcnt vmcnt(18)
	v_pk_fma_f32 v[114:115], v[114:115], v[130:131], v[220:221]
	v_pk_fma_f32 v[116:117], v[116:117], v[132:133], v[222:223]
	global_store_dwordx4 v162, v[114:117], s[40:41] sc1
	global_load_dwordx4 v[220:223], v169, s[46:47] offset:576
	s_waitcnt vmcnt(19)
	v_pk_fma_f32 v[82:83], v[82:83], v[158:159], v[224:225]
	v_pk_fma_f32 v[84:85], v[84:85], v[160:161], v[226:227]
	global_store_dwordx4 v162, v[82:85], s[40:41] offset:64 sc1
	global_load_dwordx4 v[224:227], v248, s[46:47] offset:512
	s_waitcnt vmcnt(20)
	v_pk_fma_f32 v[110:111], v[110:111], v[130:131], v[228:229]
	v_pk_fma_f32 v[112:113], v[112:113], v[132:133], v[230:231]
	global_store_dwordx4 v163, v[110:113], s[40:41] sc1
	global_load_dwordx4 v[228:231], v248, s[46:47] offset:576
	s_waitcnt vmcnt(21)
	v_pk_fma_f32 v[78:79], v[78:79], v[158:159], v[232:233]
	v_pk_fma_f32 v[80:81], v[80:81], v[160:161], v[234:235]
	global_store_dwordx4 v163, v[78:81], s[40:41] offset:64 sc1
	global_load_dwordx4 v[232:235], v162, s[46:47] offset:512
	s_waitcnt vmcnt(22)
	v_pk_fma_f32 v[106:107], v[106:107], v[130:131], v[236:237]
	v_pk_fma_f32 v[108:109], v[108:109], v[132:133], v[238:239]
	global_store_dwordx4 v164, v[106:109], s[40:41] sc1
	global_load_dwordx4 v[236:239], v162, s[46:47] offset:576
	s_waitcnt vmcnt(23)
	v_pk_fma_f32 v[70:71], v[70:71], v[158:159], v[240:241]
	v_pk_fma_f32 v[72:73], v[72:73], v[160:161], v[242:243]
	global_store_dwordx4 v164, v[70:73], s[40:41] offset:64 sc1
	global_load_dwordx4 v[240:243], v163, s[46:47] offset:512
	s_waitcnt vmcnt(24)
	v_pk_fma_f32 v[102:103], v[102:103], v[130:131], v[244:245]
	v_pk_fma_f32 v[104:105], v[104:105], v[132:133], v[246:247]
	global_store_dwordx4 v174, v[102:105], s[40:41] sc1
	global_load_dwordx4 v[244:247], v163, s[46:47] offset:576
	s_waitcnt vmcnt(24)
	v_pk_fma_f32 v[62:63], v[62:63], v[158:159], v[196:197]
	v_pk_fma_f32 v[64:65], v[64:65], v[160:161], v[198:199]
	global_store_dwordx4 v174, v[62:65], s[40:41] offset:64 sc1
	global_load_dwordx4 v[196:199], v164, s[46:47] offset:512
	s_waitcnt vmcnt(24)
	v_pk_fma_f32 v[86:87], v[86:87], v[130:131], v[200:201]
	v_pk_fma_f32 v[88:89], v[88:89], v[132:133], v[202:203]
	global_store_dwordx4 v175, v[86:89], s[40:41] sc1
	global_load_dwordx4 v[200:203], v164, s[46:47] offset:576
	s_waitcnt vmcnt(24)
	v_pk_fma_f32 v[54:55], v[54:55], v[158:159], v[204:205]
	v_pk_fma_f32 v[56:57], v[56:57], v[160:161], v[206:207]
	global_store_dwordx4 v175, v[54:57], s[40:41] offset:64 sc1
	global_load_dwordx4 v[204:207], v174, s[46:47] offset:512
	s_waitcnt vmcnt(24)
	v_pk_fma_f32 v[74:75], v[74:75], v[170:171], v[208:209]
	v_pk_fma_f32 v[76:77], v[76:77], v[172:173], v[210:211]
	global_store_dwordx4 v165, v[74:77], s[40:41] offset:512 sc1
	global_load_dwordx4 v[208:211], v174, s[46:47] offset:576
	s_waitcnt vmcnt(24)
	v_pk_fma_f32 v[46:47], v[46:47], v[192:193], v[212:213]
	v_pk_fma_f32 v[48:49], v[48:49], v[194:195], v[214:215]
	global_store_dwordx4 v165, v[46:49], s[40:41] offset:576 sc1
	global_load_dwordx4 v[212:215], v175, s[46:47] offset:512
	s_waitcnt vmcnt(24)
	v_pk_fma_f32 v[66:67], v[66:67], v[170:171], v[216:217]
	v_pk_fma_f32 v[68:69], v[68:69], v[172:173], v[218:219]
	global_store_dwordx4 v169, v[66:69], s[40:41] offset:512 sc1
	global_load_dwordx4 v[216:219], v175, s[46:47] offset:576
	s_waitcnt vmcnt(24)
	v_pk_fma_f32 v[38:39], v[38:39], v[192:193], v[220:221]
	v_pk_fma_f32 v[40:41], v[40:41], v[194:195], v[222:223]
	global_store_dwordx4 v169, v[38:41], s[40:41] offset:576 sc1
	s_waitcnt vmcnt(23)
	v_pk_fma_f32 v[58:59], v[58:59], v[170:171], v[224:225]
	v_pk_fma_f32 v[60:61], v[60:61], v[172:173], v[226:227]
	global_store_dwordx4 v248, v[58:61], s[40:41] offset:512 sc1
	s_waitcnt vmcnt(22)
	v_pk_fma_f32 v[30:31], v[30:31], v[192:193], v[228:229]
	v_pk_fma_f32 v[32:33], v[32:33], v[194:195], v[230:231]
	global_store_dwordx4 v248, v[30:33], s[40:41] offset:576 sc1
	s_waitcnt vmcnt(21)
	v_pk_fma_f32 v[50:51], v[50:51], v[170:171], v[232:233]
	v_pk_fma_f32 v[52:53], v[52:53], v[172:173], v[234:235]
	global_store_dwordx4 v162, v[50:53], s[40:41] offset:512 sc1
	s_waitcnt vmcnt(20)
	v_pk_fma_f32 v[22:23], v[22:23], v[192:193], v[236:237]
	v_pk_fma_f32 v[24:25], v[24:25], v[194:195], v[238:239]
	global_store_dwordx4 v162, v[22:25], s[40:41] offset:576 sc1
	s_waitcnt vmcnt(19)
	v_pk_fma_f32 v[42:43], v[42:43], v[170:171], v[240:241]
	v_pk_fma_f32 v[44:45], v[44:45], v[172:173], v[242:243]
	global_store_dwordx4 v163, v[42:45], s[40:41] offset:512 sc1
	s_waitcnt vmcnt(18)
	v_pk_fma_f32 v[14:15], v[14:15], v[192:193], v[244:245]
	v_pk_fma_f32 v[16:17], v[16:17], v[194:195], v[246:247]
	global_store_dwordx4 v163, v[14:17], s[40:41] offset:576 sc1
	s_waitcnt vmcnt(17)
	v_pk_fma_f32 v[34:35], v[34:35], v[170:171], v[196:197]
	v_pk_fma_f32 v[36:37], v[36:37], v[172:173], v[198:199]
	global_store_dwordx4 v164, v[34:37], s[40:41] offset:512 sc1
	s_waitcnt vmcnt(16)
	v_pk_fma_f32 v[10:11], v[10:11], v[192:193], v[200:201]
	v_pk_fma_f32 v[12:13], v[12:13], v[194:195], v[202:203]
	global_store_dwordx4 v164, v[10:13], s[40:41] offset:576 sc1
	s_waitcnt vmcnt(15)
	v_pk_fma_f32 v[26:27], v[26:27], v[170:171], v[204:205]
	v_pk_fma_f32 v[28:29], v[28:29], v[172:173], v[206:207]
	global_store_dwordx4 v174, v[26:29], s[40:41] offset:512 sc1
	s_waitcnt vmcnt(14)
	v_pk_fma_f32 v[6:7], v[6:7], v[192:193], v[208:209]
	v_pk_fma_f32 v[8:9], v[8:9], v[194:195], v[210:211]
	global_store_dwordx4 v174, v[6:9], s[40:41] offset:576 sc1
	s_waitcnt vmcnt(13)
	v_pk_fma_f32 v[18:19], v[18:19], v[170:171], v[212:213]
	v_pk_fma_f32 v[20:21], v[20:21], v[172:173], v[214:215]
	global_store_dwordx4 v175, v[18:21], s[40:41] offset:512 sc1
	s_waitcnt vmcnt(12)
	v_pk_fma_f32 v[2:3], v[2:3], v[192:193], v[216:217]
	v_pk_fma_f32 v[4:5], v[4:5], v[194:195], v[218:219]
	global_store_dwordx4 v175, v[2:5], s[40:41] offset:576 sc1
	s_mov_b64 s[40:41], s[12:13]
	s_mov_b64 s[0:1], 0x2000
	s_cbranch_vccz .LBB0_1238
	s_waitcnt vmcnt(0)
	s_cmpk_gt_u32 s4, 0xff
	s_cbranch_scc1 .LBB0_1249
	s_barrier

; #define PG8_STAGE(bufoff, gbase) do { _Pragma("unroll") for (int _i = 0; _i < 2; ++_i) \
;         __builtin_amdgcn_global_load_lds((const unsigned*)((const char*)(gbase) + voff[_i]), (LAS unsigned*)(lds + (bufoff) + ldsw + _i * 8192), 16, 0, 0); } while (0)
; #define PG8_LDA(dst, b, h) do { _Pragma("unroll") for (int m = 0; m < 4; ++m) _Pragma("unroll") for (int k = 0; k < 2; ++k) dst[m][k] = *(const LAS bf16x8*)(lds + PG8_SA(b, h) + aoff + m * 2048 + k * 1024); } while (0)
; #define PG8_LDB(dst, b, h) do { _Pragma("unroll") for (int n = 0; n < 2; ++n) _Pragma("unroll") for (int k = 0; k < 2; ++k) dst[n][k] = *(const LAS bf16x8*)(lds + PG8_SB(b, h) + boff + n * 2048 + k * 1024); } while (0)
; #define PG8_WAIT_V(n) asm volatile("s_waitcnt vmcnt(" #n ")" ::: "memory")
; #define PG8_WAIT_L(n) asm volatile("s_waitcnt lgkmcnt(" #n ")" ::: "memory")
;     ...
;         for (int t = 0; t < nt; t += 2) {
;             const bool last = (t == nt - 2);
;             const char* a1 = cA + (size_t)(t + 1) * kstep;
;             const char* a2 = last ? nA : cA + (size_t)(t + 2) * kstep; const char* b2 = last ? nB : cB + (size_t)(t + 2) * kstep;
;             const char* a3 = a2 + kstep; const char* b3 = b2 + kstep;
;             PG8_LDB(B0, 0, 0); PG8_SCHED; PG8_LDA(At, 0, 0); PG8_STAGE(PG8_SA(1, 1), a1 + hstep);
;             PG8_WAIT_L(8); PG8_BAR; PG8_WAIT_L(0); PG8_MMA(0, 0, At, B0); PG8_BAR; PG8_SCHED;
;             PG8_LDB(B1, 0, 1); PG8_STAGE(PG8_SB(0, 0), b2);
;             PG8_BAR; PG8_WAIT_L(0); PG8_MMA(0, 1, At, B1); PG8_BAR;
;             PG8_LDA(At, 0, 1); PG8_STAGE(PG8_SA(0, 0), a2);
;             PG8_BAR; PG8_WAIT_L(0); PG8_MMA(1, 0, At, B0); PG8_BAR; PG8_SCHED;
;             PG8_STAGE(PG8_SB(0, 1), b2 + hstep);
;             PG8_WAIT_V(6); PG8_BAR; PG8_MMA(1, 1, At, B1); PG8_BAR;
;             PG8_LDB(B0, 1, 0); PG8_SCHED; PG8_LDA(At, 1, 0); PG8_STAGE(PG8_SA(0, 1), a2 + hstep);
;             PG8_WAIT_L(8); PG8_BAR; PG8_WAIT_L(0); PG8_MMA(0, 0, At, B0); PG8_BAR; PG8_SCHED;
;             PG8_LDB(B1, 1, 1); PG8_STAGE(PG8_SB(1, 0), b3);
;             PG8_BAR; PG8_WAIT_L(0); PG8_MMA(0, 1, At, B1); PG8_BAR;
;             PG8_LDA(At, 1, 1); PG8_STAGE(PG8_SA(1, 0), a3);
;             PG8_BAR; PG8_WAIT_L(0); PG8_MMA(1, 0, At, B0); PG8_BAR; PG8_SCHED;
;             PG8_STAGE(PG8_SB(1, 1), b3 + hstep);
;             PG8_WAIT_V(6); PG8_BAR; PG8_MMA(1, 1, At, B1); PG8_BAR;
.LBB0_1408:
	s_add_i32 s31, s5, 2
	s_add_u32 s0, s14, 0x80
	s_addc_u32 s1, s15, 0
	s_cmp_lg_u32 s30, s5
	s_cselect_b32 s0, s0, 0
	s_cselect_b32 s1, s1, 0
	s_add_u32 s40, s12, s0
	s_addc_u32 s41, s13, s1
	s_add_i32 s5, 0, 0x10000
	v_add_u32_e32 v157, s5, v155
	ds_read_b128 v[158:161], v157
	ds_read_b128 v[162:165], v157 offset:1024
	ds_read_b128 v[166:169], v157 offset:2048
	ds_read_b128 v[170:173], v157 offset:3072
	s_add_u32 s44, s10, s0
	s_addc_u32 s45, s11, s1
	v_lshl_add_u64 v[174:175], v[150:151], 0, s[14:15]
	s_add_i32 m0, s17, 0xc000
	ds_read_b128 v[194:197], v156
	ds_read_b128 v[198:201], v156 offset:1024
	ds_read_b128 v[202:205], v156 offset:2048
	ds_read_b128 v[206:209], v156 offset:3072
	ds_read_b128 v[210:213], v156 offset:4096
	ds_read_b128 v[214:217], v156 offset:5120
	ds_read_b128 v[218:221], v156 offset:6144
	ds_read_b128 v[222:225], v156 offset:7168
	global_load_lds_dwordx4 v[174:175], off
	s_add_i32 m0, s17, 0xe000
	v_lshl_add_u64 v[174:175], v[152:153], 0, s[14:15]
	global_load_lds_dwordx4 v[174:175], off
	s_waitcnt lgkmcnt(8)
	s_barrier
	s_waitcnt lgkmcnt(0)
	s_setprio 1
	v_mfma_f32_16x16x32_bf16 v[126:129], v[158:161], v[194:197], v[126:129]
	v_mfma_f32_16x16x32_bf16 v[98:101], v[166:169], v[194:197], v[98:101]
	v_mfma_f32_16x16x32_bf16 v[122:125], v[158:161], v[202:205], v[122:125]
	v_mfma_f32_16x16x32_bf16 v[94:97], v[166:169], v[202:205], v[94:97]
	v_mfma_f32_16x16x32_bf16 v[118:121], v[158:161], v[210:213], v[118:121]
	v_mfma_f32_16x16x32_bf16 v[90:93], v[166:169], v[210:213], v[90:93]
	v_mfma_f32_16x16x32_bf16 v[114:117], v[158:161], v[218:221], v[114:117]
	v_mfma_f32_16x16x32_bf16 v[82:85], v[166:169], v[218:221], v[82:85]
	v_mfma_f32_16x16x32_bf16 v[126:129], v[162:165], v[198:201], v[126:129]
	v_mfma_f32_16x16x32_bf16 v[98:101], v[170:173], v[198:201], v[98:101]
	v_mfma_f32_16x16x32_bf16 v[122:125], v[162:165], v[206:209], v[122:125]
	v_mfma_f32_16x16x32_bf16 v[94:97], v[170:173], v[206:209], v[94:97]
	v_mfma_f32_16x16x32_bf16 v[118:121], v[162:165], v[214:217], v[118:121]
	v_mfma_f32_16x16x32_bf16 v[90:93], v[170:173], v[214:217], v[90:93]
	v_mfma_f32_16x16x32_bf16 v[114:117], v[162:165], v[222:225], v[114:117]
	v_mfma_f32_16x16x32_bf16 v[82:85], v[170:173], v[222:225], v[82:85]
	s_setprio 0
	s_barrier
	s_add_i32 s36, 0, 0x14000
	s_add_i32 s0, s5, s16
	v_add_u32_e32 v157, s36, v155
	v_lshl_add_u64 v[174:175], s[44:45], 0, v[130:131]
	s_mov_b32 m0, s0
	ds_read_b128 v[226:229], v157
	ds_read_b128 v[230:233], v157 offset:1024
	ds_read_b128 v[234:237], v157 offset:2048
	ds_read_b128 v[238:241], v157 offset:3072
	global_load_lds_dwordx4 v[174:175], off
	s_add_i32 m0, s0, 0x2000
	v_lshl_add_u64 v[192:193], s[44:45], 0, v[132:133]
	global_load_lds_dwordx4 v[192:193], off
	s_barrier
	s_waitcnt lgkmcnt(0)
	s_setprio 1
	v_mfma_f32_16x16x32_bf16 v[74:77], v[226:229], v[194:197], v[74:77]
	v_mfma_f32_16x16x32_bf16 v[46:49], v[234:237], v[194:197], v[46:49]
	v_mfma_f32_16x16x32_bf16 v[66:69], v[226:229], v[202:205], v[66:69]
	v_mfma_f32_16x16x32_bf16 v[38:41], v[234:237], v[202:205], v[38:41]
	v_mfma_f32_16x16x32_bf16 v[58:61], v[226:229], v[210:213], v[58:61]
	v_mfma_f32_16x16x32_bf16 v[30:33], v[234:237], v[210:213], v[30:33]
	v_mfma_f32_16x16x32_bf16 v[50:53], v[226:229], v[218:221], v[50:53]
	v_mfma_f32_16x16x32_bf16 v[22:25], v[234:237], v[218:221], v[22:25]
	v_mfma_f32_16x16x32_bf16 v[74:77], v[230:233], v[198:201], v[74:77]
	v_mfma_f32_16x16x32_bf16 v[46:49], v[238:241], v[198:201], v[46:49]
	v_mfma_f32_16x16x32_bf16 v[66:69], v[230:233], v[206:209], v[66:69]
	v_mfma_f32_16x16x32_bf16 v[38:41], v[238:241], v[206:209], v[38:41]
	v_mfma_f32_16x16x32_bf16 v[58:61], v[230:233], v[214:217], v[58:61]
	v_mfma_f32_16x16x32_bf16 v[30:33], v[238:241], v[214:217], v[30:33]
	v_mfma_f32_16x16x32_bf16 v[50:53], v[230:233], v[222:225], v[50:53]
	v_mfma_f32_16x16x32_bf16 v[22:25], v[238:241], v[222:225], v[22:25]
	s_setprio 0
	s_mov_b32 m0, s17
	v_lshl_add_u64 v[242:243], s[40:41], 0, v[130:131]
	s_barrier
	ds_read_b128 v[194:197], v156 offset:16384
	ds_read_b128 v[198:201], v156 offset:17408
	ds_read_b128 v[202:205], v156 offset:18432
	ds_read_b128 v[206:209], v156 offset:19456
	ds_read_b128 v[210:213], v156 offset:20480
	ds_read_b128 v[214:217], v156 offset:21504
	ds_read_b128 v[218:221], v156 offset:22528
	ds_read_b128 v[222:225], v156 offset:23552
	global_load_lds_dwordx4 v[242:243], off
	s_mov_b32 m0, s18
	v_lshl_add_u64 v[244:245], s[40:41], 0, v[132:133]
	global_load_lds_dwordx4 v[244:245], off
	s_barrier
	s_waitcnt lgkmcnt(0)
	s_setprio 1
	v_mfma_f32_16x16x32_bf16 v[110:113], v[158:161], v[194:197], v[110:113]
	v_mfma_f32_16x16x32_bf16 v[78:81], v[166:169], v[194:197], v[78:81]
	v_mfma_f32_16x16x32_bf16 v[106:109], v[158:161], v[202:205], v[106:109]
	v_mfma_f32_16x16x32_bf16 v[70:73], v[166:169], v[202:205], v[70:73]
	v_mfma_f32_16x16x32_bf16 v[102:105], v[158:161], v[210:213], v[102:105]
	v_mfma_f32_16x16x32_bf16 v[62:65], v[166:169], v[210:213], v[62:65]
	v_mfma_f32_16x16x32_bf16 v[86:89], v[158:161], v[218:221], v[86:89]
	v_mfma_f32_16x16x32_bf16 v[54:57], v[166:169], v[218:221], v[54:57]
	v_mfma_f32_16x16x32_bf16 v[110:113], v[162:165], v[198:201], v[110:113]
	v_mfma_f32_16x16x32_bf16 v[78:81], v[170:173], v[198:201], v[78:81]
	v_mfma_f32_16x16x32_bf16 v[106:109], v[162:165], v[206:209], v[106:109]
	v_mfma_f32_16x16x32_bf16 v[70:73], v[170:173], v[206:209], v[70:73]
	v_mfma_f32_16x16x32_bf16 v[102:105], v[162:165], v[214:217], v[102:105]
	v_mfma_f32_16x16x32_bf16 v[62:65], v[170:173], v[214:217], v[62:65]
	v_mfma_f32_16x16x32_bf16 v[86:89], v[162:165], v[222:225], v[86:89]
	v_mfma_f32_16x16x32_bf16 v[54:57], v[170:173], v[222:225], v[54:57]
	s_setprio 0
	s_barrier
; #define PG8_STAGE(bufoff, gbase) do { _Pragma("unroll") for (int _i = 0; _i < 2; ++_i) \
;         __builtin_amdgcn_global_load_lds((const unsigned*)((const char*)(gbase) + voff[_i]), (LAS unsigned*)(lds + (bufoff) + ldsw + _i * 8192), 16, 0, 0); } while (0)
; #define PG8_LDA(dst, b, h) do { _Pragma("unroll") for (int m = 0; m < 4; ++m) _Pragma("unroll") for (int k = 0; k < 2; ++k) dst[m][k] = *(const LAS bf16x8*)(lds + PG8_SA(b, h) + aoff + m * 2048 + k * 1024); } while (0)
; #define PG8_LDB(dst, b, h) do { _Pragma("unroll") for (int n = 0; n < 2; ++n) _Pragma("unroll") for (int k = 0; k < 2; ++k) dst[n][k] = *(const LAS bf16x8*)(lds + PG8_SB(b, h) + boff + n * 2048 + k * 1024); } while (0)
; #define PG8_WAIT_V(n) asm volatile("s_waitcnt vmcnt(" #n ")" ::: "memory")
; #define PG8_WAIT_L(n) asm volatile("s_waitcnt lgkmcnt(" #n ")" ::: "memory")
; #define PG8_BAR __builtin_amdgcn_s_barrier()
; #define PG8_SCHED __builtin_amdgcn_sched_barrier(0)
;     ...
;             PG8_STAGE(PG8_SB(0, 1), b2 + hstep);
;             PG8_WAIT_V(6); PG8_BAR; PG8_MMA(1, 1, At, B1); PG8_BAR;
;             PG8_LDB(B0, 1, 0); PG8_SCHED; PG8_LDA(At, 1, 0); PG8_STAGE(PG8_SA(0, 1), a2 + hstep);
;             PG8_WAIT_L(8); PG8_BAR; PG8_WAIT_L(0); PG8_MMA(0, 0, At, B0); PG8_BAR; PG8_SCHED;
;             PG8_LDB(B1, 1, 1); PG8_STAGE(PG8_SB(1, 0), b3);
;             PG8_BAR; PG8_WAIT_L(0); PG8_MMA(0, 1, At, B1); PG8_BAR;
;             PG8_LDA(At, 1, 1); PG8_STAGE(PG8_SA(1, 0), a3);
;             PG8_BAR; PG8_WAIT_L(0); PG8_MMA(1, 0, At, B0); PG8_BAR; PG8_SCHED;
;             PG8_STAGE(PG8_SB(1, 1), b3 + hstep);
;             PG8_WAIT_V(6); PG8_BAR; PG8_MMA(1, 1, At, B1); PG8_BAR;
	s_add_u32 s0, s44, s7
	s_addc_u32 s1, s45, 0
	s_add_i32 s5, s36, s16
	v_lshl_add_u64 v[246:247], s[0:1], 0, v[130:131]
	s_mov_b32 m0, s5
	v_lshl_add_u64 v[248:249], s[0:1], 0, v[132:133]
	global_load_lds_dwordx4 v[246:247], off
	s_add_i32 m0, s5, 0x2000
	s_nop 0
	global_load_lds_dwordx4 v[248:249], off
	s_waitcnt vmcnt(6)
	s_barrier
	s_setprio 1
	v_mfma_f32_16x16x32_bf16 v[42:45], v[226:229], v[194:197], v[42:45]
	v_mfma_f32_16x16x32_bf16 v[14:17], v[234:237], v[194:197], v[14:17]
	v_mfma_f32_16x16x32_bf16 v[34:37], v[226:229], v[202:205], v[34:37]
	v_mfma_f32_16x16x32_bf16 v[10:13], v[234:237], v[202:205], v[10:13]
	v_mfma_f32_16x16x32_bf16 v[26:29], v[226:229], v[210:213], v[26:29]
	v_mfma_f32_16x16x32_bf16 v[6:9], v[234:237], v[210:213], v[6:9]
	v_mfma_f32_16x16x32_bf16 v[18:21], v[226:229], v[218:221], v[18:21]
	v_mfma_f32_16x16x32_bf16 v[2:5], v[234:237], v[218:221], v[2:5]
	v_mfma_f32_16x16x32_bf16 v[42:45], v[230:233], v[198:201], v[42:45]
	v_mfma_f32_16x16x32_bf16 v[14:17], v[238:241], v[198:201], v[14:17]
	v_mfma_f32_16x16x32_bf16 v[34:37], v[230:233], v[206:209], v[34:37]
	v_mfma_f32_16x16x32_bf16 v[10:13], v[238:241], v[206:209], v[10:13]
	v_mfma_f32_16x16x32_bf16 v[26:29], v[230:233], v[214:217], v[26:29]
	v_mfma_f32_16x16x32_bf16 v[6:9], v[238:241], v[214:217], v[6:9]
	v_mfma_f32_16x16x32_bf16 v[18:21], v[230:233], v[222:225], v[18:21]
	v_mfma_f32_16x16x32_bf16 v[2:5], v[238:241], v[222:225], v[2:5]
	s_setprio 0
	s_add_i32 s5, 0, 0x18000
	v_add_u32_e32 v157, s5, v155
	s_barrier
	ds_read_b128 v[158:161], v157
	ds_read_b128 v[162:165], v157 offset:1024
	ds_read_b128 v[166:169], v157 offset:2048
	ds_read_b128 v[170:173], v157 offset:3072
	s_add_u32 s0, s40, s7
	s_addc_u32 s1, s41, 0
	s_mov_b32 m0, s19
	v_lshl_add_u64 v[226:227], s[0:1], 0, v[130:131]
	ds_read_b128 v[194:197], v156 offset:32768
	ds_read_b128 v[198:201], v156 offset:33792
	ds_read_b128 v[202:205], v156 offset:34816
	ds_read_b128 v[206:209], v156 offset:35840
	ds_read_b128 v[210:213], v156 offset:36864
	ds_read_b128 v[214:217], v156 offset:37888
	ds_read_b128 v[218:221], v156 offset:38912
	ds_read_b128 v[222:225], v156 offset:39936
	global_load_lds_dwordx4 v[226:227], off
	s_mov_b32 m0, s20
	v_lshl_add_u64 v[226:227], s[0:1], 0, v[132:133]
	global_load_lds_dwordx4 v[226:227], off
	s_waitcnt lgkmcnt(8)
	s_barrier
	s_waitcnt lgkmcnt(0)
	s_setprio 1
	v_mfma_f32_16x16x32_bf16 v[126:129], v[158:161], v[194:197], v[126:129]
	v_mfma_f32_16x16x32_bf16 v[98:101], v[166:169], v[194:197], v[98:101]
	v_mfma_f32_16x16x32_bf16 v[122:125], v[158:161], v[202:205], v[122:125]
	v_mfma_f32_16x16x32_bf16 v[94:97], v[166:169], v[202:205], v[94:97]
	v_mfma_f32_16x16x32_bf16 v[118:121], v[158:161], v[210:213], v[118:121]
	v_mfma_f32_16x16x32_bf16 v[90:93], v[166:169], v[210:213], v[90:93]
	v_mfma_f32_16x16x32_bf16 v[114:117], v[158:161], v[218:221], v[114:117]
	v_mfma_f32_16x16x32_bf16 v[82:85], v[166:169], v[218:221], v[82:85]
	v_mfma_f32_16x16x32_bf16 v[126:129], v[162:165], v[198:201], v[126:129]
	v_mfma_f32_16x16x32_bf16 v[98:101], v[170:173], v[198:201], v[98:101]
	v_mfma_f32_16x16x32_bf16 v[122:125], v[162:165], v[206:209], v[122:125]
	v_mfma_f32_16x16x32_bf16 v[94:97], v[170:173], v[206:209], v[94:97]
	v_mfma_f32_16x16x32_bf16 v[118:121], v[162:165], v[214:217], v[118:121]
	v_mfma_f32_16x16x32_bf16 v[90:93], v[170:173], v[214:217], v[90:93]
	v_mfma_f32_16x16x32_bf16 v[114:117], v[162:165], v[222:225], v[114:117]
	v_mfma_f32_16x16x32_bf16 v[82:85], v[170:173], v[222:225], v[82:85]
	s_setprio 0
	s_barrier
	s_add_i32 s0, 0, 0x1c000
	s_add_i32 s1, s5, s16
	v_add_u32_e32 v157, s0, v155
	v_lshl_add_u64 v[174:175], v[174:175], 0, s[88:89]
	s_mov_b32 m0, s1
	ds_read_b128 v[226:229], v157
	ds_read_b128 v[230:233], v157 offset:1024
	ds_read_b128 v[234:237], v157 offset:2048
	ds_read_b128 v[238:241], v157 offset:3072
	global_load_lds_dwordx4 v[174:175], off
	s_add_i32 m0, s1, 0x2000
	v_lshl_add_u64 v[174:175], v[192:193], 0, s[88:89]
	global_load_lds_dwordx4 v[174:175], off
	s_barrier
	s_waitcnt lgkmcnt(0)
	s_setprio 1
	v_mfma_f32_16x16x32_bf16 v[74:77], v[226:229], v[194:197], v[74:77]
	v_mfma_f32_16x16x32_bf16 v[46:49], v[234:237], v[194:197], v[46:49]
	v_mfma_f32_16x16x32_bf16 v[66:69], v[226:229], v[202:205], v[66:69]
	v_mfma_f32_16x16x32_bf16 v[38:41], v[234:237], v[202:205], v[38:41]
	v_mfma_f32_16x16x32_bf16 v[58:61], v[226:229], v[210:213], v[58:61]
	v_mfma_f32_16x16x32_bf16 v[30:33], v[234:237], v[210:213], v[30:33]
	v_mfma_f32_16x16x32_bf16 v[50:53], v[226:229], v[218:221], v[50:53]
	v_mfma_f32_16x16x32_bf16 v[22:25], v[234:237], v[218:221], v[22:25]
	v_mfma_f32_16x16x32_bf16 v[74:77], v[230:233], v[198:201], v[74:77]
	v_mfma_f32_16x16x32_bf16 v[46:49], v[238:241], v[198:201], v[46:49]
	v_mfma_f32_16x16x32_bf16 v[66:69], v[230:233], v[206:209], v[66:69]
	v_mfma_f32_16x16x32_bf16 v[38:41], v[238:241], v[206:209], v[38:41]
	v_mfma_f32_16x16x32_bf16 v[58:61], v[230:233], v[214:217], v[58:61]
	v_mfma_f32_16x16x32_bf16 v[30:33], v[238:241], v[214:217], v[30:33]
	v_mfma_f32_16x16x32_bf16 v[50:53], v[230:233], v[222:225], v[50:53]
	v_mfma_f32_16x16x32_bf16 v[22:25], v[238:241], v[222:225], v[22:25]
	s_setprio 0
	s_mov_b32 m0, s28
	v_lshl_add_u64 v[174:175], v[242:243], 0, s[88:89]
	s_barrier
	ds_read_b128 v[194:197], v156 offset:49152
	ds_read_b128 v[198:201], v156 offset:50176
	ds_read_b128 v[202:205], v156 offset:51200
	ds_read_b128 v[206:209], v156 offset:52224
	ds_read_b128 v[210:213], v156 offset:53248
	ds_read_b128 v[214:217], v156 offset:54272
	ds_read_b128 v[218:221], v156 offset:55296
	ds_read_b128 v[222:225], v156 offset:56320
	global_load_lds_dwordx4 v[174:175], off
	s_mov_b32 m0, s29
	v_lshl_add_u64 v[174:175], v[244:245], 0, s[88:89]
	global_load_lds_dwordx4 v[174:175], off
	s_barrier
; #define PG8_STAGE(bufoff, gbase) do { _Pragma("unroll") for (int _i = 0; _i < 2; ++_i) \
;         __builtin_amdgcn_global_load_lds((const unsigned*)((const char*)(gbase) + voff[_i]), (LAS unsigned*)(lds + (bufoff) + ldsw + _i * 8192), 16, 0, 0); } while (0)
; #define PG8_WAIT_V(n) asm volatile("s_waitcnt vmcnt(" #n ")" ::: "memory")
;     ...
;             PG8_WAIT_V(6); PG8_BAR; PG8_MMA(1, 1, At, B1); PG8_BAR;
;             PG8_LDB(B0, 1, 0); PG8_SCHED; PG8_LDA(At, 1, 0); PG8_STAGE(PG8_SA(0, 1), a2 + hstep);
;             PG8_WAIT_L(8); PG8_BAR; PG8_WAIT_L(0); PG8_MMA(0, 0, At, B0); PG8_BAR; PG8_SCHED;
;             PG8_LDB(B1, 1, 1); PG8_STAGE(PG8_SB(1, 0), b3);
;             PG8_BAR; PG8_WAIT_L(0); PG8_MMA(0, 1, At, B1); PG8_BAR;
;             PG8_LDA(At, 1, 1); PG8_STAGE(PG8_SA(1, 0), a3);
;             PG8_BAR; PG8_WAIT_L(0); PG8_MMA(1, 0, At, B0); PG8_BAR; PG8_SCHED;
;             PG8_STAGE(PG8_SB(1, 1), b3 + hstep);
;             PG8_WAIT_V(6); PG8_BAR; PG8_MMA(1, 1, At, B1); PG8_BAR;
;     __device__ __forceinline__ void operator()(Acc& acc, int pm, int pn, int wr, int wc, int fr, int fq) const {
;         const int brow = pm * 256;
;         const bool lat = brow < T_LAT;
;         const float* xin = lat ? xin_lat : xin_ctx;
;         float* xout = lat ? xout_lat : xout_ctx;
;         const int rsub = lat ? 0 : T_LAT;
;         const int mi = lat ? (brow >> 12) : 8;
;         const int c0 = pn * 256 + wc * 32 + fq * 4;
;         const float* gp = modv_l + (size_t)mi * 6144 + gate_i * 1024 + c0;
; #pragma unroll
;         for (int bj = 0; bj < 2; ++bj)
; #pragma unroll
;             for (int n = 0; n < 2; ++n) {
;                 const f32x4 gv = *reinterpret_cast<const f32x4*>(gp + bj * 128 + n * 16);
; #pragma unroll
;                 for (int ai = 0; ai < 2; ++ai)
; #pragma unroll
;                     for (int m = 0; m < 4; ++m) {
;                         const size_t o = (size_t)(brow + ai * 128 + wr * 64 + m * 16 + fr - rsub) * DM + c0 + bj * 128 + n * 16;
;                         const f32x4 xi = *reinterpret_cast<const f32x4*>(xin + o);
;                         const f32x4 a = acc[ai][bj][m][n];
;                         f32x4 r = {xi[0] + gv[0] * a[0], xi[1] + gv[1] * a[1], xi[2] + gv[2] * a[2], xi[3] + gv[3] * a[3]};
;                         *reinterpret_cast<f32x4*>(xout + o) = r;
;                     }
;             }
	s_waitcnt lgkmcnt(0)
	s_setprio 1
	v_mfma_f32_16x16x32_bf16 v[110:113], v[158:161], v[194:197], v[110:113]
	v_mfma_f32_16x16x32_bf16 v[78:81], v[166:169], v[194:197], v[78:81]
	v_mfma_f32_16x16x32_bf16 v[106:109], v[158:161], v[202:205], v[106:109]
	v_mfma_f32_16x16x32_bf16 v[70:73], v[166:169], v[202:205], v[70:73]
	v_mfma_f32_16x16x32_bf16 v[102:105], v[158:161], v[210:213], v[102:105]
	v_mfma_f32_16x16x32_bf16 v[62:65], v[166:169], v[210:213], v[62:65]
	v_mfma_f32_16x16x32_bf16 v[86:89], v[158:161], v[218:221], v[86:89]
	v_mfma_f32_16x16x32_bf16 v[54:57], v[166:169], v[218:221], v[54:57]
	v_mfma_f32_16x16x32_bf16 v[110:113], v[162:165], v[198:201], v[110:113]
	v_mfma_f32_16x16x32_bf16 v[78:81], v[170:173], v[198:201], v[78:81]
	v_mfma_f32_16x16x32_bf16 v[106:109], v[162:165], v[206:209], v[106:109]
	v_mfma_f32_16x16x32_bf16 v[70:73], v[170:173], v[206:209], v[70:73]
	v_mfma_f32_16x16x32_bf16 v[102:105], v[162:165], v[214:217], v[102:105]
	v_mfma_f32_16x16x32_bf16 v[62:65], v[170:173], v[214:217], v[62:65]
	v_mfma_f32_16x16x32_bf16 v[86:89], v[162:165], v[222:225], v[86:89]
	v_mfma_f32_16x16x32_bf16 v[54:57], v[170:173], v[222:225], v[54:57]
	s_setprio 0
	s_barrier
	s_add_i32 s0, s0, s16
	s_mov_b32 m0, s0
	v_lshl_add_u64 v[158:159], v[246:247], 0, s[88:89]
	global_load_lds_dwordx4 v[158:159], off
	s_add_i32 m0, s0, 0x2000
	v_lshl_add_u64 v[158:159], v[248:249], 0, s[88:89]
	global_load_lds_dwordx4 v[158:159], off
	s_waitcnt vmcnt(6)
	s_barrier
	s_setprio 1
	v_mfma_f32_16x16x32_bf16 v[42:45], v[226:229], v[194:197], v[42:45]
	v_mfma_f32_16x16x32_bf16 v[14:17], v[234:237], v[194:197], v[14:17]
	v_mfma_f32_16x16x32_bf16 v[34:37], v[226:229], v[202:205], v[34:37]
	v_mfma_f32_16x16x32_bf16 v[10:13], v[234:237], v[202:205], v[10:13]
	v_mfma_f32_16x16x32_bf16 v[26:29], v[226:229], v[210:213], v[26:29]
	v_mfma_f32_16x16x32_bf16 v[6:9], v[234:237], v[210:213], v[6:9]
	v_mfma_f32_16x16x32_bf16 v[18:21], v[226:229], v[218:221], v[18:21]
	v_mfma_f32_16x16x32_bf16 v[2:5], v[234:237], v[218:221], v[2:5]
	v_mfma_f32_16x16x32_bf16 v[42:45], v[230:233], v[198:201], v[42:45]
	v_mfma_f32_16x16x32_bf16 v[14:17], v[238:241], v[198:201], v[14:17]
	v_mfma_f32_16x16x32_bf16 v[34:37], v[230:233], v[206:209], v[34:37]
	v_mfma_f32_16x16x32_bf16 v[10:13], v[238:241], v[206:209], v[10:13]
	v_mfma_f32_16x16x32_bf16 v[26:29], v[230:233], v[214:217], v[26:29]
	v_mfma_f32_16x16x32_bf16 v[6:9], v[238:241], v[214:217], v[6:9]
	v_mfma_f32_16x16x32_bf16 v[18:21], v[230:233], v[222:225], v[18:21]
	v_mfma_f32_16x16x32_bf16 v[2:5], v[238:241], v[222:225], v[2:5]
	s_setprio 0
	s_add_u32 s14, s14, 0x100
	s_addc_u32 s15, s15, 0
	s_cmp_ge_u32 s31, s22
	s_mov_b32 s5, s31
	s_barrier
	s_cbranch_scc0 .LBB0_1408
	v_readlane_b32 s0, v253, 63
	v_readlane_b32 s10, v255, 26
	v_readlane_b32 s11, v255, 27
	v_readlane_b32 s12, v254, 6
	v_readlane_b32 s16, v254, 10
	v_readlane_b32 s17, v254, 11
	v_readlane_b32 s13, v254, 7
	v_readlane_b32 s14, v254, 8
	v_readlane_b32 s15, v254, 9
	v_readlane_b32 s18, v254, 12
	v_readlane_b32 s19, v254, 13
	v_mov_b32_e32 v161, v0
	v_lshl_or_b32 v157, v154, 2, s0
	v_or_b32_e32 v157, s23, v157
	v_lshlrev_b32_e32 v160, 2, v157
	v_readlane_b32 s0, v253, 61
	s_nop 1
	v_lshl_add_u64 v[158:159], s[50:51], 0, v[160:161]
	v_add_u32_e32 v162, s0, v1
	s_mov_b64 s[0:1], 0x32000
	v_lshl_add_u64 v[158:159], v[158:159], 0, s[0:1]
	global_load_dwordx4 v[192:195], v[158:159], off
	global_load_dwordx4 v[196:199], v[158:159], off offset:64
	global_load_dwordx4 v[200:203], v[158:159], off offset:512
	global_load_dwordx4 v[204:207], v[158:159], off offset:576
	v_add_u32_e32 v163, 0xffff8000, v162
	v_lshl_or_b32 v164, v163, 12, v160
	v_add_u32_e32 v165, 0x10000, v164
	v_add_u32_e32 v166, 0x20000, v164
	v_add_u32_e32 v167, 0x30000, v164
	v_add_u32_e32 v168, 0x80000, v164
	v_add_u32_e32 v169, 0x90000, v164
	v_add_u32_e32 v170, 0xa0000, v164
	v_add_u32_e32 v171, 0xb0000, v164
	global_load_dwordx4 v[208:211], v164, s[10:11]
	global_load_dwordx4 v[212:215], v164, s[10:11] offset:64
	global_load_dwordx4 v[216:219], v165, s[10:11]
	global_load_dwordx4 v[220:223], v165, s[10:11] offset:64
	global_load_dwordx4 v[224:227], v166, s[10:11]
	global_load_dwordx4 v[228:231], v166, s[10:11] offset:64
	global_load_dwordx4 v[232:235], v167, s[10:11]
	global_load_dwordx4 v[236:239], v167, s[10:11] offset:64
	global_load_dwordx4 v[240:243], v168, s[10:11]
	global_load_dwordx4 v[244:247], v168, s[10:11] offset:64
	s_cmpk_lt_u32 s4, 0x100
	s_waitcnt vmcnt(9)
	v_pk_fma_f32 v[126:127], v[126:127], v[192:193], v[208:209]
	v_pk_fma_f32 v[128:129], v[128:129], v[194:195], v[210:211]
	global_store_dwordx4 v164, v[126:129], s[16:17] sc1
	global_load_dwordx4 v[208:211], v169, s[10:11]
	s_waitcnt vmcnt(10)
	v_pk_fma_f32 v[98:99], v[98:99], v[196:197], v[212:213]
	v_pk_fma_f32 v[100:101], v[100:101], v[198:199], v[214:215]
	global_store_dwordx4 v164, v[98:101], s[16:17] offset:64 sc1
	global_load_dwordx4 v[212:215], v169, s[10:11] offset:64
	s_waitcnt vmcnt(11)
	v_pk_fma_f32 v[122:123], v[122:123], v[192:193], v[216:217]
	v_pk_fma_f32 v[124:125], v[124:125], v[194:195], v[218:219]
	global_store_dwordx4 v165, v[122:125], s[16:17] sc1
	global_load_dwordx4 v[216:219], v170, s[10:11]
	s_waitcnt vmcnt(12)
	v_pk_fma_f32 v[94:95], v[94:95], v[196:197], v[220:221]
	v_pk_fma_f32 v[96:97], v[96:97], v[198:199], v[222:223]
	global_store_dwordx4 v165, v[94:97], s[16:17] offset:64 sc1
	global_load_dwordx4 v[220:223], v170, s[10:11] offset:64
	s_waitcnt vmcnt(13)
	v_pk_fma_f32 v[118:119], v[118:119], v[192:193], v[224:225]
	v_pk_fma_f32 v[120:121], v[120:121], v[194:195], v[226:227]
	global_store_dwordx4 v166, v[118:121], s[16:17] sc1
	global_load_dwordx4 v[224:227], v171, s[10:11]
	s_waitcnt vmcnt(14)
; #define PG8_WAIT_V(n) asm volatile("s_waitcnt vmcnt(" #n ")" ::: "memory")
; #define PG8_BAR __builtin_amdgcn_s_barrier()
;     ...
;     PG8_WAIT_V(0);
;     if (wr == 0) PG8_BAR;
;     PG8_BAR;
;     __device__ __forceinline__ void operator()(Acc& acc, int pm, int pn, int wr, int wc, int fr, int fq) const {
;     ...
; #pragma unroll
;         for (int bj = 0; bj < 2; ++bj)
; #pragma unroll
;             for (int n = 0; n < 2; ++n) {
;                 const f32x4 gv = *reinterpret_cast<const f32x4*>(gp + bj * 128 + n * 16);
; #pragma unroll
;                 for (int ai = 0; ai < 2; ++ai)
; #pragma unroll
;                     for (int m = 0; m < 4; ++m) {
;                         const size_t o = (size_t)(brow + ai * 128 + wr * 64 + m * 16 + fr - rsub) * DM + c0 + bj * 128 + n * 16;
;                         const f32x4 xi = *reinterpret_cast<const f32x4*>(xin + o);
;                         const f32x4 a = acc[ai][bj][m][n];
;                         f32x4 r = {xi[0] + gv[0] * a[0], xi[1] + gv[1] * a[1], xi[2] + gv[2] * a[2], xi[3] + gv[3] * a[3]};
;                         *reinterpret_cast<f32x4*>(xout + o) = r;
;                     }
;             }
	v_pk_fma_f32 v[90:91], v[90:91], v[196:197], v[228:229]
	v_pk_fma_f32 v[92:93], v[92:93], v[198:199], v[230:231]
	global_store_dwordx4 v166, v[90:93], s[16:17] offset:64 sc1
	global_load_dwordx4 v[228:231], v171, s[10:11] offset:64
	s_waitcnt vmcnt(15)
	v_pk_fma_f32 v[114:115], v[114:115], v[192:193], v[232:233]
	v_pk_fma_f32 v[116:117], v[116:117], v[194:195], v[234:235]
	global_store_dwordx4 v167, v[114:117], s[16:17] sc1
	global_load_dwordx4 v[232:235], v164, s[10:11] offset:512
	s_waitcnt vmcnt(16)
	v_pk_fma_f32 v[82:83], v[82:83], v[196:197], v[236:237]
	v_pk_fma_f32 v[84:85], v[84:85], v[198:199], v[238:239]
	global_store_dwordx4 v167, v[82:85], s[16:17] offset:64 sc1
	global_load_dwordx4 v[236:239], v164, s[10:11] offset:576
	s_waitcnt vmcnt(17)
	v_pk_fma_f32 v[110:111], v[110:111], v[192:193], v[240:241]
	v_pk_fma_f32 v[112:113], v[112:113], v[194:195], v[242:243]
	global_store_dwordx4 v168, v[110:113], s[16:17] sc1
	global_load_dwordx4 v[240:243], v165, s[10:11] offset:512
	s_waitcnt vmcnt(18)
	v_pk_fma_f32 v[78:79], v[78:79], v[196:197], v[244:245]
	v_pk_fma_f32 v[80:81], v[80:81], v[198:199], v[246:247]
	global_store_dwordx4 v168, v[78:81], s[16:17] offset:64 sc1
	global_load_dwordx4 v[244:247], v165, s[10:11] offset:576
	s_waitcnt vmcnt(18)
	v_pk_fma_f32 v[106:107], v[106:107], v[192:193], v[208:209]
	v_pk_fma_f32 v[108:109], v[108:109], v[194:195], v[210:211]
	global_store_dwordx4 v169, v[106:109], s[16:17] sc1
	global_load_dwordx4 v[208:211], v166, s[10:11] offset:512
	s_waitcnt vmcnt(18)
	v_pk_fma_f32 v[70:71], v[70:71], v[196:197], v[212:213]
	v_pk_fma_f32 v[72:73], v[72:73], v[198:199], v[214:215]
	global_store_dwordx4 v169, v[70:73], s[16:17] offset:64 sc1
	global_load_dwordx4 v[212:215], v166, s[10:11] offset:576
	s_waitcnt vmcnt(18)
	v_pk_fma_f32 v[102:103], v[102:103], v[192:193], v[216:217]
	v_pk_fma_f32 v[104:105], v[104:105], v[194:195], v[218:219]
	global_store_dwordx4 v170, v[102:105], s[16:17] sc1
	global_load_dwordx4 v[216:219], v167, s[10:11] offset:512
	s_waitcnt vmcnt(18)
	v_pk_fma_f32 v[62:63], v[62:63], v[196:197], v[220:221]
	v_pk_fma_f32 v[64:65], v[64:65], v[198:199], v[222:223]
	global_store_dwordx4 v170, v[62:65], s[16:17] offset:64 sc1
	global_load_dwordx4 v[220:223], v167, s[10:11] offset:576
	s_waitcnt vmcnt(18)
	v_pk_fma_f32 v[86:87], v[86:87], v[192:193], v[224:225]
	v_pk_fma_f32 v[88:89], v[88:89], v[194:195], v[226:227]
	global_store_dwordx4 v171, v[86:89], s[16:17] sc1
	global_load_dwordx4 v[224:227], v168, s[10:11] offset:512
	s_waitcnt vmcnt(18)
	v_pk_fma_f32 v[54:55], v[54:55], v[196:197], v[228:229]
	v_pk_fma_f32 v[56:57], v[56:57], v[198:199], v[230:231]
	global_store_dwordx4 v171, v[54:57], s[16:17] offset:64 sc1
	global_load_dwordx4 v[228:231], v168, s[10:11] offset:576
	s_waitcnt vmcnt(18)
	v_pk_fma_f32 v[74:75], v[74:75], v[200:201], v[232:233]
	v_pk_fma_f32 v[76:77], v[76:77], v[202:203], v[234:235]
	global_store_dwordx4 v164, v[74:77], s[16:17] offset:512 sc1
	global_load_dwordx4 v[232:235], v169, s[10:11] offset:512
	s_waitcnt vmcnt(18)
	v_pk_fma_f32 v[46:47], v[46:47], v[204:205], v[236:237]
	v_pk_fma_f32 v[48:49], v[48:49], v[206:207], v[238:239]
	global_store_dwordx4 v164, v[46:49], s[16:17] offset:576 sc1
	global_load_dwordx4 v[236:239], v169, s[10:11] offset:576
	s_waitcnt vmcnt(18)
	v_pk_fma_f32 v[66:67], v[66:67], v[200:201], v[240:241]
	v_pk_fma_f32 v[68:69], v[68:69], v[202:203], v[242:243]
	global_store_dwordx4 v165, v[66:69], s[16:17] offset:512 sc1
	global_load_dwordx4 v[240:243], v170, s[10:11] offset:512
	s_waitcnt vmcnt(18)
	v_pk_fma_f32 v[38:39], v[38:39], v[204:205], v[244:245]
	v_pk_fma_f32 v[40:41], v[40:41], v[206:207], v[246:247]
	global_store_dwordx4 v165, v[38:41], s[16:17] offset:576 sc1
	global_load_dwordx4 v[244:247], v170, s[10:11] offset:576
	s_waitcnt vmcnt(18)
	v_pk_fma_f32 v[58:59], v[58:59], v[200:201], v[208:209]
	v_pk_fma_f32 v[60:61], v[60:61], v[202:203], v[210:211]
	global_store_dwordx4 v166, v[58:61], s[16:17] offset:512 sc1
	global_load_dwordx4 v[208:211], v171, s[10:11] offset:512
	s_waitcnt vmcnt(18)
	v_pk_fma_f32 v[30:31], v[30:31], v[204:205], v[212:213]
	v_pk_fma_f32 v[32:33], v[32:33], v[206:207], v[214:215]
	global_store_dwordx4 v166, v[30:33], s[16:17] offset:576 sc1
	global_load_dwordx4 v[212:215], v171, s[10:11] offset:576
	s_waitcnt vmcnt(18)
	v_pk_fma_f32 v[50:51], v[50:51], v[200:201], v[216:217]
	v_pk_fma_f32 v[52:53], v[52:53], v[202:203], v[218:219]
	global_store_dwordx4 v167, v[50:53], s[16:17] offset:512 sc1
	s_waitcnt vmcnt(17)
	v_pk_fma_f32 v[22:23], v[22:23], v[204:205], v[220:221]
	v_pk_fma_f32 v[24:25], v[24:25], v[206:207], v[222:223]
	global_store_dwordx4 v167, v[22:25], s[16:17] offset:576 sc1
	s_waitcnt vmcnt(16)
	v_pk_fma_f32 v[42:43], v[42:43], v[200:201], v[224:225]
	v_pk_fma_f32 v[44:45], v[44:45], v[202:203], v[226:227]
	global_store_dwordx4 v168, v[42:45], s[16:17] offset:512 sc1
	s_waitcnt vmcnt(15)
	v_pk_fma_f32 v[14:15], v[14:15], v[204:205], v[228:229]
	v_pk_fma_f32 v[16:17], v[16:17], v[206:207], v[230:231]
	global_store_dwordx4 v168, v[14:17], s[16:17] offset:576 sc1
	s_waitcnt vmcnt(14)
	v_pk_fma_f32 v[34:35], v[34:35], v[200:201], v[232:233]
	v_pk_fma_f32 v[36:37], v[36:37], v[202:203], v[234:235]
	global_store_dwordx4 v169, v[34:37], s[16:17] offset:512 sc1
	s_waitcnt vmcnt(13)
	v_pk_fma_f32 v[10:11], v[10:11], v[204:205], v[236:237]
	v_pk_fma_f32 v[12:13], v[12:13], v[206:207], v[238:239]
	global_store_dwordx4 v169, v[10:13], s[16:17] offset:576 sc1
	s_waitcnt vmcnt(12)
	v_pk_fma_f32 v[26:27], v[26:27], v[200:201], v[240:241]
	v_pk_fma_f32 v[28:29], v[28:29], v[202:203], v[242:243]
	global_store_dwordx4 v170, v[26:29], s[16:17] offset:512 sc1
	s_waitcnt vmcnt(11)
	v_pk_fma_f32 v[6:7], v[6:7], v[204:205], v[244:245]
	v_pk_fma_f32 v[8:9], v[8:9], v[206:207], v[246:247]
	global_store_dwordx4 v170, v[6:9], s[16:17] offset:576 sc1
	s_waitcnt vmcnt(10)
	v_pk_fma_f32 v[18:19], v[18:19], v[200:201], v[208:209]
	v_pk_fma_f32 v[20:21], v[20:21], v[202:203], v[210:211]
	global_store_dwordx4 v171, v[18:21], s[16:17] offset:512 sc1
	s_waitcnt vmcnt(9)
	v_pk_fma_f32 v[2:3], v[2:3], v[204:205], v[212:213]
	v_pk_fma_f32 v[4:5], v[4:5], v[206:207], v[214:215]
	global_store_dwordx4 v171, v[2:5], s[16:17] offset:576 sc1
	s_mov_b32 s0, 0xf80b0000
	s_mov_b32 s1, -1
	s_waitcnt vmcnt(0)
	s_cbranch_scc0 .LBB0_1411
	s_barrier

; #define PG8_STAGE(bufoff, gbase) do { _Pragma("unroll") for (int _i = 0; _i < 2; ++_i) \
;         __builtin_amdgcn_global_load_lds((const unsigned*)((const char*)(gbase) + voff[_i]), (LAS unsigned*)(lds + (bufoff) + ldsw + _i * 8192), 16, 0, 0); } while (0)
; #define PG8_LDA(dst, b, h) do { _Pragma("unroll") for (int m = 0; m < 4; ++m) _Pragma("unroll") for (int k = 0; k < 2; ++k) dst[m][k] = *(const LAS bf16x8*)(lds + PG8_SA(b, h) + aoff + m * 2048 + k * 1024); } while (0)
; #define PG8_LDB(dst, b, h) do { _Pragma("unroll") for (int n = 0; n < 2; ++n) _Pragma("unroll") for (int k = 0; k < 2; ++k) dst[n][k] = *(const LAS bf16x8*)(lds + PG8_SB(b, h) + boff + n * 2048 + k * 1024); } while (0)
; #define PG8_WAIT_V(n) asm volatile("s_waitcnt vmcnt(" #n ")" ::: "memory")
; #define PG8_WAIT_L(n) asm volatile("s_waitcnt lgkmcnt(" #n ")" ::: "memory")
;     ...
;         for (int t = 0; t < nt; t += 2) {
;             const bool last = (t == nt - 2);
;             const char* a1 = cA + (size_t)(t + 1) * kstep;
;             const char* a2 = last ? nA : cA + (size_t)(t + 2) * kstep; const char* b2 = last ? nB : cB + (size_t)(t + 2) * kstep;
;             const char* a3 = a2 + kstep; const char* b3 = b2 + kstep;
;             PG8_LDB(B0, 0, 0); PG8_SCHED; PG8_LDA(At, 0, 0); PG8_STAGE(PG8_SA(1, 1), a1 + hstep);
;             PG8_WAIT_L(8); PG8_BAR; PG8_WAIT_L(0); PG8_MMA(0, 0, At, B0); PG8_BAR; PG8_SCHED;
;             PG8_LDB(B1, 0, 1); PG8_STAGE(PG8_SB(0, 0), b2);
;             PG8_BAR; PG8_WAIT_L(0); PG8_MMA(0, 1, At, B1); PG8_BAR;
;             PG8_LDA(At, 0, 1); PG8_STAGE(PG8_SA(0, 0), a2);
;             PG8_BAR; PG8_WAIT_L(0); PG8_MMA(1, 0, At, B0); PG8_BAR; PG8_SCHED;
;             PG8_STAGE(PG8_SB(0, 1), b2 + hstep);
;             PG8_WAIT_V(6); PG8_BAR; PG8_MMA(1, 1, At, B1); PG8_BAR;
;             PG8_LDB(B0, 1, 0); PG8_SCHED; PG8_LDA(At, 1, 0); PG8_STAGE(PG8_SA(0, 1), a2 + hstep);
;             PG8_WAIT_L(8); PG8_BAR; PG8_WAIT_L(0); PG8_MMA(0, 0, At, B0); PG8_BAR; PG8_SCHED;
;             PG8_LDB(B1, 1, 1); PG8_STAGE(PG8_SB(1, 0), b3);
;             PG8_BAR; PG8_WAIT_L(0); PG8_MMA(0, 1, At, B1); PG8_BAR;
;             PG8_LDA(At, 1, 1); PG8_STAGE(PG8_SA(1, 0), a3);
;             PG8_BAR; PG8_WAIT_L(0); PG8_MMA(1, 0, At, B0); PG8_BAR; PG8_SCHED;
;             PG8_STAGE(PG8_SB(1, 1), b3 + hstep);
;             PG8_WAIT_V(6); PG8_BAR; PG8_MMA(1, 1, At, B1); PG8_BAR;
.LBB0_1563:
	s_add_u32 s0, s12, 0xfffc0080
	s_addc_u32 s1, s13, -1
	s_add_i32 s30, 0, 0x10000
	v_add_u32_e32 v157, s30, v154
	ds_read_b128 v[158:161], v157
	ds_read_b128 v[162:165], v157 offset:1024
	ds_read_b128 v[166:169], v157 offset:2048
	ds_read_b128 v[170:173], v157 offset:3072
	s_cmp_eq_u32 s29, 12
	s_cselect_b32 s59, s7, s1
	s_cselect_b32 s58, s18, s0
	s_cselect_b32 s15, s19, s28
	s_cselect_b32 s14, s22, s23
	v_lshl_add_u64 v[174:175], s[12:13], 0, v[150:151]
	s_add_i32 m0, s11, 0xc000
	ds_read_b128 v[194:197], v156
	ds_read_b128 v[198:201], v156 offset:1024
	ds_read_b128 v[202:205], v156 offset:2048
	ds_read_b128 v[206:209], v156 offset:3072
	ds_read_b128 v[210:213], v156 offset:4096
	ds_read_b128 v[214:217], v156 offset:5120
	ds_read_b128 v[218:221], v156 offset:6144
	ds_read_b128 v[222:225], v156 offset:7168
	global_load_lds_dwordx4 v[174:175], off
	s_add_i32 m0, s11, 0xe000
	v_lshl_add_u64 v[174:175], s[12:13], 0, v[152:153]
	global_load_lds_dwordx4 v[174:175], off
	s_waitcnt lgkmcnt(8)
	s_barrier
	s_waitcnt lgkmcnt(0)
	s_setprio 1
	v_mfma_f32_16x16x32_bf16 v[126:129], v[158:161], v[194:197], v[126:129]
	v_mfma_f32_16x16x32_bf16 v[118:121], v[166:169], v[194:197], v[118:121]
	v_mfma_f32_16x16x32_bf16 v[110:113], v[158:161], v[202:205], v[110:113]
	v_mfma_f32_16x16x32_bf16 v[102:105], v[166:169], v[202:205], v[102:105]
	v_mfma_f32_16x16x32_bf16 v[94:97], v[158:161], v[210:213], v[94:97]
	v_mfma_f32_16x16x32_bf16 v[86:89], v[166:169], v[210:213], v[86:89]
	v_mfma_f32_16x16x32_bf16 v[78:81], v[158:161], v[218:221], v[78:81]
	v_mfma_f32_16x16x32_bf16 v[70:73], v[166:169], v[218:221], v[70:73]
	v_mfma_f32_16x16x32_bf16 v[126:129], v[162:165], v[198:201], v[126:129]
	v_mfma_f32_16x16x32_bf16 v[118:121], v[170:173], v[198:201], v[118:121]
	v_mfma_f32_16x16x32_bf16 v[110:113], v[162:165], v[206:209], v[110:113]
	v_mfma_f32_16x16x32_bf16 v[102:105], v[170:173], v[206:209], v[102:105]
	v_mfma_f32_16x16x32_bf16 v[94:97], v[162:165], v[214:217], v[94:97]
	v_mfma_f32_16x16x32_bf16 v[86:89], v[170:173], v[214:217], v[86:89]
	v_mfma_f32_16x16x32_bf16 v[78:81], v[162:165], v[222:225], v[78:81]
	v_mfma_f32_16x16x32_bf16 v[70:73], v[170:173], v[222:225], v[70:73]
	s_setprio 0
	s_barrier
	s_add_i32 s31, 0, 0x14000
	s_add_i32 s0, s30, s17
	v_add_u32_e32 v157, s31, v154
	v_lshl_add_u64 v[174:175], s[14:15], 0, v[132:133]
	s_mov_b32 m0, s0
	ds_read_b128 v[226:229], v157
	ds_read_b128 v[230:233], v157 offset:1024
	ds_read_b128 v[234:237], v157 offset:2048
	ds_read_b128 v[238:241], v157 offset:3072
	global_load_lds_dwordx4 v[174:175], off
	s_add_i32 m0, s0, 0x2000
	v_lshl_add_u64 v[192:193], s[14:15], 0, v[130:131]
	global_load_lds_dwordx4 v[192:193], off
	s_barrier
	s_waitcnt lgkmcnt(0)
	s_setprio 1
	v_mfma_f32_16x16x32_bf16 v[122:125], v[226:229], v[194:197], v[122:125]
	v_mfma_f32_16x16x32_bf16 v[114:117], v[234:237], v[194:197], v[114:117]
	v_mfma_f32_16x16x32_bf16 v[106:109], v[226:229], v[202:205], v[106:109]
	v_mfma_f32_16x16x32_bf16 v[98:101], v[234:237], v[202:205], v[98:101]
	v_mfma_f32_16x16x32_bf16 v[90:93], v[226:229], v[210:213], v[90:93]
	v_mfma_f32_16x16x32_bf16 v[82:85], v[234:237], v[210:213], v[82:85]
	v_mfma_f32_16x16x32_bf16 v[74:77], v[226:229], v[218:221], v[74:77]
	v_mfma_f32_16x16x32_bf16 v[66:69], v[234:237], v[218:221], v[66:69]
	v_mfma_f32_16x16x32_bf16 v[122:125], v[230:233], v[198:201], v[122:125]
	v_mfma_f32_16x16x32_bf16 v[114:117], v[238:241], v[198:201], v[114:117]
	v_mfma_f32_16x16x32_bf16 v[106:109], v[230:233], v[206:209], v[106:109]
	v_mfma_f32_16x16x32_bf16 v[98:101], v[238:241], v[206:209], v[98:101]
	v_mfma_f32_16x16x32_bf16 v[90:93], v[230:233], v[214:217], v[90:93]
	v_mfma_f32_16x16x32_bf16 v[82:85], v[238:241], v[214:217], v[82:85]
	v_mfma_f32_16x16x32_bf16 v[74:77], v[230:233], v[222:225], v[74:77]
	v_mfma_f32_16x16x32_bf16 v[66:69], v[238:241], v[222:225], v[66:69]
	s_setprio 0
	s_mov_b32 m0, s11
	v_lshl_add_u64 v[242:243], s[58:59], 0, v[132:133]
	s_barrier
	ds_read_b128 v[194:197], v156 offset:16384
	ds_read_b128 v[198:201], v156 offset:17408
	ds_read_b128 v[202:205], v156 offset:18432
	ds_read_b128 v[206:209], v156 offset:19456
	ds_read_b128 v[210:213], v156 offset:20480
	ds_read_b128 v[214:217], v156 offset:21504
	ds_read_b128 v[218:221], v156 offset:22528
	ds_read_b128 v[222:225], v156 offset:23552
	global_load_lds_dwordx4 v[242:243], off
	s_mov_b32 m0, s36
	v_lshl_add_u64 v[244:245], s[58:59], 0, v[130:131]
	global_load_lds_dwordx4 v[244:245], off
	s_barrier
	s_waitcnt lgkmcnt(0)
	s_setprio 1
	v_mfma_f32_16x16x32_bf16 v[62:65], v[158:161], v[194:197], v[62:65]
	v_mfma_f32_16x16x32_bf16 v[54:57], v[166:169], v[194:197], v[54:57]
	v_mfma_f32_16x16x32_bf16 v[46:49], v[158:161], v[202:205], v[46:49]
	v_mfma_f32_16x16x32_bf16 v[38:41], v[166:169], v[202:205], v[38:41]
	v_mfma_f32_16x16x32_bf16 v[30:33], v[158:161], v[210:213], v[30:33]
	v_mfma_f32_16x16x32_bf16 v[22:25], v[166:169], v[210:213], v[22:25]
	v_mfma_f32_16x16x32_bf16 v[14:17], v[158:161], v[218:221], v[14:17]
	v_mfma_f32_16x16x32_bf16 v[6:9], v[166:169], v[218:221], v[6:9]
	v_mfma_f32_16x16x32_bf16 v[62:65], v[162:165], v[198:201], v[62:65]
	v_mfma_f32_16x16x32_bf16 v[54:57], v[170:173], v[198:201], v[54:57]
	v_mfma_f32_16x16x32_bf16 v[46:49], v[162:165], v[206:209], v[46:49]
	v_mfma_f32_16x16x32_bf16 v[38:41], v[170:173], v[206:209], v[38:41]
	v_mfma_f32_16x16x32_bf16 v[30:33], v[162:165], v[214:217], v[30:33]
	v_mfma_f32_16x16x32_bf16 v[22:25], v[170:173], v[214:217], v[22:25]
	v_mfma_f32_16x16x32_bf16 v[14:17], v[162:165], v[222:225], v[14:17]
	v_mfma_f32_16x16x32_bf16 v[6:9], v[170:173], v[222:225], v[6:9]
	s_setprio 0
	s_barrier
; #define PG8_STAGE(bufoff, gbase) do { _Pragma("unroll") for (int _i = 0; _i < 2; ++_i) \
;         __builtin_amdgcn_global_load_lds((const unsigned*)((const char*)(gbase) + voff[_i]), (LAS unsigned*)(lds + (bufoff) + ldsw + _i * 8192), 16, 0, 0); } while (0)
; #define PG8_LDA(dst, b, h) do { _Pragma("unroll") for (int m = 0; m < 4; ++m) _Pragma("unroll") for (int k = 0; k < 2; ++k) dst[m][k] = *(const LAS bf16x8*)(lds + PG8_SA(b, h) + aoff + m * 2048 + k * 1024); } while (0)
; #define PG8_LDB(dst, b, h) do { _Pragma("unroll") for (int n = 0; n < 2; ++n) _Pragma("unroll") for (int k = 0; k < 2; ++k) dst[n][k] = *(const LAS bf16x8*)(lds + PG8_SB(b, h) + boff + n * 2048 + k * 1024); } while (0)
; #define PG8_WAIT_V(n) asm volatile("s_waitcnt vmcnt(" #n ")" ::: "memory")
; #define PG8_WAIT_L(n) asm volatile("s_waitcnt lgkmcnt(" #n ")" ::: "memory")
; #define PG8_BAR __builtin_amdgcn_s_barrier()
; #define PG8_SCHED __builtin_amdgcn_sched_barrier(0)
;     ...
;             PG8_LDB(B1, 0, 1); PG8_STAGE(PG8_SB(0, 0), b2);
;             PG8_BAR; PG8_WAIT_L(0); PG8_MMA(0, 1, At, B1); PG8_BAR;
;             PG8_LDA(At, 0, 1); PG8_STAGE(PG8_SA(0, 0), a2);
;             PG8_BAR; PG8_WAIT_L(0); PG8_MMA(1, 0, At, B0); PG8_BAR; PG8_SCHED;
;             PG8_STAGE(PG8_SB(0, 1), b2 + hstep);
;             PG8_WAIT_V(6); PG8_BAR; PG8_MMA(1, 1, At, B1); PG8_BAR;
;             PG8_LDB(B0, 1, 0); PG8_SCHED; PG8_LDA(At, 1, 0); PG8_STAGE(PG8_SA(0, 1), a2 + hstep);
;             PG8_WAIT_L(8); PG8_BAR; PG8_WAIT_L(0); PG8_MMA(0, 0, At, B0); PG8_BAR; PG8_SCHED;
;             PG8_LDB(B1, 1, 1); PG8_STAGE(PG8_SB(1, 0), b3);
;             PG8_BAR; PG8_WAIT_L(0); PG8_MMA(0, 1, At, B1); PG8_BAR;
;             PG8_LDA(At, 1, 1); PG8_STAGE(PG8_SA(1, 0), a3);
;             PG8_BAR; PG8_WAIT_L(0); PG8_MMA(1, 0, At, B0); PG8_BAR; PG8_SCHED;
;             PG8_STAGE(PG8_SB(1, 1), b3 + hstep);
;             PG8_WAIT_V(6); PG8_BAR; PG8_MMA(1, 1, At, B1); PG8_BAR;
	s_add_u32 s0, s14, 0x40000
	s_addc_u32 s1, s15, 0
	s_add_i32 s30, s31, s17
	s_mov_b32 m0, s30
	v_lshl_add_u64 v[158:159], s[0:1], 0, v[132:133]
	global_load_lds_dwordx4 v[158:159], off
	s_add_i32 m0, s30, 0x2000
	v_lshl_add_u64 v[158:159], s[0:1], 0, v[130:131]
	global_load_lds_dwordx4 v[158:159], off
	s_waitcnt vmcnt(6)
	s_barrier
	s_setprio 1
	v_mfma_f32_16x16x32_bf16 v[58:61], v[226:229], v[194:197], v[58:61]
	v_mfma_f32_16x16x32_bf16 v[50:53], v[234:237], v[194:197], v[50:53]
	v_mfma_f32_16x16x32_bf16 v[42:45], v[226:229], v[202:205], v[42:45]
	v_mfma_f32_16x16x32_bf16 v[34:37], v[234:237], v[202:205], v[34:37]
	v_mfma_f32_16x16x32_bf16 v[26:29], v[226:229], v[210:213], v[26:29]
	v_mfma_f32_16x16x32_bf16 v[18:21], v[234:237], v[210:213], v[18:21]
	v_mfma_f32_16x16x32_bf16 v[10:13], v[226:229], v[218:221], v[10:13]
	v_mfma_f32_16x16x32_bf16 v[2:5], v[234:237], v[218:221], v[2:5]
	v_mfma_f32_16x16x32_bf16 v[58:61], v[230:233], v[198:201], v[58:61]
	v_mfma_f32_16x16x32_bf16 v[50:53], v[238:241], v[198:201], v[50:53]
	v_mfma_f32_16x16x32_bf16 v[42:45], v[230:233], v[206:209], v[42:45]
	v_mfma_f32_16x16x32_bf16 v[34:37], v[238:241], v[206:209], v[34:37]
	v_mfma_f32_16x16x32_bf16 v[26:29], v[230:233], v[214:217], v[26:29]
	v_mfma_f32_16x16x32_bf16 v[18:21], v[238:241], v[214:217], v[18:21]
	v_mfma_f32_16x16x32_bf16 v[10:13], v[230:233], v[222:225], v[10:13]
	v_mfma_f32_16x16x32_bf16 v[2:5], v[238:241], v[222:225], v[2:5]
	s_setprio 0
	s_add_i32 s30, 0, 0x18000
	v_add_u32_e32 v157, s30, v154
	s_barrier
	ds_read_b128 v[158:161], v157
	ds_read_b128 v[162:165], v157 offset:1024
	ds_read_b128 v[166:169], v157 offset:2048
	ds_read_b128 v[170:173], v157 offset:3072
	s_add_u32 s0, s58, 0x40000
	s_addc_u32 s1, s59, 0
	s_mov_b32 m0, s63
	v_lshl_add_u64 v[226:227], s[0:1], 0, v[132:133]
	ds_read_b128 v[194:197], v156 offset:32768
	ds_read_b128 v[198:201], v156 offset:33792
	ds_read_b128 v[202:205], v156 offset:34816
	ds_read_b128 v[206:209], v156 offset:35840
	ds_read_b128 v[210:213], v156 offset:36864
	ds_read_b128 v[214:217], v156 offset:37888
	ds_read_b128 v[218:221], v156 offset:38912
	ds_read_b128 v[222:225], v156 offset:39936
	global_load_lds_dwordx4 v[226:227], off
	s_mov_b32 m0, s64
	v_lshl_add_u64 v[226:227], s[0:1], 0, v[130:131]
	global_load_lds_dwordx4 v[226:227], off
	s_waitcnt lgkmcnt(8)
	s_barrier
	s_waitcnt lgkmcnt(0)
	s_setprio 1
	v_mfma_f32_16x16x32_bf16 v[126:129], v[158:161], v[194:197], v[126:129]
	v_mfma_f32_16x16x32_bf16 v[118:121], v[166:169], v[194:197], v[118:121]
	v_mfma_f32_16x16x32_bf16 v[110:113], v[158:161], v[202:205], v[110:113]
	v_mfma_f32_16x16x32_bf16 v[102:105], v[166:169], v[202:205], v[102:105]
	v_mfma_f32_16x16x32_bf16 v[94:97], v[158:161], v[210:213], v[94:97]
	v_mfma_f32_16x16x32_bf16 v[86:89], v[166:169], v[210:213], v[86:89]
	v_mfma_f32_16x16x32_bf16 v[78:81], v[158:161], v[218:221], v[78:81]
	v_mfma_f32_16x16x32_bf16 v[70:73], v[166:169], v[218:221], v[70:73]
	v_mfma_f32_16x16x32_bf16 v[126:129], v[162:165], v[198:201], v[126:129]
	v_mfma_f32_16x16x32_bf16 v[118:121], v[170:173], v[198:201], v[118:121]
	v_mfma_f32_16x16x32_bf16 v[110:113], v[162:165], v[206:209], v[110:113]
	v_mfma_f32_16x16x32_bf16 v[102:105], v[170:173], v[206:209], v[102:105]
	v_mfma_f32_16x16x32_bf16 v[94:97], v[162:165], v[214:217], v[94:97]
	v_mfma_f32_16x16x32_bf16 v[86:89], v[170:173], v[214:217], v[86:89]
	v_mfma_f32_16x16x32_bf16 v[78:81], v[162:165], v[222:225], v[78:81]
	v_mfma_f32_16x16x32_bf16 v[70:73], v[170:173], v[222:225], v[70:73]
	s_setprio 0
	s_barrier
	s_add_i32 s31, 0, 0x1c000
	s_add_i32 s0, s30, s17
	v_add_u32_e32 v157, s31, v154
	v_lshl_add_u64 v[174:175], v[174:175], 0, s[88:89]
	s_mov_b32 m0, s0
	ds_read_b128 v[226:229], v157
	ds_read_b128 v[230:233], v157 offset:1024
	ds_read_b128 v[234:237], v157 offset:2048
	ds_read_b128 v[238:241], v157 offset:3072
	global_load_lds_dwordx4 v[174:175], off
	s_add_i32 m0, s0, 0x2000
	v_lshl_add_u64 v[174:175], v[192:193], 0, s[88:89]
	global_load_lds_dwordx4 v[174:175], off
	s_barrier
	s_waitcnt lgkmcnt(0)
	s_setprio 1
	v_mfma_f32_16x16x32_bf16 v[122:125], v[226:229], v[194:197], v[122:125]
	v_mfma_f32_16x16x32_bf16 v[114:117], v[234:237], v[194:197], v[114:117]
	v_mfma_f32_16x16x32_bf16 v[106:109], v[226:229], v[202:205], v[106:109]
	v_mfma_f32_16x16x32_bf16 v[98:101], v[234:237], v[202:205], v[98:101]
	v_mfma_f32_16x16x32_bf16 v[90:93], v[226:229], v[210:213], v[90:93]
	v_mfma_f32_16x16x32_bf16 v[82:85], v[234:237], v[210:213], v[82:85]
	v_mfma_f32_16x16x32_bf16 v[74:77], v[226:229], v[218:221], v[74:77]
	v_mfma_f32_16x16x32_bf16 v[66:69], v[234:237], v[218:221], v[66:69]
	v_mfma_f32_16x16x32_bf16 v[122:125], v[230:233], v[198:201], v[122:125]
	v_mfma_f32_16x16x32_bf16 v[114:117], v[238:241], v[198:201], v[114:117]
	v_mfma_f32_16x16x32_bf16 v[106:109], v[230:233], v[206:209], v[106:109]
	v_mfma_f32_16x16x32_bf16 v[98:101], v[238:241], v[206:209], v[98:101]
	v_mfma_f32_16x16x32_bf16 v[90:93], v[230:233], v[214:217], v[90:93]
	v_mfma_f32_16x16x32_bf16 v[82:85], v[238:241], v[214:217], v[82:85]
	v_mfma_f32_16x16x32_bf16 v[74:77], v[230:233], v[222:225], v[74:77]
	v_mfma_f32_16x16x32_bf16 v[66:69], v[238:241], v[222:225], v[66:69]
	s_setprio 0
	s_mov_b32 m0, s65
	v_lshl_add_u64 v[174:175], v[242:243], 0, s[88:89]
	s_barrier
	ds_read_b128 v[194:197], v156 offset:49152
	ds_read_b128 v[198:201], v156 offset:50176
	ds_read_b128 v[202:205], v156 offset:51200
	ds_read_b128 v[206:209], v156 offset:52224
	ds_read_b128 v[210:213], v156 offset:53248
	ds_read_b128 v[214:217], v156 offset:54272
	ds_read_b128 v[218:221], v156 offset:55296
	ds_read_b128 v[222:225], v156 offset:56320
	global_load_lds_dwordx4 v[174:175], off
	s_mov_b32 m0, s66
	v_lshl_add_u64 v[174:175], v[244:245], 0, s[88:89]
	global_load_lds_dwordx4 v[174:175], off
	s_barrier
; __device__ __forceinline__ float siluf_(float x) { return x * frcp(1.0f + fexp(-x)); }
; #define PG8_WAIT_V(n) asm volatile("s_waitcnt vmcnt(" #n ")" ::: "memory")
; #define PG8_BAR __builtin_amdgcn_s_barrier()
;     ...
;             PG8_WAIT_V(6); PG8_BAR; PG8_MMA(1, 1, At, B1); PG8_BAR;
;     __device__ __forceinline__ void operator()(Acc& acc, int pm, int pn, int wr, int wc, int fr, int fq) const {
;         const int hb = pn * 128 + wc * 32 + fq * 4;
; #pragma unroll
;         for (int ai = 0; ai < 2; ++ai)
; #pragma unroll
;             for (int m = 0; m < 4; ++m) {
;                 const size_t ro = (size_t)(pm * 256 + ai * 128 + wr * 64 + m * 16 + fr) * DFF + hb;
; #pragma unroll
;                 for (int n = 0; n < 2; ++n) {
;                     const f32x4 a = acc[ai][0][m][n], b = acc[ai][1][m][n];
;                     u32x2 o = {pack2(siluf_(a[0]) * b[0], siluf_(a[1]) * b[1]), pack2(siluf_(a[2]) * b[2], siluf_(a[3]) * b[3])};
;                     *reinterpret_cast<u32x2*>(ffh + ro + n * 16) = o;
;                 }
;             }
;     }
	s_waitcnt lgkmcnt(0)
	s_setprio 1
	v_mfma_f32_16x16x32_bf16 v[62:65], v[158:161], v[194:197], v[62:65]
	v_mfma_f32_16x16x32_bf16 v[54:57], v[166:169], v[194:197], v[54:57]
	v_mfma_f32_16x16x32_bf16 v[46:49], v[158:161], v[202:205], v[46:49]
	v_mfma_f32_16x16x32_bf16 v[38:41], v[166:169], v[202:205], v[38:41]
	v_mfma_f32_16x16x32_bf16 v[30:33], v[158:161], v[210:213], v[30:33]
	v_mfma_f32_16x16x32_bf16 v[22:25], v[166:169], v[210:213], v[22:25]
	v_mfma_f32_16x16x32_bf16 v[14:17], v[158:161], v[218:221], v[14:17]
	v_mfma_f32_16x16x32_bf16 v[6:9], v[166:169], v[218:221], v[6:9]
	v_mfma_f32_16x16x32_bf16 v[62:65], v[162:165], v[198:201], v[62:65]
	v_mfma_f32_16x16x32_bf16 v[54:57], v[170:173], v[198:201], v[54:57]
	v_mfma_f32_16x16x32_bf16 v[46:49], v[162:165], v[206:209], v[46:49]
	v_mfma_f32_16x16x32_bf16 v[38:41], v[170:173], v[206:209], v[38:41]
	v_mfma_f32_16x16x32_bf16 v[30:33], v[162:165], v[214:217], v[30:33]
	v_mfma_f32_16x16x32_bf16 v[22:25], v[170:173], v[214:217], v[22:25]
	v_mfma_f32_16x16x32_bf16 v[14:17], v[162:165], v[222:225], v[14:17]
	v_mfma_f32_16x16x32_bf16 v[6:9], v[170:173], v[222:225], v[6:9]
	s_setprio 0
	s_barrier
	s_add_u32 s0, s14, 0x40080
	s_addc_u32 s1, s15, 0
	s_add_i32 s14, s31, s17
	s_mov_b32 m0, s14
	v_lshl_add_u64 v[158:159], s[0:1], 0, v[132:133]
	global_load_lds_dwordx4 v[158:159], off
	s_add_i32 m0, s14, 0x2000
	v_lshl_add_u64 v[158:159], s[0:1], 0, v[130:131]
	global_load_lds_dwordx4 v[158:159], off
	s_waitcnt vmcnt(6)
	s_barrier
	s_setprio 1
	v_mfma_f32_16x16x32_bf16 v[58:61], v[226:229], v[194:197], v[58:61]
	v_mfma_f32_16x16x32_bf16 v[50:53], v[234:237], v[194:197], v[50:53]
	v_mfma_f32_16x16x32_bf16 v[42:45], v[226:229], v[202:205], v[42:45]
	v_mfma_f32_16x16x32_bf16 v[34:37], v[234:237], v[202:205], v[34:37]
	v_mfma_f32_16x16x32_bf16 v[26:29], v[226:229], v[210:213], v[26:29]
	v_mfma_f32_16x16x32_bf16 v[18:21], v[234:237], v[210:213], v[18:21]
	v_mfma_f32_16x16x32_bf16 v[10:13], v[226:229], v[218:221], v[10:13]
	v_mfma_f32_16x16x32_bf16 v[2:5], v[234:237], v[218:221], v[2:5]
	v_mfma_f32_16x16x32_bf16 v[58:61], v[230:233], v[198:201], v[58:61]
	v_mfma_f32_16x16x32_bf16 v[50:53], v[238:241], v[198:201], v[50:53]
	v_mfma_f32_16x16x32_bf16 v[42:45], v[230:233], v[206:209], v[42:45]
	v_mfma_f32_16x16x32_bf16 v[34:37], v[238:241], v[206:209], v[34:37]
	v_mfma_f32_16x16x32_bf16 v[26:29], v[230:233], v[214:217], v[26:29]
	v_mfma_f32_16x16x32_bf16 v[18:21], v[238:241], v[214:217], v[18:21]
	v_mfma_f32_16x16x32_bf16 v[10:13], v[230:233], v[222:225], v[10:13]
	v_mfma_f32_16x16x32_bf16 v[2:5], v[238:241], v[222:225], v[2:5]
	s_setprio 0
	s_add_i32 s29, s29, 2
	s_add_u32 s12, s12, 0x100
	s_addc_u32 s13, s13, 0
	s_add_u32 s23, s23, 0x100
	s_addc_u32 s28, s28, 0
	s_cmp_gt_u32 s29, 13
	s_barrier
	s_cbranch_scc0 .LBB0_1563
	v_mul_f32_e32 v160, 0xbfb8aa3b, v126
	v_mul_f32_e32 v161, 0xbfb8aa3b, v127
	v_exp_f32_e32 v160, v160
	v_exp_f32_e32 v161, v161
	v_lshl_or_b32 v158, s4, 7, v155
	v_lshl_add_u32 v157, s10, 8, v1
	v_add_f32_e32 v160, 1.0, v160
	v_add_f32_e32 v161, 1.0, v161
	v_rcp_f32_e32 v160, v160
	v_rcp_f32_e32 v161, v161
	v_ashrrev_i32_e32 v159, 31, v158
	s_and_b64 vcc, exec, s[44:45]
	s_mov_b32 s4, s40
	v_pk_mul_f32 v[126:127], v[126:127], v[160:161]
	s_mov_b32 s10, s48
	v_pk_mul_f32 v[122:123], v[126:127], v[122:123]
	s_mov_b64 s[14:15], s[56:57]
	v_cvt_pk_bf16_f32 v126, v122, v123
	v_mul_f32_e32 v122, 0xbfb8aa3b, v128
	v_mul_f32_e32 v123, 0xbfb8aa3b, v129
	v_exp_f32_e32 v122, v122
	v_exp_f32_e32 v123, v123
	s_mov_b64 s[12:13], s[52:53]
	v_add_f32_e32 v122, 1.0, v122
	v_add_f32_e32 v123, 1.0, v123
	v_rcp_f32_e32 v122, v122
	v_rcp_f32_e32 v123, v123
	s_nop 0
	v_pk_mul_f32 v[122:123], v[128:129], v[122:123]
	s_nop 0
	v_pk_mul_f32 v[122:123], v[122:123], v[124:125]
	v_lshlrev_b64 v[124:125], 1, v[158:159]
	v_cvt_pk_bf16_f32 v127, v122, v123
	v_mov_b64_e32 v[122:123], s[26:27]
	v_mad_i64_i32 v[128:129], s[0:1], v157, s68, v[122:123]
	v_lshl_add_u64 v[128:129], v[128:129], 0, v[124:125]
	global_store_dwordx2 v[128:129], v[126:127], off
	v_mul_f32_e32 v126, 0xbfb8aa3b, v118
	v_mul_f32_e32 v127, 0xbfb8aa3b, v119
	v_exp_f32_e32 v126, v126
	v_exp_f32_e32 v127, v127
	v_add_f32_e32 v126, 1.0, v126
	v_add_f32_e32 v127, 1.0, v127
	v_rcp_f32_e32 v126, v126
	v_rcp_f32_e32 v127, v127
	s_nop 0
	v_pk_mul_f32 v[118:119], v[118:119], v[126:127]
	s_nop 0
	v_pk_mul_f32 v[114:115], v[118:119], v[114:115]
	s_nop 0
	v_cvt_pk_bf16_f32 v114, v114, v115
	v_mul_f32_e32 v115, 0xbfb8aa3b, v120
	v_exp_f32_e32 v115, v115
	s_nop 0
	v_add_f32_e32 v115, 1.0, v115
	v_rcp_f32_e32 v118, v115
	v_mul_f32_e32 v115, 0xbfb8aa3b, v121
	v_exp_f32_e32 v115, v115
	s_nop 0
	v_add_f32_e32 v115, 1.0, v115
	v_rcp_f32_e32 v119, v115
	s_nop 0
	v_pk_mul_f32 v[118:119], v[120:121], v[118:119]
	s_nop 0
	v_pk_mul_f32 v[116:117], v[118:119], v[116:117]
	s_nop 0
	v_cvt_pk_bf16_f32 v115, v116, v117
	global_store_dwordx2 v[128:129], v[114:115], off offset:32
	v_mul_f32_e32 v114, 0xbfb8aa3b, v110
	v_mul_f32_e32 v115, 0xbfb8aa3b, v111
	v_exp_f32_e32 v114, v114
	v_exp_f32_e32 v115, v115
	v_or_b32_e32 v116, 16, v157
	v_add_f32_e32 v114, 1.0, v114
	v_add_f32_e32 v115, 1.0, v115
	v_rcp_f32_e32 v114, v114
	v_rcp_f32_e32 v115, v115
	s_nop 0
	v_pk_mul_f32 v[110:111], v[110:111], v[114:115]
	s_nop 0
	v_pk_mul_f32 v[106:107], v[110:111], v[106:107]
	s_nop 0
	v_cvt_pk_bf16_f32 v106, v106, v107
	v_mul_f32_e32 v107, 0xbfb8aa3b, v112
	v_exp_f32_e32 v107, v107
	s_nop 0
	v_add_f32_e32 v107, 1.0, v107
	v_rcp_f32_e32 v110, v107
	v_mul_f32_e32 v107, 0xbfb8aa3b, v113
	v_exp_f32_e32 v107, v107
	s_nop 0
	v_add_f32_e32 v107, 1.0, v107
	v_rcp_f32_e32 v111, v107
	s_nop 0
; __device__ __forceinline__ float siluf_(float x) { return x * frcp(1.0f + fexp(-x)); }
;     __device__ __forceinline__ void operator()(Acc& acc, int pm, int pn, int wr, int wc, int fr, int fq) const {
;     ...
; #pragma unroll
;         for (int ai = 0; ai < 2; ++ai)
; #pragma unroll
;             for (int m = 0; m < 4; ++m) {
;                 const size_t ro = (size_t)(pm * 256 + ai * 128 + wr * 64 + m * 16 + fr) * DFF + hb;
; #pragma unroll
;                 for (int n = 0; n < 2; ++n) {
;                     const f32x4 a = acc[ai][0][m][n], b = acc[ai][1][m][n];
;                     u32x2 o = {pack2(siluf_(a[0]) * b[0], siluf_(a[1]) * b[1]), pack2(siluf_(a[2]) * b[2], siluf_(a[3]) * b[3])};
;                     *reinterpret_cast<u32x2*>(ffh + ro + n * 16) = o;
;                 }
;             }
	v_pk_mul_f32 v[110:111], v[112:113], v[110:111]
	s_nop 0
	v_pk_mul_f32 v[108:109], v[110:111], v[108:109]
	s_nop 0
	v_cvt_pk_bf16_f32 v107, v108, v109
	v_mad_i64_i32 v[108:109], s[0:1], v116, s68, v[122:123]
	v_lshl_add_u64 v[108:109], v[108:109], 0, v[124:125]
	global_store_dwordx2 v[108:109], v[106:107], off
	v_mul_f32_e32 v106, 0xbfb8aa3b, v102
	v_mul_f32_e32 v107, 0xbfb8aa3b, v103
	v_exp_f32_e32 v106, v106
	v_exp_f32_e32 v107, v107
	v_add_f32_e32 v106, 1.0, v106
	v_add_f32_e32 v107, 1.0, v107
	v_rcp_f32_e32 v106, v106
	v_rcp_f32_e32 v107, v107
	s_nop 0
	v_pk_mul_f32 v[102:103], v[102:103], v[106:107]
	s_nop 0
	v_pk_mul_f32 v[98:99], v[102:103], v[98:99]
	s_nop 0
	v_cvt_pk_bf16_f32 v98, v98, v99
	v_mul_f32_e32 v99, 0xbfb8aa3b, v104
	v_exp_f32_e32 v99, v99
	s_nop 0
	v_add_f32_e32 v99, 1.0, v99
	v_rcp_f32_e32 v102, v99
	v_mul_f32_e32 v99, 0xbfb8aa3b, v105
	v_exp_f32_e32 v99, v99
	s_nop 0
	v_add_f32_e32 v99, 1.0, v99
	v_rcp_f32_e32 v103, v99
	s_nop 0
	v_pk_mul_f32 v[102:103], v[104:105], v[102:103]
	s_nop 0
	v_pk_mul_f32 v[100:101], v[102:103], v[100:101]
	s_nop 0
	v_cvt_pk_bf16_f32 v99, v100, v101
	global_store_dwordx2 v[108:109], v[98:99], off offset:32
	v_mul_f32_e32 v98, 0xbfb8aa3b, v94
	v_mul_f32_e32 v99, 0xbfb8aa3b, v95
	v_exp_f32_e32 v98, v98
	v_exp_f32_e32 v99, v99
	v_or_b32_e32 v100, 32, v157
	v_add_f32_e32 v98, 1.0, v98
	v_add_f32_e32 v99, 1.0, v99
	v_rcp_f32_e32 v98, v98
	v_rcp_f32_e32 v99, v99
	s_nop 0
	v_pk_mul_f32 v[94:95], v[94:95], v[98:99]
	s_nop 0
	v_pk_mul_f32 v[90:91], v[94:95], v[90:91]
	s_nop 0
	v_cvt_pk_bf16_f32 v90, v90, v91
	v_mul_f32_e32 v91, 0xbfb8aa3b, v96
	v_exp_f32_e32 v91, v91
	s_nop 0
	v_add_f32_e32 v91, 1.0, v91
	v_rcp_f32_e32 v94, v91
	v_mul_f32_e32 v91, 0xbfb8aa3b, v97
	v_exp_f32_e32 v91, v91
	s_nop 0
	v_add_f32_e32 v91, 1.0, v91
	v_rcp_f32_e32 v95, v91
	s_nop 0
	v_pk_mul_f32 v[94:95], v[96:97], v[94:95]
	s_nop 0
	v_pk_mul_f32 v[92:93], v[94:95], v[92:93]
	s_nop 0
	v_cvt_pk_bf16_f32 v91, v92, v93
	v_mad_i64_i32 v[92:93], s[0:1], v100, s68, v[122:123]
	v_lshl_add_u64 v[92:93], v[92:93], 0, v[124:125]
	global_store_dwordx2 v[92:93], v[90:91], off
	v_mul_f32_e32 v90, 0xbfb8aa3b, v86
	v_mul_f32_e32 v91, 0xbfb8aa3b, v87
	v_exp_f32_e32 v90, v90
	v_exp_f32_e32 v91, v91
	v_add_f32_e32 v90, 1.0, v90
	v_add_f32_e32 v91, 1.0, v91
	v_rcp_f32_e32 v90, v90
	v_rcp_f32_e32 v91, v91
	s_nop 0
	v_pk_mul_f32 v[86:87], v[86:87], v[90:91]
	s_nop 0
	v_pk_mul_f32 v[82:83], v[86:87], v[82:83]
	s_nop 0
	v_cvt_pk_bf16_f32 v82, v82, v83
	v_mul_f32_e32 v83, 0xbfb8aa3b, v88
	v_exp_f32_e32 v83, v83
	s_nop 0
	v_add_f32_e32 v83, 1.0, v83
	v_rcp_f32_e32 v86, v83
	v_mul_f32_e32 v83, 0xbfb8aa3b, v89
	v_exp_f32_e32 v83, v83
	s_nop 0
	v_add_f32_e32 v83, 1.0, v83
	v_rcp_f32_e32 v87, v83
	s_nop 0
	v_pk_mul_f32 v[86:87], v[88:89], v[86:87]
	s_nop 0
	v_pk_mul_f32 v[84:85], v[86:87], v[84:85]
	s_nop 0
	v_cvt_pk_bf16_f32 v83, v84, v85
	global_store_dwordx2 v[92:93], v[82:83], off offset:32
	v_mul_f32_e32 v82, 0xbfb8aa3b, v78
	v_mul_f32_e32 v83, 0xbfb8aa3b, v79
	v_exp_f32_e32 v82, v82
	v_exp_f32_e32 v83, v83
	v_or_b32_e32 v84, 48, v157
	v_add_f32_e32 v82, 1.0, v82
	v_add_f32_e32 v83, 1.0, v83
	v_rcp_f32_e32 v82, v82
	v_rcp_f32_e32 v83, v83
	s_nop 0
	v_pk_mul_f32 v[78:79], v[78:79], v[82:83]
	s_nop 0
	v_pk_mul_f32 v[74:75], v[78:79], v[74:75]
	s_nop 0
	v_cvt_pk_bf16_f32 v74, v74, v75
	v_mul_f32_e32 v75, 0xbfb8aa3b, v80
	v_exp_f32_e32 v75, v75
	s_nop 0
	v_add_f32_e32 v75, 1.0, v75
	v_rcp_f32_e32 v78, v75
	v_mul_f32_e32 v75, 0xbfb8aa3b, v81
	v_exp_f32_e32 v75, v75
	s_nop 0
	v_add_f32_e32 v75, 1.0, v75
	v_rcp_f32_e32 v79, v75
	s_nop 0
	v_pk_mul_f32 v[78:79], v[80:81], v[78:79]
	s_nop 0
	v_pk_mul_f32 v[76:77], v[78:79], v[76:77]
	s_nop 0
	v_cvt_pk_bf16_f32 v75, v76, v77
	v_mad_i64_i32 v[76:77], s[0:1], v84, s68, v[122:123]
	v_lshl_add_u64 v[76:77], v[76:77], 0, v[124:125]
	global_store_dwordx2 v[76:77], v[74:75], off
	v_mul_f32_e32 v74, 0xbfb8aa3b, v70
	v_mul_f32_e32 v75, 0xbfb8aa3b, v71
	v_exp_f32_e32 v74, v74
	v_exp_f32_e32 v75, v75
	v_add_f32_e32 v74, 1.0, v74
	v_add_f32_e32 v75, 1.0, v75
	v_rcp_f32_e32 v74, v74
	v_rcp_f32_e32 v75, v75
	s_nop 0
	v_pk_mul_f32 v[70:71], v[70:71], v[74:75]
	s_nop 0
	v_pk_mul_f32 v[66:67], v[70:71], v[66:67]
	s_nop 0
	v_cvt_pk_bf16_f32 v66, v66, v67
	v_mul_f32_e32 v67, 0xbfb8aa3b, v72
	v_exp_f32_e32 v67, v67
	s_nop 0
	v_add_f32_e32 v67, 1.0, v67
	v_rcp_f32_e32 v70, v67
	v_mul_f32_e32 v67, 0xbfb8aa3b, v73
	v_exp_f32_e32 v67, v67
	s_nop 0
	v_add_f32_e32 v67, 1.0, v67
	v_rcp_f32_e32 v71, v67
	s_nop 0
	v_pk_mul_f32 v[70:71], v[72:73], v[70:71]
	s_nop 0
	v_pk_mul_f32 v[68:69], v[70:71], v[68:69]
	s_nop 0
	v_cvt_pk_bf16_f32 v67, v68, v69
	global_store_dwordx2 v[76:77], v[66:67], off offset:32
	v_mul_f32_e32 v66, 0xbfb8aa3b, v62
	v_mul_f32_e32 v67, 0xbfb8aa3b, v63
	v_exp_f32_e32 v66, v66
	v_exp_f32_e32 v67, v67
	v_add_u32_e32 v68, 0x80, v157
	v_add_f32_e32 v66, 1.0, v66
	v_add_f32_e32 v67, 1.0, v67
	v_rcp_f32_e32 v66, v66
	v_rcp_f32_e32 v67, v67
	s_nop 0
	v_pk_mul_f32 v[62:63], v[62:63], v[66:67]
	s_nop 0
	v_pk_mul_f32 v[58:59], v[62:63], v[58:59]
	s_nop 0
	v_cvt_pk_bf16_f32 v58, v58, v59
	v_mul_f32_e32 v59, 0xbfb8aa3b, v64
	v_exp_f32_e32 v59, v59
	s_nop 0
	v_add_f32_e32 v59, 1.0, v59
	v_rcp_f32_e32 v62, v59
	v_mul_f32_e32 v59, 0xbfb8aa3b, v65
	v_exp_f32_e32 v59, v59
	s_nop 0
	v_add_f32_e32 v59, 1.0, v59
	v_rcp_f32_e32 v63, v59
	s_nop 0
	v_pk_mul_f32 v[62:63], v[64:65], v[62:63]
	s_nop 0
	v_pk_mul_f32 v[60:61], v[62:63], v[60:61]
	s_nop 0
	v_cvt_pk_bf16_f32 v59, v60, v61
	v_mad_i64_i32 v[60:61], s[0:1], v68, s68, v[122:123]
	v_lshl_add_u64 v[60:61], v[60:61], 0, v[124:125]
	global_store_dwordx2 v[60:61], v[58:59], off
; __device__ __forceinline__ float siluf_(float x) { return x * frcp(1.0f + fexp(-x)); }
; #define PG8_WAIT_V(n) asm volatile("s_waitcnt vmcnt(" #n ")" ::: "memory")
; #define PG8_BAR __builtin_amdgcn_s_barrier()
;     ...
;         if (!has_next) break;
;     ...
;     PG8_WAIT_V(0);
;     if (wr == 0) PG8_BAR;
;     PG8_BAR;
;     __device__ __forceinline__ void operator()(Acc& acc, int pm, int pn, int wr, int wc, int fr, int fq) const {
;     ...
; #pragma unroll
;         for (int ai = 0; ai < 2; ++ai)
; #pragma unroll
;             for (int m = 0; m < 4; ++m) {
;                 const size_t ro = (size_t)(pm * 256 + ai * 128 + wr * 64 + m * 16 + fr) * DFF + hb;
; #pragma unroll
;                 for (int n = 0; n < 2; ++n) {
;                     const f32x4 a = acc[ai][0][m][n], b = acc[ai][1][m][n];
;                     u32x2 o = {pack2(siluf_(a[0]) * b[0], siluf_(a[1]) * b[1]), pack2(siluf_(a[2]) * b[2], siluf_(a[3]) * b[3])};
;                     *reinterpret_cast<u32x2*>(ffh + ro + n * 16) = o;
;                 }
;             }
	v_mul_f32_e32 v58, 0xbfb8aa3b, v54
	v_mul_f32_e32 v59, 0xbfb8aa3b, v55
	v_exp_f32_e32 v58, v58
	v_exp_f32_e32 v59, v59
	v_add_f32_e32 v58, 1.0, v58
	v_add_f32_e32 v59, 1.0, v59
	v_rcp_f32_e32 v58, v58
	v_rcp_f32_e32 v59, v59
	s_nop 0
	v_pk_mul_f32 v[54:55], v[54:55], v[58:59]
	s_nop 0
	v_pk_mul_f32 v[50:51], v[54:55], v[50:51]
	s_nop 0
	v_cvt_pk_bf16_f32 v50, v50, v51
	v_mul_f32_e32 v51, 0xbfb8aa3b, v56
	v_exp_f32_e32 v51, v51
	s_nop 0
	v_add_f32_e32 v51, 1.0, v51
	v_rcp_f32_e32 v54, v51
	v_mul_f32_e32 v51, 0xbfb8aa3b, v57
	v_exp_f32_e32 v51, v51
	s_nop 0
	v_add_f32_e32 v51, 1.0, v51
	v_rcp_f32_e32 v55, v51
	s_nop 0
	v_pk_mul_f32 v[54:55], v[56:57], v[54:55]
	s_nop 0
	v_pk_mul_f32 v[52:53], v[54:55], v[52:53]
	s_nop 0
	v_cvt_pk_bf16_f32 v51, v52, v53
	global_store_dwordx2 v[60:61], v[50:51], off offset:32
	v_mul_f32_e32 v50, 0xbfb8aa3b, v46
	v_mul_f32_e32 v51, 0xbfb8aa3b, v47
	v_exp_f32_e32 v50, v50
	v_exp_f32_e32 v51, v51
	v_add_u32_e32 v52, 0x90, v157
	v_add_f32_e32 v50, 1.0, v50
	v_add_f32_e32 v51, 1.0, v51
	v_rcp_f32_e32 v50, v50
	v_rcp_f32_e32 v51, v51
	s_nop 0
	v_pk_mul_f32 v[46:47], v[46:47], v[50:51]
	s_nop 0
	v_pk_mul_f32 v[42:43], v[46:47], v[42:43]
	s_nop 0
	v_cvt_pk_bf16_f32 v42, v42, v43
	v_mul_f32_e32 v43, 0xbfb8aa3b, v48
	v_exp_f32_e32 v43, v43
	s_nop 0
	v_add_f32_e32 v43, 1.0, v43
	v_rcp_f32_e32 v46, v43
	v_mul_f32_e32 v43, 0xbfb8aa3b, v49
	v_exp_f32_e32 v43, v43
	s_nop 0
	v_add_f32_e32 v43, 1.0, v43
	v_rcp_f32_e32 v47, v43
	s_nop 0
	v_pk_mul_f32 v[46:47], v[48:49], v[46:47]
	s_nop 0
	v_pk_mul_f32 v[44:45], v[46:47], v[44:45]
	s_nop 0
	v_cvt_pk_bf16_f32 v43, v44, v45
	v_mad_i64_i32 v[44:45], s[0:1], v52, s68, v[122:123]
	v_lshl_add_u64 v[44:45], v[44:45], 0, v[124:125]
	global_store_dwordx2 v[44:45], v[42:43], off
	v_mul_f32_e32 v42, 0xbfb8aa3b, v38
	v_mul_f32_e32 v43, 0xbfb8aa3b, v39
	v_exp_f32_e32 v42, v42
	v_exp_f32_e32 v43, v43
	v_add_f32_e32 v42, 1.0, v42
	v_add_f32_e32 v43, 1.0, v43
	v_rcp_f32_e32 v42, v42
	v_rcp_f32_e32 v43, v43
	s_nop 0
	v_pk_mul_f32 v[38:39], v[38:39], v[42:43]
	s_nop 0
	v_pk_mul_f32 v[34:35], v[38:39], v[34:35]
	s_nop 0
	v_cvt_pk_bf16_f32 v34, v34, v35
	v_mul_f32_e32 v35, 0xbfb8aa3b, v40
	v_exp_f32_e32 v35, v35
	s_nop 0
	v_add_f32_e32 v35, 1.0, v35
	v_rcp_f32_e32 v38, v35
	v_mul_f32_e32 v35, 0xbfb8aa3b, v41
	v_exp_f32_e32 v35, v35
	s_nop 0
	v_add_f32_e32 v35, 1.0, v35
	v_rcp_f32_e32 v39, v35
	s_nop 0
	v_pk_mul_f32 v[38:39], v[40:41], v[38:39]
	s_nop 0
	v_pk_mul_f32 v[36:37], v[38:39], v[36:37]
	s_nop 0
	v_cvt_pk_bf16_f32 v35, v36, v37
	global_store_dwordx2 v[44:45], v[34:35], off offset:32
	v_mul_f32_e32 v34, 0xbfb8aa3b, v30
	v_mul_f32_e32 v35, 0xbfb8aa3b, v31
	v_exp_f32_e32 v34, v34
	v_exp_f32_e32 v35, v35
	v_add_u32_e32 v36, 0xa0, v157
	v_add_f32_e32 v34, 1.0, v34
	v_add_f32_e32 v35, 1.0, v35
	v_rcp_f32_e32 v34, v34
	v_rcp_f32_e32 v35, v35
	s_nop 0
	v_pk_mul_f32 v[30:31], v[30:31], v[34:35]
	s_nop 0
	v_pk_mul_f32 v[26:27], v[30:31], v[26:27]
	s_nop 0
	v_cvt_pk_bf16_f32 v26, v26, v27
	v_mul_f32_e32 v27, 0xbfb8aa3b, v32
	v_exp_f32_e32 v27, v27
	s_nop 0
	v_add_f32_e32 v27, 1.0, v27
	v_rcp_f32_e32 v30, v27
	v_mul_f32_e32 v27, 0xbfb8aa3b, v33
	v_exp_f32_e32 v27, v27
	s_nop 0
	v_add_f32_e32 v27, 1.0, v27
	v_rcp_f32_e32 v31, v27
	s_nop 0
	v_pk_mul_f32 v[30:31], v[32:33], v[30:31]
	s_nop 0
	v_pk_mul_f32 v[28:29], v[30:31], v[28:29]
	s_nop 0
	v_cvt_pk_bf16_f32 v27, v28, v29
	v_mad_i64_i32 v[28:29], s[0:1], v36, s68, v[122:123]
	v_lshl_add_u64 v[28:29], v[28:29], 0, v[124:125]
	global_store_dwordx2 v[28:29], v[26:27], off
	v_mul_f32_e32 v26, 0xbfb8aa3b, v22
	v_mul_f32_e32 v27, 0xbfb8aa3b, v23
	v_exp_f32_e32 v26, v26
	v_exp_f32_e32 v27, v27
	v_add_f32_e32 v26, 1.0, v26
	v_add_f32_e32 v27, 1.0, v27
	v_rcp_f32_e32 v26, v26
	v_rcp_f32_e32 v27, v27
	s_nop 0
	v_pk_mul_f32 v[22:23], v[22:23], v[26:27]
	s_nop 0
	v_pk_mul_f32 v[18:19], v[22:23], v[18:19]
	s_nop 0
	v_cvt_pk_bf16_f32 v18, v18, v19
	v_mul_f32_e32 v19, 0xbfb8aa3b, v24
	v_exp_f32_e32 v19, v19
	s_nop 0
	v_add_f32_e32 v19, 1.0, v19
	v_rcp_f32_e32 v22, v19
	v_mul_f32_e32 v19, 0xbfb8aa3b, v25
	v_exp_f32_e32 v19, v19
	s_nop 0
	v_add_f32_e32 v19, 1.0, v19
	v_rcp_f32_e32 v23, v19
	s_nop 0
	v_pk_mul_f32 v[22:23], v[24:25], v[22:23]
	s_nop 0
	v_pk_mul_f32 v[20:21], v[22:23], v[20:21]
	s_nop 0
	v_cvt_pk_bf16_f32 v19, v20, v21
	global_store_dwordx2 v[28:29], v[18:19], off offset:32
	v_mul_f32_e32 v18, 0xbfb8aa3b, v14
	v_mul_f32_e32 v19, 0xbfb8aa3b, v15
	v_exp_f32_e32 v18, v18
	v_exp_f32_e32 v19, v19
	v_add_u32_e32 v20, 0xb0, v157
	v_add_f32_e32 v18, 1.0, v18
	v_add_f32_e32 v19, 1.0, v19
	v_rcp_f32_e32 v18, v18
	v_rcp_f32_e32 v19, v19
	s_nop 0
	v_pk_mul_f32 v[14:15], v[14:15], v[18:19]
	s_nop 0
	v_pk_mul_f32 v[10:11], v[14:15], v[10:11]
	s_nop 0
	v_cvt_pk_bf16_f32 v10, v10, v11
	v_mul_f32_e32 v11, 0xbfb8aa3b, v16
	v_exp_f32_e32 v11, v11
	s_nop 0
	v_add_f32_e32 v11, 1.0, v11
	v_rcp_f32_e32 v14, v11
	v_mul_f32_e32 v11, 0xbfb8aa3b, v17
	v_exp_f32_e32 v11, v11
	s_nop 0
	v_add_f32_e32 v11, 1.0, v11
	v_rcp_f32_e32 v15, v11
	s_nop 0
	v_pk_mul_f32 v[14:15], v[16:17], v[14:15]
	s_nop 0
	v_pk_mul_f32 v[12:13], v[14:15], v[12:13]
	s_nop 0
	v_cvt_pk_bf16_f32 v11, v12, v13
	v_mad_i64_i32 v[12:13], s[0:1], v20, s68, v[122:123]
	v_lshl_add_u64 v[12:13], v[12:13], 0, v[124:125]
	global_store_dwordx2 v[12:13], v[10:11], off
	v_mul_f32_e32 v10, 0xbfb8aa3b, v6
	v_mul_f32_e32 v11, 0xbfb8aa3b, v7
	v_exp_f32_e32 v10, v10
	v_exp_f32_e32 v11, v11
	v_add_f32_e32 v10, 1.0, v10
	v_add_f32_e32 v11, 1.0, v11
	v_rcp_f32_e32 v10, v10
	v_rcp_f32_e32 v11, v11
	s_nop 0
	v_pk_mul_f32 v[6:7], v[6:7], v[10:11]
	s_nop 0
	v_pk_mul_f32 v[2:3], v[6:7], v[2:3]
	s_nop 0
	v_cvt_pk_bf16_f32 v2, v2, v3
	v_mul_f32_e32 v3, 0xbfb8aa3b, v8
	v_exp_f32_e32 v3, v3
	s_nop 0
	v_add_f32_e32 v3, 1.0, v3
	v_rcp_f32_e32 v6, v3
	v_mul_f32_e32 v3, 0xbfb8aa3b, v9
	v_exp_f32_e32 v3, v3
	s_nop 0
	v_add_f32_e32 v3, 1.0, v3
	v_rcp_f32_e32 v7, v3
	s_nop 0
	v_pk_mul_f32 v[6:7], v[8:9], v[6:7]
	s_nop 0
	v_pk_mul_f32 v[4:5], v[6:7], v[4:5]
	s_nop 0
	v_cvt_pk_bf16_f32 v3, v4, v5
	global_store_dwordx2 v[12:13], v[2:3], off offset:32
	s_cbranch_vccz .LBB0_1560
	s_waitcnt vmcnt(0)
	s_cmpk_gt_u32 s16, 0xff
	s_cbranch_scc1 .LBB0_1567
	s_barrier

; #define PG8_STAGE(bufoff, gbase) do { _Pragma("unroll") for (int _i = 0; _i < 2; ++_i) \
;         __builtin_amdgcn_global_load_lds((const unsigned*)((const char*)(gbase) + voff[_i]), (LAS unsigned*)(lds + (bufoff) + ldsw + _i * 8192), 16, 0, 0); } while (0)
; #define PG8_LDA(dst, b, h) do { _Pragma("unroll") for (int m = 0; m < 4; ++m) _Pragma("unroll") for (int k = 0; k < 2; ++k) dst[m][k] = *(const LAS bf16x8*)(lds + PG8_SA(b, h) + aoff + m * 2048 + k * 1024); } while (0)
; #define PG8_LDB(dst, b, h) do { _Pragma("unroll") for (int n = 0; n < 2; ++n) _Pragma("unroll") for (int k = 0; k < 2; ++k) dst[n][k] = *(const LAS bf16x8*)(lds + PG8_SB(b, h) + boff + n * 2048 + k * 1024); } while (0)
; #define PG8_WAIT_V(n) asm volatile("s_waitcnt vmcnt(" #n ")" ::: "memory")
; #define PG8_WAIT_L(n) asm volatile("s_waitcnt lgkmcnt(" #n ")" ::: "memory")
;     ...
;         for (int t = 0; t < nt; t += 2) {
;             const bool last = (t == nt - 2);
;             const char* a1 = cA + (size_t)(t + 1) * kstep;
;             const char* a2 = last ? nA : cA + (size_t)(t + 2) * kstep; const char* b2 = last ? nB : cB + (size_t)(t + 2) * kstep;
;             const char* a3 = a2 + kstep; const char* b3 = b2 + kstep;
;             PG8_LDB(B0, 0, 0); PG8_SCHED; PG8_LDA(At, 0, 0); PG8_STAGE(PG8_SA(1, 1), a1 + hstep);
;             PG8_WAIT_L(8); PG8_BAR; PG8_WAIT_L(0); PG8_MMA(0, 0, At, B0); PG8_BAR; PG8_SCHED;
;             PG8_LDB(B1, 0, 1); PG8_STAGE(PG8_SB(0, 0), b2);
;             PG8_BAR; PG8_WAIT_L(0); PG8_MMA(0, 1, At, B1); PG8_BAR;
;             PG8_LDA(At, 0, 1); PG8_STAGE(PG8_SA(0, 0), a2);
;             PG8_BAR; PG8_WAIT_L(0); PG8_MMA(1, 0, At, B0); PG8_BAR; PG8_SCHED;
;             PG8_STAGE(PG8_SB(0, 1), b2 + hstep);
;             PG8_WAIT_V(6); PG8_BAR; PG8_MMA(1, 1, At, B1); PG8_BAR;
;             PG8_LDB(B0, 1, 0); PG8_SCHED; PG8_LDA(At, 1, 0); PG8_STAGE(PG8_SA(0, 1), a2 + hstep);
;             PG8_WAIT_L(8); PG8_BAR; PG8_WAIT_L(0); PG8_MMA(0, 0, At, B0); PG8_BAR; PG8_SCHED;
;             PG8_LDB(B1, 1, 1); PG8_STAGE(PG8_SB(1, 0), b3);
;             PG8_BAR; PG8_WAIT_L(0); PG8_MMA(0, 1, At, B1); PG8_BAR;
;             PG8_LDA(At, 1, 1); PG8_STAGE(PG8_SA(1, 0), a3);
;             PG8_BAR; PG8_WAIT_L(0); PG8_MMA(1, 0, At, B0); PG8_BAR; PG8_SCHED;
;             PG8_STAGE(PG8_SB(1, 1), b3 + hstep);
;             PG8_WAIT_V(6); PG8_BAR; PG8_MMA(1, 1, At, B1); PG8_BAR;
.LBB0_1649:
	s_add_u32 s46, s14, 0x100
	s_addc_u32 s47, s15, 0
	s_add_i32 s0, 0, 0x10000
	v_add_u32_e32 v161, s0, v158
	ds_read_b128 v[154:157], v161
	ds_read_b128 v[162:165], v161 offset:1024
	ds_read_b128 v[166:169], v161 offset:2048
	ds_read_b128 v[170:173], v161 offset:3072
	s_cmp_eq_u32 s28, 40
	s_cselect_b32 s53, s11, s47
	s_cselect_b32 s52, s10, s46
	s_cselect_b32 s49, s13, s23
	s_cselect_b32 s48, s12, s22
	v_lshl_add_u64 v[174:175], s[14:15], 0, v[150:151]
	s_add_i32 m0, s56, 0xc000
	ds_read_b128 v[194:197], v160
	ds_read_b128 v[198:201], v160 offset:1024
	ds_read_b128 v[202:205], v160 offset:2048
	ds_read_b128 v[206:209], v160 offset:3072
	ds_read_b128 v[210:213], v160 offset:4096
	ds_read_b128 v[214:217], v160 offset:5120
	ds_read_b128 v[218:221], v160 offset:6144
	ds_read_b128 v[222:225], v160 offset:7168
	global_load_lds_dwordx4 v[174:175], off
	s_add_i32 m0, s56, 0xe000
	v_lshl_add_u64 v[174:175], s[14:15], 0, v[152:153]
	global_load_lds_dwordx4 v[174:175], off
	s_waitcnt lgkmcnt(8)
	s_barrier
	s_waitcnt lgkmcnt(0)
	s_setprio 1
	v_mfma_f32_16x16x32_bf16 v[126:129], v[154:157], v[194:197], v[126:129]
	v_mfma_f32_16x16x32_bf16 v[102:105], v[166:169], v[194:197], v[102:105]
	v_mfma_f32_16x16x32_bf16 v[122:125], v[154:157], v[202:205], v[122:125]
	v_mfma_f32_16x16x32_bf16 v[90:93], v[166:169], v[202:205], v[90:93]
	v_mfma_f32_16x16x32_bf16 v[118:121], v[154:157], v[210:213], v[118:121]
	v_mfma_f32_16x16x32_bf16 v[86:89], v[166:169], v[210:213], v[86:89]
	v_mfma_f32_16x16x32_bf16 v[114:117], v[154:157], v[218:221], v[114:117]
	v_mfma_f32_16x16x32_bf16 v[82:85], v[166:169], v[218:221], v[82:85]
	v_mfma_f32_16x16x32_bf16 v[126:129], v[162:165], v[198:201], v[126:129]
	v_mfma_f32_16x16x32_bf16 v[102:105], v[170:173], v[198:201], v[102:105]
	v_mfma_f32_16x16x32_bf16 v[122:125], v[162:165], v[206:209], v[122:125]
	v_mfma_f32_16x16x32_bf16 v[90:93], v[170:173], v[206:209], v[90:93]
	v_mfma_f32_16x16x32_bf16 v[118:121], v[162:165], v[214:217], v[118:121]
	v_mfma_f32_16x16x32_bf16 v[86:89], v[170:173], v[214:217], v[86:89]
	v_mfma_f32_16x16x32_bf16 v[114:117], v[162:165], v[222:225], v[114:117]
	v_mfma_f32_16x16x32_bf16 v[82:85], v[170:173], v[222:225], v[82:85]
	s_setprio 0
	s_barrier
	s_add_i32 s14, 0, 0x14000
	s_add_i32 s0, s0, s36
	v_add_u32_e32 v161, s14, v158
	v_lshl_add_u64 v[174:175], s[48:49], 0, v[132:133]
	s_mov_b32 m0, s0
	ds_read_b128 v[226:229], v161
	ds_read_b128 v[230:233], v161 offset:1024
	ds_read_b128 v[234:237], v161 offset:2048
	ds_read_b128 v[238:241], v161 offset:3072
	global_load_lds_dwordx4 v[174:175], off
	s_add_i32 m0, s0, 0x2000
	v_lshl_add_u64 v[192:193], s[48:49], 0, v[130:131]
	global_load_lds_dwordx4 v[192:193], off
	s_barrier
	s_waitcnt lgkmcnt(0)
	s_setprio 1
	v_mfma_f32_16x16x32_bf16 v[66:69], v[226:229], v[194:197], v[66:69]
	v_mfma_f32_16x16x32_bf16 v[38:41], v[234:237], v[194:197], v[38:41]
	v_mfma_f32_16x16x32_bf16 v[58:61], v[226:229], v[202:205], v[58:61]
	v_mfma_f32_16x16x32_bf16 v[26:29], v[234:237], v[202:205], v[26:29]
	v_mfma_f32_16x16x32_bf16 v[54:57], v[226:229], v[210:213], v[54:57]
	v_mfma_f32_16x16x32_bf16 v[22:25], v[234:237], v[210:213], v[22:25]
	v_mfma_f32_16x16x32_bf16 v[50:53], v[226:229], v[218:221], v[50:53]
	v_mfma_f32_16x16x32_bf16 v[18:21], v[234:237], v[218:221], v[18:21]
	v_mfma_f32_16x16x32_bf16 v[66:69], v[230:233], v[198:201], v[66:69]
	v_mfma_f32_16x16x32_bf16 v[38:41], v[238:241], v[198:201], v[38:41]
	v_mfma_f32_16x16x32_bf16 v[58:61], v[230:233], v[206:209], v[58:61]
	v_mfma_f32_16x16x32_bf16 v[26:29], v[238:241], v[206:209], v[26:29]
	v_mfma_f32_16x16x32_bf16 v[54:57], v[230:233], v[214:217], v[54:57]
	v_mfma_f32_16x16x32_bf16 v[22:25], v[238:241], v[214:217], v[22:25]
	v_mfma_f32_16x16x32_bf16 v[50:53], v[230:233], v[222:225], v[50:53]
	v_mfma_f32_16x16x32_bf16 v[18:21], v[238:241], v[222:225], v[18:21]
	s_setprio 0
	s_mov_b32 m0, s56
	v_lshl_add_u64 v[242:243], s[52:53], 0, v[132:133]
	s_barrier
	ds_read_b128 v[194:197], v160 offset:16384
	ds_read_b128 v[198:201], v160 offset:17408
	ds_read_b128 v[202:205], v160 offset:18432
	ds_read_b128 v[206:209], v160 offset:19456
	ds_read_b128 v[210:213], v160 offset:20480
	ds_read_b128 v[214:217], v160 offset:21504
	ds_read_b128 v[218:221], v160 offset:22528
	ds_read_b128 v[222:225], v160 offset:23552
	global_load_lds_dwordx4 v[242:243], off
	s_mov_b32 m0, s57
	v_lshl_add_u64 v[244:245], s[52:53], 0, v[130:131]
	global_load_lds_dwordx4 v[244:245], off
	s_barrier
	s_waitcnt lgkmcnt(0)
	s_setprio 1
	v_mfma_f32_16x16x32_bf16 v[110:113], v[154:157], v[194:197], v[110:113]
	v_mfma_f32_16x16x32_bf16 v[78:81], v[166:169], v[194:197], v[78:81]
	v_mfma_f32_16x16x32_bf16 v[106:109], v[154:157], v[202:205], v[106:109]
	v_mfma_f32_16x16x32_bf16 v[74:77], v[166:169], v[202:205], v[74:77]
	v_mfma_f32_16x16x32_bf16 v[98:101], v[154:157], v[210:213], v[98:101]
	v_mfma_f32_16x16x32_bf16 v[70:73], v[166:169], v[210:213], v[70:73]
	v_mfma_f32_16x16x32_bf16 v[94:97], v[154:157], v[218:221], v[94:97]
	v_mfma_f32_16x16x32_bf16 v[62:65], v[166:169], v[218:221], v[62:65]
	v_mfma_f32_16x16x32_bf16 v[110:113], v[162:165], v[198:201], v[110:113]
	v_mfma_f32_16x16x32_bf16 v[78:81], v[170:173], v[198:201], v[78:81]
	v_mfma_f32_16x16x32_bf16 v[106:109], v[162:165], v[206:209], v[106:109]
	v_mfma_f32_16x16x32_bf16 v[74:77], v[170:173], v[206:209], v[74:77]
	v_mfma_f32_16x16x32_bf16 v[98:101], v[162:165], v[214:217], v[98:101]
	v_mfma_f32_16x16x32_bf16 v[70:73], v[170:173], v[214:217], v[70:73]
	v_mfma_f32_16x16x32_bf16 v[94:97], v[162:165], v[222:225], v[94:97]
	v_mfma_f32_16x16x32_bf16 v[62:65], v[170:173], v[222:225], v[62:65]
	s_setprio 0
	s_barrier
; #define PG8_STAGE(bufoff, gbase) do { _Pragma("unroll") for (int _i = 0; _i < 2; ++_i) \
;         __builtin_amdgcn_global_load_lds((const unsigned*)((const char*)(gbase) + voff[_i]), (LAS unsigned*)(lds + (bufoff) + ldsw + _i * 8192), 16, 0, 0); } while (0)
; #define PG8_LDA(dst, b, h) do { _Pragma("unroll") for (int m = 0; m < 4; ++m) _Pragma("unroll") for (int k = 0; k < 2; ++k) dst[m][k] = *(const LAS bf16x8*)(lds + PG8_SA(b, h) + aoff + m * 2048 + k * 1024); } while (0)
; #define PG8_LDB(dst, b, h) do { _Pragma("unroll") for (int n = 0; n < 2; ++n) _Pragma("unroll") for (int k = 0; k < 2; ++k) dst[n][k] = *(const LAS bf16x8*)(lds + PG8_SB(b, h) + boff + n * 2048 + k * 1024); } while (0)
; #define PG8_WAIT_V(n) asm volatile("s_waitcnt vmcnt(" #n ")" ::: "memory")
; #define PG8_WAIT_L(n) asm volatile("s_waitcnt lgkmcnt(" #n ")" ::: "memory")
; #define PG8_BAR __builtin_amdgcn_s_barrier()
; #define PG8_SCHED __builtin_amdgcn_sched_barrier(0)
;     ...
;             PG8_LDB(B1, 0, 1); PG8_STAGE(PG8_SB(0, 0), b2);
;             PG8_BAR; PG8_WAIT_L(0); PG8_MMA(0, 1, At, B1); PG8_BAR;
;             PG8_LDA(At, 0, 1); PG8_STAGE(PG8_SA(0, 0), a2);
;             PG8_BAR; PG8_WAIT_L(0); PG8_MMA(1, 0, At, B0); PG8_BAR; PG8_SCHED;
;             PG8_STAGE(PG8_SB(0, 1), b2 + hstep);
;             PG8_WAIT_V(6); PG8_BAR; PG8_MMA(1, 1, At, B1); PG8_BAR;
;             PG8_LDB(B0, 1, 0); PG8_SCHED; PG8_LDA(At, 1, 0); PG8_STAGE(PG8_SA(0, 1), a2 + hstep);
;             PG8_WAIT_L(8); PG8_BAR; PG8_WAIT_L(0); PG8_MMA(0, 0, At, B0); PG8_BAR; PG8_SCHED;
;             PG8_LDB(B1, 1, 1); PG8_STAGE(PG8_SB(1, 0), b3);
;             PG8_BAR; PG8_WAIT_L(0); PG8_MMA(0, 1, At, B1); PG8_BAR;
;             PG8_LDA(At, 1, 1); PG8_STAGE(PG8_SA(1, 0), a3);
;             PG8_BAR; PG8_WAIT_L(0); PG8_MMA(1, 0, At, B0); PG8_BAR; PG8_SCHED;
;             PG8_STAGE(PG8_SB(1, 1), b3 + hstep);
;             PG8_WAIT_V(6); PG8_BAR; PG8_MMA(1, 1, At, B1); PG8_BAR;
	s_add_u32 s0, s48, 0xb0000
	s_addc_u32 s1, s49, 0
	s_add_i32 s14, s14, s36
	s_mov_b32 m0, s14
	v_lshl_add_u64 v[154:155], s[0:1], 0, v[132:133]
	global_load_lds_dwordx4 v[154:155], off
	s_add_i32 m0, s14, 0x2000
	v_lshl_add_u64 v[154:155], s[0:1], 0, v[130:131]
	global_load_lds_dwordx4 v[154:155], off
	s_waitcnt vmcnt(6)
	s_barrier
	s_setprio 1
	v_mfma_f32_16x16x32_bf16 v[46:49], v[226:229], v[194:197], v[46:49]
	v_mfma_f32_16x16x32_bf16 v[14:17], v[234:237], v[194:197], v[14:17]
	v_mfma_f32_16x16x32_bf16 v[42:45], v[226:229], v[202:205], v[42:45]
	v_mfma_f32_16x16x32_bf16 v[10:13], v[234:237], v[202:205], v[10:13]
	v_mfma_f32_16x16x32_bf16 v[34:37], v[226:229], v[210:213], v[34:37]
	v_mfma_f32_16x16x32_bf16 v[6:9], v[234:237], v[210:213], v[6:9]
	v_mfma_f32_16x16x32_bf16 v[30:33], v[226:229], v[218:221], v[30:33]
	v_mfma_f32_16x16x32_bf16 v[2:5], v[234:237], v[218:221], v[2:5]
	v_mfma_f32_16x16x32_bf16 v[46:49], v[230:233], v[198:201], v[46:49]
	v_mfma_f32_16x16x32_bf16 v[14:17], v[238:241], v[198:201], v[14:17]
	v_mfma_f32_16x16x32_bf16 v[42:45], v[230:233], v[206:209], v[42:45]
	v_mfma_f32_16x16x32_bf16 v[10:13], v[238:241], v[206:209], v[10:13]
	v_mfma_f32_16x16x32_bf16 v[34:37], v[230:233], v[214:217], v[34:37]
	v_mfma_f32_16x16x32_bf16 v[6:9], v[238:241], v[214:217], v[6:9]
	v_mfma_f32_16x16x32_bf16 v[30:33], v[230:233], v[222:225], v[30:33]
	v_mfma_f32_16x16x32_bf16 v[2:5], v[238:241], v[222:225], v[2:5]
	s_setprio 0
	s_add_i32 s14, 0, 0x18000
	v_add_u32_e32 v161, s14, v158
	s_barrier
	ds_read_b128 v[154:157], v161
	ds_read_b128 v[162:165], v161 offset:1024
	ds_read_b128 v[166:169], v161 offset:2048
	ds_read_b128 v[170:173], v161 offset:3072
	s_add_u32 s0, s52, 0xb0000
	s_addc_u32 s1, s53, 0
	s_mov_b32 m0, s58
	v_lshl_add_u64 v[226:227], s[0:1], 0, v[132:133]
	ds_read_b128 v[194:197], v160 offset:32768
	ds_read_b128 v[198:201], v160 offset:33792
	ds_read_b128 v[202:205], v160 offset:34816
	ds_read_b128 v[206:209], v160 offset:35840
	ds_read_b128 v[210:213], v160 offset:36864
	ds_read_b128 v[214:217], v160 offset:37888
	ds_read_b128 v[218:221], v160 offset:38912
	ds_read_b128 v[222:225], v160 offset:39936
	global_load_lds_dwordx4 v[226:227], off
	s_mov_b32 m0, s59
	v_lshl_add_u64 v[226:227], s[0:1], 0, v[130:131]
	global_load_lds_dwordx4 v[226:227], off
	s_waitcnt lgkmcnt(8)
	s_barrier
	s_waitcnt lgkmcnt(0)
	s_setprio 1
	v_mfma_f32_16x16x32_bf16 v[126:129], v[154:157], v[194:197], v[126:129]
	v_mfma_f32_16x16x32_bf16 v[102:105], v[166:169], v[194:197], v[102:105]
	v_mfma_f32_16x16x32_bf16 v[122:125], v[154:157], v[202:205], v[122:125]
	v_mfma_f32_16x16x32_bf16 v[90:93], v[166:169], v[202:205], v[90:93]
	v_mfma_f32_16x16x32_bf16 v[118:121], v[154:157], v[210:213], v[118:121]
	v_mfma_f32_16x16x32_bf16 v[86:89], v[166:169], v[210:213], v[86:89]
	v_mfma_f32_16x16x32_bf16 v[114:117], v[154:157], v[218:221], v[114:117]
	v_mfma_f32_16x16x32_bf16 v[82:85], v[166:169], v[218:221], v[82:85]
	v_mfma_f32_16x16x32_bf16 v[126:129], v[162:165], v[198:201], v[126:129]
	v_mfma_f32_16x16x32_bf16 v[102:105], v[170:173], v[198:201], v[102:105]
	v_mfma_f32_16x16x32_bf16 v[122:125], v[162:165], v[206:209], v[122:125]
	v_mfma_f32_16x16x32_bf16 v[90:93], v[170:173], v[206:209], v[90:93]
	v_mfma_f32_16x16x32_bf16 v[118:121], v[162:165], v[214:217], v[118:121]
	v_mfma_f32_16x16x32_bf16 v[86:89], v[170:173], v[214:217], v[86:89]
	v_mfma_f32_16x16x32_bf16 v[114:117], v[162:165], v[222:225], v[114:117]
	v_mfma_f32_16x16x32_bf16 v[82:85], v[170:173], v[222:225], v[82:85]
	s_setprio 0
	s_barrier
	s_add_i32 s15, 0, 0x1c000
	s_add_i32 s0, s14, s36
	v_add_u32_e32 v161, s15, v158
	v_lshl_add_u64 v[174:175], v[174:175], 0, s[88:89]
	s_mov_b32 m0, s0
	ds_read_b128 v[226:229], v161
	ds_read_b128 v[230:233], v161 offset:1024
	ds_read_b128 v[234:237], v161 offset:2048
	ds_read_b128 v[238:241], v161 offset:3072
	global_load_lds_dwordx4 v[174:175], off
	s_add_i32 m0, s0, 0x2000
	v_lshl_add_u64 v[174:175], v[192:193], 0, s[88:89]
	global_load_lds_dwordx4 v[174:175], off
	s_barrier
	s_waitcnt lgkmcnt(0)
	s_setprio 1
	v_mfma_f32_16x16x32_bf16 v[66:69], v[226:229], v[194:197], v[66:69]
	v_mfma_f32_16x16x32_bf16 v[38:41], v[234:237], v[194:197], v[38:41]
	v_mfma_f32_16x16x32_bf16 v[58:61], v[226:229], v[202:205], v[58:61]
	v_mfma_f32_16x16x32_bf16 v[26:29], v[234:237], v[202:205], v[26:29]
	v_mfma_f32_16x16x32_bf16 v[54:57], v[226:229], v[210:213], v[54:57]
	v_mfma_f32_16x16x32_bf16 v[22:25], v[234:237], v[210:213], v[22:25]
	v_mfma_f32_16x16x32_bf16 v[50:53], v[226:229], v[218:221], v[50:53]
	v_mfma_f32_16x16x32_bf16 v[18:21], v[234:237], v[218:221], v[18:21]
	v_mfma_f32_16x16x32_bf16 v[66:69], v[230:233], v[198:201], v[66:69]
	v_mfma_f32_16x16x32_bf16 v[38:41], v[238:241], v[198:201], v[38:41]
	v_mfma_f32_16x16x32_bf16 v[58:61], v[230:233], v[206:209], v[58:61]
	v_mfma_f32_16x16x32_bf16 v[26:29], v[238:241], v[206:209], v[26:29]
	v_mfma_f32_16x16x32_bf16 v[54:57], v[230:233], v[214:217], v[54:57]
	v_mfma_f32_16x16x32_bf16 v[22:25], v[238:241], v[214:217], v[22:25]
	v_mfma_f32_16x16x32_bf16 v[50:53], v[230:233], v[222:225], v[50:53]
	v_mfma_f32_16x16x32_bf16 v[18:21], v[238:241], v[222:225], v[18:21]
	s_setprio 0
	s_mov_b32 m0, s60
	v_lshl_add_u64 v[174:175], v[242:243], 0, s[88:89]
	s_barrier
	ds_read_b128 v[194:197], v160 offset:49152
	ds_read_b128 v[198:201], v160 offset:50176
	ds_read_b128 v[202:205], v160 offset:51200
	ds_read_b128 v[206:209], v160 offset:52224
	ds_read_b128 v[210:213], v160 offset:53248
	ds_read_b128 v[214:217], v160 offset:54272
	ds_read_b128 v[218:221], v160 offset:55296
	ds_read_b128 v[222:225], v160 offset:56320
	global_load_lds_dwordx4 v[174:175], off
	s_mov_b32 m0, s61
	v_lshl_add_u64 v[174:175], v[244:245], 0, s[88:89]
	global_load_lds_dwordx4 v[174:175], off
	s_barrier
; #define PG8_WAIT_V(n) asm volatile("s_waitcnt vmcnt(" #n ")" ::: "memory")
; #define PG8_BAR __builtin_amdgcn_s_barrier()
;     ...
;             PG8_WAIT_V(6); PG8_BAR; PG8_MMA(1, 1, At, B1); PG8_BAR;
;     __device__ __forceinline__ void operator()(Acc& acc, int pm, int pn, int wr, int wc, int fr, int fq) const {
;         const int brow = pm * 256;
;         const bool lat = brow < T_LAT;
;         const float* xin = lat ? xin_lat : xin_ctx;
;         float* xout = lat ? xout_lat : xout_ctx;
;         const int rsub = lat ? 0 : T_LAT;
;         const int mi = lat ? (brow >> 12) : 8;
;         const int c0 = pn * 256 + wc * 32 + fq * 4;
;         const float* gp = modv_l + (size_t)mi * 6144 + gate_i * 1024 + c0;
; #pragma unroll
;         for (int bj = 0; bj < 2; ++bj)
; #pragma unroll
;             for (int n = 0; n < 2; ++n) {
;                 const f32x4 gv = *reinterpret_cast<const f32x4*>(gp + bj * 128 + n * 16);
; #pragma unroll
;                 for (int ai = 0; ai < 2; ++ai)
; #pragma unroll
;                     for (int m = 0; m < 4; ++m) {
;                         const size_t o = (size_t)(brow + ai * 128 + wr * 64 + m * 16 + fr - rsub) * DM + c0 + bj * 128 + n * 16;
;                         const f32x4 xi = *reinterpret_cast<const f32x4*>(xin + o);
;                         const f32x4 a = acc[ai][bj][m][n];
;                         f32x4 r = {xi[0] + gv[0] * a[0], xi[1] + gv[1] * a[1], xi[2] + gv[2] * a[2], xi[3] + gv[3] * a[3]};
;                         *reinterpret_cast<f32x4*>(xout + o) = r;
;                     }
;             }
	s_waitcnt lgkmcnt(0)
	s_setprio 1
	v_mfma_f32_16x16x32_bf16 v[110:113], v[154:157], v[194:197], v[110:113]
	v_mfma_f32_16x16x32_bf16 v[78:81], v[166:169], v[194:197], v[78:81]
	v_mfma_f32_16x16x32_bf16 v[106:109], v[154:157], v[202:205], v[106:109]
	v_mfma_f32_16x16x32_bf16 v[74:77], v[166:169], v[202:205], v[74:77]
	v_mfma_f32_16x16x32_bf16 v[98:101], v[154:157], v[210:213], v[98:101]
	v_mfma_f32_16x16x32_bf16 v[70:73], v[166:169], v[210:213], v[70:73]
	v_mfma_f32_16x16x32_bf16 v[94:97], v[154:157], v[218:221], v[94:97]
	v_mfma_f32_16x16x32_bf16 v[62:65], v[166:169], v[218:221], v[62:65]
	v_mfma_f32_16x16x32_bf16 v[110:113], v[162:165], v[198:201], v[110:113]
	v_mfma_f32_16x16x32_bf16 v[78:81], v[170:173], v[198:201], v[78:81]
	v_mfma_f32_16x16x32_bf16 v[106:109], v[162:165], v[206:209], v[106:109]
	v_mfma_f32_16x16x32_bf16 v[74:77], v[170:173], v[206:209], v[74:77]
	v_mfma_f32_16x16x32_bf16 v[98:101], v[162:165], v[214:217], v[98:101]
	v_mfma_f32_16x16x32_bf16 v[70:73], v[170:173], v[214:217], v[70:73]
	v_mfma_f32_16x16x32_bf16 v[94:97], v[162:165], v[222:225], v[94:97]
	v_mfma_f32_16x16x32_bf16 v[62:65], v[170:173], v[222:225], v[62:65]
	s_setprio 0
	s_barrier
	s_add_u32 s0, s48, 0xb0080
	s_addc_u32 s1, s49, 0
	s_add_i32 s14, s15, s36
	s_mov_b32 m0, s14
	v_lshl_add_u64 v[154:155], s[0:1], 0, v[132:133]
	global_load_lds_dwordx4 v[154:155], off
	s_add_i32 m0, s14, 0x2000
	v_lshl_add_u64 v[154:155], s[0:1], 0, v[130:131]
	global_load_lds_dwordx4 v[154:155], off
	s_waitcnt vmcnt(6)
	s_barrier
	s_setprio 1
	v_mfma_f32_16x16x32_bf16 v[46:49], v[226:229], v[194:197], v[46:49]
	v_mfma_f32_16x16x32_bf16 v[14:17], v[234:237], v[194:197], v[14:17]
	v_mfma_f32_16x16x32_bf16 v[42:45], v[226:229], v[202:205], v[42:45]
	v_mfma_f32_16x16x32_bf16 v[10:13], v[234:237], v[202:205], v[10:13]
	v_mfma_f32_16x16x32_bf16 v[34:37], v[226:229], v[210:213], v[34:37]
	v_mfma_f32_16x16x32_bf16 v[6:9], v[234:237], v[210:213], v[6:9]
	v_mfma_f32_16x16x32_bf16 v[30:33], v[226:229], v[218:221], v[30:33]
	v_mfma_f32_16x16x32_bf16 v[2:5], v[234:237], v[218:221], v[2:5]
	v_mfma_f32_16x16x32_bf16 v[46:49], v[230:233], v[198:201], v[46:49]
	v_mfma_f32_16x16x32_bf16 v[14:17], v[238:241], v[198:201], v[14:17]
	v_mfma_f32_16x16x32_bf16 v[42:45], v[230:233], v[206:209], v[42:45]
	v_mfma_f32_16x16x32_bf16 v[10:13], v[238:241], v[206:209], v[10:13]
	v_mfma_f32_16x16x32_bf16 v[34:37], v[230:233], v[214:217], v[34:37]
	v_mfma_f32_16x16x32_bf16 v[6:9], v[238:241], v[214:217], v[6:9]
	v_mfma_f32_16x16x32_bf16 v[30:33], v[230:233], v[222:225], v[30:33]
	v_mfma_f32_16x16x32_bf16 v[2:5], v[238:241], v[222:225], v[2:5]
	s_setprio 0
	s_add_i32 s28, s28, 2
	s_add_u32 s22, s22, 0x100
	s_addc_u32 s23, s23, 0
	s_cmp_gt_u32 s28, 41
	s_mov_b64 s[14:15], s[46:47]
	s_barrier
	s_cbranch_scc0 .LBB0_1649
	s_lshl_b32 s22, s4, 8
	v_readlane_b32 s64, v254, 6
	s_cmpk_lt_i32 s4, 0x80
	v_readlane_b32 s66, v254, 8
	v_readlane_b32 s67, v254, 9
	v_readlane_b32 s68, v254, 10
	v_readlane_b32 s69, v254, 11
	s_cselect_b32 s15, s67, s69
	s_cselect_b32 s14, s66, s68
	s_cselect_b32 s23, 0, 0xffff8000
	s_min_i32 s0, s4, 0x80
	s_ashr_i32 s0, s0, 4
	s_mul_hi_i32 s1, s0, 0x6000
	s_mulk_i32 s0, 0x6000
	s_add_u32 s0, s50, s0
	s_addc_u32 s1, s51, s1
	s_add_i32 s23, s23, s22
	s_add_u32 s0, s0, 0x5000
	s_addc_u32 s1, s1, 0
	v_lshl_or_b32 v154, s7, 8, v159
	v_add_u32_e32 v172, s23, v1
	v_ashrrev_i32_e32 v155, 31, v154
	v_lshl_add_u64 v[156:157], v[154:155], 2, s[0:1]
	global_load_dwordx4 v[162:165], v[156:157], off
	global_load_dwordx4 v[166:169], v[156:157], off offset:64
	global_load_dwordx4 v[192:195], v[156:157], off offset:512
	global_load_dwordx4 v[196:199], v[156:157], off offset:576
	v_lshl_add_u32 v161, v172, 10, v154
	v_lshlrev_b32_e32 v161, 2, v161
	v_add_u32_e32 v170, 0x10000, v161
	v_add_u32_e32 v171, 0x20000, v161
	v_add_u32_e32 v154, 0x30000, v161
	v_add_u32_e32 v155, 0x80000, v161
	v_add_u32_e32 v172, 0x90000, v161
	v_add_u32_e32 v156, 0xa0000, v161
	v_add_u32_e32 v157, 0xb0000, v161
	global_load_dwordx4 v[200:203], v161, s[14:15]
	global_load_dwordx4 v[204:207], v161, s[14:15] offset:64
	global_load_dwordx4 v[208:211], v170, s[14:15]
	global_load_dwordx4 v[212:215], v170, s[14:15] offset:64
	global_load_dwordx4 v[216:219], v171, s[14:15]
	global_load_dwordx4 v[220:223], v171, s[14:15] offset:64
	global_load_dwordx4 v[224:227], v154, s[14:15]
	global_load_dwordx4 v[228:231], v154, s[14:15] offset:64
	global_load_dwordx4 v[232:235], v155, s[14:15]
	global_load_dwordx4 v[236:239], v155, s[14:15] offset:64
	global_load_dwordx4 v[240:243], v172, s[14:15]
	s_and_b64 vcc, exec, s[44:45]
	s_mov_b32 s7, s18
	s_mov_b32 s4, s19
	s_mov_b64 s[52:53], s[12:13]
	v_readlane_b32 s65, v254, 7
	v_readlane_b32 s70, v254, 12
	v_readlane_b32 s71, v254, 13
	s_waitcnt vmcnt(10)
	v_pk_fma_f32 v[126:127], v[126:127], v[162:163], v[200:201]
	v_pk_fma_f32 v[128:129], v[128:129], v[164:165], v[202:203]
	global_store_dwordx4 v161, v[126:129], s[14:15] sc1
	global_load_dwordx4 v[200:203], v172, s[14:15] offset:64
	s_waitcnt vmcnt(11)
	v_pk_fma_f32 v[102:103], v[102:103], v[166:167], v[204:205]
	v_pk_fma_f32 v[104:105], v[104:105], v[168:169], v[206:207]
	global_store_dwordx4 v161, v[102:105], s[14:15] offset:64 sc1
	global_load_dwordx4 v[204:207], v156, s[14:15]
	s_waitcnt vmcnt(12)
	v_pk_fma_f32 v[122:123], v[122:123], v[162:163], v[208:209]
	v_pk_fma_f32 v[124:125], v[124:125], v[164:165], v[210:211]
	global_store_dwordx4 v170, v[122:125], s[14:15] sc1
	global_load_dwordx4 v[208:211], v156, s[14:15] offset:64
	s_waitcnt vmcnt(13)
; #define PG8_WAIT_V(n) asm volatile("s_waitcnt vmcnt(" #n ")" ::: "memory")
; #define PG8_BAR __builtin_amdgcn_s_barrier()
;     ...
;         if (!has_next) break;
;     ...
;     PG8_WAIT_V(0);
;     if (wr == 0) PG8_BAR;
;     PG8_BAR;
;     __device__ __forceinline__ void operator()(Acc& acc, int pm, int pn, int wr, int wc, int fr, int fq) const {
;     ...
; #pragma unroll
;         for (int bj = 0; bj < 2; ++bj)
; #pragma unroll
;             for (int n = 0; n < 2; ++n) {
;                 const f32x4 gv = *reinterpret_cast<const f32x4*>(gp + bj * 128 + n * 16);
; #pragma unroll
;                 for (int ai = 0; ai < 2; ++ai)
; #pragma unroll
;                     for (int m = 0; m < 4; ++m) {
;                         const size_t o = (size_t)(brow + ai * 128 + wr * 64 + m * 16 + fr - rsub) * DM + c0 + bj * 128 + n * 16;
;                         const f32x4 xi = *reinterpret_cast<const f32x4*>(xin + o);
;                         const f32x4 a = acc[ai][bj][m][n];
;                         f32x4 r = {xi[0] + gv[0] * a[0], xi[1] + gv[1] * a[1], xi[2] + gv[2] * a[2], xi[3] + gv[3] * a[3]};
;                         *reinterpret_cast<f32x4*>(xout + o) = r;
;                     }
;             }
	v_pk_fma_f32 v[90:91], v[90:91], v[166:167], v[212:213]
	v_pk_fma_f32 v[92:93], v[92:93], v[168:169], v[214:215]
	global_store_dwordx4 v170, v[90:93], s[14:15] offset:64 sc1
	global_load_dwordx4 v[212:215], v157, s[14:15]
	s_waitcnt vmcnt(14)
	v_pk_fma_f32 v[118:119], v[118:119], v[162:163], v[216:217]
	v_pk_fma_f32 v[120:121], v[120:121], v[164:165], v[218:219]
	global_store_dwordx4 v171, v[118:121], s[14:15] sc1
	global_load_dwordx4 v[216:219], v157, s[14:15] offset:64
	s_waitcnt vmcnt(15)
	v_pk_fma_f32 v[86:87], v[86:87], v[166:167], v[220:221]
	v_pk_fma_f32 v[88:89], v[88:89], v[168:169], v[222:223]
	global_store_dwordx4 v171, v[86:89], s[14:15] offset:64 sc1
	global_load_dwordx4 v[220:223], v161, s[14:15] offset:512
	s_waitcnt vmcnt(16)
	v_pk_fma_f32 v[114:115], v[114:115], v[162:163], v[224:225]
	v_pk_fma_f32 v[116:117], v[116:117], v[164:165], v[226:227]
	global_store_dwordx4 v154, v[114:117], s[14:15] sc1
	global_load_dwordx4 v[224:227], v161, s[14:15] offset:576
	s_waitcnt vmcnt(17)
	v_pk_fma_f32 v[82:83], v[82:83], v[166:167], v[228:229]
	v_pk_fma_f32 v[84:85], v[84:85], v[168:169], v[230:231]
	global_store_dwordx4 v154, v[82:85], s[14:15] offset:64 sc1
	global_load_dwordx4 v[228:231], v170, s[14:15] offset:512
	s_waitcnt vmcnt(18)
	v_pk_fma_f32 v[110:111], v[110:111], v[162:163], v[232:233]
	v_pk_fma_f32 v[112:113], v[112:113], v[164:165], v[234:235]
	global_store_dwordx4 v155, v[110:113], s[14:15] sc1
	global_load_dwordx4 v[232:235], v170, s[14:15] offset:576
	s_waitcnt vmcnt(19)
	v_pk_fma_f32 v[78:79], v[78:79], v[166:167], v[236:237]
	v_pk_fma_f32 v[80:81], v[80:81], v[168:169], v[238:239]
	global_store_dwordx4 v155, v[78:81], s[14:15] offset:64 sc1
	global_load_dwordx4 v[236:239], v171, s[14:15] offset:512
	s_waitcnt vmcnt(20)
	v_pk_fma_f32 v[106:107], v[106:107], v[162:163], v[240:241]
	v_pk_fma_f32 v[108:109], v[108:109], v[164:165], v[242:243]
	global_store_dwordx4 v172, v[106:109], s[14:15] sc1
	global_load_dwordx4 v[240:243], v171, s[14:15] offset:576
	s_waitcnt vmcnt(20)
	v_pk_fma_f32 v[74:75], v[74:75], v[166:167], v[200:201]
	v_pk_fma_f32 v[76:77], v[76:77], v[168:169], v[202:203]
	global_store_dwordx4 v172, v[74:77], s[14:15] offset:64 sc1
	global_load_dwordx4 v[200:203], v154, s[14:15] offset:512
	s_waitcnt vmcnt(20)
	v_pk_fma_f32 v[98:99], v[98:99], v[162:163], v[204:205]
	v_pk_fma_f32 v[100:101], v[100:101], v[164:165], v[206:207]
	global_store_dwordx4 v156, v[98:101], s[14:15] sc1
	global_load_dwordx4 v[204:207], v154, s[14:15] offset:576
	s_waitcnt vmcnt(20)
	v_pk_fma_f32 v[70:71], v[70:71], v[166:167], v[208:209]
	v_pk_fma_f32 v[72:73], v[72:73], v[168:169], v[210:211]
	global_store_dwordx4 v156, v[70:73], s[14:15] offset:64 sc1
	global_load_dwordx4 v[208:211], v155, s[14:15] offset:512
	s_waitcnt vmcnt(20)
	v_pk_fma_f32 v[94:95], v[94:95], v[162:163], v[212:213]
	v_pk_fma_f32 v[96:97], v[96:97], v[164:165], v[214:215]
	global_store_dwordx4 v157, v[94:97], s[14:15] sc1
	global_load_dwordx4 v[212:215], v155, s[14:15] offset:576
	s_waitcnt vmcnt(20)
	v_pk_fma_f32 v[62:63], v[62:63], v[166:167], v[216:217]
	v_pk_fma_f32 v[64:65], v[64:65], v[168:169], v[218:219]
	global_store_dwordx4 v157, v[62:65], s[14:15] offset:64 sc1
	global_load_dwordx4 v[216:219], v172, s[14:15] offset:512
	s_waitcnt vmcnt(20)
	v_pk_fma_f32 v[66:67], v[66:67], v[192:193], v[220:221]
	v_pk_fma_f32 v[68:69], v[68:69], v[194:195], v[222:223]
	global_store_dwordx4 v161, v[66:69], s[14:15] offset:512 sc1
	global_load_dwordx4 v[220:223], v172, s[14:15] offset:576
	s_waitcnt vmcnt(20)
	v_pk_fma_f32 v[38:39], v[38:39], v[196:197], v[224:225]
	v_pk_fma_f32 v[40:41], v[40:41], v[198:199], v[226:227]
	global_store_dwordx4 v161, v[38:41], s[14:15] offset:576 sc1
	global_load_dwordx4 v[224:227], v156, s[14:15] offset:512
	s_waitcnt vmcnt(20)
	v_pk_fma_f32 v[58:59], v[58:59], v[192:193], v[228:229]
	v_pk_fma_f32 v[60:61], v[60:61], v[194:195], v[230:231]
	global_store_dwordx4 v170, v[58:61], s[14:15] offset:512 sc1
	global_load_dwordx4 v[228:231], v156, s[14:15] offset:576
	s_waitcnt vmcnt(20)
	v_pk_fma_f32 v[26:27], v[26:27], v[196:197], v[232:233]
	v_pk_fma_f32 v[28:29], v[28:29], v[198:199], v[234:235]
	global_store_dwordx4 v170, v[26:29], s[14:15] offset:576 sc1
	global_load_dwordx4 v[232:235], v157, s[14:15] offset:512
	s_waitcnt vmcnt(20)
	v_pk_fma_f32 v[54:55], v[54:55], v[192:193], v[236:237]
	v_pk_fma_f32 v[56:57], v[56:57], v[194:195], v[238:239]
	global_store_dwordx4 v171, v[54:57], s[14:15] offset:512 sc1
	global_load_dwordx4 v[236:239], v157, s[14:15] offset:576
	s_waitcnt vmcnt(20)
	v_pk_fma_f32 v[22:23], v[22:23], v[196:197], v[240:241]
	v_pk_fma_f32 v[24:25], v[24:25], v[198:199], v[242:243]
	global_store_dwordx4 v171, v[22:25], s[14:15] offset:576 sc1
	s_waitcnt vmcnt(19)
	v_pk_fma_f32 v[50:51], v[50:51], v[192:193], v[200:201]
	v_pk_fma_f32 v[52:53], v[52:53], v[194:195], v[202:203]
	global_store_dwordx4 v154, v[50:53], s[14:15] offset:512 sc1
	s_waitcnt vmcnt(18)
	v_pk_fma_f32 v[18:19], v[18:19], v[196:197], v[204:205]
	v_pk_fma_f32 v[20:21], v[20:21], v[198:199], v[206:207]
	global_store_dwordx4 v154, v[18:21], s[14:15] offset:576 sc1
	s_waitcnt vmcnt(17)
	v_pk_fma_f32 v[46:47], v[46:47], v[192:193], v[208:209]
	v_pk_fma_f32 v[48:49], v[48:49], v[194:195], v[210:211]
	global_store_dwordx4 v155, v[46:49], s[14:15] offset:512 sc1
	s_waitcnt vmcnt(16)
	v_pk_fma_f32 v[14:15], v[14:15], v[196:197], v[212:213]
	v_pk_fma_f32 v[16:17], v[16:17], v[198:199], v[214:215]
	global_store_dwordx4 v155, v[14:17], s[14:15] offset:576 sc1
	s_waitcnt vmcnt(15)
	v_pk_fma_f32 v[42:43], v[42:43], v[192:193], v[216:217]
	v_pk_fma_f32 v[44:45], v[44:45], v[194:195], v[218:219]
	global_store_dwordx4 v172, v[42:45], s[14:15] offset:512 sc1
	s_waitcnt vmcnt(14)
	v_pk_fma_f32 v[10:11], v[10:11], v[196:197], v[220:221]
	v_pk_fma_f32 v[12:13], v[12:13], v[198:199], v[222:223]
	global_store_dwordx4 v172, v[10:13], s[14:15] offset:576 sc1
	s_waitcnt vmcnt(13)
	v_pk_fma_f32 v[34:35], v[34:35], v[192:193], v[224:225]
	v_pk_fma_f32 v[36:37], v[36:37], v[194:195], v[226:227]
	global_store_dwordx4 v156, v[34:37], s[14:15] offset:512 sc1
	s_waitcnt vmcnt(12)
	v_pk_fma_f32 v[6:7], v[6:7], v[196:197], v[228:229]
	v_pk_fma_f32 v[8:9], v[8:9], v[198:199], v[230:231]
	global_store_dwordx4 v156, v[6:9], s[14:15] offset:576 sc1
	s_waitcnt vmcnt(11)
	v_pk_fma_f32 v[30:31], v[30:31], v[192:193], v[232:233]
	v_pk_fma_f32 v[32:33], v[32:33], v[194:195], v[234:235]
	global_store_dwordx4 v157, v[30:33], s[14:15] offset:512 sc1
	s_waitcnt vmcnt(10)
	v_pk_fma_f32 v[2:3], v[2:3], v[196:197], v[236:237]
	v_pk_fma_f32 v[4:5], v[4:5], v[198:199], v[238:239]
	global_store_dwordx4 v157, v[2:5], s[14:15] offset:576 sc1
	s_mov_b64 s[14:15], s[10:11]
	s_mov_b64 s[0:1], 0x5000
	s_cbranch_vccz .LBB0_1642
	s_waitcnt vmcnt(0)
	s_cmpk_gt_u32 s16, 0xff
	s_cbranch_scc1 .LBB0_1653
	s_barrier

; #define PG8_STAGE(bufoff, gbase) do { _Pragma("unroll") for (int _i = 0; _i < 2; ++_i) \
;         __builtin_amdgcn_global_load_lds((const unsigned*)((const char*)(gbase) + voff[_i]), (LAS unsigned*)(lds + (bufoff) + ldsw + _i * 8192), 16, 0, 0); } while (0)
; #define PG8_LDA(dst, b, h) do { _Pragma("unroll") for (int m = 0; m < 4; ++m) _Pragma("unroll") for (int k = 0; k < 2; ++k) dst[m][k] = *(const LAS bf16x8*)(lds + PG8_SA(b, h) + aoff + m * 2048 + k * 1024); } while (0)
; #define PG8_LDB(dst, b, h) do { _Pragma("unroll") for (int n = 0; n < 2; ++n) _Pragma("unroll") for (int k = 0; k < 2; ++k) dst[n][k] = *(const LAS bf16x8*)(lds + PG8_SB(b, h) + boff + n * 2048 + k * 1024); } while (0)
; #define PG8_WAIT_V(n) asm volatile("s_waitcnt vmcnt(" #n ")" ::: "memory")
; #define PG8_WAIT_L(n) asm volatile("s_waitcnt lgkmcnt(" #n ")" ::: "memory")
;     ...
;         for (int t = 0; t < nt; t += 2) {
;             const bool last = (t == nt - 2);
;             const char* a1 = cA + (size_t)(t + 1) * kstep;
;             const char* a2 = last ? nA : cA + (size_t)(t + 2) * kstep; const char* b2 = last ? nB : cB + (size_t)(t + 2) * kstep;
;             const char* a3 = a2 + kstep; const char* b3 = b2 + kstep;
;             PG8_LDB(B0, 0, 0); PG8_SCHED; PG8_LDA(At, 0, 0); PG8_STAGE(PG8_SA(1, 1), a1 + hstep);
;             PG8_WAIT_L(8); PG8_BAR; PG8_WAIT_L(0); PG8_MMA(0, 0, At, B0); PG8_BAR; PG8_SCHED;
;             PG8_LDB(B1, 0, 1); PG8_STAGE(PG8_SB(0, 0), b2);
;             PG8_BAR; PG8_WAIT_L(0); PG8_MMA(0, 1, At, B1); PG8_BAR;
;             PG8_LDA(At, 0, 1); PG8_STAGE(PG8_SA(0, 0), a2);
;             PG8_BAR; PG8_WAIT_L(0); PG8_MMA(1, 0, At, B0); PG8_BAR; PG8_SCHED;
;             PG8_STAGE(PG8_SB(0, 1), b2 + hstep);
;             PG8_WAIT_V(6); PG8_BAR; PG8_MMA(1, 1, At, B1); PG8_BAR;
;             PG8_LDB(B0, 1, 0); PG8_SCHED; PG8_LDA(At, 1, 0); PG8_STAGE(PG8_SA(0, 1), a2 + hstep);
;             PG8_WAIT_L(8); PG8_BAR; PG8_WAIT_L(0); PG8_MMA(0, 0, At, B0); PG8_BAR; PG8_SCHED;
;             PG8_LDB(B1, 1, 1); PG8_STAGE(PG8_SB(1, 0), b3);
;             PG8_BAR; PG8_WAIT_L(0); PG8_MMA(0, 1, At, B1); PG8_BAR;
;             PG8_LDA(At, 1, 1); PG8_STAGE(PG8_SA(1, 0), a3);
;             PG8_BAR; PG8_WAIT_L(0); PG8_MMA(1, 0, At, B0); PG8_BAR; PG8_SCHED;
;             PG8_STAGE(PG8_SB(1, 1), b3 + hstep);
;             PG8_WAIT_V(6); PG8_BAR; PG8_MMA(1, 1, At, B1); PG8_BAR;
.LBB0_1832:
	s_add_u32 s0, s12, 0xf4f50080
	s_addc_u32 s1, s13, -1
	s_cmp_lg_u32 s28, 40
	s_cselect_b32 s0, s0, 0
	s_cselect_b32 s1, s1, 0
	s_add_u32 s40, s44, s0
	s_addc_u32 s41, s45, s1
	s_add_i32 s29, 0, 0x10000
	v_add_u32_e32 v157, s29, v155
	ds_read_b128 v[158:161], v157
	ds_read_b128 v[162:165], v157 offset:1024
	ds_read_b128 v[166:169], v157 offset:2048
	ds_read_b128 v[170:173], v157 offset:3072
	s_add_u32 s14, s10, s0
	s_addc_u32 s15, s11, s1
	v_lshl_add_u64 v[174:175], v[150:151], 0, s[12:13]
	s_add_i32 m0, s7, 0xc000
	ds_read_b128 v[194:197], v156
	ds_read_b128 v[198:201], v156 offset:1024
	ds_read_b128 v[202:205], v156 offset:2048
	ds_read_b128 v[206:209], v156 offset:3072
	ds_read_b128 v[210:213], v156 offset:4096
	ds_read_b128 v[214:217], v156 offset:5120
	ds_read_b128 v[218:221], v156 offset:6144
	ds_read_b128 v[222:225], v156 offset:7168
	global_load_lds_dwordx4 v[174:175], off
	s_add_i32 m0, s7, 0xe000
	v_lshl_add_u64 v[174:175], v[152:153], 0, s[12:13]
	global_load_lds_dwordx4 v[174:175], off
	s_waitcnt lgkmcnt(8)
	s_barrier
	s_waitcnt lgkmcnt(0)
	s_setprio 1
	v_mfma_f32_16x16x32_bf16 v[126:129], v[158:161], v[194:197], v[126:129]
	v_mfma_f32_16x16x32_bf16 v[102:105], v[166:169], v[194:197], v[102:105]
	v_mfma_f32_16x16x32_bf16 v[122:125], v[158:161], v[202:205], v[122:125]
	v_mfma_f32_16x16x32_bf16 v[90:93], v[166:169], v[202:205], v[90:93]
	v_mfma_f32_16x16x32_bf16 v[118:121], v[158:161], v[210:213], v[118:121]
	v_mfma_f32_16x16x32_bf16 v[86:89], v[166:169], v[210:213], v[86:89]
	v_mfma_f32_16x16x32_bf16 v[114:117], v[158:161], v[218:221], v[114:117]
	v_mfma_f32_16x16x32_bf16 v[82:85], v[166:169], v[218:221], v[82:85]
	v_mfma_f32_16x16x32_bf16 v[126:129], v[162:165], v[198:201], v[126:129]
	v_mfma_f32_16x16x32_bf16 v[102:105], v[170:173], v[198:201], v[102:105]
	v_mfma_f32_16x16x32_bf16 v[122:125], v[162:165], v[206:209], v[122:125]
	v_mfma_f32_16x16x32_bf16 v[90:93], v[170:173], v[206:209], v[90:93]
	v_mfma_f32_16x16x32_bf16 v[118:121], v[162:165], v[214:217], v[118:121]
	v_mfma_f32_16x16x32_bf16 v[86:89], v[170:173], v[214:217], v[86:89]
	v_mfma_f32_16x16x32_bf16 v[114:117], v[162:165], v[222:225], v[114:117]
	v_mfma_f32_16x16x32_bf16 v[82:85], v[170:173], v[222:225], v[82:85]
	s_setprio 0
	s_barrier
	s_add_i32 s30, 0, 0x14000
	s_add_i32 s0, s29, s4
	v_add_u32_e32 v157, s30, v155
	v_lshl_add_u64 v[174:175], s[14:15], 0, v[130:131]
	s_mov_b32 m0, s0
	ds_read_b128 v[226:229], v157
	ds_read_b128 v[230:233], v157 offset:1024
	ds_read_b128 v[234:237], v157 offset:2048
	ds_read_b128 v[238:241], v157 offset:3072
	global_load_lds_dwordx4 v[174:175], off
	s_add_i32 m0, s0, 0x2000
	v_lshl_add_u64 v[192:193], s[14:15], 0, v[132:133]
	global_load_lds_dwordx4 v[192:193], off
	s_barrier
	s_waitcnt lgkmcnt(0)
	s_setprio 1
	v_mfma_f32_16x16x32_bf16 v[78:81], v[226:229], v[194:197], v[78:81]
	v_mfma_f32_16x16x32_bf16 v[54:57], v[234:237], v[194:197], v[54:57]
	v_mfma_f32_16x16x32_bf16 v[74:77], v[226:229], v[202:205], v[74:77]
	v_mfma_f32_16x16x32_bf16 v[46:49], v[234:237], v[202:205], v[46:49]
	v_mfma_f32_16x16x32_bf16 v[66:69], v[226:229], v[210:213], v[66:69]
	v_mfma_f32_16x16x32_bf16 v[38:41], v[234:237], v[210:213], v[38:41]
	v_mfma_f32_16x16x32_bf16 v[58:61], v[226:229], v[218:221], v[58:61]
	v_mfma_f32_16x16x32_bf16 v[34:37], v[234:237], v[218:221], v[34:37]
	v_mfma_f32_16x16x32_bf16 v[78:81], v[230:233], v[198:201], v[78:81]
	v_mfma_f32_16x16x32_bf16 v[54:57], v[238:241], v[198:201], v[54:57]
	v_mfma_f32_16x16x32_bf16 v[74:77], v[230:233], v[206:209], v[74:77]
	v_mfma_f32_16x16x32_bf16 v[46:49], v[238:241], v[206:209], v[46:49]
	v_mfma_f32_16x16x32_bf16 v[66:69], v[230:233], v[214:217], v[66:69]
	v_mfma_f32_16x16x32_bf16 v[38:41], v[238:241], v[214:217], v[38:41]
	v_mfma_f32_16x16x32_bf16 v[58:61], v[230:233], v[222:225], v[58:61]
	v_mfma_f32_16x16x32_bf16 v[34:37], v[238:241], v[222:225], v[34:37]
	s_setprio 0
	s_mov_b32 m0, s7
	v_lshl_add_u64 v[242:243], s[40:41], 0, v[130:131]
	s_barrier
	ds_read_b128 v[194:197], v156 offset:16384
	ds_read_b128 v[198:201], v156 offset:17408
	ds_read_b128 v[202:205], v156 offset:18432
	ds_read_b128 v[206:209], v156 offset:19456
	ds_read_b128 v[210:213], v156 offset:20480
	ds_read_b128 v[214:217], v156 offset:21504
	ds_read_b128 v[218:221], v156 offset:22528
	ds_read_b128 v[222:225], v156 offset:23552
	global_load_lds_dwordx4 v[242:243], off
	s_mov_b32 m0, s17
	v_lshl_add_u64 v[244:245], s[40:41], 0, v[132:133]
	global_load_lds_dwordx4 v[244:245], off
	s_barrier
	s_waitcnt lgkmcnt(0)
	s_setprio 1
	v_mfma_f32_16x16x32_bf16 v[110:113], v[158:161], v[194:197], v[110:113]
	v_mfma_f32_16x16x32_bf16 v[70:73], v[166:169], v[194:197], v[70:73]
	v_mfma_f32_16x16x32_bf16 v[106:109], v[158:161], v[202:205], v[106:109]
	v_mfma_f32_16x16x32_bf16 v[62:65], v[166:169], v[202:205], v[62:65]
	v_mfma_f32_16x16x32_bf16 v[98:101], v[158:161], v[210:213], v[98:101]
	v_mfma_f32_16x16x32_bf16 v[50:53], v[166:169], v[210:213], v[50:53]
	v_mfma_f32_16x16x32_bf16 v[94:97], v[158:161], v[218:221], v[94:97]
	v_mfma_f32_16x16x32_bf16 v[42:45], v[166:169], v[218:221], v[42:45]
	v_mfma_f32_16x16x32_bf16 v[110:113], v[162:165], v[198:201], v[110:113]
	v_mfma_f32_16x16x32_bf16 v[70:73], v[170:173], v[198:201], v[70:73]
	v_mfma_f32_16x16x32_bf16 v[106:109], v[162:165], v[206:209], v[106:109]
	v_mfma_f32_16x16x32_bf16 v[62:65], v[170:173], v[206:209], v[62:65]
	v_mfma_f32_16x16x32_bf16 v[98:101], v[162:165], v[214:217], v[98:101]
	v_mfma_f32_16x16x32_bf16 v[50:53], v[170:173], v[214:217], v[50:53]
	v_mfma_f32_16x16x32_bf16 v[94:97], v[162:165], v[222:225], v[94:97]
	v_mfma_f32_16x16x32_bf16 v[42:45], v[170:173], v[222:225], v[42:45]
	s_setprio 0
	s_barrier
; #define PG8_STAGE(bufoff, gbase) do { _Pragma("unroll") for (int _i = 0; _i < 2; ++_i) \
;         __builtin_amdgcn_global_load_lds((const unsigned*)((const char*)(gbase) + voff[_i]), (LAS unsigned*)(lds + (bufoff) + ldsw + _i * 8192), 16, 0, 0); } while (0)
; #define PG8_LDA(dst, b, h) do { _Pragma("unroll") for (int m = 0; m < 4; ++m) _Pragma("unroll") for (int k = 0; k < 2; ++k) dst[m][k] = *(const LAS bf16x8*)(lds + PG8_SA(b, h) + aoff + m * 2048 + k * 1024); } while (0)
; #define PG8_LDB(dst, b, h) do { _Pragma("unroll") for (int n = 0; n < 2; ++n) _Pragma("unroll") for (int k = 0; k < 2; ++k) dst[n][k] = *(const LAS bf16x8*)(lds + PG8_SB(b, h) + boff + n * 2048 + k * 1024); } while (0)
; #define PG8_WAIT_V(n) asm volatile("s_waitcnt vmcnt(" #n ")" ::: "memory")
; #define PG8_WAIT_L(n) asm volatile("s_waitcnt lgkmcnt(" #n ")" ::: "memory")
; #define PG8_BAR __builtin_amdgcn_s_barrier()
; #define PG8_SCHED __builtin_amdgcn_sched_barrier(0)
;     ...
;             PG8_LDB(B0, 0, 0); PG8_SCHED; PG8_LDA(At, 0, 0); PG8_STAGE(PG8_SA(1, 1), a1 + hstep);
;             PG8_WAIT_L(8); PG8_BAR; PG8_WAIT_L(0); PG8_MMA(0, 0, At, B0); PG8_BAR; PG8_SCHED;
;             PG8_LDB(B1, 0, 1); PG8_STAGE(PG8_SB(0, 0), b2);
;             PG8_BAR; PG8_WAIT_L(0); PG8_MMA(0, 1, At, B1); PG8_BAR;
;             PG8_LDA(At, 0, 1); PG8_STAGE(PG8_SA(0, 0), a2);
;             PG8_BAR; PG8_WAIT_L(0); PG8_MMA(1, 0, At, B0); PG8_BAR; PG8_SCHED;
;             PG8_STAGE(PG8_SB(0, 1), b2 + hstep);
;             PG8_WAIT_V(6); PG8_BAR; PG8_MMA(1, 1, At, B1); PG8_BAR;
;             PG8_LDB(B0, 1, 0); PG8_SCHED; PG8_LDA(At, 1, 0); PG8_STAGE(PG8_SA(0, 1), a2 + hstep);
;             PG8_WAIT_L(8); PG8_BAR; PG8_WAIT_L(0); PG8_MMA(0, 0, At, B0); PG8_BAR; PG8_SCHED;
;             PG8_LDB(B1, 1, 1); PG8_STAGE(PG8_SB(1, 0), b3);
;             PG8_BAR; PG8_WAIT_L(0); PG8_MMA(0, 1, At, B1); PG8_BAR;
;             PG8_LDA(At, 1, 1); PG8_STAGE(PG8_SA(1, 0), a3);
;             PG8_BAR; PG8_WAIT_L(0); PG8_MMA(1, 0, At, B0); PG8_BAR; PG8_SCHED;
;             PG8_STAGE(PG8_SB(1, 1), b3 + hstep);
;             PG8_WAIT_V(6); PG8_BAR; PG8_MMA(1, 1, At, B1); PG8_BAR;
	s_add_u32 s0, s14, 0xb0000
	s_addc_u32 s1, s15, 0
	s_add_i32 s29, s30, s4
	s_mov_b32 m0, s29
	v_lshl_add_u64 v[158:159], s[0:1], 0, v[130:131]
	global_load_lds_dwordx4 v[158:159], off
	s_add_i32 m0, s29, 0x2000
	v_lshl_add_u64 v[158:159], s[0:1], 0, v[132:133]
	global_load_lds_dwordx4 v[158:159], off
	s_waitcnt vmcnt(6)
	s_barrier
	s_setprio 1
	v_mfma_f32_16x16x32_bf16 v[30:33], v[226:229], v[194:197], v[30:33]
	v_mfma_f32_16x16x32_bf16 v[14:17], v[234:237], v[194:197], v[14:17]
	v_mfma_f32_16x16x32_bf16 v[26:29], v[226:229], v[202:205], v[26:29]
	v_mfma_f32_16x16x32_bf16 v[10:13], v[234:237], v[202:205], v[10:13]
	v_mfma_f32_16x16x32_bf16 v[22:25], v[226:229], v[210:213], v[22:25]
	v_mfma_f32_16x16x32_bf16 v[6:9], v[234:237], v[210:213], v[6:9]
	v_mfma_f32_16x16x32_bf16 v[18:21], v[226:229], v[218:221], v[18:21]
	v_mfma_f32_16x16x32_bf16 v[2:5], v[234:237], v[218:221], v[2:5]
	v_mfma_f32_16x16x32_bf16 v[30:33], v[230:233], v[198:201], v[30:33]
	v_mfma_f32_16x16x32_bf16 v[14:17], v[238:241], v[198:201], v[14:17]
	v_mfma_f32_16x16x32_bf16 v[26:29], v[230:233], v[206:209], v[26:29]
	v_mfma_f32_16x16x32_bf16 v[10:13], v[238:241], v[206:209], v[10:13]
	v_mfma_f32_16x16x32_bf16 v[22:25], v[230:233], v[214:217], v[22:25]
	v_mfma_f32_16x16x32_bf16 v[6:9], v[238:241], v[214:217], v[6:9]
	v_mfma_f32_16x16x32_bf16 v[18:21], v[230:233], v[222:225], v[18:21]
	v_mfma_f32_16x16x32_bf16 v[2:5], v[238:241], v[222:225], v[2:5]
	s_setprio 0
	s_add_i32 s29, 0, 0x18000
	v_add_u32_e32 v157, s29, v155
	s_barrier
	ds_read_b128 v[158:161], v157
	ds_read_b128 v[162:165], v157 offset:1024
	ds_read_b128 v[166:169], v157 offset:2048
	ds_read_b128 v[170:173], v157 offset:3072
	s_add_u32 s0, s40, 0xb0000
	s_addc_u32 s1, s41, 0
	s_mov_b32 m0, s18
	v_lshl_add_u64 v[226:227], s[0:1], 0, v[130:131]
	ds_read_b128 v[194:197], v156 offset:32768
	ds_read_b128 v[198:201], v156 offset:33792
	ds_read_b128 v[202:205], v156 offset:34816
	ds_read_b128 v[206:209], v156 offset:35840
	ds_read_b128 v[210:213], v156 offset:36864
	ds_read_b128 v[214:217], v156 offset:37888
	ds_read_b128 v[218:221], v156 offset:38912
	ds_read_b128 v[222:225], v156 offset:39936
	global_load_lds_dwordx4 v[226:227], off
	s_mov_b32 m0, s19
	v_lshl_add_u64 v[226:227], s[0:1], 0, v[132:133]
	global_load_lds_dwordx4 v[226:227], off
	s_waitcnt lgkmcnt(8)
	s_barrier
	s_waitcnt lgkmcnt(0)
	s_setprio 1
	v_mfma_f32_16x16x32_bf16 v[126:129], v[158:161], v[194:197], v[126:129]
	v_mfma_f32_16x16x32_bf16 v[102:105], v[166:169], v[194:197], v[102:105]
	v_mfma_f32_16x16x32_bf16 v[122:125], v[158:161], v[202:205], v[122:125]
	v_mfma_f32_16x16x32_bf16 v[90:93], v[166:169], v[202:205], v[90:93]
	v_mfma_f32_16x16x32_bf16 v[118:121], v[158:161], v[210:213], v[118:121]
	v_mfma_f32_16x16x32_bf16 v[86:89], v[166:169], v[210:213], v[86:89]
	v_mfma_f32_16x16x32_bf16 v[114:117], v[158:161], v[218:221], v[114:117]
	v_mfma_f32_16x16x32_bf16 v[82:85], v[166:169], v[218:221], v[82:85]
	v_mfma_f32_16x16x32_bf16 v[126:129], v[162:165], v[198:201], v[126:129]
	v_mfma_f32_16x16x32_bf16 v[102:105], v[170:173], v[198:201], v[102:105]
	v_mfma_f32_16x16x32_bf16 v[122:125], v[162:165], v[206:209], v[122:125]
	v_mfma_f32_16x16x32_bf16 v[90:93], v[170:173], v[206:209], v[90:93]
	v_mfma_f32_16x16x32_bf16 v[118:121], v[162:165], v[214:217], v[118:121]
	v_mfma_f32_16x16x32_bf16 v[86:89], v[170:173], v[214:217], v[86:89]
	v_mfma_f32_16x16x32_bf16 v[114:117], v[162:165], v[222:225], v[114:117]
	v_mfma_f32_16x16x32_bf16 v[82:85], v[170:173], v[222:225], v[82:85]
	s_setprio 0
	s_barrier
	s_add_i32 s30, 0, 0x1c000
	s_add_i32 s0, s29, s4
	v_add_u32_e32 v157, s30, v155
	v_lshl_add_u64 v[174:175], v[174:175], 0, s[88:89]
	s_mov_b32 m0, s0
	ds_read_b128 v[226:229], v157
	ds_read_b128 v[230:233], v157 offset:1024
	ds_read_b128 v[234:237], v157 offset:2048
	ds_read_b128 v[238:241], v157 offset:3072
	global_load_lds_dwordx4 v[174:175], off
	s_add_i32 m0, s0, 0x2000
	v_lshl_add_u64 v[174:175], v[192:193], 0, s[88:89]
	global_load_lds_dwordx4 v[174:175], off
	s_barrier
	s_waitcnt lgkmcnt(0)
	s_setprio 1
	v_mfma_f32_16x16x32_bf16 v[78:81], v[226:229], v[194:197], v[78:81]
	v_mfma_f32_16x16x32_bf16 v[54:57], v[234:237], v[194:197], v[54:57]
	v_mfma_f32_16x16x32_bf16 v[74:77], v[226:229], v[202:205], v[74:77]
	v_mfma_f32_16x16x32_bf16 v[46:49], v[234:237], v[202:205], v[46:49]
	v_mfma_f32_16x16x32_bf16 v[66:69], v[226:229], v[210:213], v[66:69]
	v_mfma_f32_16x16x32_bf16 v[38:41], v[234:237], v[210:213], v[38:41]
	v_mfma_f32_16x16x32_bf16 v[58:61], v[226:229], v[218:221], v[58:61]
	v_mfma_f32_16x16x32_bf16 v[34:37], v[234:237], v[218:221], v[34:37]
	v_mfma_f32_16x16x32_bf16 v[78:81], v[230:233], v[198:201], v[78:81]
	v_mfma_f32_16x16x32_bf16 v[54:57], v[238:241], v[198:201], v[54:57]
	v_mfma_f32_16x16x32_bf16 v[74:77], v[230:233], v[206:209], v[74:77]
	v_mfma_f32_16x16x32_bf16 v[46:49], v[238:241], v[206:209], v[46:49]
	v_mfma_f32_16x16x32_bf16 v[66:69], v[230:233], v[214:217], v[66:69]
	v_mfma_f32_16x16x32_bf16 v[38:41], v[238:241], v[214:217], v[38:41]
	v_mfma_f32_16x16x32_bf16 v[58:61], v[230:233], v[222:225], v[58:61]
	v_mfma_f32_16x16x32_bf16 v[34:37], v[238:241], v[222:225], v[34:37]
	s_setprio 0
	s_mov_b32 m0, s22
	v_lshl_add_u64 v[174:175], v[242:243], 0, s[88:89]
	s_barrier
	ds_read_b128 v[194:197], v156 offset:49152
	ds_read_b128 v[198:201], v156 offset:50176
	ds_read_b128 v[202:205], v156 offset:51200
	ds_read_b128 v[206:209], v156 offset:52224
	ds_read_b128 v[210:213], v156 offset:53248
	ds_read_b128 v[214:217], v156 offset:54272
	ds_read_b128 v[218:221], v156 offset:55296
	ds_read_b128 v[222:225], v156 offset:56320
	global_load_lds_dwordx4 v[174:175], off
	s_mov_b32 m0, s23
	v_lshl_add_u64 v[174:175], v[244:245], 0, s[88:89]
	global_load_lds_dwordx4 v[174:175], off
	s_barrier
; #define PG8_STAGE(bufoff, gbase) do { _Pragma("unroll") for (int _i = 0; _i < 2; ++_i) \
;         __builtin_amdgcn_global_load_lds((const unsigned*)((const char*)(gbase) + voff[_i]), (LAS unsigned*)(lds + (bufoff) + ldsw + _i * 8192), 16, 0, 0); } while (0)
; #define PG8_LDA(dst, b, h) do { _Pragma("unroll") for (int m = 0; m < 4; ++m) _Pragma("unroll") for (int k = 0; k < 2; ++k) dst[m][k] = *(const LAS bf16x8*)(lds + PG8_SA(b, h) + aoff + m * 2048 + k * 1024); } while (0)
; #define PG8_WAIT_V(n) asm volatile("s_waitcnt vmcnt(" #n ")" ::: "memory")
; #define PG8_WAIT_L(n) asm volatile("s_waitcnt lgkmcnt(" #n ")" ::: "memory")
;     ...
;             PG8_WAIT_V(6); PG8_BAR; PG8_MMA(1, 1, At, B1); PG8_BAR;
;             PG8_LDB(B0, 1, 0); PG8_SCHED; PG8_LDA(At, 1, 0); PG8_STAGE(PG8_SA(0, 1), a2 + hstep);
;             PG8_WAIT_L(8); PG8_BAR; PG8_WAIT_L(0); PG8_MMA(0, 0, At, B0); PG8_BAR; PG8_SCHED;
;             PG8_LDB(B1, 1, 1); PG8_STAGE(PG8_SB(1, 0), b3);
;             PG8_BAR; PG8_WAIT_L(0); PG8_MMA(0, 1, At, B1); PG8_BAR;
;             PG8_LDA(At, 1, 1); PG8_STAGE(PG8_SA(1, 0), a3);
;             PG8_BAR; PG8_WAIT_L(0); PG8_MMA(1, 0, At, B0); PG8_BAR; PG8_SCHED;
;             PG8_STAGE(PG8_SB(1, 1), b3 + hstep);
;             PG8_WAIT_V(6); PG8_BAR; PG8_MMA(1, 1, At, B1); PG8_BAR;
;         }
;         E(acc, cur.pm + pm0, cur.pn, wr, wc, fr, fq);
;     __device__ __forceinline__ void operator()(Acc& acc, int pm, int pn, int wr, int wc, int fr, int fq) const {
;     ...
;         const float* gp = modv_l + (size_t)mi * 6144 + gate_i * 1024 + c0;
; #pragma unroll
;         for (int bj = 0; bj < 2; ++bj)
; #pragma unroll
;             for (int n = 0; n < 2; ++n) {
;                 const f32x4 gv = *reinterpret_cast<const f32x4*>(gp + bj * 128 + n * 16);
; #pragma unroll
;                 for (int ai = 0; ai < 2; ++ai)
; #pragma unroll
;                     for (int m = 0; m < 4; ++m) {
;                         const size_t o = (size_t)(brow + ai * 128 + wr * 64 + m * 16 + fr - rsub) * DM + c0 + bj * 128 + n * 16;
;                         const f32x4 xi = *reinterpret_cast<const f32x4*>(xin + o);
;                         const f32x4 a = acc[ai][bj][m][n];
;                         f32x4 r = {xi[0] + gv[0] * a[0], xi[1] + gv[1] * a[1], xi[2] + gv[2] * a[2], xi[3] + gv[3] * a[3]};
;                         *reinterpret_cast<f32x4*>(xout + o) = r;
;                     }
	s_waitcnt lgkmcnt(0)
	s_setprio 1
	v_mfma_f32_16x16x32_bf16 v[110:113], v[158:161], v[194:197], v[110:113]
	v_mfma_f32_16x16x32_bf16 v[70:73], v[166:169], v[194:197], v[70:73]
	v_mfma_f32_16x16x32_bf16 v[106:109], v[158:161], v[202:205], v[106:109]
	v_mfma_f32_16x16x32_bf16 v[62:65], v[166:169], v[202:205], v[62:65]
	v_mfma_f32_16x16x32_bf16 v[98:101], v[158:161], v[210:213], v[98:101]
	v_mfma_f32_16x16x32_bf16 v[50:53], v[166:169], v[210:213], v[50:53]
	v_mfma_f32_16x16x32_bf16 v[94:97], v[158:161], v[218:221], v[94:97]
	v_mfma_f32_16x16x32_bf16 v[42:45], v[166:169], v[218:221], v[42:45]
	v_mfma_f32_16x16x32_bf16 v[110:113], v[162:165], v[198:201], v[110:113]
	v_mfma_f32_16x16x32_bf16 v[70:73], v[170:173], v[198:201], v[70:73]
	v_mfma_f32_16x16x32_bf16 v[106:109], v[162:165], v[206:209], v[106:109]
	v_mfma_f32_16x16x32_bf16 v[62:65], v[170:173], v[206:209], v[62:65]
	v_mfma_f32_16x16x32_bf16 v[98:101], v[162:165], v[214:217], v[98:101]
	v_mfma_f32_16x16x32_bf16 v[50:53], v[170:173], v[214:217], v[50:53]
	v_mfma_f32_16x16x32_bf16 v[94:97], v[162:165], v[222:225], v[94:97]
	v_mfma_f32_16x16x32_bf16 v[42:45], v[170:173], v[222:225], v[42:45]
	s_setprio 0
	s_barrier
	s_add_u32 s0, s14, 0xb0080
	s_addc_u32 s1, s15, 0
	s_add_i32 s14, s30, s4
	s_mov_b32 m0, s14
	v_lshl_add_u64 v[158:159], s[0:1], 0, v[130:131]
	global_load_lds_dwordx4 v[158:159], off
	s_add_i32 m0, s14, 0x2000
	v_lshl_add_u64 v[158:159], s[0:1], 0, v[132:133]
	global_load_lds_dwordx4 v[158:159], off
	s_waitcnt vmcnt(6)
	s_barrier
	s_setprio 1
	v_mfma_f32_16x16x32_bf16 v[30:33], v[226:229], v[194:197], v[30:33]
	v_mfma_f32_16x16x32_bf16 v[14:17], v[234:237], v[194:197], v[14:17]
	v_mfma_f32_16x16x32_bf16 v[26:29], v[226:229], v[202:205], v[26:29]
	v_mfma_f32_16x16x32_bf16 v[10:13], v[234:237], v[202:205], v[10:13]
	v_mfma_f32_16x16x32_bf16 v[22:25], v[226:229], v[210:213], v[22:25]
	v_mfma_f32_16x16x32_bf16 v[6:9], v[234:237], v[210:213], v[6:9]
	v_mfma_f32_16x16x32_bf16 v[18:21], v[226:229], v[218:221], v[18:21]
	v_mfma_f32_16x16x32_bf16 v[2:5], v[234:237], v[218:221], v[2:5]
	v_mfma_f32_16x16x32_bf16 v[30:33], v[230:233], v[198:201], v[30:33]
	v_mfma_f32_16x16x32_bf16 v[14:17], v[238:241], v[198:201], v[14:17]
	v_mfma_f32_16x16x32_bf16 v[26:29], v[230:233], v[206:209], v[26:29]
	v_mfma_f32_16x16x32_bf16 v[10:13], v[238:241], v[206:209], v[10:13]
	v_mfma_f32_16x16x32_bf16 v[22:25], v[230:233], v[214:217], v[22:25]
	v_mfma_f32_16x16x32_bf16 v[6:9], v[238:241], v[214:217], v[6:9]
	v_mfma_f32_16x16x32_bf16 v[18:21], v[230:233], v[222:225], v[18:21]
	v_mfma_f32_16x16x32_bf16 v[2:5], v[238:241], v[222:225], v[2:5]
	s_setprio 0
	s_add_i32 s28, s28, 2
	s_add_u32 s12, s12, 0x100
	s_addc_u32 s13, s13, 0
	s_cmp_gt_u32 s28, 41
	s_barrier
	s_cbranch_scc0 .LBB0_1832
	v_readlane_b32 s0, v253, 63
	v_readlane_b32 s64, v254, 6
	v_readlane_b32 s68, v254, 10
	v_readlane_b32 s69, v254, 11
	v_readlane_b32 s65, v254, 7
	v_readlane_b32 s66, v254, 8
	v_readlane_b32 s67, v254, 9
	v_readlane_b32 s70, v254, 12
	v_readlane_b32 s71, v254, 13
	v_mov_b32_e32 v161, v0
	v_lshl_or_b32 v157, v154, 2, s0
	v_or_b32_e32 v157, s20, v157
	v_lshlrev_b32_e32 v160, 2, v157
	v_readlane_b32 s0, v253, 61
	s_nop 1
	v_lshl_add_u64 v[158:159], s[50:51], 0, v[160:161]
	v_add_u32_e32 v162, s0, v1
	s_mov_b64 s[0:1], 0x35000
	v_lshl_add_u64 v[158:159], v[158:159], 0, s[0:1]
	global_load_dwordx4 v[192:195], v[158:159], off
	global_load_dwordx4 v[196:199], v[158:159], off offset:64
	global_load_dwordx4 v[200:203], v[158:159], off offset:512
	global_load_dwordx4 v[204:207], v[158:159], off offset:576
	v_add_u32_e32 v163, 0xffff8000, v162
	v_lshl_or_b32 v164, v163, 12, v160
	v_add_u32_e32 v165, 0x10000, v164
	v_add_u32_e32 v166, 0x20000, v164
	v_add_u32_e32 v167, 0x30000, v164
	v_add_u32_e32 v168, 0x80000, v164
	v_add_u32_e32 v169, 0x90000, v164
	v_add_u32_e32 v170, 0xa0000, v164
	v_add_u32_e32 v171, 0xb0000, v164
	global_load_dwordx4 v[208:211], v164, s[68:69]
	global_load_dwordx4 v[212:215], v164, s[68:69] offset:64
	global_load_dwordx4 v[216:219], v165, s[68:69]
	global_load_dwordx4 v[220:223], v165, s[68:69] offset:64
	global_load_dwordx4 v[224:227], v166, s[68:69]
	global_load_dwordx4 v[228:231], v166, s[68:69] offset:64
	global_load_dwordx4 v[232:235], v167, s[68:69]
	global_load_dwordx4 v[236:239], v167, s[68:69] offset:64
	global_load_dwordx4 v[240:243], v168, s[68:69]
	s_cmpk_lt_u32 s16, 0x100
	s_waitcnt vmcnt(8)
	v_pk_fma_f32 v[126:127], v[126:127], v[192:193], v[208:209]
	v_pk_fma_f32 v[128:129], v[128:129], v[194:195], v[210:211]
	global_store_dwordx4 v164, v[126:129], s[68:69] sc1
	global_load_dwordx4 v[208:211], v168, s[68:69] offset:64
	s_waitcnt vmcnt(9)
	v_pk_fma_f32 v[102:103], v[102:103], v[196:197], v[212:213]
	v_pk_fma_f32 v[104:105], v[104:105], v[198:199], v[214:215]
	global_store_dwordx4 v164, v[102:105], s[68:69] offset:64 sc1
	global_load_dwordx4 v[212:215], v169, s[68:69]
	s_waitcnt vmcnt(10)
	v_pk_fma_f32 v[122:123], v[122:123], v[192:193], v[216:217]
	v_pk_fma_f32 v[124:125], v[124:125], v[194:195], v[218:219]
	global_store_dwordx4 v165, v[122:125], s[68:69] sc1
	global_load_dwordx4 v[216:219], v169, s[68:69] offset:64
	s_waitcnt vmcnt(11)
	v_pk_fma_f32 v[90:91], v[90:91], v[196:197], v[220:221]
	v_pk_fma_f32 v[92:93], v[92:93], v[198:199], v[222:223]
	global_store_dwordx4 v165, v[90:93], s[68:69] offset:64 sc1
	global_load_dwordx4 v[220:223], v170, s[68:69]
	s_waitcnt vmcnt(12)
	v_pk_fma_f32 v[118:119], v[118:119], v[192:193], v[224:225]
	v_pk_fma_f32 v[120:121], v[120:121], v[194:195], v[226:227]
	global_store_dwordx4 v166, v[118:121], s[68:69] sc1
	global_load_dwordx4 v[224:227], v170, s[68:69] offset:64
	s_waitcnt vmcnt(13)
;     __device__ __forceinline__ void operator()(Acc& acc, int pm, int pn, int wr, int wc, int fr, int fq) const {
;     ...
;         for (int bj = 0; bj < 2; ++bj)
; #pragma unroll
;             for (int n = 0; n < 2; ++n) {
;                 const f32x4 gv = *reinterpret_cast<const f32x4*>(gp + bj * 128 + n * 16);
; #pragma unroll
;                 for (int ai = 0; ai < 2; ++ai)
; #pragma unroll
;                     for (int m = 0; m < 4; ++m) {
;                         const size_t o = (size_t)(brow + ai * 128 + wr * 64 + m * 16 + fr - rsub) * DM + c0 + bj * 128 + n * 16;
;                         const f32x4 xi = *reinterpret_cast<const f32x4*>(xin + o);
;                         const f32x4 a = acc[ai][bj][m][n];
;                         f32x4 r = {xi[0] + gv[0] * a[0], xi[1] + gv[1] * a[1], xi[2] + gv[2] * a[2], xi[3] + gv[3] * a[3]};
;                         *reinterpret_cast<f32x4*>(xout + o) = r;
;                     }
	v_pk_fma_f32 v[86:87], v[86:87], v[196:197], v[228:229]
	v_pk_fma_f32 v[88:89], v[88:89], v[198:199], v[230:231]
	global_store_dwordx4 v166, v[86:89], s[68:69] offset:64 sc1
	global_load_dwordx4 v[228:231], v171, s[68:69]
	s_waitcnt vmcnt(14)
	v_pk_fma_f32 v[114:115], v[114:115], v[192:193], v[232:233]
	v_pk_fma_f32 v[116:117], v[116:117], v[194:195], v[234:235]
	global_store_dwordx4 v167, v[114:117], s[68:69] sc1
	global_load_dwordx4 v[232:235], v171, s[68:69] offset:64
	s_waitcnt vmcnt(15)
	v_pk_fma_f32 v[82:83], v[82:83], v[196:197], v[236:237]
	v_pk_fma_f32 v[84:85], v[84:85], v[198:199], v[238:239]
	global_store_dwordx4 v167, v[82:85], s[68:69] offset:64 sc1
	global_load_dwordx4 v[236:239], v164, s[68:69] offset:512
	s_waitcnt vmcnt(16)
	v_pk_fma_f32 v[110:111], v[110:111], v[192:193], v[240:241]
	v_pk_fma_f32 v[112:113], v[112:113], v[194:195], v[242:243]
	global_store_dwordx4 v168, v[110:113], s[68:69] sc1
	global_load_dwordx4 v[240:243], v164, s[68:69] offset:576
	s_waitcnt vmcnt(16)
	v_pk_fma_f32 v[70:71], v[70:71], v[196:197], v[208:209]
	v_pk_fma_f32 v[72:73], v[72:73], v[198:199], v[210:211]
	global_store_dwordx4 v168, v[70:73], s[68:69] offset:64 sc1
	global_load_dwordx4 v[208:211], v165, s[68:69] offset:512
	s_waitcnt vmcnt(16)
	v_pk_fma_f32 v[106:107], v[106:107], v[192:193], v[212:213]
	v_pk_fma_f32 v[108:109], v[108:109], v[194:195], v[214:215]
	global_store_dwordx4 v169, v[106:109], s[68:69] sc1
	global_load_dwordx4 v[212:215], v165, s[68:69] offset:576
	s_waitcnt vmcnt(16)
	v_pk_fma_f32 v[62:63], v[62:63], v[196:197], v[216:217]
	v_pk_fma_f32 v[64:65], v[64:65], v[198:199], v[218:219]
	global_store_dwordx4 v169, v[62:65], s[68:69] offset:64 sc1
	global_load_dwordx4 v[216:219], v166, s[68:69] offset:512
	s_waitcnt vmcnt(16)
	v_pk_fma_f32 v[98:99], v[98:99], v[192:193], v[220:221]
	v_pk_fma_f32 v[100:101], v[100:101], v[194:195], v[222:223]
	global_store_dwordx4 v170, v[98:101], s[68:69] sc1
	global_load_dwordx4 v[220:223], v166, s[68:69] offset:576
	s_waitcnt vmcnt(16)
	v_pk_fma_f32 v[50:51], v[50:51], v[196:197], v[224:225]
	v_pk_fma_f32 v[52:53], v[52:53], v[198:199], v[226:227]
	global_store_dwordx4 v170, v[50:53], s[68:69] offset:64 sc1
	global_load_dwordx4 v[224:227], v167, s[68:69] offset:512
	s_waitcnt vmcnt(16)
	v_pk_fma_f32 v[94:95], v[94:95], v[192:193], v[228:229]
	v_pk_fma_f32 v[96:97], v[96:97], v[194:195], v[230:231]
	global_store_dwordx4 v171, v[94:97], s[68:69] sc1
	global_load_dwordx4 v[228:231], v167, s[68:69] offset:576
	s_waitcnt vmcnt(16)
	v_pk_fma_f32 v[42:43], v[42:43], v[196:197], v[232:233]
	v_pk_fma_f32 v[44:45], v[44:45], v[198:199], v[234:235]
	global_store_dwordx4 v171, v[42:45], s[68:69] offset:64 sc1
	global_load_dwordx4 v[232:235], v168, s[68:69] offset:512
	s_waitcnt vmcnt(16)
	v_pk_fma_f32 v[78:79], v[78:79], v[200:201], v[236:237]
	v_pk_fma_f32 v[80:81], v[80:81], v[202:203], v[238:239]
	global_store_dwordx4 v164, v[78:81], s[68:69] offset:512 sc1
	global_load_dwordx4 v[236:239], v168, s[68:69] offset:576
	s_waitcnt vmcnt(16)
	v_pk_fma_f32 v[54:55], v[54:55], v[204:205], v[240:241]
	v_pk_fma_f32 v[56:57], v[56:57], v[206:207], v[242:243]
	global_store_dwordx4 v164, v[54:57], s[68:69] offset:576 sc1
	global_load_dwordx4 v[240:243], v169, s[68:69] offset:512
	s_waitcnt vmcnt(16)
	v_pk_fma_f32 v[74:75], v[74:75], v[200:201], v[208:209]
	v_pk_fma_f32 v[76:77], v[76:77], v[202:203], v[210:211]
	global_store_dwordx4 v165, v[74:77], s[68:69] offset:512 sc1
	global_load_dwordx4 v[208:211], v169, s[68:69] offset:576
	s_waitcnt vmcnt(16)
	v_pk_fma_f32 v[46:47], v[46:47], v[204:205], v[212:213]
	v_pk_fma_f32 v[48:49], v[48:49], v[206:207], v[214:215]
	global_store_dwordx4 v165, v[46:49], s[68:69] offset:576 sc1
	global_load_dwordx4 v[212:215], v170, s[68:69] offset:512
	s_waitcnt vmcnt(16)
	v_pk_fma_f32 v[66:67], v[66:67], v[200:201], v[216:217]
	v_pk_fma_f32 v[68:69], v[68:69], v[202:203], v[218:219]
	global_store_dwordx4 v166, v[66:69], s[68:69] offset:512 sc1
	global_load_dwordx4 v[216:219], v170, s[68:69] offset:576
	s_waitcnt vmcnt(16)
	v_pk_fma_f32 v[38:39], v[38:39], v[204:205], v[220:221]
	v_pk_fma_f32 v[40:41], v[40:41], v[206:207], v[222:223]
	global_store_dwordx4 v166, v[38:41], s[68:69] offset:576 sc1
	global_load_dwordx4 v[220:223], v171, s[68:69] offset:512
	s_waitcnt vmcnt(16)
	v_pk_fma_f32 v[58:59], v[58:59], v[200:201], v[224:225]
	v_pk_fma_f32 v[60:61], v[60:61], v[202:203], v[226:227]
	global_store_dwordx4 v167, v[58:61], s[68:69] offset:512 sc1
	global_load_dwordx4 v[224:227], v171, s[68:69] offset:576
	s_waitcnt vmcnt(16)
	v_pk_fma_f32 v[34:35], v[34:35], v[204:205], v[228:229]
	v_pk_fma_f32 v[36:37], v[36:37], v[206:207], v[230:231]
	global_store_dwordx4 v167, v[34:37], s[68:69] offset:576 sc1
	s_waitcnt vmcnt(15)
	v_pk_fma_f32 v[30:31], v[30:31], v[200:201], v[232:233]
	v_pk_fma_f32 v[32:33], v[32:33], v[202:203], v[234:235]
	global_store_dwordx4 v168, v[30:33], s[68:69] offset:512 sc1
	s_waitcnt vmcnt(14)
	v_pk_fma_f32 v[14:15], v[14:15], v[204:205], v[236:237]
	v_pk_fma_f32 v[16:17], v[16:17], v[206:207], v[238:239]
	global_store_dwordx4 v168, v[14:17], s[68:69] offset:576 sc1
	s_waitcnt vmcnt(13)
	v_pk_fma_f32 v[26:27], v[26:27], v[200:201], v[240:241]
	v_pk_fma_f32 v[28:29], v[28:29], v[202:203], v[242:243]
	global_store_dwordx4 v169, v[26:29], s[68:69] offset:512 sc1
	s_waitcnt vmcnt(12)
	v_pk_fma_f32 v[10:11], v[10:11], v[204:205], v[208:209]
	v_pk_fma_f32 v[12:13], v[12:13], v[206:207], v[210:211]
	global_store_dwordx4 v169, v[10:13], s[68:69] offset:576 sc1
	s_waitcnt vmcnt(11)
	v_pk_fma_f32 v[22:23], v[22:23], v[200:201], v[212:213]
	v_pk_fma_f32 v[24:25], v[24:25], v[202:203], v[214:215]
	global_store_dwordx4 v170, v[22:25], s[68:69] offset:512 sc1
	s_waitcnt vmcnt(10)
	v_pk_fma_f32 v[6:7], v[6:7], v[204:205], v[216:217]
	v_pk_fma_f32 v[8:9], v[8:9], v[206:207], v[218:219]
	global_store_dwordx4 v170, v[6:9], s[68:69] offset:576 sc1
	s_waitcnt vmcnt(9)
	v_pk_fma_f32 v[18:19], v[18:19], v[200:201], v[220:221]
	v_pk_fma_f32 v[20:21], v[20:21], v[202:203], v[222:223]
	global_store_dwordx4 v171, v[18:21], s[68:69] offset:512 sc1
	s_waitcnt vmcnt(8)
	v_pk_fma_f32 v[2:3], v[2:3], v[204:205], v[224:225]
	v_pk_fma_f32 v[4:5], v[4:5], v[206:207], v[226:227]
	global_store_dwordx4 v171, v[2:5], s[68:69] offset:576 sc1
	s_mov_b32 s0, 0xf80b0000
	s_mov_b32 s1, -1
	s_waitcnt vmcnt(0)
	s_cbranch_scc0 .LBB0_1835
	s_barrier
